# in-projection GEMMs (k1,k8): sample rows moved to split-K LDS-reduce prepass, main GEMM exactly 3 rounds; k9 early V-fragment reads; rows sample quarter-row path
# speedup vs baseline: 1.0129x; 1.0129x over previous
.LBB1_82:
	s_load_dwordx2 s[16:17], s[0:1], 0xd8
	s_load_dwordx2 s[40:41], s[0:1], 0xd0
	v_readfirstlane_b32 s4, v0
	s_lshr_b32 s4, s4, 6
	s_and_b32 s5, s4, 3
	s_lshr_b32 s6, s4, 2
	s_mov_b32 s12, s2
	v_and_b32_e32 v202, 15, v0
	v_bfe_u32 v203, v0, 4, 2
	v_and_b32_e32 v205, 63, v0
	v_lshlrev_b32_e32 v204, 11, v202
	v_lshl_add_u32 v204, v203, 4, v204
	s_lshl_b32 s7, s5, 9
	v_add_u32_e32 v204, s7, v204
	s_lshl_b32 s7, s4, 14
	v_lshl_add_u32 v206, v205, 4, s7
	s_lshl_b32 s7, s6, 16
	s_lshl_b32 s8, s5, 12
	s_add_u32 s7, s7, s8
	v_lshl_add_u32 v207, v205, 4, s7
	s_lshl_b32 s7, s5, 4
	v_add_u32_e32 v208, s7, v202
	v_mul_u32_u24_e32 v209, 0x1800, v208
	v_lshl_add_u32 v209, v203, 3, v209
	v_lshlrev_b32_e32 v210, 11, v208
	v_lshl_add_u32 v210, v203, 4, v210
	s_waitcnt lgkmcnt(0)
.Linp1_unit:
	s_lshr_b32 s29, s12, 3
	s_cmp_lt_u32 s29, 8
	s_cbranch_scc1 .Linp1_qok
	s_cmp_le_u32 s29, 9
	s_cbranch_scc1 .Linp1_next
	s_sub_u32 s29, s29, 2
.Linp1_qok:
	s_cmp_gt_u32 s29, 23
	s_cbranch_scc1 .Linp1_next
	s_add_u32 s20, s16, 0x5100000
	s_addc_u32 s21, s17, 0
	s_add_u32 s22, s16, 0x100000
	s_addc_u32 s23, s17, 0
	s_add_u32 s24, s16, 0xd400000
	s_addc_u32 s25, s17, 0
	s_and_b32 s28, s12, 7
	s_lshl_b32 s29, s29, 1
	s_add_u32 s29, s29, s6
	s_lshr_b32 s30, s29, 3
	s_mul_i32 s28, s28, 6
	s_add_u32 s30, s30, s28
	s_and_b32 s31, s29, 7
	s_lshl_b32 s33, s31, 17
	s_lshl_b32 s34, s30, 17
	v_add_u32_e32 v194, s33, v204
	v_add_u32_e32 v198, s34, v204
	v_add_u32_e32 v195, s33, v204
	v_add_u32_e32 v199, s34, v204
	v_add_u32_e32 v196, s33, v204
	v_add_u32_e32 v200, s34, v204
	v_add_u32_e32 v197, s33, v204
	v_add_u32_e32 v201, s34, v204
	v_add_u32_e32 v195, 0x8000, v195
	v_add_u32_e32 v199, 0x8000, v199
	v_add_u32_e32 v196, 0x10000, v196
	v_add_u32_e32 v200, 0x10000, v200
	v_add_u32_e32 v197, 0x18000, v197
	v_add_u32_e32 v201, 0x18000, v201
	s_mul_i32 s33, s31, 0x60000
	s_lshl_b32 s34, s30, 7
	s_add_u32 s33, s33, s34
	v_add_u32_e32 v211, s33, v209
	s_lshr_b32 s35, s30, 3
	s_and_b32 s36, s30, 7
	s_lshl_b32 s36, s36, 8
	s_mov_b32 s37, 0x3f800000
	s_mov_b32 s42, 1
	s_cmp_eq_u32 s35, 0
	s_cselect_b32 s37, 0x3e38aa3b, s37
	s_cselect_b32 s42, 0, s42
	s_cmp_eq_u32 s35, 3
	s_cselect_b32 s37, 0x3e38aa3b, s37
	s_cselect_b32 s42, 0, s42
	s_sub_u32 s43, s35, 1
	s_cmp_gt_u32 s35, 3
	s_cselect_b32 s44, 1, 0
	s_sub_u32 s43, s43, s44
	s_lshl_b32 s43, s43, 20
	s_lshl_b32 s44, s31, 17
	s_add_u32 s43, s43, s44
	s_add_u32 s43, s43, s36
	s_add_u32 s38, s40, s43
	s_addc_u32 s39, s41, 0
	s_add_u32 s38, s38, 0xd280000
	s_addc_u32 s39, s39, 0
	global_load_dwordx4 v[66:69], v194, s[20:21] offset:0
	global_load_dwordx4 v[82:85], v198, s[22:23] offset:0
	global_load_dwordx4 v[70:73], v195, s[20:21] offset:0
	global_load_dwordx4 v[86:89], v199, s[22:23] offset:0
	global_load_dwordx4 v[74:77], v196, s[20:21] offset:0
	global_load_dwordx4 v[90:93], v200, s[22:23] offset:0
	global_load_dwordx4 v[78:81], v197, s[20:21] offset:0
	global_load_dwordx4 v[94:97], v201, s[22:23] offset:0
	global_load_dwordx4 v[98:101], v194, s[20:21] offset:64
	global_load_dwordx4 v[114:117], v198, s[22:23] offset:64
	global_load_dwordx4 v[102:105], v195, s[20:21] offset:64
	global_load_dwordx4 v[118:121], v199, s[22:23] offset:64
	global_load_dwordx4 v[106:109], v196, s[20:21] offset:64
	global_load_dwordx4 v[122:125], v200, s[22:23] offset:64
	global_load_dwordx4 v[110:113], v197, s[20:21] offset:64
	global_load_dwordx4 v[126:129], v201, s[22:23] offset:64
	global_load_dwordx4 v[130:133], v194, s[20:21] offset:128
	global_load_dwordx4 v[146:149], v198, s[22:23] offset:128
	global_load_dwordx4 v[134:137], v195, s[20:21] offset:128
	global_load_dwordx4 v[150:153], v199, s[22:23] offset:128
	global_load_dwordx4 v[138:141], v196, s[20:21] offset:128
	global_load_dwordx4 v[154:157], v200, s[22:23] offset:128
	global_load_dwordx4 v[142:145], v197, s[20:21] offset:128
	global_load_dwordx4 v[158:161], v201, s[22:23] offset:128
	global_load_dwordx4 v[162:165], v194, s[20:21] offset:192
	global_load_dwordx4 v[178:181], v198, s[22:23] offset:192
	global_load_dwordx4 v[166:169], v195, s[20:21] offset:192
	global_load_dwordx4 v[182:185], v199, s[22:23] offset:192
	global_load_dwordx4 v[170:173], v196, s[20:21] offset:192
	global_load_dwordx4 v[186:189], v200, s[22:23] offset:192
	global_load_dwordx4 v[174:177], v197, s[20:21] offset:192
	global_load_dwordx4 v[190:193], v201, s[22:23] offset:192
	s_waitcnt vmcnt(28)
	v_mfma_f32_16x16x32_bf16 v[2:5], v[82:85], v[66:69], 0
	v_mfma_f32_16x16x32_bf16 v[6:9], v[86:89], v[66:69], 0
	v_mfma_f32_16x16x32_bf16 v[18:21], v[82:85], v[70:73], 0
	v_mfma_f32_16x16x32_bf16 v[22:25], v[86:89], v[70:73], 0
	s_waitcnt vmcnt(24)
	v_mfma_f32_16x16x32_bf16 v[10:13], v[90:93], v[66:69], 0
	v_mfma_f32_16x16x32_bf16 v[14:17], v[94:97], v[66:69], 0
	v_mfma_f32_16x16x32_bf16 v[26:29], v[90:93], v[70:73], 0
	v_mfma_f32_16x16x32_bf16 v[30:33], v[94:97], v[70:73], 0
	v_mfma_f32_16x16x32_bf16 v[34:37], v[82:85], v[74:77], 0
	v_mfma_f32_16x16x32_bf16 v[38:41], v[86:89], v[74:77], 0
	v_mfma_f32_16x16x32_bf16 v[42:45], v[90:93], v[74:77], 0
	v_mfma_f32_16x16x32_bf16 v[46:49], v[94:97], v[74:77], 0
	v_mfma_f32_16x16x32_bf16 v[50:53], v[82:85], v[78:81], 0
	v_mfma_f32_16x16x32_bf16 v[54:57], v[86:89], v[78:81], 0
	v_mfma_f32_16x16x32_bf16 v[58:61], v[90:93], v[78:81], 0
	v_mfma_f32_16x16x32_bf16 v[62:65], v[94:97], v[78:81], 0
	global_load_dwordx4 v[66:69], v194, s[20:21] offset:256
	global_load_dwordx4 v[82:85], v198, s[22:23] offset:256
	global_load_dwordx4 v[70:73], v195, s[20:21] offset:256
	global_load_dwordx4 v[86:89], v199, s[22:23] offset:256
	global_load_dwordx4 v[74:77], v196, s[20:21] offset:256
	global_load_dwordx4 v[90:93], v200, s[22:23] offset:256
	global_load_dwordx4 v[78:81], v197, s[20:21] offset:256
	global_load_dwordx4 v[94:97], v201, s[22:23] offset:256
	s_waitcnt vmcnt(28)
	v_mfma_f32_16x16x32_bf16 v[2:5], v[114:117], v[98:101], v[2:5]
	v_mfma_f32_16x16x32_bf16 v[6:9], v[118:121], v[98:101], v[6:9]
	v_mfma_f32_16x16x32_bf16 v[18:21], v[114:117], v[102:105], v[18:21]
	v_mfma_f32_16x16x32_bf16 v[22:25], v[118:121], v[102:105], v[22:25]
	s_waitcnt vmcnt(24)
	v_mfma_f32_16x16x32_bf16 v[10:13], v[122:125], v[98:101], v[10:13]
	v_mfma_f32_16x16x32_bf16 v[14:17], v[126:129], v[98:101], v[14:17]
	v_mfma_f32_16x16x32_bf16 v[26:29], v[122:125], v[102:105], v[26:29]
	v_mfma_f32_16x16x32_bf16 v[30:33], v[126:129], v[102:105], v[30:33]
	v_mfma_f32_16x16x32_bf16 v[34:37], v[114:117], v[106:109], v[34:37]
	v_mfma_f32_16x16x32_bf16 v[38:41], v[118:121], v[106:109], v[38:41]
	v_mfma_f32_16x16x32_bf16 v[42:45], v[122:125], v[106:109], v[42:45]
	v_mfma_f32_16x16x32_bf16 v[46:49], v[126:129], v[106:109], v[46:49]
	v_mfma_f32_16x16x32_bf16 v[50:53], v[114:117], v[110:113], v[50:53]
	v_mfma_f32_16x16x32_bf16 v[54:57], v[118:121], v[110:113], v[54:57]
	v_mfma_f32_16x16x32_bf16 v[58:61], v[122:125], v[110:113], v[58:61]
	v_mfma_f32_16x16x32_bf16 v[62:65], v[126:129], v[110:113], v[62:65]
	global_load_dwordx4 v[98:101], v194, s[20:21] offset:320
	global_load_dwordx4 v[114:117], v198, s[22:23] offset:320
	global_load_dwordx4 v[102:105], v195, s[20:21] offset:320
	global_load_dwordx4 v[118:121], v199, s[22:23] offset:320
	global_load_dwordx4 v[106:109], v196, s[20:21] offset:320
	global_load_dwordx4 v[122:125], v200, s[22:23] offset:320
	global_load_dwordx4 v[110:113], v197, s[20:21] offset:320
	global_load_dwordx4 v[126:129], v201, s[22:23] offset:320
	s_waitcnt vmcnt(28)
	v_mfma_f32_16x16x32_bf16 v[2:5], v[146:149], v[130:133], v[2:5]
	v_mfma_f32_16x16x32_bf16 v[6:9], v[150:153], v[130:133], v[6:9]
	v_mfma_f32_16x16x32_bf16 v[18:21], v[146:149], v[134:137], v[18:21]
	v_mfma_f32_16x16x32_bf16 v[22:25], v[150:153], v[134:137], v[22:25]
	s_waitcnt vmcnt(24)
	v_mfma_f32_16x16x32_bf16 v[10:13], v[154:157], v[130:133], v[10:13]
	v_mfma_f32_16x16x32_bf16 v[14:17], v[158:161], v[130:133], v[14:17]
	v_mfma_f32_16x16x32_bf16 v[26:29], v[154:157], v[134:137], v[26:29]
	v_mfma_f32_16x16x32_bf16 v[30:33], v[158:161], v[134:137], v[30:33]
	v_mfma_f32_16x16x32_bf16 v[34:37], v[146:149], v[138:141], v[34:37]
	v_mfma_f32_16x16x32_bf16 v[38:41], v[150:153], v[138:141], v[38:41]
	v_mfma_f32_16x16x32_bf16 v[42:45], v[154:157], v[138:141], v[42:45]
	v_mfma_f32_16x16x32_bf16 v[46:49], v[158:161], v[138:141], v[46:49]
	v_mfma_f32_16x16x32_bf16 v[50:53], v[146:149], v[142:145], v[50:53]
	v_mfma_f32_16x16x32_bf16 v[54:57], v[150:153], v[142:145], v[54:57]
	v_mfma_f32_16x16x32_bf16 v[58:61], v[154:157], v[142:145], v[58:61]
	v_mfma_f32_16x16x32_bf16 v[62:65], v[158:161], v[142:145], v[62:65]
	global_load_dwordx4 v[130:133], v194, s[20:21] offset:384
	global_load_dwordx4 v[146:149], v198, s[22:23] offset:384
	global_load_dwordx4 v[134:137], v195, s[20:21] offset:384
	global_load_dwordx4 v[150:153], v199, s[22:23] offset:384
	global_load_dwordx4 v[138:141], v196, s[20:21] offset:384
	global_load_dwordx4 v[154:157], v200, s[22:23] offset:384
	global_load_dwordx4 v[142:145], v197, s[20:21] offset:384
	global_load_dwordx4 v[158:161], v201, s[22:23] offset:384
	s_waitcnt vmcnt(28)
	v_mfma_f32_16x16x32_bf16 v[2:5], v[178:181], v[162:165], v[2:5]
	v_mfma_f32_16x16x32_bf16 v[6:9], v[182:185], v[162:165], v[6:9]
	v_mfma_f32_16x16x32_bf16 v[18:21], v[178:181], v[166:169], v[18:21]
	v_mfma_f32_16x16x32_bf16 v[22:25], v[182:185], v[166:169], v[22:25]
	s_waitcnt vmcnt(24)
	v_mfma_f32_16x16x32_bf16 v[10:13], v[186:189], v[162:165], v[10:13]
	v_mfma_f32_16x16x32_bf16 v[14:17], v[190:193], v[162:165], v[14:17]
	v_mfma_f32_16x16x32_bf16 v[26:29], v[186:189], v[166:169], v[26:29]
	v_mfma_f32_16x16x32_bf16 v[30:33], v[190:193], v[166:169], v[30:33]
	v_mfma_f32_16x16x32_bf16 v[34:37], v[178:181], v[170:173], v[34:37]
	v_mfma_f32_16x16x32_bf16 v[38:41], v[182:185], v[170:173], v[38:41]
	v_mfma_f32_16x16x32_bf16 v[42:45], v[186:189], v[170:173], v[42:45]
	v_mfma_f32_16x16x32_bf16 v[46:49], v[190:193], v[170:173], v[46:49]
	v_mfma_f32_16x16x32_bf16 v[50:53], v[178:181], v[174:177], v[50:53]
	v_mfma_f32_16x16x32_bf16 v[54:57], v[182:185], v[174:177], v[54:57]
	v_mfma_f32_16x16x32_bf16 v[58:61], v[186:189], v[174:177], v[58:61]
	v_mfma_f32_16x16x32_bf16 v[62:65], v[190:193], v[174:177], v[62:65]
	global_load_dwordx4 v[162:165], v194, s[20:21] offset:448
	global_load_dwordx4 v[178:181], v198, s[22:23] offset:448
	global_load_dwordx4 v[166:169], v195, s[20:21] offset:448
	global_load_dwordx4 v[182:185], v199, s[22:23] offset:448
	global_load_dwordx4 v[170:173], v196, s[20:21] offset:448
	global_load_dwordx4 v[186:189], v200, s[22:23] offset:448
	global_load_dwordx4 v[174:177], v197, s[20:21] offset:448
	global_load_dwordx4 v[190:193], v201, s[22:23] offset:448
	s_waitcnt vmcnt(28)
	v_mfma_f32_16x16x32_bf16 v[2:5], v[82:85], v[66:69], v[2:5]
	v_mfma_f32_16x16x32_bf16 v[6:9], v[86:89], v[66:69], v[6:9]
	v_mfma_f32_16x16x32_bf16 v[18:21], v[82:85], v[70:73], v[18:21]
	v_mfma_f32_16x16x32_bf16 v[22:25], v[86:89], v[70:73], v[22:25]
	s_waitcnt vmcnt(24)
	v_mfma_f32_16x16x32_bf16 v[10:13], v[90:93], v[66:69], v[10:13]
	v_mfma_f32_16x16x32_bf16 v[14:17], v[94:97], v[66:69], v[14:17]
	v_mfma_f32_16x16x32_bf16 v[26:29], v[90:93], v[70:73], v[26:29]
	v_mfma_f32_16x16x32_bf16 v[30:33], v[94:97], v[70:73], v[30:33]
	v_mfma_f32_16x16x32_bf16 v[34:37], v[82:85], v[74:77], v[34:37]
	v_mfma_f32_16x16x32_bf16 v[38:41], v[86:89], v[74:77], v[38:41]
	v_mfma_f32_16x16x32_bf16 v[42:45], v[90:93], v[74:77], v[42:45]
	v_mfma_f32_16x16x32_bf16 v[46:49], v[94:97], v[74:77], v[46:49]
	v_mfma_f32_16x16x32_bf16 v[50:53], v[82:85], v[78:81], v[50:53]
	v_mfma_f32_16x16x32_bf16 v[54:57], v[86:89], v[78:81], v[54:57]
	v_mfma_f32_16x16x32_bf16 v[58:61], v[90:93], v[78:81], v[58:61]
	v_mfma_f32_16x16x32_bf16 v[62:65], v[94:97], v[78:81], v[62:65]
	s_waitcnt vmcnt(20)
	v_mfma_f32_16x16x32_bf16 v[2:5], v[114:117], v[98:101], v[2:5]
	v_mfma_f32_16x16x32_bf16 v[6:9], v[118:121], v[98:101], v[6:9]
	v_mfma_f32_16x16x32_bf16 v[18:21], v[114:117], v[102:105], v[18:21]
	v_mfma_f32_16x16x32_bf16 v[22:25], v[118:121], v[102:105], v[22:25]
	s_waitcnt vmcnt(16)
	v_mfma_f32_16x16x32_bf16 v[10:13], v[122:125], v[98:101], v[10:13]
	v_mfma_f32_16x16x32_bf16 v[14:17], v[126:129], v[98:101], v[14:17]
	v_mfma_f32_16x16x32_bf16 v[26:29], v[122:125], v[102:105], v[26:29]
	v_mfma_f32_16x16x32_bf16 v[30:33], v[126:129], v[102:105], v[30:33]
	v_mfma_f32_16x16x32_bf16 v[34:37], v[114:117], v[106:109], v[34:37]
	v_mfma_f32_16x16x32_bf16 v[38:41], v[118:121], v[106:109], v[38:41]
	v_mfma_f32_16x16x32_bf16 v[42:45], v[122:125], v[106:109], v[42:45]
	v_mfma_f32_16x16x32_bf16 v[46:49], v[126:129], v[106:109], v[46:49]
	v_mfma_f32_16x16x32_bf16 v[50:53], v[114:117], v[110:113], v[50:53]
	v_mfma_f32_16x16x32_bf16 v[54:57], v[118:121], v[110:113], v[54:57]
	v_mfma_f32_16x16x32_bf16 v[58:61], v[122:125], v[110:113], v[58:61]
	v_mfma_f32_16x16x32_bf16 v[62:65], v[126:129], v[110:113], v[62:65]
	s_waitcnt vmcnt(12)
	v_mfma_f32_16x16x32_bf16 v[2:5], v[146:149], v[130:133], v[2:5]
	v_mfma_f32_16x16x32_bf16 v[6:9], v[150:153], v[130:133], v[6:9]
	v_mfma_f32_16x16x32_bf16 v[18:21], v[146:149], v[134:137], v[18:21]
	v_mfma_f32_16x16x32_bf16 v[22:25], v[150:153], v[134:137], v[22:25]
	s_waitcnt vmcnt(8)
	v_mfma_f32_16x16x32_bf16 v[10:13], v[154:157], v[130:133], v[10:13]
	v_mfma_f32_16x16x32_bf16 v[14:17], v[158:161], v[130:133], v[14:17]
	v_mfma_f32_16x16x32_bf16 v[26:29], v[154:157], v[134:137], v[26:29]
	v_mfma_f32_16x16x32_bf16 v[30:33], v[158:161], v[134:137], v[30:33]
	v_mfma_f32_16x16x32_bf16 v[34:37], v[146:149], v[138:141], v[34:37]
	v_mfma_f32_16x16x32_bf16 v[38:41], v[150:153], v[138:141], v[38:41]
	v_mfma_f32_16x16x32_bf16 v[42:45], v[154:157], v[138:141], v[42:45]
	v_mfma_f32_16x16x32_bf16 v[46:49], v[158:161], v[138:141], v[46:49]
	v_mfma_f32_16x16x32_bf16 v[50:53], v[146:149], v[142:145], v[50:53]
	v_mfma_f32_16x16x32_bf16 v[54:57], v[150:153], v[142:145], v[54:57]
	v_mfma_f32_16x16x32_bf16 v[58:61], v[154:157], v[142:145], v[58:61]
	v_mfma_f32_16x16x32_bf16 v[62:65], v[158:161], v[142:145], v[62:65]
	s_waitcnt vmcnt(4)
	v_mfma_f32_16x16x32_bf16 v[2:5], v[178:181], v[162:165], v[2:5]
	v_mfma_f32_16x16x32_bf16 v[6:9], v[182:185], v[162:165], v[6:9]
	v_mfma_f32_16x16x32_bf16 v[18:21], v[178:181], v[166:169], v[18:21]
	v_mfma_f32_16x16x32_bf16 v[22:25], v[182:185], v[166:169], v[22:25]
	s_waitcnt vmcnt(0)
	v_mfma_f32_16x16x32_bf16 v[10:13], v[186:189], v[162:165], v[10:13]
	v_mfma_f32_16x16x32_bf16 v[14:17], v[190:193], v[162:165], v[14:17]
	v_mfma_f32_16x16x32_bf16 v[26:29], v[186:189], v[166:169], v[26:29]
	v_mfma_f32_16x16x32_bf16 v[30:33], v[190:193], v[166:169], v[30:33]
	v_mfma_f32_16x16x32_bf16 v[34:37], v[178:181], v[170:173], v[34:37]
	v_mfma_f32_16x16x32_bf16 v[38:41], v[182:185], v[170:173], v[38:41]
	v_mfma_f32_16x16x32_bf16 v[42:45], v[186:189], v[170:173], v[42:45]
	v_mfma_f32_16x16x32_bf16 v[46:49], v[190:193], v[170:173], v[46:49]
	v_mfma_f32_16x16x32_bf16 v[50:53], v[178:181], v[174:177], v[50:53]
	v_mfma_f32_16x16x32_bf16 v[54:57], v[182:185], v[174:177], v[54:57]
	v_mfma_f32_16x16x32_bf16 v[58:61], v[186:189], v[174:177], v[58:61]
	v_mfma_f32_16x16x32_bf16 v[62:65], v[190:193], v[174:177], v[62:65]
	s_nop 7
	ds_write_b128 v206, v[2:5] offset:0
	ds_write_b128 v206, v[6:9] offset:1024
	ds_write_b128 v206, v[10:13] offset:2048
	ds_write_b128 v206, v[14:17] offset:3072
	ds_write_b128 v206, v[18:21] offset:4096
	ds_write_b128 v206, v[22:25] offset:5120
	ds_write_b128 v206, v[26:29] offset:6144
	ds_write_b128 v206, v[30:33] offset:7168
	ds_write_b128 v206, v[34:37] offset:8192
	ds_write_b128 v206, v[38:41] offset:9216
	ds_write_b128 v206, v[42:45] offset:10240
	ds_write_b128 v206, v[46:49] offset:11264
	ds_write_b128 v206, v[50:53] offset:12288
	ds_write_b128 v206, v[54:57] offset:13312
	ds_write_b128 v206, v[58:61] offset:14336
	ds_write_b128 v206, v[62:65] offset:15360
	s_waitcnt lgkmcnt(0)
	s_barrier
	ds_read_b128 v[2:5], v207 offset:0
	ds_read_b128 v[6:9], v207 offset:16384
	ds_read_b128 v[10:13], v207 offset:32768
	ds_read_b128 v[14:17], v207 offset:49152
	ds_read_b128 v[18:21], v207 offset:1024
	ds_read_b128 v[22:25], v207 offset:17408
	ds_read_b128 v[26:29], v207 offset:33792
	ds_read_b128 v[30:33], v207 offset:50176
	ds_read_b128 v[34:37], v207 offset:2048
	ds_read_b128 v[38:41], v207 offset:18432
	ds_read_b128 v[42:45], v207 offset:34816
	ds_read_b128 v[46:49], v207 offset:51200
	ds_read_b128 v[50:53], v207 offset:3072
	ds_read_b128 v[54:57], v207 offset:19456
	ds_read_b128 v[58:61], v207 offset:35840
	ds_read_b128 v[62:65], v207 offset:52224
	s_waitcnt lgkmcnt(12)
	v_add_f32_e32 v2, v2, v6
	v_add_f32_e32 v3, v3, v7
	v_add_f32_e32 v4, v4, v8
	v_add_f32_e32 v5, v5, v9
	v_add_f32_e32 v10, v10, v14
	v_add_f32_e32 v11, v11, v15
	v_add_f32_e32 v12, v12, v16
	v_add_f32_e32 v13, v13, v17
	v_add_f32_e32 v2, v2, v10
	v_add_f32_e32 v3, v3, v11
	v_add_f32_e32 v4, v4, v12
	v_add_f32_e32 v5, v5, v13
	s_waitcnt lgkmcnt(8)
	v_add_f32_e32 v18, v18, v22
	v_add_f32_e32 v19, v19, v23
	v_add_f32_e32 v20, v20, v24
	v_add_f32_e32 v21, v21, v25
	v_add_f32_e32 v26, v26, v30
	v_add_f32_e32 v27, v27, v31
	v_add_f32_e32 v28, v28, v32
	v_add_f32_e32 v29, v29, v33
	v_add_f32_e32 v18, v18, v26
	v_add_f32_e32 v19, v19, v27
	v_add_f32_e32 v20, v20, v28
	v_add_f32_e32 v21, v21, v29
	s_waitcnt lgkmcnt(4)
	v_add_f32_e32 v34, v34, v38
	v_add_f32_e32 v35, v35, v39
	v_add_f32_e32 v36, v36, v40
	v_add_f32_e32 v37, v37, v41
	v_add_f32_e32 v42, v42, v46
	v_add_f32_e32 v43, v43, v47
	v_add_f32_e32 v44, v44, v48
	v_add_f32_e32 v45, v45, v49
	v_add_f32_e32 v34, v34, v42
	v_add_f32_e32 v35, v35, v43
	v_add_f32_e32 v36, v36, v44
	v_add_f32_e32 v37, v37, v45
	s_waitcnt lgkmcnt(0)
	v_add_f32_e32 v50, v50, v54
	v_add_f32_e32 v51, v51, v55
	v_add_f32_e32 v52, v52, v56
	v_add_f32_e32 v53, v53, v57
	v_add_f32_e32 v58, v58, v62
	v_add_f32_e32 v59, v59, v63
	v_add_f32_e32 v60, v60, v64
	v_add_f32_e32 v61, v61, v65
	v_add_f32_e32 v50, v50, v58
	v_add_f32_e32 v51, v51, v59
	v_add_f32_e32 v52, v52, v60
	v_add_f32_e32 v53, v53, v61
	s_cmp_eq_u32 s42, 0
	s_cbranch_scc1 .Linp1_nof32
	global_store_dwordx4 v210, v[2:5], s[38:39] offset:0
	global_store_dwordx4 v210, v[18:21], s[38:39] offset:64
	global_store_dwordx4 v210, v[34:37], s[38:39] offset:128
	global_store_dwordx4 v210, v[50:53], s[38:39] offset:192
	s_nop 1
.Linp1_nof32:
	v_mul_f32_e32 v2, s37, v2
	v_mul_f32_e32 v3, s37, v3
	v_mul_f32_e32 v4, s37, v4
	v_mul_f32_e32 v5, s37, v5
	v_cvt_pk_bf16_f32 v212, v2, v3
	v_cvt_pk_bf16_f32 v213, v4, v5
	global_store_dwordx2 v211, v[212:213], s[24:25] offset:0
	v_mul_f32_e32 v18, s37, v18
	v_mul_f32_e32 v19, s37, v19
	v_mul_f32_e32 v20, s37, v20
	v_mul_f32_e32 v21, s37, v21
	v_cvt_pk_bf16_f32 v214, v18, v19
	v_cvt_pk_bf16_f32 v215, v20, v21
	global_store_dwordx2 v211, v[214:215], s[24:25] offset:32
	v_mul_f32_e32 v34, s37, v34
	v_mul_f32_e32 v35, s37, v35
	v_mul_f32_e32 v36, s37, v36
	v_mul_f32_e32 v37, s37, v37
	v_cvt_pk_bf16_f32 v216, v34, v35
	v_cvt_pk_bf16_f32 v217, v36, v37
	global_store_dwordx2 v211, v[216:217], s[24:25] offset:64
	v_mul_f32_e32 v50, s37, v50
	v_mul_f32_e32 v51, s37, v51
	v_mul_f32_e32 v52, s37, v52
	v_mul_f32_e32 v53, s37, v53
	v_cvt_pk_bf16_f32 v218, v50, v51
	v_cvt_pk_bf16_f32 v219, v52, v53
	global_store_dwordx2 v211, v[218:219], s[24:25] offset:96
	s_barrier
.Linp1_next:
	s_add_i32 s12, s12, s3
	s_cmpk_lt_u32 s12, 0x100
	s_cbranch_scc1 .Linp1_unit
	s_load_dwordx2 s[20:21], s[0:1], 0xd8
	s_waitcnt lgkmcnt(0)
	s_cmpk_lt_i32 s2, 0x300
	s_barrier
	s_cselect_b64 s[6:7], -1, 0
	s_cmpk_gt_i32 s2, 0x2ff
	v_readfirstlane_b32 s14, v0
	s_cbranch_scc0 .LBB1_85
	s_andn2_b64 vcc, exec, s[6:7]
	s_cbranch_vccz .LBB1_86

.LBB1_85:
	s_ashr_i32 s4, s2, 31
	s_lshr_b32 s4, s4, 29
	s_add_i32 s4, s2, s4
	s_ashr_i32 s5, s4, 3
	s_and_b32 s4, s4, -8
	s_sub_i32 s4, s2, s4
	s_cmp_lt_i32 s4, 0
	s_movk_i32 s8, 0x61
	s_cselect_b32 s8, s8, 0x60
	s_mul_i32 s4, s4, s8
	s_add_i32 s4, s4, s5
	s_mul_hi_i32 s5, s4, 0x2aaaaaab
	s_lshr_b32 s8, s5, 31
	s_ashr_i32 s5, s5, 4
	s_add_i32 s5, s5, s8
	s_lshl_b32 s8, s5, 3
	s_sub_i32 s9, 0x40, s8
	s_min_u32 s9, s9, 8
	s_mulk_i32 s5, 0x60
	s_sub_i32 s10, s4, s5
	v_cvt_f32_ubyte0_e32 v2, s9
	v_cvt_f32_i32_e32 v1, s10
	v_rcp_iflag_f32_e32 v3, v2
	s_ashr_i32 s4, s10, 30
	s_or_b32 s11, s4, 1
	v_mul_f32_e32 v3, v1, v3
	v_trunc_f32_e32 v3, v3
	v_fma_f32 v1, -v3, v2, v1
	v_cvt_i32_f32_e32 v3, v3
	v_cmp_ge_f32_e64 s[4:5], |v1|, v2
	s_and_b64 s[4:5], s[4:5], exec
	s_cselect_b32 s4, s11, 0
	v_readfirstlane_b32 s5, v3
	s_add_i32 s4, s5, s4
	s_sext_i32_i8 s24, s4
	s_mul_i32 s4, s4, s9
	s_sub_i32 s4, s10, s4
	s_sext_i32_i8 s4, s4
	s_add_i32 s4, s8, s4
	s_andn2_b64 vcc, exec, s[6:7]
	s_cbranch_vccnz .LBB1_84

.LBB1_88:
	s_lshl_b32 s0, s12, 5
	s_mov_b64 s[12:13], 0x80
	s_lshl_b32 s42, s8, 6
	s_lshl_b32 s5, s8, 13
	s_and_b32 s8, s0, 0x60
	s_add_i32 m0, s38, 0x18000
	v_lshl_add_u64 v[8:9], v[8:9], 0, s[12:13]
	s_lshl_b32 s15, s8, 7
	s_waitcnt vmcnt(2)
	s_barrier
	global_load_lds_dwordx4 v[8:9], off
	v_lshl_add_u64 v[6:7], v[6:7], 0, s[12:13]
	s_add_i32 m0, s38, 0x1a000
	s_add_i32 s43, s38, 0x8000
	s_add_i32 s44, s38, 0xa000
	global_load_lds_dwordx4 v[6:7], off
	v_lshl_add_u64 v[2:3], v[2:3], 0, s[12:13]
	s_mov_b32 m0, s43
	s_add_u32 s0, s28, 0x40080
	global_load_lds_dwordx4 v[2:3], off
	v_lshl_add_u64 v[2:3], v[4:5], 0, s[12:13]
	s_mov_b32 m0, s44
	s_addc_u32 s1, s29, 0
	global_load_lds_dwordx4 v[2:3], off
	s_add_i32 m0, s38, 0x1c000
	v_lshl_add_u64 v[2:3], s[0:1], 0, v[130:131]
	global_load_lds_dwordx4 v[2:3], off
	v_lshl_add_u64 v[2:3], s[0:1], 0, v[134:135]
	s_add_i32 m0, s38, 0x1e000
	s_cmpk_lt_u32 s14, 0x100
	global_load_lds_dwordx4 v[2:3], off
	v_bfe_u32 v3, v0, 4, 2
	v_and_b32_e32 v2, 15, v0
	v_lshlrev_b32_e32 v4, 4, v3
	v_lshlrev_b32_e32 v0, 2, v0
	v_lshl_or_b32 v5, v2, 6, v4
	v_and_b32_e32 v0, 32, v0
	v_bitop3_b32 v6, v5, s5, v0 bitop3:0xde
	v_bitop3_b32 v152, v5, s15, v0 bitop3:0xde
	v_lshlrev_b32_e32 v0, 11, v2
	v_lshl_or_b32 v136, v3, 5, v0
	v_mul_u32_u24_e32 v0, 0x1800, v2
	v_or_b32_e32 v2, v4, v0
	v_lshlrev_b32_e32 v0, 14, v1
	v_and_b32_e32 v0, 0xffff8000, v0
	v_lshl_add_u32 v0, v10, 11, v0
	v_and_b32_e32 v1, 1, v1
	v_lshl_or_b32 v0, v1, 6, v0
	v_lshl_add_u32 v140, v11, 1, v0
	v_lshlrev_b32_e32 v0, 14, v12
	v_and_b32_e32 v0, 0xffff8000, v0
	s_waitcnt vmcnt(6)
	v_mov_b32_e32 v3, v131
	v_lshl_add_u32 v0, v13, 11, v0
	v_and_b32_e32 v1, 1, v12
	s_cselect_b64 s[14:15], -1, 0
	v_lshl_add_u64 v[2:3], s[20:21], 0, v[2:3]
	s_mov_b64 s[0:1], 0x7400000
	v_lshl_or_b32 v0, v1, 6, v0
	s_add_i32 s48, 0, 0x10000
	s_add_i32 s49, 0, 0x14000
	v_mov_b32_e32 v137, v131
	s_ashr_i32 s45, s3, 31
	s_ashr_i32 s46, s2, 31
	v_lshl_add_u64 v[138:139], v[2:3], 0, s[0:1]
	v_mov_b32_e32 v141, v131
	v_lshl_add_u32 v142, v14, 1, v0
	v_mov_b32_e32 v143, v131
	v_mov_b64_e32 v[144:145], 0x300
	v_mov_b64_e32 v[146:147], 0x2ff
	s_movk_i32 s47, 0x61
	v_add_u32_e32 v153, s48, v152
	v_add_u32_e32 v154, s49, v152
	v_add_u32_e32 v155, 0, v6
	s_mov_b32 s50, 0x3520000
	s_mov_b32 s51, s9
	s_barrier
	s_branch .LBB1_91

.LBB1_91:
	s_add_i32 s51, s51, 1
	s_mul_i32 s0, s51, s45
	s_mul_hi_u32 s1, s51, s3
	s_add_i32 s1, s1, s0
	s_mul_i32 s0, s51, s3
	s_add_u32 s20, s0, s2
	s_addc_u32 s21, s1, s46
	v_cmp_gt_i64_e32 vcc, s[20:21], v[146:147]
	v_cmp_lt_i64_e64 s[0:1], s[20:21], v[144:145]
	s_cbranch_vccnz .LBB1_93
	s_ashr_i32 s5, s20, 31
	s_lshr_b32 s5, s5, 29
	s_add_i32 s5, s20, s5
	s_ashr_i32 s16, s5, 3
	s_and_b32 s5, s5, -8
	s_sub_i32 s5, s20, s5
	s_cmp_lt_i32 s5, 0
	s_cselect_b32 s17, s47, 0x60
	s_mul_i32 s5, s5, s17
	s_add_i32 s5, s5, s16
	s_mul_hi_i32 s16, s5, 0x2aaaaaab
	s_lshr_b32 s17, s16, 31
	s_ashr_i32 s16, s16, 4
	s_add_i32 s16, s16, s17
	s_lshl_b32 s17, s16, 3
	s_sub_i32 s18, 0x40, s17
	s_min_i32 s18, s18, 8
	s_abs_i32 s19, s18
	v_cvt_f32_u32_e32 v0, s19
	s_sub_i32 s21, 0, s19
	s_mulk_i32 s16, 0x60
	s_sub_i32 s5, s5, s16
	v_rcp_iflag_f32_e32 v0, v0
	s_abs_i32 s16, s5
	s_xor_b32 s20, s5, s18
	s_ashr_i32 s20, s20, 31
	v_mul_f32_e32 v0, 0x4f7ffffe, v0
	v_cvt_u32_f32_e32 v0, v0
	s_nop 0
	v_readfirstlane_b32 s22, v0
	s_mul_i32 s21, s21, s22
	s_mul_hi_u32 s21, s22, s21
	s_add_i32 s22, s22, s21
	s_mul_hi_u32 s21, s16, s22
	s_mul_i32 s22, s21, s19
	s_sub_i32 s16, s16, s22
	s_add_i32 s23, s21, 1
	s_sub_i32 s22, s16, s19
	s_cmp_ge_u32 s16, s19
	s_cselect_b32 s21, s23, s21
	s_cselect_b32 s16, s22, s16
	s_add_i32 s22, s21, 1
	s_cmp_ge_u32 s16, s19
	s_cselect_b32 s16, s22, s21
	s_xor_b32 s16, s16, s20
	s_sub_i32 s16, s16, s20
	s_mul_i32 s18, s16, s18
	s_sub_i32 s5, s5, s18
	s_add_i32 s18, s17, s5

_Z10fwd_kernelILi4ELi5EEv4Args:
	s_load_dword s3, s[0:1], 0xe8
	s_load_dwordx4 s[4:7], s[0:1], 0xd0
	s_load_dwordx2 s[8:9], s[0:1], 0xa8
	s_load_dwordx2 s[10:11], s[0:1], 0xb0
	s_load_dwordx4 s[12:15], s[0:1], 0x0
	s_waitcnt lgkmcnt(0)
	s_cmp_lg_u32 s3, 0x100
	s_cbranch_scc1 .Lrows4_orig
	v_readfirstlane_b32 s16, v0
	s_lshr_b32 s16, s16, 6
	s_lshl_b32 s18, s2, 3
	s_add_u32 s16, s16, s18
	s_mov_b32 s17, 0x3a800000
	v_mov_b32_e32 v3, 0x358637bd
	v_and_b32_e32 v10, 63, v0
	v_lshlrev_b32_e32 v1, 4, v10
	v_lshlrev_b32_e32 v2, 3, v10
	v_xor_b32_e32 v4, 1, v10
	v_xor_b32_e32 v5, 2, v10
	v_xor_b32_e32 v6, 4, v10
	v_xor_b32_e32 v7, 8, v10
	v_xor_b32_e32 v8, 16, v10
	v_xor_b32_e32 v9, 32, v10
	v_lshlrev_b32_e32 v4, 2, v4
	v_lshlrev_b32_e32 v5, 2, v5
	v_lshlrev_b32_e32 v6, 2, v6
	v_lshlrev_b32_e32 v7, 2, v7
	v_lshlrev_b32_e32 v8, 2, v8
	v_lshlrev_b32_e32 v9, 2, v9
	global_load_dwordx4 v[20:23], v1, s[8:9] offset:0
	global_load_dwordx4 v[24:27], v1, s[8:9] offset:1024
	global_load_dwordx4 v[28:31], v1, s[8:9] offset:2048
	global_load_dwordx4 v[32:35], v1, s[8:9] offset:3072
	global_load_dwordx4 v[36:39], v1, s[10:11] offset:0
	global_load_dwordx4 v[40:43], v1, s[10:11] offset:1024
	global_load_dwordx4 v[44:47], v1, s[10:11] offset:2048
	global_load_dwordx4 v[48:51], v1, s[10:11] offset:3072
	s_lshr_b32 s54, s16, 2
	s_and_b32 s55, s16, 3
	s_lshl_b32 s55, s55, 10
	s_lshl_b32 s18, s54, 12
	s_add_u32 s18, s18, s55
	s_add_u32 s56, s6, s18
	s_addc_u32 s57, s7, 0
	s_add_u32 s56, s56, 0x7400000
	s_addc_u32 s57, s57, 0
	global_load_dwordx4 v[208:211], v1, s[56:57]
	s_add_u32 s56, s56, 0x200000
	s_addc_u32 s57, s57, 0
	global_load_dwordx4 v[212:215], v1, s[56:57]
	s_add_u32 s56, s14, s18
	s_addc_u32 s57, s15, 0
	global_load_dwordx4 v[240:243], v1, s[56:57]
	s_add_u32 s56, s8, s55
	s_addc_u32 s57, s9, 0
	global_load_dwordx4 v[244:247], v1, s[56:57]
	s_add_u32 s56, s10, s55
	s_addc_u32 s57, s11, 0
	global_load_dwordx4 v[248:251], v1, s[56:57]
	s_add_u32 s53, s16, 0x0
	s_lshl_b32 s18, s53, 12
	s_lshl_b32 s19, s53, 11
	s_add_u32 s20, s12, s18
	s_addc_u32 s21, s13, 0
	s_add_u32 s22, s6, s19
	s_addc_u32 s23, s7, 0
	s_add_u32 s22, s22, 0x5200000
	s_addc_u32 s23, s23, 0
	s_add_u32 s24, s4, s18
	s_addc_u32 s25, s5, 0
	s_add_u32 s26, s6, s19
	s_addc_u32 s27, s7, 0
	s_add_u32 s26, s26, 0x3100000
	s_addc_u32 s27, s27, 0
	global_load_dwordx2 v[66:67], v2, s[22:23] offset:0
	global_load_dwordx2 v[70:71], v2, s[22:23] offset:512
	global_load_dwordx2 v[74:75], v2, s[22:23] offset:1024
	global_load_dwordx2 v[78:79], v2, s[22:23] offset:1536
	global_load_dwordx4 v[80:83], v1, s[20:21] offset:0
	global_load_dwordx4 v[84:87], v1, s[20:21] offset:1024
	global_load_dwordx4 v[88:91], v1, s[20:21] offset:2048
	global_load_dwordx4 v[92:95], v1, s[20:21] offset:3072
	s_add_u32 s53, s16, 0x800
	s_lshl_b32 s18, s53, 12
	s_lshl_b32 s19, s53, 11
	s_add_u32 s28, s12, s18
	s_addc_u32 s29, s13, 0
	s_add_u32 s30, s6, s19
	s_addc_u32 s31, s7, 0
	s_add_u32 s30, s30, 0x5200000
	s_addc_u32 s31, s31, 0
	s_add_u32 s32, s4, s18
	s_addc_u32 s33, s5, 0
	s_add_u32 s34, s6, s19
	s_addc_u32 s35, s7, 0
	s_add_u32 s34, s34, 0x3100000
	s_addc_u32 s35, s35, 0
	global_load_dwordx2 v[98:99], v2, s[30:31] offset:0
	global_load_dwordx2 v[102:103], v2, s[30:31] offset:512
	global_load_dwordx2 v[106:107], v2, s[30:31] offset:1024
	global_load_dwordx2 v[110:111], v2, s[30:31] offset:1536
	global_load_dwordx4 v[112:115], v1, s[28:29] offset:0
	global_load_dwordx4 v[116:119], v1, s[28:29] offset:1024
	global_load_dwordx4 v[120:123], v1, s[28:29] offset:2048
	global_load_dwordx4 v[124:127], v1, s[28:29] offset:3072
	s_add_u32 s53, s16, 0x1000
	s_lshl_b32 s18, s53, 12
	s_lshl_b32 s19, s53, 11
	s_add_u32 s36, s12, s18
	s_addc_u32 s37, s13, 0
	s_add_u32 s38, s6, s19
	s_addc_u32 s39, s7, 0
	s_add_u32 s38, s38, 0x5200000
	s_addc_u32 s39, s39, 0
	s_add_u32 s40, s4, s18
	s_addc_u32 s41, s5, 0
	s_add_u32 s42, s6, s19
	s_addc_u32 s43, s7, 0
	s_add_u32 s42, s42, 0x3100000
	s_addc_u32 s43, s43, 0
	global_load_dwordx2 v[130:131], v2, s[38:39] offset:0
	global_load_dwordx2 v[134:135], v2, s[38:39] offset:512
	global_load_dwordx2 v[138:139], v2, s[38:39] offset:1024
	global_load_dwordx2 v[142:143], v2, s[38:39] offset:1536
	global_load_dwordx4 v[144:147], v1, s[36:37] offset:0
	global_load_dwordx4 v[148:151], v1, s[36:37] offset:1024
	global_load_dwordx4 v[152:155], v1, s[36:37] offset:2048
	global_load_dwordx4 v[156:159], v1, s[36:37] offset:3072
	s_add_u32 s53, s16, 0x1800
	s_lshl_b32 s18, s53, 12
	s_lshl_b32 s19, s53, 11
	s_add_u32 s44, s12, s18
	s_addc_u32 s45, s13, 0
	s_add_u32 s46, s6, s19
	s_addc_u32 s47, s7, 0
	s_add_u32 s46, s46, 0x5200000
	s_addc_u32 s47, s47, 0
	s_add_u32 s48, s4, s18
	s_addc_u32 s49, s5, 0
	s_add_u32 s50, s6, s19
	s_addc_u32 s51, s7, 0
	s_add_u32 s50, s50, 0x3100000
	s_addc_u32 s51, s51, 0
	global_load_dwordx2 v[162:163], v2, s[46:47] offset:0
	global_load_dwordx2 v[166:167], v2, s[46:47] offset:512
	global_load_dwordx2 v[170:171], v2, s[46:47] offset:1024
	global_load_dwordx2 v[174:175], v2, s[46:47] offset:1536
	global_load_dwordx4 v[176:179], v1, s[44:45] offset:0
	global_load_dwordx4 v[180:183], v1, s[44:45] offset:1024
	global_load_dwordx4 v[184:187], v1, s[44:45] offset:2048
	global_load_dwordx4 v[188:191], v1, s[44:45] offset:3072
	s_waitcnt vmcnt(16)
	v_lshlrev_b32_e32 v64, 16, v66
	v_and_b32_e32 v65, 0xffff0000, v66
	v_lshlrev_b32_e32 v66, 16, v67
	v_and_b32_e32 v67, 0xffff0000, v67
	v_lshlrev_b32_e32 v68, 16, v70
	v_and_b32_e32 v69, 0xffff0000, v70
	v_lshlrev_b32_e32 v70, 16, v71
	v_and_b32_e32 v71, 0xffff0000, v71
	v_lshlrev_b32_e32 v72, 16, v74
	v_and_b32_e32 v73, 0xffff0000, v74
	v_lshlrev_b32_e32 v74, 16, v75
	v_and_b32_e32 v75, 0xffff0000, v75
	v_lshlrev_b32_e32 v76, 16, v78
	v_and_b32_e32 v77, 0xffff0000, v78
	v_lshlrev_b32_e32 v78, 16, v79
	v_and_b32_e32 v79, 0xffff0000, v79
	v_lshlrev_b32_e32 v96, 16, v98
	v_and_b32_e32 v97, 0xffff0000, v98
	v_lshlrev_b32_e32 v98, 16, v99
	v_and_b32_e32 v99, 0xffff0000, v99
	v_lshlrev_b32_e32 v100, 16, v102
	v_and_b32_e32 v101, 0xffff0000, v102
	v_lshlrev_b32_e32 v102, 16, v103
	v_and_b32_e32 v103, 0xffff0000, v103
	v_lshlrev_b32_e32 v104, 16, v106
	v_and_b32_e32 v105, 0xffff0000, v106
	v_lshlrev_b32_e32 v106, 16, v107
	v_and_b32_e32 v107, 0xffff0000, v107
	v_lshlrev_b32_e32 v108, 16, v110
	v_and_b32_e32 v109, 0xffff0000, v110
	v_lshlrev_b32_e32 v110, 16, v111
	v_and_b32_e32 v111, 0xffff0000, v111
	v_mul_f32_e32 v10, v64, v64
	v_fmac_f32_e32 v10, v65, v65
	v_fmac_f32_e32 v10, v66, v66
	v_fmac_f32_e32 v10, v67, v67
	v_fmac_f32_e32 v10, v68, v68
	v_fmac_f32_e32 v10, v69, v69
	v_fmac_f32_e32 v10, v70, v70
	v_fmac_f32_e32 v10, v71, v71
	v_fmac_f32_e32 v10, v72, v72
	v_fmac_f32_e32 v10, v73, v73
	v_fmac_f32_e32 v10, v74, v74
	v_fmac_f32_e32 v10, v75, v75
	v_fmac_f32_e32 v10, v76, v76
	v_fmac_f32_e32 v10, v77, v77
	v_fmac_f32_e32 v10, v78, v78
	v_fmac_f32_e32 v10, v79, v79
	v_mul_f32_e32 v11, v96, v96
	v_fmac_f32_e32 v11, v97, v97
	v_fmac_f32_e32 v11, v98, v98
	v_fmac_f32_e32 v11, v99, v99
	v_fmac_f32_e32 v11, v100, v100
	v_fmac_f32_e32 v11, v101, v101
	v_fmac_f32_e32 v11, v102, v102
	v_fmac_f32_e32 v11, v103, v103
	v_fmac_f32_e32 v11, v104, v104
	v_fmac_f32_e32 v11, v105, v105
	v_fmac_f32_e32 v11, v106, v106
	v_fmac_f32_e32 v11, v107, v107
	v_fmac_f32_e32 v11, v108, v108
	v_fmac_f32_e32 v11, v109, v109
	v_fmac_f32_e32 v11, v110, v110
	v_fmac_f32_e32 v11, v111, v111
	ds_bpermute_b32 v12, v4, v10
	ds_bpermute_b32 v13, v4, v11
	s_waitcnt lgkmcnt(0)
	v_add_f32_e32 v10, v10, v12
	v_add_f32_e32 v11, v11, v13
	ds_bpermute_b32 v12, v5, v10
	ds_bpermute_b32 v13, v5, v11
	s_waitcnt lgkmcnt(0)
	v_add_f32_e32 v10, v10, v12
	v_add_f32_e32 v11, v11, v13
	ds_bpermute_b32 v12, v6, v10
	ds_bpermute_b32 v13, v6, v11
	s_waitcnt lgkmcnt(0)
	v_add_f32_e32 v10, v10, v12
	v_add_f32_e32 v11, v11, v13
	ds_bpermute_b32 v12, v7, v10
	ds_bpermute_b32 v13, v7, v11
	s_waitcnt lgkmcnt(0)
	v_add_f32_e32 v10, v10, v12
	v_add_f32_e32 v11, v11, v13
	ds_bpermute_b32 v12, v8, v10
	ds_bpermute_b32 v13, v8, v11
	s_waitcnt lgkmcnt(0)
	v_add_f32_e32 v10, v10, v12
	v_add_f32_e32 v11, v11, v13
	ds_bpermute_b32 v12, v9, v10
	ds_bpermute_b32 v13, v9, v11
	s_waitcnt lgkmcnt(0)
	v_add_f32_e32 v10, v10, v12
	v_add_f32_e32 v11, v11, v13
	v_fma_f32 v14, v10, s17, v3
	v_fma_f32 v15, v11, s17, v3
	v_rsq_f32_e32 v14, v14
	v_rsq_f32_e32 v15, v15
	s_nop 0
	v_mul_f32_e32 v64, v64, v14
	v_mul_f32_e32 v65, v65, v14
	v_mul_f32_e32 v66, v66, v14
	v_mul_f32_e32 v67, v67, v14
	v_mul_f32_e32 v68, v68, v14
	v_mul_f32_e32 v69, v69, v14
	v_mul_f32_e32 v70, v70, v14
	v_mul_f32_e32 v71, v71, v14
	v_mul_f32_e32 v72, v72, v14
	v_mul_f32_e32 v73, v73, v14
	v_mul_f32_e32 v74, v74, v14
	v_mul_f32_e32 v75, v75, v14
	v_mul_f32_e32 v76, v76, v14
	v_mul_f32_e32 v77, v77, v14
	v_mul_f32_e32 v78, v78, v14
	v_mul_f32_e32 v79, v79, v14
	v_fmac_f32_e32 v80, v64, v20
	v_fmac_f32_e32 v81, v65, v21
	v_fmac_f32_e32 v82, v66, v22
	v_fmac_f32_e32 v83, v67, v23
	v_fmac_f32_e32 v84, v68, v24
	v_fmac_f32_e32 v85, v69, v25
	v_fmac_f32_e32 v86, v70, v26
	v_fmac_f32_e32 v87, v71, v27
	v_fmac_f32_e32 v88, v72, v28
	v_fmac_f32_e32 v89, v73, v29
	v_fmac_f32_e32 v90, v74, v30
	v_fmac_f32_e32 v91, v75, v31
	v_fmac_f32_e32 v92, v76, v32
	v_fmac_f32_e32 v93, v77, v33
	v_fmac_f32_e32 v94, v78, v34
	v_fmac_f32_e32 v95, v79, v35
	global_store_dwordx4 v1, v[80:83], s[24:25] offset:0
	global_store_dwordx4 v1, v[84:87], s[24:25] offset:1024
	global_store_dwordx4 v1, v[88:91], s[24:25] offset:2048
	global_store_dwordx4 v1, v[92:95], s[24:25] offset:3072
	v_mul_f32_e32 v96, v96, v15
	v_mul_f32_e32 v97, v97, v15
	v_mul_f32_e32 v98, v98, v15
	v_mul_f32_e32 v99, v99, v15
	v_mul_f32_e32 v100, v100, v15
	v_mul_f32_e32 v101, v101, v15
	v_mul_f32_e32 v102, v102, v15
	v_mul_f32_e32 v103, v103, v15
	v_mul_f32_e32 v104, v104, v15
	v_mul_f32_e32 v105, v105, v15
	v_mul_f32_e32 v106, v106, v15
	v_mul_f32_e32 v107, v107, v15
	v_mul_f32_e32 v108, v108, v15
	v_mul_f32_e32 v109, v109, v15
	v_mul_f32_e32 v110, v110, v15
	v_mul_f32_e32 v111, v111, v15
	v_fmac_f32_e32 v112, v96, v20
	v_fmac_f32_e32 v113, v97, v21
	v_fmac_f32_e32 v114, v98, v22
	v_fmac_f32_e32 v115, v99, v23
	v_fmac_f32_e32 v116, v100, v24
	v_fmac_f32_e32 v117, v101, v25
	v_fmac_f32_e32 v118, v102, v26
	v_fmac_f32_e32 v119, v103, v27
	v_fmac_f32_e32 v120, v104, v28
	v_fmac_f32_e32 v121, v105, v29
	v_fmac_f32_e32 v122, v106, v30
	v_fmac_f32_e32 v123, v107, v31
	v_fmac_f32_e32 v124, v108, v32
	v_fmac_f32_e32 v125, v109, v33
	v_fmac_f32_e32 v126, v110, v34
	v_fmac_f32_e32 v127, v111, v35
	global_store_dwordx4 v1, v[112:115], s[32:33] offset:0
	global_store_dwordx4 v1, v[116:119], s[32:33] offset:1024
	global_store_dwordx4 v1, v[120:123], s[32:33] offset:2048
	global_store_dwordx4 v1, v[124:127], s[32:33] offset:3072
	v_mul_f32_e32 v10, v80, v80
	v_fmac_f32_e32 v10, v81, v81
	v_fmac_f32_e32 v10, v82, v82
	v_fmac_f32_e32 v10, v83, v83
	v_fmac_f32_e32 v10, v84, v84
	v_fmac_f32_e32 v10, v85, v85
	v_fmac_f32_e32 v10, v86, v86
	v_fmac_f32_e32 v10, v87, v87
	v_fmac_f32_e32 v10, v88, v88
	v_fmac_f32_e32 v10, v89, v89
	v_fmac_f32_e32 v10, v90, v90
	v_fmac_f32_e32 v10, v91, v91
	v_fmac_f32_e32 v10, v92, v92
	v_fmac_f32_e32 v10, v93, v93
	v_fmac_f32_e32 v10, v94, v94
	v_fmac_f32_e32 v10, v95, v95
	v_mul_f32_e32 v11, v112, v112
	v_fmac_f32_e32 v11, v113, v113
	v_fmac_f32_e32 v11, v114, v114
	v_fmac_f32_e32 v11, v115, v115
	v_fmac_f32_e32 v11, v116, v116
	v_fmac_f32_e32 v11, v117, v117
	v_fmac_f32_e32 v11, v118, v118
	v_fmac_f32_e32 v11, v119, v119
	v_fmac_f32_e32 v11, v120, v120
	v_fmac_f32_e32 v11, v121, v121
	v_fmac_f32_e32 v11, v122, v122
	v_fmac_f32_e32 v11, v123, v123
	v_fmac_f32_e32 v11, v124, v124
	v_fmac_f32_e32 v11, v125, v125
	v_fmac_f32_e32 v11, v126, v126
	v_fmac_f32_e32 v11, v127, v127
	ds_bpermute_b32 v12, v4, v10
	ds_bpermute_b32 v13, v4, v11
	s_waitcnt lgkmcnt(0)
	v_add_f32_e32 v10, v10, v12
	v_add_f32_e32 v11, v11, v13
	ds_bpermute_b32 v12, v5, v10
	ds_bpermute_b32 v13, v5, v11
	s_waitcnt lgkmcnt(0)
	v_add_f32_e32 v10, v10, v12
	v_add_f32_e32 v11, v11, v13
	ds_bpermute_b32 v12, v6, v10
	ds_bpermute_b32 v13, v6, v11
	s_waitcnt lgkmcnt(0)
	v_add_f32_e32 v10, v10, v12
	v_add_f32_e32 v11, v11, v13
	ds_bpermute_b32 v12, v7, v10
	ds_bpermute_b32 v13, v7, v11
	s_waitcnt lgkmcnt(0)
	v_add_f32_e32 v10, v10, v12
	v_add_f32_e32 v11, v11, v13
	ds_bpermute_b32 v12, v8, v10
	ds_bpermute_b32 v13, v8, v11
	s_waitcnt lgkmcnt(0)
	v_add_f32_e32 v10, v10, v12
	v_add_f32_e32 v11, v11, v13
	ds_bpermute_b32 v12, v9, v10
	ds_bpermute_b32 v13, v9, v11
	s_waitcnt lgkmcnt(0)
	v_add_f32_e32 v10, v10, v12
	v_add_f32_e32 v11, v11, v13
	v_fma_f32 v14, v10, s17, v3
	v_fma_f32 v15, v11, s17, v3
	v_rsq_f32_e32 v14, v14
	v_rsq_f32_e32 v15, v15
	s_nop 0
	v_mul_f32_e32 v64, v80, v14
	v_mul_f32_e32 v65, v81, v14
	v_mul_f32_e32 v66, v82, v14
	v_mul_f32_e32 v67, v83, v14
	v_mul_f32_e32 v68, v84, v14
	v_mul_f32_e32 v69, v85, v14
	v_mul_f32_e32 v70, v86, v14
	v_mul_f32_e32 v71, v87, v14
	v_mul_f32_e32 v72, v88, v14
	v_mul_f32_e32 v73, v89, v14
	v_mul_f32_e32 v74, v90, v14
	v_mul_f32_e32 v75, v91, v14
	v_mul_f32_e32 v76, v92, v14
	v_mul_f32_e32 v77, v93, v14
	v_mul_f32_e32 v78, v94, v14
	v_mul_f32_e32 v79, v95, v14
	v_mul_f32_e32 v64, v64, v36
	v_mul_f32_e32 v65, v65, v37
	v_mul_f32_e32 v66, v66, v38
	v_mul_f32_e32 v67, v67, v39
	v_mul_f32_e32 v68, v68, v40
	v_mul_f32_e32 v69, v69, v41
	v_mul_f32_e32 v70, v70, v42
	v_mul_f32_e32 v71, v71, v43
	v_mul_f32_e32 v72, v72, v44
	v_mul_f32_e32 v73, v73, v45
	v_mul_f32_e32 v74, v74, v46
	v_mul_f32_e32 v75, v75, v47
	v_mul_f32_e32 v76, v76, v48
	v_mul_f32_e32 v77, v77, v49
	v_mul_f32_e32 v78, v78, v50
	v_mul_f32_e32 v79, v79, v51
	v_cvt_pk_bf16_f32 v64, v64, v65
	v_cvt_pk_bf16_f32 v65, v66, v67
	v_cvt_pk_bf16_f32 v68, v68, v69
	v_cvt_pk_bf16_f32 v69, v70, v71
	v_cvt_pk_bf16_f32 v72, v72, v73
	v_cvt_pk_bf16_f32 v73, v74, v75
	v_cvt_pk_bf16_f32 v76, v76, v77
	v_cvt_pk_bf16_f32 v77, v78, v79
	global_store_dwordx2 v2, v[64:65], s[26:27] offset:0
	global_store_dwordx2 v2, v[68:69], s[26:27] offset:512
	global_store_dwordx2 v2, v[72:73], s[26:27] offset:1024
	global_store_dwordx2 v2, v[76:77], s[26:27] offset:1536
	v_mul_f32_e32 v96, v112, v15
	v_mul_f32_e32 v97, v113, v15
	v_mul_f32_e32 v98, v114, v15
	v_mul_f32_e32 v99, v115, v15
	v_mul_f32_e32 v100, v116, v15
	v_mul_f32_e32 v101, v117, v15
	v_mul_f32_e32 v102, v118, v15
	v_mul_f32_e32 v103, v119, v15
	v_mul_f32_e32 v104, v120, v15
	v_mul_f32_e32 v105, v121, v15
	v_mul_f32_e32 v106, v122, v15
	v_mul_f32_e32 v107, v123, v15
	v_mul_f32_e32 v108, v124, v15
	v_mul_f32_e32 v109, v125, v15
	v_mul_f32_e32 v110, v126, v15
	v_mul_f32_e32 v111, v127, v15
	v_mul_f32_e32 v96, v96, v36
	v_mul_f32_e32 v97, v97, v37
	v_mul_f32_e32 v98, v98, v38
	v_mul_f32_e32 v99, v99, v39
	v_mul_f32_e32 v100, v100, v40
	v_mul_f32_e32 v101, v101, v41
	v_mul_f32_e32 v102, v102, v42
	v_mul_f32_e32 v103, v103, v43
	v_mul_f32_e32 v104, v104, v44
	v_mul_f32_e32 v105, v105, v45
	v_mul_f32_e32 v106, v106, v46
	v_mul_f32_e32 v107, v107, v47
	v_mul_f32_e32 v108, v108, v48
	v_mul_f32_e32 v109, v109, v49
	v_mul_f32_e32 v110, v110, v50
	v_mul_f32_e32 v111, v111, v51
	v_cvt_pk_bf16_f32 v96, v96, v97
	v_cvt_pk_bf16_f32 v97, v98, v99
	v_cvt_pk_bf16_f32 v100, v100, v101
	v_cvt_pk_bf16_f32 v101, v102, v103
	v_cvt_pk_bf16_f32 v104, v104, v105
	v_cvt_pk_bf16_f32 v105, v106, v107
	v_cvt_pk_bf16_f32 v108, v108, v109
	v_cvt_pk_bf16_f32 v109, v110, v111
	global_store_dwordx2 v2, v[96:97], s[34:35] offset:0
	global_store_dwordx2 v2, v[100:101], s[34:35] offset:512
	global_store_dwordx2 v2, v[104:105], s[34:35] offset:1024
	global_store_dwordx2 v2, v[108:109], s[34:35] offset:1536
	s_add_u32 s53, s16, 0x2000
	s_lshl_b32 s18, s53, 12
	s_lshl_b32 s19, s53, 11
	s_add_u32 s20, s12, s18
	s_addc_u32 s21, s13, 0
	s_add_u32 s22, s6, s19
	s_addc_u32 s23, s7, 0
	s_add_u32 s22, s22, 0x5200000
	s_addc_u32 s23, s23, 0
	s_add_u32 s24, s4, s18
	s_addc_u32 s25, s5, 0
	s_add_u32 s26, s6, s19
	s_addc_u32 s27, s7, 0
	s_add_u32 s26, s26, 0x3100000
	s_addc_u32 s27, s27, 0
	global_load_dwordx2 v[66:67], v2, s[22:23] offset:0
	global_load_dwordx2 v[70:71], v2, s[22:23] offset:512
	global_load_dwordx2 v[74:75], v2, s[22:23] offset:1024
	global_load_dwordx2 v[78:79], v2, s[22:23] offset:1536
	global_load_dwordx4 v[80:83], v1, s[20:21] offset:0
	global_load_dwordx4 v[84:87], v1, s[20:21] offset:1024
	global_load_dwordx4 v[88:91], v1, s[20:21] offset:2048
	global_load_dwordx4 v[92:95], v1, s[20:21] offset:3072
	s_add_u32 s53, s16, 0x2800
	s_lshl_b32 s18, s53, 12
	s_lshl_b32 s19, s53, 11
	s_add_u32 s28, s12, s18
	s_addc_u32 s29, s13, 0
	s_add_u32 s30, s6, s19
	s_addc_u32 s31, s7, 0
	s_add_u32 s30, s30, 0x5200000
	s_addc_u32 s31, s31, 0
	s_add_u32 s32, s4, s18
	s_addc_u32 s33, s5, 0
	s_add_u32 s34, s6, s19
	s_addc_u32 s35, s7, 0
	s_add_u32 s34, s34, 0x3100000
	s_addc_u32 s35, s35, 0
	global_load_dwordx2 v[98:99], v2, s[30:31] offset:0
	global_load_dwordx2 v[102:103], v2, s[30:31] offset:512
	global_load_dwordx2 v[106:107], v2, s[30:31] offset:1024
	global_load_dwordx2 v[110:111], v2, s[30:31] offset:1536
	global_load_dwordx4 v[112:115], v1, s[28:29] offset:0
	global_load_dwordx4 v[116:119], v1, s[28:29] offset:1024
	global_load_dwordx4 v[120:123], v1, s[28:29] offset:2048
	global_load_dwordx4 v[124:127], v1, s[28:29] offset:3072
	s_waitcnt vmcnt(32)
	v_lshlrev_b32_e32 v128, 16, v130
	v_and_b32_e32 v129, 0xffff0000, v130
	v_lshlrev_b32_e32 v130, 16, v131
	v_and_b32_e32 v131, 0xffff0000, v131
	v_lshlrev_b32_e32 v132, 16, v134
	v_and_b32_e32 v133, 0xffff0000, v134
	v_lshlrev_b32_e32 v134, 16, v135
	v_and_b32_e32 v135, 0xffff0000, v135
	v_lshlrev_b32_e32 v136, 16, v138
	v_and_b32_e32 v137, 0xffff0000, v138
	v_lshlrev_b32_e32 v138, 16, v139
	v_and_b32_e32 v139, 0xffff0000, v139
	v_lshlrev_b32_e32 v140, 16, v142
	v_and_b32_e32 v141, 0xffff0000, v142
	v_lshlrev_b32_e32 v142, 16, v143
	v_and_b32_e32 v143, 0xffff0000, v143
	v_lshlrev_b32_e32 v160, 16, v162
	v_and_b32_e32 v161, 0xffff0000, v162
	v_lshlrev_b32_e32 v162, 16, v163
	v_and_b32_e32 v163, 0xffff0000, v163
	v_lshlrev_b32_e32 v164, 16, v166
	v_and_b32_e32 v165, 0xffff0000, v166
	v_lshlrev_b32_e32 v166, 16, v167
	v_and_b32_e32 v167, 0xffff0000, v167
	v_lshlrev_b32_e32 v168, 16, v170
	v_and_b32_e32 v169, 0xffff0000, v170
	v_lshlrev_b32_e32 v170, 16, v171
	v_and_b32_e32 v171, 0xffff0000, v171
	v_lshlrev_b32_e32 v172, 16, v174
	v_and_b32_e32 v173, 0xffff0000, v174
	v_lshlrev_b32_e32 v174, 16, v175
	v_and_b32_e32 v175, 0xffff0000, v175
	v_mul_f32_e32 v10, v128, v128
	v_fmac_f32_e32 v10, v129, v129
	v_fmac_f32_e32 v10, v130, v130
	v_fmac_f32_e32 v10, v131, v131
	v_fmac_f32_e32 v10, v132, v132
	v_fmac_f32_e32 v10, v133, v133
	v_fmac_f32_e32 v10, v134, v134
	v_fmac_f32_e32 v10, v135, v135
	v_fmac_f32_e32 v10, v136, v136
	v_fmac_f32_e32 v10, v137, v137
	v_fmac_f32_e32 v10, v138, v138
	v_fmac_f32_e32 v10, v139, v139
	v_fmac_f32_e32 v10, v140, v140
	v_fmac_f32_e32 v10, v141, v141
	v_fmac_f32_e32 v10, v142, v142
	v_fmac_f32_e32 v10, v143, v143
	v_mul_f32_e32 v11, v160, v160
	v_fmac_f32_e32 v11, v161, v161
	v_fmac_f32_e32 v11, v162, v162
	v_fmac_f32_e32 v11, v163, v163
	v_fmac_f32_e32 v11, v164, v164
	v_fmac_f32_e32 v11, v165, v165
	v_fmac_f32_e32 v11, v166, v166
	v_fmac_f32_e32 v11, v167, v167
	v_fmac_f32_e32 v11, v168, v168
	v_fmac_f32_e32 v11, v169, v169
	v_fmac_f32_e32 v11, v170, v170
	v_fmac_f32_e32 v11, v171, v171
	v_fmac_f32_e32 v11, v172, v172
	v_fmac_f32_e32 v11, v173, v173
	v_fmac_f32_e32 v11, v174, v174
	v_fmac_f32_e32 v11, v175, v175
	ds_bpermute_b32 v12, v4, v10
	ds_bpermute_b32 v13, v4, v11
	s_waitcnt lgkmcnt(0)
	v_add_f32_e32 v10, v10, v12
	v_add_f32_e32 v11, v11, v13
	ds_bpermute_b32 v12, v5, v10
	ds_bpermute_b32 v13, v5, v11
	s_waitcnt lgkmcnt(0)
	v_add_f32_e32 v10, v10, v12
	v_add_f32_e32 v11, v11, v13
	ds_bpermute_b32 v12, v6, v10
	ds_bpermute_b32 v13, v6, v11
	s_waitcnt lgkmcnt(0)
	v_add_f32_e32 v10, v10, v12
	v_add_f32_e32 v11, v11, v13
	ds_bpermute_b32 v12, v7, v10
	ds_bpermute_b32 v13, v7, v11
	s_waitcnt lgkmcnt(0)
	v_add_f32_e32 v10, v10, v12
	v_add_f32_e32 v11, v11, v13
	ds_bpermute_b32 v12, v8, v10
	ds_bpermute_b32 v13, v8, v11
	s_waitcnt lgkmcnt(0)
	v_add_f32_e32 v10, v10, v12
	v_add_f32_e32 v11, v11, v13
	ds_bpermute_b32 v12, v9, v10
	ds_bpermute_b32 v13, v9, v11
	s_waitcnt lgkmcnt(0)
	v_add_f32_e32 v10, v10, v12
	v_add_f32_e32 v11, v11, v13
	v_fma_f32 v14, v10, s17, v3
	v_fma_f32 v15, v11, s17, v3
	v_rsq_f32_e32 v14, v14
	v_rsq_f32_e32 v15, v15
	s_nop 0
	v_mul_f32_e32 v128, v128, v14
	v_mul_f32_e32 v129, v129, v14
	v_mul_f32_e32 v130, v130, v14
	v_mul_f32_e32 v131, v131, v14
	v_mul_f32_e32 v132, v132, v14
	v_mul_f32_e32 v133, v133, v14
	v_mul_f32_e32 v134, v134, v14
	v_mul_f32_e32 v135, v135, v14
	v_mul_f32_e32 v136, v136, v14
	v_mul_f32_e32 v137, v137, v14
	v_mul_f32_e32 v138, v138, v14
	v_mul_f32_e32 v139, v139, v14
	v_mul_f32_e32 v140, v140, v14
	v_mul_f32_e32 v141, v141, v14
	v_mul_f32_e32 v142, v142, v14
	v_mul_f32_e32 v143, v143, v14
	v_fmac_f32_e32 v144, v128, v20
	v_fmac_f32_e32 v145, v129, v21
	v_fmac_f32_e32 v146, v130, v22
	v_fmac_f32_e32 v147, v131, v23
	v_fmac_f32_e32 v148, v132, v24
	v_fmac_f32_e32 v149, v133, v25
	v_fmac_f32_e32 v150, v134, v26
	v_fmac_f32_e32 v151, v135, v27
	v_fmac_f32_e32 v152, v136, v28
	v_fmac_f32_e32 v153, v137, v29
	v_fmac_f32_e32 v154, v138, v30
	v_fmac_f32_e32 v155, v139, v31
	v_fmac_f32_e32 v156, v140, v32
	v_fmac_f32_e32 v157, v141, v33
	v_fmac_f32_e32 v158, v142, v34
	v_fmac_f32_e32 v159, v143, v35
	global_store_dwordx4 v1, v[144:147], s[40:41] offset:0
	global_store_dwordx4 v1, v[148:151], s[40:41] offset:1024
	global_store_dwordx4 v1, v[152:155], s[40:41] offset:2048
	global_store_dwordx4 v1, v[156:159], s[40:41] offset:3072
	v_mul_f32_e32 v160, v160, v15
	v_mul_f32_e32 v161, v161, v15
	v_mul_f32_e32 v162, v162, v15
	v_mul_f32_e32 v163, v163, v15
	v_mul_f32_e32 v164, v164, v15
	v_mul_f32_e32 v165, v165, v15
	v_mul_f32_e32 v166, v166, v15
	v_mul_f32_e32 v167, v167, v15
	v_mul_f32_e32 v168, v168, v15
	v_mul_f32_e32 v169, v169, v15
	v_mul_f32_e32 v170, v170, v15
	v_mul_f32_e32 v171, v171, v15
	v_mul_f32_e32 v172, v172, v15
	v_mul_f32_e32 v173, v173, v15
	v_mul_f32_e32 v174, v174, v15
	v_mul_f32_e32 v175, v175, v15
	v_fmac_f32_e32 v176, v160, v20
	v_fmac_f32_e32 v177, v161, v21
	v_fmac_f32_e32 v178, v162, v22
	v_fmac_f32_e32 v179, v163, v23
	v_fmac_f32_e32 v180, v164, v24
	v_fmac_f32_e32 v181, v165, v25
	v_fmac_f32_e32 v182, v166, v26
	v_fmac_f32_e32 v183, v167, v27
	v_fmac_f32_e32 v184, v168, v28
	v_fmac_f32_e32 v185, v169, v29
	v_fmac_f32_e32 v186, v170, v30
	v_fmac_f32_e32 v187, v171, v31
	v_fmac_f32_e32 v188, v172, v32
	v_fmac_f32_e32 v189, v173, v33
	v_fmac_f32_e32 v190, v174, v34
	v_fmac_f32_e32 v191, v175, v35
	global_store_dwordx4 v1, v[176:179], s[48:49] offset:0
	global_store_dwordx4 v1, v[180:183], s[48:49] offset:1024
	global_store_dwordx4 v1, v[184:187], s[48:49] offset:2048
	global_store_dwordx4 v1, v[188:191], s[48:49] offset:3072
	v_mul_f32_e32 v10, v144, v144
	v_fmac_f32_e32 v10, v145, v145
	v_fmac_f32_e32 v10, v146, v146
	v_fmac_f32_e32 v10, v147, v147
	v_fmac_f32_e32 v10, v148, v148
	v_fmac_f32_e32 v10, v149, v149
	v_fmac_f32_e32 v10, v150, v150
	v_fmac_f32_e32 v10, v151, v151
	v_fmac_f32_e32 v10, v152, v152
	v_fmac_f32_e32 v10, v153, v153
	v_fmac_f32_e32 v10, v154, v154
	v_fmac_f32_e32 v10, v155, v155
	v_fmac_f32_e32 v10, v156, v156
	v_fmac_f32_e32 v10, v157, v157
	v_fmac_f32_e32 v10, v158, v158
	v_fmac_f32_e32 v10, v159, v159
	v_mul_f32_e32 v11, v176, v176
	v_fmac_f32_e32 v11, v177, v177
	v_fmac_f32_e32 v11, v178, v178
	v_fmac_f32_e32 v11, v179, v179
	v_fmac_f32_e32 v11, v180, v180
	v_fmac_f32_e32 v11, v181, v181
	v_fmac_f32_e32 v11, v182, v182
	v_fmac_f32_e32 v11, v183, v183
	v_fmac_f32_e32 v11, v184, v184
	v_fmac_f32_e32 v11, v185, v185
	v_fmac_f32_e32 v11, v186, v186
	v_fmac_f32_e32 v11, v187, v187
	v_fmac_f32_e32 v11, v188, v188
	v_fmac_f32_e32 v11, v189, v189
	v_fmac_f32_e32 v11, v190, v190
	v_fmac_f32_e32 v11, v191, v191
	ds_bpermute_b32 v12, v4, v10
	ds_bpermute_b32 v13, v4, v11
	s_waitcnt lgkmcnt(0)
	v_add_f32_e32 v10, v10, v12
	v_add_f32_e32 v11, v11, v13
	ds_bpermute_b32 v12, v5, v10
	ds_bpermute_b32 v13, v5, v11
	s_waitcnt lgkmcnt(0)
	v_add_f32_e32 v10, v10, v12
	v_add_f32_e32 v11, v11, v13
	ds_bpermute_b32 v12, v6, v10
	ds_bpermute_b32 v13, v6, v11
	s_waitcnt lgkmcnt(0)
	v_add_f32_e32 v10, v10, v12
	v_add_f32_e32 v11, v11, v13
	ds_bpermute_b32 v12, v7, v10
	ds_bpermute_b32 v13, v7, v11
	s_waitcnt lgkmcnt(0)
	v_add_f32_e32 v10, v10, v12
	v_add_f32_e32 v11, v11, v13
	ds_bpermute_b32 v12, v8, v10
	ds_bpermute_b32 v13, v8, v11
	s_waitcnt lgkmcnt(0)
	v_add_f32_e32 v10, v10, v12
	v_add_f32_e32 v11, v11, v13
	ds_bpermute_b32 v12, v9, v10
	ds_bpermute_b32 v13, v9, v11
	s_waitcnt lgkmcnt(0)
	v_add_f32_e32 v10, v10, v12
	v_add_f32_e32 v11, v11, v13
	v_fma_f32 v14, v10, s17, v3
	v_fma_f32 v15, v11, s17, v3
	v_rsq_f32_e32 v14, v14
	v_rsq_f32_e32 v15, v15
	s_nop 0
	v_mul_f32_e32 v128, v144, v14
	v_mul_f32_e32 v129, v145, v14
	v_mul_f32_e32 v130, v146, v14
	v_mul_f32_e32 v131, v147, v14
	v_mul_f32_e32 v132, v148, v14
	v_mul_f32_e32 v133, v149, v14
	v_mul_f32_e32 v134, v150, v14
	v_mul_f32_e32 v135, v151, v14
	v_mul_f32_e32 v136, v152, v14
	v_mul_f32_e32 v137, v153, v14
	v_mul_f32_e32 v138, v154, v14
	v_mul_f32_e32 v139, v155, v14
	v_mul_f32_e32 v140, v156, v14
	v_mul_f32_e32 v141, v157, v14
	v_mul_f32_e32 v142, v158, v14
	v_mul_f32_e32 v143, v159, v14
	v_mul_f32_e32 v128, v128, v36
	v_mul_f32_e32 v129, v129, v37
	v_mul_f32_e32 v130, v130, v38
	v_mul_f32_e32 v131, v131, v39
	v_mul_f32_e32 v132, v132, v40
	v_mul_f32_e32 v133, v133, v41
	v_mul_f32_e32 v134, v134, v42
	v_mul_f32_e32 v135, v135, v43
	v_mul_f32_e32 v136, v136, v44
	v_mul_f32_e32 v137, v137, v45
	v_mul_f32_e32 v138, v138, v46
	v_mul_f32_e32 v139, v139, v47
	v_mul_f32_e32 v140, v140, v48
	v_mul_f32_e32 v141, v141, v49
	v_mul_f32_e32 v142, v142, v50
	v_mul_f32_e32 v143, v143, v51
	v_cvt_pk_bf16_f32 v128, v128, v129
	v_cvt_pk_bf16_f32 v129, v130, v131
	v_cvt_pk_bf16_f32 v132, v132, v133
	v_cvt_pk_bf16_f32 v133, v134, v135
	v_cvt_pk_bf16_f32 v136, v136, v137
	v_cvt_pk_bf16_f32 v137, v138, v139
	v_cvt_pk_bf16_f32 v140, v140, v141
	v_cvt_pk_bf16_f32 v141, v142, v143
	global_store_dwordx2 v2, v[128:129], s[42:43] offset:0
	global_store_dwordx2 v2, v[132:133], s[42:43] offset:512
	global_store_dwordx2 v2, v[136:137], s[42:43] offset:1024
	global_store_dwordx2 v2, v[140:141], s[42:43] offset:1536
	v_mul_f32_e32 v160, v176, v15
	v_mul_f32_e32 v161, v177, v15
	v_mul_f32_e32 v162, v178, v15
	v_mul_f32_e32 v163, v179, v15
	v_mul_f32_e32 v164, v180, v15
	v_mul_f32_e32 v165, v181, v15
	v_mul_f32_e32 v166, v182, v15
	v_mul_f32_e32 v167, v183, v15
	v_mul_f32_e32 v168, v184, v15
	v_mul_f32_e32 v169, v185, v15
	v_mul_f32_e32 v170, v186, v15
	v_mul_f32_e32 v171, v187, v15
	v_mul_f32_e32 v172, v188, v15
	v_mul_f32_e32 v173, v189, v15
	v_mul_f32_e32 v174, v190, v15
	v_mul_f32_e32 v175, v191, v15
	v_mul_f32_e32 v160, v160, v36
	v_mul_f32_e32 v161, v161, v37
	v_mul_f32_e32 v162, v162, v38
	v_mul_f32_e32 v163, v163, v39
	v_mul_f32_e32 v164, v164, v40
	v_mul_f32_e32 v165, v165, v41
	v_mul_f32_e32 v166, v166, v42
	v_mul_f32_e32 v167, v167, v43
	v_mul_f32_e32 v168, v168, v44
	v_mul_f32_e32 v169, v169, v45
	v_mul_f32_e32 v170, v170, v46
	v_mul_f32_e32 v171, v171, v47
	v_mul_f32_e32 v172, v172, v48
	v_mul_f32_e32 v173, v173, v49
	v_mul_f32_e32 v174, v174, v50
	v_mul_f32_e32 v175, v175, v51
	v_cvt_pk_bf16_f32 v160, v160, v161
	v_cvt_pk_bf16_f32 v161, v162, v163
	v_cvt_pk_bf16_f32 v164, v164, v165
	v_cvt_pk_bf16_f32 v165, v166, v167
	v_cvt_pk_bf16_f32 v168, v168, v169
	v_cvt_pk_bf16_f32 v169, v170, v171
	v_cvt_pk_bf16_f32 v172, v172, v173
	v_cvt_pk_bf16_f32 v173, v174, v175
	global_store_dwordx2 v2, v[160:161], s[50:51] offset:0
	global_store_dwordx2 v2, v[164:165], s[50:51] offset:512
	global_store_dwordx2 v2, v[168:169], s[50:51] offset:1024
	global_store_dwordx2 v2, v[172:173], s[50:51] offset:1536
	s_add_u32 s53, s16, 0x3000
	s_lshl_b32 s18, s53, 12
	s_lshl_b32 s19, s53, 11
	s_add_u32 s36, s12, s18
	s_addc_u32 s37, s13, 0
	s_add_u32 s38, s6, s19
	s_addc_u32 s39, s7, 0
	s_add_u32 s38, s38, 0x5200000
	s_addc_u32 s39, s39, 0
	s_add_u32 s40, s4, s18
	s_addc_u32 s41, s5, 0
	s_add_u32 s42, s6, s19
	s_addc_u32 s43, s7, 0
	s_add_u32 s42, s42, 0x3100000
	s_addc_u32 s43, s43, 0
	global_load_dwordx2 v[130:131], v2, s[38:39] offset:0
	global_load_dwordx2 v[134:135], v2, s[38:39] offset:512
	global_load_dwordx2 v[138:139], v2, s[38:39] offset:1024
	global_load_dwordx2 v[142:143], v2, s[38:39] offset:1536
	global_load_dwordx4 v[144:147], v1, s[36:37] offset:0
	global_load_dwordx4 v[148:151], v1, s[36:37] offset:1024
	global_load_dwordx4 v[152:155], v1, s[36:37] offset:2048
	global_load_dwordx4 v[156:159], v1, s[36:37] offset:3072
	s_add_u32 s53, s16, 0x3800
	s_lshl_b32 s18, s53, 12
	s_lshl_b32 s19, s53, 11
	s_add_u32 s44, s12, s18
	s_addc_u32 s45, s13, 0
	s_add_u32 s46, s6, s19
	s_addc_u32 s47, s7, 0
	s_add_u32 s46, s46, 0x5200000
	s_addc_u32 s47, s47, 0
	s_add_u32 s48, s4, s18
	s_addc_u32 s49, s5, 0
	s_add_u32 s50, s6, s19
	s_addc_u32 s51, s7, 0
	s_add_u32 s50, s50, 0x3100000
	s_addc_u32 s51, s51, 0
	global_load_dwordx2 v[162:163], v2, s[46:47] offset:0
	global_load_dwordx2 v[166:167], v2, s[46:47] offset:512
	global_load_dwordx2 v[170:171], v2, s[46:47] offset:1024
	global_load_dwordx2 v[174:175], v2, s[46:47] offset:1536
	global_load_dwordx4 v[176:179], v1, s[44:45] offset:0
	global_load_dwordx4 v[180:183], v1, s[44:45] offset:1024
	global_load_dwordx4 v[184:187], v1, s[44:45] offset:2048
	global_load_dwordx4 v[188:191], v1, s[44:45] offset:3072
	s_waitcnt vmcnt(32)
	v_lshlrev_b32_e32 v64, 16, v66
	v_and_b32_e32 v65, 0xffff0000, v66
	v_lshlrev_b32_e32 v66, 16, v67
	v_and_b32_e32 v67, 0xffff0000, v67
	v_lshlrev_b32_e32 v68, 16, v70
	v_and_b32_e32 v69, 0xffff0000, v70
	v_lshlrev_b32_e32 v70, 16, v71
	v_and_b32_e32 v71, 0xffff0000, v71
	v_lshlrev_b32_e32 v72, 16, v74
	v_and_b32_e32 v73, 0xffff0000, v74
	v_lshlrev_b32_e32 v74, 16, v75
	v_and_b32_e32 v75, 0xffff0000, v75
	v_lshlrev_b32_e32 v76, 16, v78
	v_and_b32_e32 v77, 0xffff0000, v78
	v_lshlrev_b32_e32 v78, 16, v79
	v_and_b32_e32 v79, 0xffff0000, v79
	v_lshlrev_b32_e32 v96, 16, v98
	v_and_b32_e32 v97, 0xffff0000, v98
	v_lshlrev_b32_e32 v98, 16, v99
	v_and_b32_e32 v99, 0xffff0000, v99
	v_lshlrev_b32_e32 v100, 16, v102
	v_and_b32_e32 v101, 0xffff0000, v102
	v_lshlrev_b32_e32 v102, 16, v103
	v_and_b32_e32 v103, 0xffff0000, v103
	v_lshlrev_b32_e32 v104, 16, v106
	v_and_b32_e32 v105, 0xffff0000, v106
	v_lshlrev_b32_e32 v106, 16, v107
	v_and_b32_e32 v107, 0xffff0000, v107
	v_lshlrev_b32_e32 v108, 16, v110
	v_and_b32_e32 v109, 0xffff0000, v110
	v_lshlrev_b32_e32 v110, 16, v111
	v_and_b32_e32 v111, 0xffff0000, v111
	v_mul_f32_e32 v10, v64, v64
	v_fmac_f32_e32 v10, v65, v65
	v_fmac_f32_e32 v10, v66, v66
	v_fmac_f32_e32 v10, v67, v67
	v_fmac_f32_e32 v10, v68, v68
	v_fmac_f32_e32 v10, v69, v69
	v_fmac_f32_e32 v10, v70, v70
	v_fmac_f32_e32 v10, v71, v71
	v_fmac_f32_e32 v10, v72, v72
	v_fmac_f32_e32 v10, v73, v73
	v_fmac_f32_e32 v10, v74, v74
	v_fmac_f32_e32 v10, v75, v75
	v_fmac_f32_e32 v10, v76, v76
	v_fmac_f32_e32 v10, v77, v77
	v_fmac_f32_e32 v10, v78, v78
	v_fmac_f32_e32 v10, v79, v79
	v_mul_f32_e32 v11, v96, v96
	v_fmac_f32_e32 v11, v97, v97
	v_fmac_f32_e32 v11, v98, v98
	v_fmac_f32_e32 v11, v99, v99
	v_fmac_f32_e32 v11, v100, v100
	v_fmac_f32_e32 v11, v101, v101
	v_fmac_f32_e32 v11, v102, v102
	v_fmac_f32_e32 v11, v103, v103
	v_fmac_f32_e32 v11, v104, v104
	v_fmac_f32_e32 v11, v105, v105
	v_fmac_f32_e32 v11, v106, v106
	v_fmac_f32_e32 v11, v107, v107
	v_fmac_f32_e32 v11, v108, v108
	v_fmac_f32_e32 v11, v109, v109
	v_fmac_f32_e32 v11, v110, v110
	v_fmac_f32_e32 v11, v111, v111
	ds_bpermute_b32 v12, v4, v10
	ds_bpermute_b32 v13, v4, v11
	s_waitcnt lgkmcnt(0)
	v_add_f32_e32 v10, v10, v12
	v_add_f32_e32 v11, v11, v13
	ds_bpermute_b32 v12, v5, v10
	ds_bpermute_b32 v13, v5, v11
	s_waitcnt lgkmcnt(0)
	v_add_f32_e32 v10, v10, v12
	v_add_f32_e32 v11, v11, v13
	ds_bpermute_b32 v12, v6, v10
	ds_bpermute_b32 v13, v6, v11
	s_waitcnt lgkmcnt(0)
	v_add_f32_e32 v10, v10, v12
	v_add_f32_e32 v11, v11, v13
	ds_bpermute_b32 v12, v7, v10
	ds_bpermute_b32 v13, v7, v11
	s_waitcnt lgkmcnt(0)
	v_add_f32_e32 v10, v10, v12
	v_add_f32_e32 v11, v11, v13
	ds_bpermute_b32 v12, v8, v10
	ds_bpermute_b32 v13, v8, v11
	s_waitcnt lgkmcnt(0)
	v_add_f32_e32 v10, v10, v12
	v_add_f32_e32 v11, v11, v13
	ds_bpermute_b32 v12, v9, v10
	ds_bpermute_b32 v13, v9, v11
	s_waitcnt lgkmcnt(0)
	v_add_f32_e32 v10, v10, v12
	v_add_f32_e32 v11, v11, v13
	v_fma_f32 v14, v10, s17, v3
	v_fma_f32 v15, v11, s17, v3
	v_rsq_f32_e32 v14, v14
	v_rsq_f32_e32 v15, v15
	s_nop 0
	v_mul_f32_e32 v64, v64, v14
	v_mul_f32_e32 v65, v65, v14
	v_mul_f32_e32 v66, v66, v14
	v_mul_f32_e32 v67, v67, v14
	v_mul_f32_e32 v68, v68, v14
	v_mul_f32_e32 v69, v69, v14
	v_mul_f32_e32 v70, v70, v14
	v_mul_f32_e32 v71, v71, v14
	v_mul_f32_e32 v72, v72, v14
	v_mul_f32_e32 v73, v73, v14
	v_mul_f32_e32 v74, v74, v14
	v_mul_f32_e32 v75, v75, v14
	v_mul_f32_e32 v76, v76, v14
	v_mul_f32_e32 v77, v77, v14
	v_mul_f32_e32 v78, v78, v14
	v_mul_f32_e32 v79, v79, v14
	v_fmac_f32_e32 v80, v64, v20
	v_fmac_f32_e32 v81, v65, v21
	v_fmac_f32_e32 v82, v66, v22
	v_fmac_f32_e32 v83, v67, v23
	v_fmac_f32_e32 v84, v68, v24
	v_fmac_f32_e32 v85, v69, v25
	v_fmac_f32_e32 v86, v70, v26
	v_fmac_f32_e32 v87, v71, v27
	v_fmac_f32_e32 v88, v72, v28
	v_fmac_f32_e32 v89, v73, v29
	v_fmac_f32_e32 v90, v74, v30
	v_fmac_f32_e32 v91, v75, v31
	v_fmac_f32_e32 v92, v76, v32
	v_fmac_f32_e32 v93, v77, v33
	v_fmac_f32_e32 v94, v78, v34
	v_fmac_f32_e32 v95, v79, v35
	global_store_dwordx4 v1, v[80:83], s[24:25] offset:0
	global_store_dwordx4 v1, v[84:87], s[24:25] offset:1024
	global_store_dwordx4 v1, v[88:91], s[24:25] offset:2048
	global_store_dwordx4 v1, v[92:95], s[24:25] offset:3072
	v_mul_f32_e32 v96, v96, v15
	v_mul_f32_e32 v97, v97, v15
	v_mul_f32_e32 v98, v98, v15
	v_mul_f32_e32 v99, v99, v15
	v_mul_f32_e32 v100, v100, v15
	v_mul_f32_e32 v101, v101, v15
	v_mul_f32_e32 v102, v102, v15
	v_mul_f32_e32 v103, v103, v15
	v_mul_f32_e32 v104, v104, v15
	v_mul_f32_e32 v105, v105, v15
	v_mul_f32_e32 v106, v106, v15
	v_mul_f32_e32 v107, v107, v15
	v_mul_f32_e32 v108, v108, v15
	v_mul_f32_e32 v109, v109, v15
	v_mul_f32_e32 v110, v110, v15
	v_mul_f32_e32 v111, v111, v15
	v_fmac_f32_e32 v112, v96, v20
	v_fmac_f32_e32 v113, v97, v21
	v_fmac_f32_e32 v114, v98, v22
	v_fmac_f32_e32 v115, v99, v23
	v_fmac_f32_e32 v116, v100, v24
	v_fmac_f32_e32 v117, v101, v25
	v_fmac_f32_e32 v118, v102, v26
	v_fmac_f32_e32 v119, v103, v27
	v_fmac_f32_e32 v120, v104, v28
	v_fmac_f32_e32 v121, v105, v29
	v_fmac_f32_e32 v122, v106, v30
	v_fmac_f32_e32 v123, v107, v31
	v_fmac_f32_e32 v124, v108, v32
	v_fmac_f32_e32 v125, v109, v33
	v_fmac_f32_e32 v126, v110, v34
	v_fmac_f32_e32 v127, v111, v35
	global_store_dwordx4 v1, v[112:115], s[32:33] offset:0
	global_store_dwordx4 v1, v[116:119], s[32:33] offset:1024
	global_store_dwordx4 v1, v[120:123], s[32:33] offset:2048
	global_store_dwordx4 v1, v[124:127], s[32:33] offset:3072
	v_mul_f32_e32 v10, v80, v80
	v_fmac_f32_e32 v10, v81, v81
	v_fmac_f32_e32 v10, v82, v82
	v_fmac_f32_e32 v10, v83, v83
	v_fmac_f32_e32 v10, v84, v84
	v_fmac_f32_e32 v10, v85, v85
	v_fmac_f32_e32 v10, v86, v86
	v_fmac_f32_e32 v10, v87, v87
	v_fmac_f32_e32 v10, v88, v88
	v_fmac_f32_e32 v10, v89, v89
	v_fmac_f32_e32 v10, v90, v90
	v_fmac_f32_e32 v10, v91, v91
	v_fmac_f32_e32 v10, v92, v92
	v_fmac_f32_e32 v10, v93, v93
	v_fmac_f32_e32 v10, v94, v94
	v_fmac_f32_e32 v10, v95, v95
	v_mul_f32_e32 v11, v112, v112
	v_fmac_f32_e32 v11, v113, v113
	v_fmac_f32_e32 v11, v114, v114
	v_fmac_f32_e32 v11, v115, v115
	v_fmac_f32_e32 v11, v116, v116
	v_fmac_f32_e32 v11, v117, v117
	v_fmac_f32_e32 v11, v118, v118
	v_fmac_f32_e32 v11, v119, v119
	v_fmac_f32_e32 v11, v120, v120
	v_fmac_f32_e32 v11, v121, v121
	v_fmac_f32_e32 v11, v122, v122
	v_fmac_f32_e32 v11, v123, v123
	v_fmac_f32_e32 v11, v124, v124
	v_fmac_f32_e32 v11, v125, v125
	v_fmac_f32_e32 v11, v126, v126
	v_fmac_f32_e32 v11, v127, v127
	ds_bpermute_b32 v12, v4, v10
	ds_bpermute_b32 v13, v4, v11
	s_waitcnt lgkmcnt(0)
	v_add_f32_e32 v10, v10, v12
	v_add_f32_e32 v11, v11, v13
	ds_bpermute_b32 v12, v5, v10
	ds_bpermute_b32 v13, v5, v11
	s_waitcnt lgkmcnt(0)
	v_add_f32_e32 v10, v10, v12
	v_add_f32_e32 v11, v11, v13
	ds_bpermute_b32 v12, v6, v10
	ds_bpermute_b32 v13, v6, v11
	s_waitcnt lgkmcnt(0)
	v_add_f32_e32 v10, v10, v12
	v_add_f32_e32 v11, v11, v13
	ds_bpermute_b32 v12, v7, v10
	ds_bpermute_b32 v13, v7, v11
	s_waitcnt lgkmcnt(0)
	v_add_f32_e32 v10, v10, v12
	v_add_f32_e32 v11, v11, v13
	ds_bpermute_b32 v12, v8, v10
	ds_bpermute_b32 v13, v8, v11
	s_waitcnt lgkmcnt(0)
	v_add_f32_e32 v10, v10, v12
	v_add_f32_e32 v11, v11, v13
	ds_bpermute_b32 v12, v9, v10
	ds_bpermute_b32 v13, v9, v11
	s_waitcnt lgkmcnt(0)
	v_add_f32_e32 v10, v10, v12
	v_add_f32_e32 v11, v11, v13
	v_fma_f32 v14, v10, s17, v3
	v_fma_f32 v15, v11, s17, v3
	v_rsq_f32_e32 v14, v14
	v_rsq_f32_e32 v15, v15
	s_nop 0
	v_mul_f32_e32 v64, v80, v14
	v_mul_f32_e32 v65, v81, v14
	v_mul_f32_e32 v66, v82, v14
	v_mul_f32_e32 v67, v83, v14
	v_mul_f32_e32 v68, v84, v14
	v_mul_f32_e32 v69, v85, v14
	v_mul_f32_e32 v70, v86, v14
	v_mul_f32_e32 v71, v87, v14
	v_mul_f32_e32 v72, v88, v14
	v_mul_f32_e32 v73, v89, v14
	v_mul_f32_e32 v74, v90, v14
	v_mul_f32_e32 v75, v91, v14
	v_mul_f32_e32 v76, v92, v14
	v_mul_f32_e32 v77, v93, v14
	v_mul_f32_e32 v78, v94, v14
	v_mul_f32_e32 v79, v95, v14
	v_mul_f32_e32 v64, v64, v36
	v_mul_f32_e32 v65, v65, v37
	v_mul_f32_e32 v66, v66, v38
	v_mul_f32_e32 v67, v67, v39
	v_mul_f32_e32 v68, v68, v40
	v_mul_f32_e32 v69, v69, v41
	v_mul_f32_e32 v70, v70, v42
	v_mul_f32_e32 v71, v71, v43
	v_mul_f32_e32 v72, v72, v44
	v_mul_f32_e32 v73, v73, v45
	v_mul_f32_e32 v74, v74, v46
	v_mul_f32_e32 v75, v75, v47
	v_mul_f32_e32 v76, v76, v48
	v_mul_f32_e32 v77, v77, v49
	v_mul_f32_e32 v78, v78, v50
	v_mul_f32_e32 v79, v79, v51
	v_cvt_pk_bf16_f32 v64, v64, v65
	v_cvt_pk_bf16_f32 v65, v66, v67
	v_cvt_pk_bf16_f32 v68, v68, v69
	v_cvt_pk_bf16_f32 v69, v70, v71
	v_cvt_pk_bf16_f32 v72, v72, v73
	v_cvt_pk_bf16_f32 v73, v74, v75
	v_cvt_pk_bf16_f32 v76, v76, v77
	v_cvt_pk_bf16_f32 v77, v78, v79
	global_store_dwordx2 v2, v[64:65], s[26:27] offset:0
	global_store_dwordx2 v2, v[68:69], s[26:27] offset:512
	global_store_dwordx2 v2, v[72:73], s[26:27] offset:1024
	global_store_dwordx2 v2, v[76:77], s[26:27] offset:1536
	v_mul_f32_e32 v96, v112, v15
	v_mul_f32_e32 v97, v113, v15
	v_mul_f32_e32 v98, v114, v15
	v_mul_f32_e32 v99, v115, v15
	v_mul_f32_e32 v100, v116, v15
	v_mul_f32_e32 v101, v117, v15
	v_mul_f32_e32 v102, v118, v15
	v_mul_f32_e32 v103, v119, v15
	v_mul_f32_e32 v104, v120, v15
	v_mul_f32_e32 v105, v121, v15
	v_mul_f32_e32 v106, v122, v15
	v_mul_f32_e32 v107, v123, v15
	v_mul_f32_e32 v108, v124, v15
	v_mul_f32_e32 v109, v125, v15
	v_mul_f32_e32 v110, v126, v15
	v_mul_f32_e32 v111, v127, v15
	v_mul_f32_e32 v96, v96, v36
	v_mul_f32_e32 v97, v97, v37
	v_mul_f32_e32 v98, v98, v38
	v_mul_f32_e32 v99, v99, v39
	v_mul_f32_e32 v100, v100, v40
	v_mul_f32_e32 v101, v101, v41
	v_mul_f32_e32 v102, v102, v42
	v_mul_f32_e32 v103, v103, v43
	v_mul_f32_e32 v104, v104, v44
	v_mul_f32_e32 v105, v105, v45
	v_mul_f32_e32 v106, v106, v46
	v_mul_f32_e32 v107, v107, v47
	v_mul_f32_e32 v108, v108, v48
	v_mul_f32_e32 v109, v109, v49
	v_mul_f32_e32 v110, v110, v50
	v_mul_f32_e32 v111, v111, v51
	v_cvt_pk_bf16_f32 v96, v96, v97
	v_cvt_pk_bf16_f32 v97, v98, v99
	v_cvt_pk_bf16_f32 v100, v100, v101
	v_cvt_pk_bf16_f32 v101, v102, v103
	v_cvt_pk_bf16_f32 v104, v104, v105
	v_cvt_pk_bf16_f32 v105, v106, v107
	v_cvt_pk_bf16_f32 v108, v108, v109
	v_cvt_pk_bf16_f32 v109, v110, v111
	global_store_dwordx2 v2, v[96:97], s[34:35] offset:0
	global_store_dwordx2 v2, v[100:101], s[34:35] offset:512
	global_store_dwordx2 v2, v[104:105], s[34:35] offset:1024
	global_store_dwordx2 v2, v[108:109], s[34:35] offset:1536
	s_waitcnt vmcnt(16)
	v_lshlrev_b32_e32 v128, 16, v130
	v_and_b32_e32 v129, 0xffff0000, v130
	v_lshlrev_b32_e32 v130, 16, v131
	v_and_b32_e32 v131, 0xffff0000, v131
	v_lshlrev_b32_e32 v132, 16, v134
	v_and_b32_e32 v133, 0xffff0000, v134
	v_lshlrev_b32_e32 v134, 16, v135
	v_and_b32_e32 v135, 0xffff0000, v135
	v_lshlrev_b32_e32 v136, 16, v138
	v_and_b32_e32 v137, 0xffff0000, v138
	v_lshlrev_b32_e32 v138, 16, v139
	v_and_b32_e32 v139, 0xffff0000, v139
	v_lshlrev_b32_e32 v140, 16, v142
	v_and_b32_e32 v141, 0xffff0000, v142
	v_lshlrev_b32_e32 v142, 16, v143
	v_and_b32_e32 v143, 0xffff0000, v143
	v_lshlrev_b32_e32 v160, 16, v162
	v_and_b32_e32 v161, 0xffff0000, v162
	v_lshlrev_b32_e32 v162, 16, v163
	v_and_b32_e32 v163, 0xffff0000, v163
	v_lshlrev_b32_e32 v164, 16, v166
	v_and_b32_e32 v165, 0xffff0000, v166
	v_lshlrev_b32_e32 v166, 16, v167
	v_and_b32_e32 v167, 0xffff0000, v167
	v_lshlrev_b32_e32 v168, 16, v170
	v_and_b32_e32 v169, 0xffff0000, v170
	v_lshlrev_b32_e32 v170, 16, v171
	v_and_b32_e32 v171, 0xffff0000, v171
	v_lshlrev_b32_e32 v172, 16, v174
	v_and_b32_e32 v173, 0xffff0000, v174
	v_lshlrev_b32_e32 v174, 16, v175
	v_and_b32_e32 v175, 0xffff0000, v175
	v_mul_f32_e32 v10, v128, v128
	v_fmac_f32_e32 v10, v129, v129
	v_fmac_f32_e32 v10, v130, v130
	v_fmac_f32_e32 v10, v131, v131
	v_fmac_f32_e32 v10, v132, v132
	v_fmac_f32_e32 v10, v133, v133
	v_fmac_f32_e32 v10, v134, v134
	v_fmac_f32_e32 v10, v135, v135
	v_fmac_f32_e32 v10, v136, v136
	v_fmac_f32_e32 v10, v137, v137
	v_fmac_f32_e32 v10, v138, v138
	v_fmac_f32_e32 v10, v139, v139
	v_fmac_f32_e32 v10, v140, v140
	v_fmac_f32_e32 v10, v141, v141
	v_fmac_f32_e32 v10, v142, v142
	v_fmac_f32_e32 v10, v143, v143
	v_mul_f32_e32 v11, v160, v160
	v_fmac_f32_e32 v11, v161, v161
	v_fmac_f32_e32 v11, v162, v162
	v_fmac_f32_e32 v11, v163, v163
	v_fmac_f32_e32 v11, v164, v164
	v_fmac_f32_e32 v11, v165, v165
	v_fmac_f32_e32 v11, v166, v166
	v_fmac_f32_e32 v11, v167, v167
	v_fmac_f32_e32 v11, v168, v168
	v_fmac_f32_e32 v11, v169, v169
	v_fmac_f32_e32 v11, v170, v170
	v_fmac_f32_e32 v11, v171, v171
	v_fmac_f32_e32 v11, v172, v172
	v_fmac_f32_e32 v11, v173, v173
	v_fmac_f32_e32 v11, v174, v174
	v_fmac_f32_e32 v11, v175, v175
	ds_bpermute_b32 v12, v4, v10
	ds_bpermute_b32 v13, v4, v11
	s_waitcnt lgkmcnt(0)
	v_add_f32_e32 v10, v10, v12
	v_add_f32_e32 v11, v11, v13
	ds_bpermute_b32 v12, v5, v10
	ds_bpermute_b32 v13, v5, v11
	s_waitcnt lgkmcnt(0)
	v_add_f32_e32 v10, v10, v12
	v_add_f32_e32 v11, v11, v13
	ds_bpermute_b32 v12, v6, v10
	ds_bpermute_b32 v13, v6, v11
	s_waitcnt lgkmcnt(0)
	v_add_f32_e32 v10, v10, v12
	v_add_f32_e32 v11, v11, v13
	ds_bpermute_b32 v12, v7, v10
	ds_bpermute_b32 v13, v7, v11
	s_waitcnt lgkmcnt(0)
	v_add_f32_e32 v10, v10, v12
	v_add_f32_e32 v11, v11, v13
	ds_bpermute_b32 v12, v8, v10
	ds_bpermute_b32 v13, v8, v11
	s_waitcnt lgkmcnt(0)
	v_add_f32_e32 v10, v10, v12
	v_add_f32_e32 v11, v11, v13
	ds_bpermute_b32 v12, v9, v10
	ds_bpermute_b32 v13, v9, v11
	s_waitcnt lgkmcnt(0)
	v_add_f32_e32 v10, v10, v12
	v_add_f32_e32 v11, v11, v13
	v_fma_f32 v14, v10, s17, v3
	v_fma_f32 v15, v11, s17, v3
	v_rsq_f32_e32 v14, v14
	v_rsq_f32_e32 v15, v15
	s_nop 0
	v_mul_f32_e32 v128, v128, v14
	v_mul_f32_e32 v129, v129, v14
	v_mul_f32_e32 v130, v130, v14
	v_mul_f32_e32 v131, v131, v14
	v_mul_f32_e32 v132, v132, v14
	v_mul_f32_e32 v133, v133, v14
	v_mul_f32_e32 v134, v134, v14
	v_mul_f32_e32 v135, v135, v14
	v_mul_f32_e32 v136, v136, v14
	v_mul_f32_e32 v137, v137, v14
	v_mul_f32_e32 v138, v138, v14
	v_mul_f32_e32 v139, v139, v14
	v_mul_f32_e32 v140, v140, v14
	v_mul_f32_e32 v141, v141, v14
	v_mul_f32_e32 v142, v142, v14
	v_mul_f32_e32 v143, v143, v14
	v_fmac_f32_e32 v144, v128, v20
	v_fmac_f32_e32 v145, v129, v21
	v_fmac_f32_e32 v146, v130, v22
	v_fmac_f32_e32 v147, v131, v23
	v_fmac_f32_e32 v148, v132, v24
	v_fmac_f32_e32 v149, v133, v25
	v_fmac_f32_e32 v150, v134, v26
	v_fmac_f32_e32 v151, v135, v27
	v_fmac_f32_e32 v152, v136, v28
	v_fmac_f32_e32 v153, v137, v29
	v_fmac_f32_e32 v154, v138, v30
	v_fmac_f32_e32 v155, v139, v31
	v_fmac_f32_e32 v156, v140, v32
	v_fmac_f32_e32 v157, v141, v33
	v_fmac_f32_e32 v158, v142, v34
	v_fmac_f32_e32 v159, v143, v35
	global_store_dwordx4 v1, v[144:147], s[40:41] offset:0
	global_store_dwordx4 v1, v[148:151], s[40:41] offset:1024
	global_store_dwordx4 v1, v[152:155], s[40:41] offset:2048
	global_store_dwordx4 v1, v[156:159], s[40:41] offset:3072
	v_mul_f32_e32 v160, v160, v15
	v_mul_f32_e32 v161, v161, v15
	v_mul_f32_e32 v162, v162, v15
	v_mul_f32_e32 v163, v163, v15
	v_mul_f32_e32 v164, v164, v15
	v_mul_f32_e32 v165, v165, v15
	v_mul_f32_e32 v166, v166, v15
	v_mul_f32_e32 v167, v167, v15
	v_mul_f32_e32 v168, v168, v15
	v_mul_f32_e32 v169, v169, v15
	v_mul_f32_e32 v170, v170, v15
	v_mul_f32_e32 v171, v171, v15
	v_mul_f32_e32 v172, v172, v15
	v_mul_f32_e32 v173, v173, v15
	v_mul_f32_e32 v174, v174, v15
	v_mul_f32_e32 v175, v175, v15
	v_fmac_f32_e32 v176, v160, v20
	v_fmac_f32_e32 v177, v161, v21
	v_fmac_f32_e32 v178, v162, v22
	v_fmac_f32_e32 v179, v163, v23
	v_fmac_f32_e32 v180, v164, v24
	v_fmac_f32_e32 v181, v165, v25
	v_fmac_f32_e32 v182, v166, v26
	v_fmac_f32_e32 v183, v167, v27
	v_fmac_f32_e32 v184, v168, v28
	v_fmac_f32_e32 v185, v169, v29
	v_fmac_f32_e32 v186, v170, v30
	v_fmac_f32_e32 v187, v171, v31
	v_fmac_f32_e32 v188, v172, v32
	v_fmac_f32_e32 v189, v173, v33
	v_fmac_f32_e32 v190, v174, v34
	v_fmac_f32_e32 v191, v175, v35
	global_store_dwordx4 v1, v[176:179], s[48:49] offset:0
	global_store_dwordx4 v1, v[180:183], s[48:49] offset:1024
	global_store_dwordx4 v1, v[184:187], s[48:49] offset:2048
	global_store_dwordx4 v1, v[188:191], s[48:49] offset:3072
	v_mul_f32_e32 v10, v144, v144
	v_fmac_f32_e32 v10, v145, v145
	v_fmac_f32_e32 v10, v146, v146
	v_fmac_f32_e32 v10, v147, v147
	v_fmac_f32_e32 v10, v148, v148
	v_fmac_f32_e32 v10, v149, v149
	v_fmac_f32_e32 v10, v150, v150
	v_fmac_f32_e32 v10, v151, v151
	v_fmac_f32_e32 v10, v152, v152
	v_fmac_f32_e32 v10, v153, v153
	v_fmac_f32_e32 v10, v154, v154
	v_fmac_f32_e32 v10, v155, v155
	v_fmac_f32_e32 v10, v156, v156
	v_fmac_f32_e32 v10, v157, v157
	v_fmac_f32_e32 v10, v158, v158
	v_fmac_f32_e32 v10, v159, v159
	v_mul_f32_e32 v11, v176, v176
	v_fmac_f32_e32 v11, v177, v177
	v_fmac_f32_e32 v11, v178, v178
	v_fmac_f32_e32 v11, v179, v179
	v_fmac_f32_e32 v11, v180, v180
	v_fmac_f32_e32 v11, v181, v181
	v_fmac_f32_e32 v11, v182, v182
	v_fmac_f32_e32 v11, v183, v183
	v_fmac_f32_e32 v11, v184, v184
	v_fmac_f32_e32 v11, v185, v185
	v_fmac_f32_e32 v11, v186, v186
	v_fmac_f32_e32 v11, v187, v187
	v_fmac_f32_e32 v11, v188, v188
	v_fmac_f32_e32 v11, v189, v189
	v_fmac_f32_e32 v11, v190, v190
	v_fmac_f32_e32 v11, v191, v191
	ds_bpermute_b32 v12, v4, v10
	ds_bpermute_b32 v13, v4, v11
	s_waitcnt lgkmcnt(0)
	v_add_f32_e32 v10, v10, v12
	v_add_f32_e32 v11, v11, v13
	ds_bpermute_b32 v12, v5, v10
	ds_bpermute_b32 v13, v5, v11
	s_waitcnt lgkmcnt(0)
	v_add_f32_e32 v10, v10, v12
	v_add_f32_e32 v11, v11, v13
	ds_bpermute_b32 v12, v6, v10
	ds_bpermute_b32 v13, v6, v11
	s_waitcnt lgkmcnt(0)
	v_add_f32_e32 v10, v10, v12
	v_add_f32_e32 v11, v11, v13
	ds_bpermute_b32 v12, v7, v10
	ds_bpermute_b32 v13, v7, v11
	s_waitcnt lgkmcnt(0)
	v_add_f32_e32 v10, v10, v12
	v_add_f32_e32 v11, v11, v13
	ds_bpermute_b32 v12, v8, v10
	ds_bpermute_b32 v13, v8, v11
	s_waitcnt lgkmcnt(0)
	v_add_f32_e32 v10, v10, v12
	v_add_f32_e32 v11, v11, v13
	ds_bpermute_b32 v12, v9, v10
	ds_bpermute_b32 v13, v9, v11
	s_waitcnt lgkmcnt(0)
	v_add_f32_e32 v10, v10, v12
	v_add_f32_e32 v11, v11, v13
	v_fma_f32 v14, v10, s17, v3
	v_fma_f32 v15, v11, s17, v3
	v_rsq_f32_e32 v14, v14
	v_rsq_f32_e32 v15, v15
	s_nop 0
	v_mul_f32_e32 v128, v144, v14
	v_mul_f32_e32 v129, v145, v14
	v_mul_f32_e32 v130, v146, v14
	v_mul_f32_e32 v131, v147, v14
	v_mul_f32_e32 v132, v148, v14
	v_mul_f32_e32 v133, v149, v14
	v_mul_f32_e32 v134, v150, v14
	v_mul_f32_e32 v135, v151, v14
	v_mul_f32_e32 v136, v152, v14
	v_mul_f32_e32 v137, v153, v14
	v_mul_f32_e32 v138, v154, v14
	v_mul_f32_e32 v139, v155, v14
	v_mul_f32_e32 v140, v156, v14
	v_mul_f32_e32 v141, v157, v14
	v_mul_f32_e32 v142, v158, v14
	v_mul_f32_e32 v143, v159, v14
	v_mul_f32_e32 v128, v128, v36
	v_mul_f32_e32 v129, v129, v37
	v_mul_f32_e32 v130, v130, v38
	v_mul_f32_e32 v131, v131, v39
	v_mul_f32_e32 v132, v132, v40
	v_mul_f32_e32 v133, v133, v41
	v_mul_f32_e32 v134, v134, v42
	v_mul_f32_e32 v135, v135, v43
	v_mul_f32_e32 v136, v136, v44
	v_mul_f32_e32 v137, v137, v45
	v_mul_f32_e32 v138, v138, v46
	v_mul_f32_e32 v139, v139, v47
	v_mul_f32_e32 v140, v140, v48
	v_mul_f32_e32 v141, v141, v49
	v_mul_f32_e32 v142, v142, v50
	v_mul_f32_e32 v143, v143, v51
	v_cvt_pk_bf16_f32 v128, v128, v129
	v_cvt_pk_bf16_f32 v129, v130, v131
	v_cvt_pk_bf16_f32 v132, v132, v133
	v_cvt_pk_bf16_f32 v133, v134, v135
	v_cvt_pk_bf16_f32 v136, v136, v137
	v_cvt_pk_bf16_f32 v137, v138, v139
	v_cvt_pk_bf16_f32 v140, v140, v141
	v_cvt_pk_bf16_f32 v141, v142, v143
	global_store_dwordx2 v2, v[128:129], s[42:43] offset:0
	global_store_dwordx2 v2, v[132:133], s[42:43] offset:512
	global_store_dwordx2 v2, v[136:137], s[42:43] offset:1024
	global_store_dwordx2 v2, v[140:141], s[42:43] offset:1536
	v_mul_f32_e32 v160, v176, v15
	v_mul_f32_e32 v161, v177, v15
	v_mul_f32_e32 v162, v178, v15
	v_mul_f32_e32 v163, v179, v15
	v_mul_f32_e32 v164, v180, v15
	v_mul_f32_e32 v165, v181, v15
	v_mul_f32_e32 v166, v182, v15
	v_mul_f32_e32 v167, v183, v15
	v_mul_f32_e32 v168, v184, v15
	v_mul_f32_e32 v169, v185, v15
	v_mul_f32_e32 v170, v186, v15
	v_mul_f32_e32 v171, v187, v15
	v_mul_f32_e32 v172, v188, v15
	v_mul_f32_e32 v173, v189, v15
	v_mul_f32_e32 v174, v190, v15
	v_mul_f32_e32 v175, v191, v15
	v_mul_f32_e32 v160, v160, v36
	v_mul_f32_e32 v161, v161, v37
	v_mul_f32_e32 v162, v162, v38
	v_mul_f32_e32 v163, v163, v39
	v_mul_f32_e32 v164, v164, v40
	v_mul_f32_e32 v165, v165, v41
	v_mul_f32_e32 v166, v166, v42
	v_mul_f32_e32 v167, v167, v43
	v_mul_f32_e32 v168, v168, v44
	v_mul_f32_e32 v169, v169, v45
	v_mul_f32_e32 v170, v170, v46
	v_mul_f32_e32 v171, v171, v47
	v_mul_f32_e32 v172, v172, v48
	v_mul_f32_e32 v173, v173, v49
	v_mul_f32_e32 v174, v174, v50
	v_mul_f32_e32 v175, v175, v51
	v_cvt_pk_bf16_f32 v160, v160, v161
	v_cvt_pk_bf16_f32 v161, v162, v163
	v_cvt_pk_bf16_f32 v164, v164, v165
	v_cvt_pk_bf16_f32 v165, v166, v167
	v_cvt_pk_bf16_f32 v168, v168, v169
	v_cvt_pk_bf16_f32 v169, v170, v171
	v_cvt_pk_bf16_f32 v172, v172, v173
	v_cvt_pk_bf16_f32 v173, v174, v175
	global_store_dwordx2 v2, v[160:161], s[50:51] offset:0
	global_store_dwordx2 v2, v[164:165], s[50:51] offset:512
	global_store_dwordx2 v2, v[168:169], s[50:51] offset:1024
	global_store_dwordx2 v2, v[172:173], s[50:51] offset:1536
	v_add_f32_e32 v208, v208, v212
	v_add_f32_e32 v209, v209, v213
	v_add_f32_e32 v210, v210, v214
	v_add_f32_e32 v211, v211, v215
	v_readfirstlane_b32 s18, v0
	s_lshr_b32 s18, s18, 6
	s_lshl_b32 s19, s18, 2
	s_and_b32 s52, s18, 4
	s_lshl_b32 s52, s52, 2
	v_mov_b32_e32 v16, s19
	v_mov_b32_e32 v17, s52
	v_mul_f32_e32 v10, v208, v208
	v_fmac_f32_e32 v10, v209, v209
	v_fmac_f32_e32 v10, v210, v210
	v_fmac_f32_e32 v10, v211, v211
	ds_bpermute_b32 v11, v4, v10
	s_waitcnt lgkmcnt(0)
	v_add_f32_e32 v10, v10, v11
	ds_bpermute_b32 v11, v5, v10
	s_waitcnt lgkmcnt(0)
	v_add_f32_e32 v10, v10, v11
	ds_bpermute_b32 v11, v6, v10
	s_waitcnt lgkmcnt(0)
	v_add_f32_e32 v10, v10, v11
	ds_bpermute_b32 v11, v7, v10
	s_waitcnt lgkmcnt(0)
	v_add_f32_e32 v10, v10, v11
	ds_bpermute_b32 v11, v8, v10
	s_waitcnt lgkmcnt(0)
	v_add_f32_e32 v10, v10, v11
	ds_bpermute_b32 v11, v9, v10
	s_waitcnt lgkmcnt(0)
	v_add_f32_e32 v10, v10, v11
	ds_write_b32 v16, v10 offset:0
	s_waitcnt lgkmcnt(0)
	s_barrier
	ds_read_b128 v[12:15], v17 offset:0
	s_waitcnt lgkmcnt(0)
	v_add_f32_e32 v12, v12, v13
	v_add_f32_e32 v14, v14, v15
	v_add_f32_e32 v10, v12, v14
	v_fma_f32 v11, v10, s17, v3
	v_rsq_f32_e32 v11, v11
	s_nop 0
	v_mul_f32_e32 v208, v208, v11
	v_mul_f32_e32 v209, v209, v11
	v_mul_f32_e32 v210, v210, v11
	v_mul_f32_e32 v211, v211, v11
	v_fmac_f32_e32 v240, v208, v244
	v_fmac_f32_e32 v241, v209, v245
	v_fmac_f32_e32 v242, v210, v246
	v_fmac_f32_e32 v243, v211, v247
	s_lshl_b32 s18, s54, 12
	s_add_u32 s18, s18, s55
	s_add_u32 s56, s4, s18
	s_addc_u32 s57, s5, 0
	s_add_u32 s56, s56, 0x4000000
	s_addc_u32 s57, s57, 0
	global_store_dwordx4 v1, v[240:243], s[56:57]
	v_mul_f32_e32 v10, v240, v240
	v_fmac_f32_e32 v10, v241, v241
	v_fmac_f32_e32 v10, v242, v242
	v_fmac_f32_e32 v10, v243, v243
	ds_bpermute_b32 v11, v4, v10
	s_waitcnt lgkmcnt(0)
	v_add_f32_e32 v10, v10, v11
	ds_bpermute_b32 v11, v5, v10
	s_waitcnt lgkmcnt(0)
	v_add_f32_e32 v10, v10, v11
	ds_bpermute_b32 v11, v6, v10
	s_waitcnt lgkmcnt(0)
	v_add_f32_e32 v10, v10, v11
	ds_bpermute_b32 v11, v7, v10
	s_waitcnt lgkmcnt(0)
	v_add_f32_e32 v10, v10, v11
	ds_bpermute_b32 v11, v8, v10
	s_waitcnt lgkmcnt(0)
	v_add_f32_e32 v10, v10, v11
	ds_bpermute_b32 v11, v9, v10
	s_waitcnt lgkmcnt(0)
	v_add_f32_e32 v10, v10, v11
	ds_write_b32 v16, v10 offset:64
	s_waitcnt lgkmcnt(0)
	s_barrier
	ds_read_b128 v[12:15], v17 offset:64
	s_waitcnt lgkmcnt(0)
	v_add_f32_e32 v12, v12, v13
	v_add_f32_e32 v14, v14, v15
	v_add_f32_e32 v10, v12, v14
	v_fma_f32 v11, v10, s17, v3
	v_rsq_f32_e32 v11, v11
	s_nop 0
	v_mul_f32_e32 v208, v240, v11
	v_mul_f32_e32 v209, v241, v11
	v_mul_f32_e32 v210, v242, v11
	v_mul_f32_e32 v211, v243, v11
	v_mul_f32_e32 v208, v208, v248
	v_mul_f32_e32 v209, v209, v249
	v_mul_f32_e32 v210, v210, v250
	v_mul_f32_e32 v211, v211, v251
	v_cvt_pk_bf16_f32 v208, v208, v209
	v_cvt_pk_bf16_f32 v209, v210, v211
	s_lshl_b32 s18, s54, 11
	s_lshr_b32 s19, s55, 1
	s_add_u32 s18, s18, s19
	s_add_u32 s56, s6, s18
	s_addc_u32 s57, s7, 0
	s_add_u32 s56, s56, 0x5100000
	s_addc_u32 s57, s57, 0
	global_store_dwordx2 v2, v[208:209], s[56:57]

	.amdhsa_kernel _Z10fwd_kernelILi4ELi5EEv4Args
		.amdhsa_group_segment_fixed_size 0
		.amdhsa_private_segment_fixed_size 0
		.amdhsa_kernarg_size 488
		.amdhsa_user_sgpr_count 2
		.amdhsa_user_sgpr_dispatch_ptr 0
		.amdhsa_user_sgpr_queue_ptr 0
		.amdhsa_user_sgpr_kernarg_segment_ptr 1
		.amdhsa_user_sgpr_dispatch_id 0
		.amdhsa_user_sgpr_kernarg_preload_length 0
		.amdhsa_user_sgpr_kernarg_preload_offset 0
		.amdhsa_user_sgpr_private_segment_size 0
		.amdhsa_uses_dynamic_stack 0
		.amdhsa_enable_private_segment 0
		.amdhsa_system_sgpr_workgroup_id_x 1
		.amdhsa_system_sgpr_workgroup_id_y 0
		.amdhsa_system_sgpr_workgroup_id_z 0
		.amdhsa_system_sgpr_workgroup_info 0
		.amdhsa_system_vgpr_workitem_id 0
		.amdhsa_next_free_vgpr 256
		.amdhsa_next_free_sgpr 60
		.amdhsa_accum_offset 256
		.amdhsa_reserve_vcc 1
		.amdhsa_float_round_mode_32 0
		.amdhsa_float_round_mode_16_64 0
		.amdhsa_float_denorm_mode_32 3
		.amdhsa_float_denorm_mode_16_64 3
		.amdhsa_dx10_clamp 1
		.amdhsa_ieee_mode 1
		.amdhsa_fp16_overflow 0
		.amdhsa_tg_split 0
		.amdhsa_exception_fp_ieee_invalid_op 0
		.amdhsa_exception_fp_denorm_src 0
		.amdhsa_exception_fp_ieee_div_zero 0
		.amdhsa_exception_fp_ieee_overflow 0
		.amdhsa_exception_fp_ieee_underflow 0
		.amdhsa_exception_fp_ieee_inexact 0
		.amdhsa_exception_int_div_zero 0
	.end_amdhsa_kernel

_Z10fwd_kernelILi7ELi8EEv4Args:
	s_load_dword s3, s[0:1], 0xe8
	s_load_dwordx4 s[4:7], s[0:1], 0xd0
	s_load_dwordx2 s[8:9], s[0:1], 0xb8
	s_load_dwordx2 s[10:11], s[0:1], 0xa0
	s_waitcnt lgkmcnt(0)
	s_cmp_lg_u32 s3, 0x100
	s_cbranch_scc1 .Lrows7_orig
	s_add_u32 s10, s10, 0x1000
	s_addc_u32 s11, s11, 0
	v_readfirstlane_b32 s16, v0
	s_lshr_b32 s16, s16, 6
	s_lshl_b32 s18, s2, 3
	s_add_u32 s16, s16, s18
	s_mov_b32 s17, 0x3a800000
	v_mov_b32_e32 v3, 0x358637bd
	v_and_b32_e32 v10, 63, v0
	v_lshlrev_b32_e32 v1, 4, v10
	v_lshlrev_b32_e32 v2, 3, v10
	v_xor_b32_e32 v4, 1, v10
	v_xor_b32_e32 v5, 2, v10
	v_xor_b32_e32 v6, 4, v10
	v_xor_b32_e32 v7, 8, v10
	v_xor_b32_e32 v8, 16, v10
	v_xor_b32_e32 v9, 32, v10
	v_lshlrev_b32_e32 v4, 2, v4
	v_lshlrev_b32_e32 v5, 2, v5
	v_lshlrev_b32_e32 v6, 2, v6
	v_lshlrev_b32_e32 v7, 2, v7
	v_lshlrev_b32_e32 v8, 2, v8
	v_lshlrev_b32_e32 v9, 2, v9
	global_load_dwordx4 v[20:23], v1, s[8:9] offset:0
	global_load_dwordx4 v[24:27], v1, s[8:9] offset:1024
	global_load_dwordx4 v[28:31], v1, s[8:9] offset:2048
	global_load_dwordx4 v[32:35], v1, s[8:9] offset:3072
	global_load_dwordx4 v[36:39], v1, s[10:11] offset:0
	global_load_dwordx4 v[40:43], v1, s[10:11] offset:1024
	global_load_dwordx4 v[44:47], v1, s[10:11] offset:2048
	global_load_dwordx4 v[48:51], v1, s[10:11] offset:3072
	s_lshr_b32 s54, s16, 2
	s_and_b32 s55, s16, 3
	s_lshl_b32 s55, s55, 10
	s_lshl_b32 s18, s54, 12
	s_add_u32 s18, s18, s55
	s_add_u32 s56, s6, s18
	s_addc_u32 s57, s7, 0
	s_add_u32 s56, s56, 0x100000
	s_addc_u32 s57, s57, 0
	global_load_dwordx4 v[208:211], v1, s[56:57]
	s_add_u32 s56, s56, 0x200000
	s_addc_u32 s57, s57, 0
	global_load_dwordx4 v[212:215], v1, s[56:57]
	s_add_u32 s56, s56, 0x200000
	s_addc_u32 s57, s57, 0
	global_load_dwordx4 v[216:219], v1, s[56:57]
	s_add_u32 s56, s56, 0x200000
	s_addc_u32 s57, s57, 0
	global_load_dwordx4 v[220:223], v1, s[56:57]
	s_add_u32 s56, s56, 0x200000
	s_addc_u32 s57, s57, 0
	global_load_dwordx4 v[224:227], v1, s[56:57]
	s_add_u32 s56, s56, 0x200000
	s_addc_u32 s57, s57, 0
	global_load_dwordx4 v[228:231], v1, s[56:57]
	s_add_u32 s56, s56, 0x200000
	s_addc_u32 s57, s57, 0
	global_load_dwordx4 v[232:235], v1, s[56:57]
	s_add_u32 s56, s56, 0x200000
	s_addc_u32 s57, s57, 0
	global_load_dwordx4 v[236:239], v1, s[56:57]
	s_add_u32 s56, s4, s18
	s_addc_u32 s57, s5, 0
	s_add_u32 s56, s56, 0x4000000
	s_addc_u32 s57, s57, 0
	global_load_dwordx4 v[240:243], v1, s[56:57]
	s_add_u32 s56, s8, s55
	s_addc_u32 s57, s9, 0
	global_load_dwordx4 v[244:247], v1, s[56:57]
	s_add_u32 s56, s10, s55
	s_addc_u32 s57, s11, 0
	global_load_dwordx4 v[248:251], v1, s[56:57]
	s_add_u32 s53, s16, 0x0
	s_lshl_b32 s18, s53, 12
	s_lshl_b32 s19, s53, 11
	s_add_u32 s20, s4, s18
	s_addc_u32 s21, s5, 0
	s_add_u32 s22, s6, s19
	s_addc_u32 s23, s7, 0
	s_add_u32 s22, s22, 0x5200000
	s_addc_u32 s23, s23, 0
	s_add_u32 s24, s4, s18
	s_addc_u32 s25, s5, 0
	s_add_u32 s26, s6, s19
	s_addc_u32 s27, s7, 0
	s_add_u32 s26, s26, 0x3100000
	s_addc_u32 s27, s27, 0
	global_load_dwordx2 v[66:67], v2, s[22:23] offset:0
	global_load_dwordx2 v[70:71], v2, s[22:23] offset:512
	global_load_dwordx2 v[74:75], v2, s[22:23] offset:1024
	global_load_dwordx2 v[78:79], v2, s[22:23] offset:1536
	global_load_dwordx4 v[80:83], v1, s[20:21] offset:0
	global_load_dwordx4 v[84:87], v1, s[20:21] offset:1024
	global_load_dwordx4 v[88:91], v1, s[20:21] offset:2048
	global_load_dwordx4 v[92:95], v1, s[20:21] offset:3072
	s_add_u32 s53, s16, 0x800
	s_lshl_b32 s18, s53, 12
	s_lshl_b32 s19, s53, 11
	s_add_u32 s28, s4, s18
	s_addc_u32 s29, s5, 0
	s_add_u32 s30, s6, s19
	s_addc_u32 s31, s7, 0
	s_add_u32 s30, s30, 0x5200000
	s_addc_u32 s31, s31, 0
	s_add_u32 s32, s4, s18
	s_addc_u32 s33, s5, 0
	s_add_u32 s34, s6, s19
	s_addc_u32 s35, s7, 0
	s_add_u32 s34, s34, 0x3100000
	s_addc_u32 s35, s35, 0
	global_load_dwordx2 v[98:99], v2, s[30:31] offset:0
	global_load_dwordx2 v[102:103], v2, s[30:31] offset:512
	global_load_dwordx2 v[106:107], v2, s[30:31] offset:1024
	global_load_dwordx2 v[110:111], v2, s[30:31] offset:1536
	global_load_dwordx4 v[112:115], v1, s[28:29] offset:0
	global_load_dwordx4 v[116:119], v1, s[28:29] offset:1024
	global_load_dwordx4 v[120:123], v1, s[28:29] offset:2048
	global_load_dwordx4 v[124:127], v1, s[28:29] offset:3072
	s_add_u32 s53, s16, 0x1000
	s_lshl_b32 s18, s53, 12
	s_lshl_b32 s19, s53, 11
	s_add_u32 s36, s4, s18
	s_addc_u32 s37, s5, 0
	s_add_u32 s38, s6, s19
	s_addc_u32 s39, s7, 0
	s_add_u32 s38, s38, 0x5200000
	s_addc_u32 s39, s39, 0
	s_add_u32 s40, s4, s18
	s_addc_u32 s41, s5, 0
	s_add_u32 s42, s6, s19
	s_addc_u32 s43, s7, 0
	s_add_u32 s42, s42, 0x3100000
	s_addc_u32 s43, s43, 0
	global_load_dwordx2 v[130:131], v2, s[38:39] offset:0
	global_load_dwordx2 v[134:135], v2, s[38:39] offset:512
	global_load_dwordx2 v[138:139], v2, s[38:39] offset:1024
	global_load_dwordx2 v[142:143], v2, s[38:39] offset:1536
	global_load_dwordx4 v[144:147], v1, s[36:37] offset:0
	global_load_dwordx4 v[148:151], v1, s[36:37] offset:1024
	global_load_dwordx4 v[152:155], v1, s[36:37] offset:2048
	global_load_dwordx4 v[156:159], v1, s[36:37] offset:3072
	s_add_u32 s53, s16, 0x1800
	s_lshl_b32 s18, s53, 12
	s_lshl_b32 s19, s53, 11
	s_add_u32 s44, s4, s18
	s_addc_u32 s45, s5, 0
	s_add_u32 s46, s6, s19
	s_addc_u32 s47, s7, 0
	s_add_u32 s46, s46, 0x5200000
	s_addc_u32 s47, s47, 0
	s_add_u32 s48, s4, s18
	s_addc_u32 s49, s5, 0
	s_add_u32 s50, s6, s19
	s_addc_u32 s51, s7, 0
	s_add_u32 s50, s50, 0x3100000
	s_addc_u32 s51, s51, 0
	global_load_dwordx2 v[162:163], v2, s[46:47] offset:0
	global_load_dwordx2 v[166:167], v2, s[46:47] offset:512
	global_load_dwordx2 v[170:171], v2, s[46:47] offset:1024
	global_load_dwordx2 v[174:175], v2, s[46:47] offset:1536
	global_load_dwordx4 v[176:179], v1, s[44:45] offset:0
	global_load_dwordx4 v[180:183], v1, s[44:45] offset:1024
	global_load_dwordx4 v[184:187], v1, s[44:45] offset:2048
	global_load_dwordx4 v[188:191], v1, s[44:45] offset:3072
	s_waitcnt vmcnt(16)
	v_lshlrev_b32_e32 v64, 16, v66
	v_and_b32_e32 v65, 0xffff0000, v66
	v_lshlrev_b32_e32 v66, 16, v67
	v_and_b32_e32 v67, 0xffff0000, v67
	v_lshlrev_b32_e32 v68, 16, v70
	v_and_b32_e32 v69, 0xffff0000, v70
	v_lshlrev_b32_e32 v70, 16, v71
	v_and_b32_e32 v71, 0xffff0000, v71
	v_lshlrev_b32_e32 v72, 16, v74
	v_and_b32_e32 v73, 0xffff0000, v74
	v_lshlrev_b32_e32 v74, 16, v75
	v_and_b32_e32 v75, 0xffff0000, v75
	v_lshlrev_b32_e32 v76, 16, v78
	v_and_b32_e32 v77, 0xffff0000, v78
	v_lshlrev_b32_e32 v78, 16, v79
	v_and_b32_e32 v79, 0xffff0000, v79
	v_lshlrev_b32_e32 v96, 16, v98
	v_and_b32_e32 v97, 0xffff0000, v98
	v_lshlrev_b32_e32 v98, 16, v99
	v_and_b32_e32 v99, 0xffff0000, v99
	v_lshlrev_b32_e32 v100, 16, v102
	v_and_b32_e32 v101, 0xffff0000, v102
	v_lshlrev_b32_e32 v102, 16, v103
	v_and_b32_e32 v103, 0xffff0000, v103
	v_lshlrev_b32_e32 v104, 16, v106
	v_and_b32_e32 v105, 0xffff0000, v106
	v_lshlrev_b32_e32 v106, 16, v107
	v_and_b32_e32 v107, 0xffff0000, v107
	v_lshlrev_b32_e32 v108, 16, v110
	v_and_b32_e32 v109, 0xffff0000, v110
	v_lshlrev_b32_e32 v110, 16, v111
	v_and_b32_e32 v111, 0xffff0000, v111
	v_mul_f32_e32 v10, v64, v64
	v_fmac_f32_e32 v10, v65, v65
	v_fmac_f32_e32 v10, v66, v66
	v_fmac_f32_e32 v10, v67, v67
	v_fmac_f32_e32 v10, v68, v68
	v_fmac_f32_e32 v10, v69, v69
	v_fmac_f32_e32 v10, v70, v70
	v_fmac_f32_e32 v10, v71, v71
	v_fmac_f32_e32 v10, v72, v72
	v_fmac_f32_e32 v10, v73, v73
	v_fmac_f32_e32 v10, v74, v74
	v_fmac_f32_e32 v10, v75, v75
	v_fmac_f32_e32 v10, v76, v76
	v_fmac_f32_e32 v10, v77, v77
	v_fmac_f32_e32 v10, v78, v78
	v_fmac_f32_e32 v10, v79, v79
	v_mul_f32_e32 v11, v96, v96
	v_fmac_f32_e32 v11, v97, v97
	v_fmac_f32_e32 v11, v98, v98
	v_fmac_f32_e32 v11, v99, v99
	v_fmac_f32_e32 v11, v100, v100
	v_fmac_f32_e32 v11, v101, v101
	v_fmac_f32_e32 v11, v102, v102
	v_fmac_f32_e32 v11, v103, v103
	v_fmac_f32_e32 v11, v104, v104
	v_fmac_f32_e32 v11, v105, v105
	v_fmac_f32_e32 v11, v106, v106
	v_fmac_f32_e32 v11, v107, v107
	v_fmac_f32_e32 v11, v108, v108
	v_fmac_f32_e32 v11, v109, v109
	v_fmac_f32_e32 v11, v110, v110
	v_fmac_f32_e32 v11, v111, v111
	ds_bpermute_b32 v12, v4, v10
	ds_bpermute_b32 v13, v4, v11
	s_waitcnt lgkmcnt(0)
	v_add_f32_e32 v10, v10, v12
	v_add_f32_e32 v11, v11, v13
	ds_bpermute_b32 v12, v5, v10
	ds_bpermute_b32 v13, v5, v11
	s_waitcnt lgkmcnt(0)
	v_add_f32_e32 v10, v10, v12
	v_add_f32_e32 v11, v11, v13
	ds_bpermute_b32 v12, v6, v10
	ds_bpermute_b32 v13, v6, v11
	s_waitcnt lgkmcnt(0)
	v_add_f32_e32 v10, v10, v12
	v_add_f32_e32 v11, v11, v13
	ds_bpermute_b32 v12, v7, v10
	ds_bpermute_b32 v13, v7, v11
	s_waitcnt lgkmcnt(0)
	v_add_f32_e32 v10, v10, v12
	v_add_f32_e32 v11, v11, v13
	ds_bpermute_b32 v12, v8, v10
	ds_bpermute_b32 v13, v8, v11
	s_waitcnt lgkmcnt(0)
	v_add_f32_e32 v10, v10, v12
	v_add_f32_e32 v11, v11, v13
	ds_bpermute_b32 v12, v9, v10
	ds_bpermute_b32 v13, v9, v11
	s_waitcnt lgkmcnt(0)
	v_add_f32_e32 v10, v10, v12
	v_add_f32_e32 v11, v11, v13
	v_fma_f32 v14, v10, s17, v3
	v_fma_f32 v15, v11, s17, v3
	v_rsq_f32_e32 v14, v14
	v_rsq_f32_e32 v15, v15
	s_nop 0
	v_mul_f32_e32 v64, v64, v14
	v_mul_f32_e32 v65, v65, v14
	v_mul_f32_e32 v66, v66, v14
	v_mul_f32_e32 v67, v67, v14
	v_mul_f32_e32 v68, v68, v14
	v_mul_f32_e32 v69, v69, v14
	v_mul_f32_e32 v70, v70, v14
	v_mul_f32_e32 v71, v71, v14
	v_mul_f32_e32 v72, v72, v14
	v_mul_f32_e32 v73, v73, v14
	v_mul_f32_e32 v74, v74, v14
	v_mul_f32_e32 v75, v75, v14
	v_mul_f32_e32 v76, v76, v14
	v_mul_f32_e32 v77, v77, v14
	v_mul_f32_e32 v78, v78, v14
	v_mul_f32_e32 v79, v79, v14
	v_fmac_f32_e32 v80, v64, v20
	v_fmac_f32_e32 v81, v65, v21
	v_fmac_f32_e32 v82, v66, v22
	v_fmac_f32_e32 v83, v67, v23
	v_fmac_f32_e32 v84, v68, v24
	v_fmac_f32_e32 v85, v69, v25
	v_fmac_f32_e32 v86, v70, v26
	v_fmac_f32_e32 v87, v71, v27
	v_fmac_f32_e32 v88, v72, v28
	v_fmac_f32_e32 v89, v73, v29
	v_fmac_f32_e32 v90, v74, v30
	v_fmac_f32_e32 v91, v75, v31
	v_fmac_f32_e32 v92, v76, v32
	v_fmac_f32_e32 v93, v77, v33
	v_fmac_f32_e32 v94, v78, v34
	v_fmac_f32_e32 v95, v79, v35
	global_store_dwordx4 v1, v[80:83], s[24:25] offset:0
	global_store_dwordx4 v1, v[84:87], s[24:25] offset:1024
	global_store_dwordx4 v1, v[88:91], s[24:25] offset:2048
	global_store_dwordx4 v1, v[92:95], s[24:25] offset:3072
	v_mul_f32_e32 v96, v96, v15
	v_mul_f32_e32 v97, v97, v15
	v_mul_f32_e32 v98, v98, v15
	v_mul_f32_e32 v99, v99, v15
	v_mul_f32_e32 v100, v100, v15
	v_mul_f32_e32 v101, v101, v15
	v_mul_f32_e32 v102, v102, v15
	v_mul_f32_e32 v103, v103, v15
	v_mul_f32_e32 v104, v104, v15
	v_mul_f32_e32 v105, v105, v15
	v_mul_f32_e32 v106, v106, v15
	v_mul_f32_e32 v107, v107, v15
	v_mul_f32_e32 v108, v108, v15
	v_mul_f32_e32 v109, v109, v15
	v_mul_f32_e32 v110, v110, v15
	v_mul_f32_e32 v111, v111, v15
	v_fmac_f32_e32 v112, v96, v20
	v_fmac_f32_e32 v113, v97, v21
	v_fmac_f32_e32 v114, v98, v22
	v_fmac_f32_e32 v115, v99, v23
	v_fmac_f32_e32 v116, v100, v24
	v_fmac_f32_e32 v117, v101, v25
	v_fmac_f32_e32 v118, v102, v26
	v_fmac_f32_e32 v119, v103, v27
	v_fmac_f32_e32 v120, v104, v28
	v_fmac_f32_e32 v121, v105, v29
	v_fmac_f32_e32 v122, v106, v30
	v_fmac_f32_e32 v123, v107, v31
	v_fmac_f32_e32 v124, v108, v32
	v_fmac_f32_e32 v125, v109, v33
	v_fmac_f32_e32 v126, v110, v34
	v_fmac_f32_e32 v127, v111, v35
	global_store_dwordx4 v1, v[112:115], s[32:33] offset:0
	global_store_dwordx4 v1, v[116:119], s[32:33] offset:1024
	global_store_dwordx4 v1, v[120:123], s[32:33] offset:2048
	global_store_dwordx4 v1, v[124:127], s[32:33] offset:3072
	v_mul_f32_e32 v10, v80, v80
	v_fmac_f32_e32 v10, v81, v81
	v_fmac_f32_e32 v10, v82, v82
	v_fmac_f32_e32 v10, v83, v83
	v_fmac_f32_e32 v10, v84, v84
	v_fmac_f32_e32 v10, v85, v85
	v_fmac_f32_e32 v10, v86, v86
	v_fmac_f32_e32 v10, v87, v87
	v_fmac_f32_e32 v10, v88, v88
	v_fmac_f32_e32 v10, v89, v89
	v_fmac_f32_e32 v10, v90, v90
	v_fmac_f32_e32 v10, v91, v91
	v_fmac_f32_e32 v10, v92, v92
	v_fmac_f32_e32 v10, v93, v93
	v_fmac_f32_e32 v10, v94, v94
	v_fmac_f32_e32 v10, v95, v95
	v_mul_f32_e32 v11, v112, v112
	v_fmac_f32_e32 v11, v113, v113
	v_fmac_f32_e32 v11, v114, v114
	v_fmac_f32_e32 v11, v115, v115
	v_fmac_f32_e32 v11, v116, v116
	v_fmac_f32_e32 v11, v117, v117
	v_fmac_f32_e32 v11, v118, v118
	v_fmac_f32_e32 v11, v119, v119
	v_fmac_f32_e32 v11, v120, v120
	v_fmac_f32_e32 v11, v121, v121
	v_fmac_f32_e32 v11, v122, v122
	v_fmac_f32_e32 v11, v123, v123
	v_fmac_f32_e32 v11, v124, v124
	v_fmac_f32_e32 v11, v125, v125
	v_fmac_f32_e32 v11, v126, v126
	v_fmac_f32_e32 v11, v127, v127
	ds_bpermute_b32 v12, v4, v10
	ds_bpermute_b32 v13, v4, v11
	s_waitcnt lgkmcnt(0)
	v_add_f32_e32 v10, v10, v12
	v_add_f32_e32 v11, v11, v13
	ds_bpermute_b32 v12, v5, v10
	ds_bpermute_b32 v13, v5, v11
	s_waitcnt lgkmcnt(0)
	v_add_f32_e32 v10, v10, v12
	v_add_f32_e32 v11, v11, v13
	ds_bpermute_b32 v12, v6, v10
	ds_bpermute_b32 v13, v6, v11
	s_waitcnt lgkmcnt(0)
	v_add_f32_e32 v10, v10, v12
	v_add_f32_e32 v11, v11, v13
	ds_bpermute_b32 v12, v7, v10
	ds_bpermute_b32 v13, v7, v11
	s_waitcnt lgkmcnt(0)
	v_add_f32_e32 v10, v10, v12
	v_add_f32_e32 v11, v11, v13
	ds_bpermute_b32 v12, v8, v10
	ds_bpermute_b32 v13, v8, v11
	s_waitcnt lgkmcnt(0)
	v_add_f32_e32 v10, v10, v12
	v_add_f32_e32 v11, v11, v13
	ds_bpermute_b32 v12, v9, v10
	ds_bpermute_b32 v13, v9, v11
	s_waitcnt lgkmcnt(0)
	v_add_f32_e32 v10, v10, v12
	v_add_f32_e32 v11, v11, v13
	v_fma_f32 v14, v10, s17, v3
	v_fma_f32 v15, v11, s17, v3
	v_rsq_f32_e32 v14, v14
	v_rsq_f32_e32 v15, v15
	s_nop 0
	v_mul_f32_e32 v64, v80, v14
	v_mul_f32_e32 v65, v81, v14
	v_mul_f32_e32 v66, v82, v14
	v_mul_f32_e32 v67, v83, v14
	v_mul_f32_e32 v68, v84, v14
	v_mul_f32_e32 v69, v85, v14
	v_mul_f32_e32 v70, v86, v14
	v_mul_f32_e32 v71, v87, v14
	v_mul_f32_e32 v72, v88, v14
	v_mul_f32_e32 v73, v89, v14
	v_mul_f32_e32 v74, v90, v14
	v_mul_f32_e32 v75, v91, v14
	v_mul_f32_e32 v76, v92, v14
	v_mul_f32_e32 v77, v93, v14
	v_mul_f32_e32 v78, v94, v14
	v_mul_f32_e32 v79, v95, v14
	v_mul_f32_e32 v64, v64, v36
	v_mul_f32_e32 v65, v65, v37
	v_mul_f32_e32 v66, v66, v38
	v_mul_f32_e32 v67, v67, v39
	v_mul_f32_e32 v68, v68, v40
	v_mul_f32_e32 v69, v69, v41
	v_mul_f32_e32 v70, v70, v42
	v_mul_f32_e32 v71, v71, v43
	v_mul_f32_e32 v72, v72, v44
	v_mul_f32_e32 v73, v73, v45
	v_mul_f32_e32 v74, v74, v46
	v_mul_f32_e32 v75, v75, v47
	v_mul_f32_e32 v76, v76, v48
	v_mul_f32_e32 v77, v77, v49
	v_mul_f32_e32 v78, v78, v50
	v_mul_f32_e32 v79, v79, v51
	v_cvt_pk_bf16_f32 v64, v64, v65
	v_cvt_pk_bf16_f32 v65, v66, v67
	v_cvt_pk_bf16_f32 v68, v68, v69
	v_cvt_pk_bf16_f32 v69, v70, v71
	v_cvt_pk_bf16_f32 v72, v72, v73
	v_cvt_pk_bf16_f32 v73, v74, v75
	v_cvt_pk_bf16_f32 v76, v76, v77
	v_cvt_pk_bf16_f32 v77, v78, v79
	global_store_dwordx2 v2, v[64:65], s[26:27] offset:0
	global_store_dwordx2 v2, v[68:69], s[26:27] offset:512
	global_store_dwordx2 v2, v[72:73], s[26:27] offset:1024
	global_store_dwordx2 v2, v[76:77], s[26:27] offset:1536
	v_mul_f32_e32 v96, v112, v15
	v_mul_f32_e32 v97, v113, v15
	v_mul_f32_e32 v98, v114, v15
	v_mul_f32_e32 v99, v115, v15
	v_mul_f32_e32 v100, v116, v15
	v_mul_f32_e32 v101, v117, v15
	v_mul_f32_e32 v102, v118, v15
	v_mul_f32_e32 v103, v119, v15
	v_mul_f32_e32 v104, v120, v15
	v_mul_f32_e32 v105, v121, v15
	v_mul_f32_e32 v106, v122, v15
	v_mul_f32_e32 v107, v123, v15
	v_mul_f32_e32 v108, v124, v15
	v_mul_f32_e32 v109, v125, v15
	v_mul_f32_e32 v110, v126, v15
	v_mul_f32_e32 v111, v127, v15
	v_mul_f32_e32 v96, v96, v36
	v_mul_f32_e32 v97, v97, v37
	v_mul_f32_e32 v98, v98, v38
	v_mul_f32_e32 v99, v99, v39
	v_mul_f32_e32 v100, v100, v40
	v_mul_f32_e32 v101, v101, v41
	v_mul_f32_e32 v102, v102, v42
	v_mul_f32_e32 v103, v103, v43
	v_mul_f32_e32 v104, v104, v44
	v_mul_f32_e32 v105, v105, v45
	v_mul_f32_e32 v106, v106, v46
	v_mul_f32_e32 v107, v107, v47
	v_mul_f32_e32 v108, v108, v48
	v_mul_f32_e32 v109, v109, v49
	v_mul_f32_e32 v110, v110, v50
	v_mul_f32_e32 v111, v111, v51
	v_cvt_pk_bf16_f32 v96, v96, v97
	v_cvt_pk_bf16_f32 v97, v98, v99
	v_cvt_pk_bf16_f32 v100, v100, v101
	v_cvt_pk_bf16_f32 v101, v102, v103
	v_cvt_pk_bf16_f32 v104, v104, v105
	v_cvt_pk_bf16_f32 v105, v106, v107
	v_cvt_pk_bf16_f32 v108, v108, v109
	v_cvt_pk_bf16_f32 v109, v110, v111
	global_store_dwordx2 v2, v[96:97], s[34:35] offset:0
	global_store_dwordx2 v2, v[100:101], s[34:35] offset:512
	global_store_dwordx2 v2, v[104:105], s[34:35] offset:1024
	global_store_dwordx2 v2, v[108:109], s[34:35] offset:1536
	s_add_u32 s53, s16, 0x2000
	s_lshl_b32 s18, s53, 12
	s_lshl_b32 s19, s53, 11
	s_add_u32 s20, s4, s18
	s_addc_u32 s21, s5, 0
	s_add_u32 s22, s6, s19
	s_addc_u32 s23, s7, 0
	s_add_u32 s22, s22, 0x5200000
	s_addc_u32 s23, s23, 0
	s_add_u32 s24, s4, s18
	s_addc_u32 s25, s5, 0
	s_add_u32 s26, s6, s19
	s_addc_u32 s27, s7, 0
	s_add_u32 s26, s26, 0x3100000
	s_addc_u32 s27, s27, 0
	global_load_dwordx2 v[66:67], v2, s[22:23] offset:0
	global_load_dwordx2 v[70:71], v2, s[22:23] offset:512
	global_load_dwordx2 v[74:75], v2, s[22:23] offset:1024
	global_load_dwordx2 v[78:79], v2, s[22:23] offset:1536
	global_load_dwordx4 v[80:83], v1, s[20:21] offset:0
	global_load_dwordx4 v[84:87], v1, s[20:21] offset:1024
	global_load_dwordx4 v[88:91], v1, s[20:21] offset:2048
	global_load_dwordx4 v[92:95], v1, s[20:21] offset:3072
	s_add_u32 s53, s16, 0x2800
	s_lshl_b32 s18, s53, 12
	s_lshl_b32 s19, s53, 11
	s_add_u32 s28, s4, s18
	s_addc_u32 s29, s5, 0
	s_add_u32 s30, s6, s19
	s_addc_u32 s31, s7, 0
	s_add_u32 s30, s30, 0x5200000
	s_addc_u32 s31, s31, 0
	s_add_u32 s32, s4, s18
	s_addc_u32 s33, s5, 0
	s_add_u32 s34, s6, s19
	s_addc_u32 s35, s7, 0
	s_add_u32 s34, s34, 0x3100000
	s_addc_u32 s35, s35, 0
	global_load_dwordx2 v[98:99], v2, s[30:31] offset:0
	global_load_dwordx2 v[102:103], v2, s[30:31] offset:512
	global_load_dwordx2 v[106:107], v2, s[30:31] offset:1024
	global_load_dwordx2 v[110:111], v2, s[30:31] offset:1536
	global_load_dwordx4 v[112:115], v1, s[28:29] offset:0
	global_load_dwordx4 v[116:119], v1, s[28:29] offset:1024
	global_load_dwordx4 v[120:123], v1, s[28:29] offset:2048
	global_load_dwordx4 v[124:127], v1, s[28:29] offset:3072
	s_waitcnt vmcnt(32)
	v_lshlrev_b32_e32 v128, 16, v130
	v_and_b32_e32 v129, 0xffff0000, v130
	v_lshlrev_b32_e32 v130, 16, v131
	v_and_b32_e32 v131, 0xffff0000, v131
	v_lshlrev_b32_e32 v132, 16, v134
	v_and_b32_e32 v133, 0xffff0000, v134
	v_lshlrev_b32_e32 v134, 16, v135
	v_and_b32_e32 v135, 0xffff0000, v135
	v_lshlrev_b32_e32 v136, 16, v138
	v_and_b32_e32 v137, 0xffff0000, v138
	v_lshlrev_b32_e32 v138, 16, v139
	v_and_b32_e32 v139, 0xffff0000, v139
	v_lshlrev_b32_e32 v140, 16, v142
	v_and_b32_e32 v141, 0xffff0000, v142
	v_lshlrev_b32_e32 v142, 16, v143
	v_and_b32_e32 v143, 0xffff0000, v143
	v_lshlrev_b32_e32 v160, 16, v162
	v_and_b32_e32 v161, 0xffff0000, v162
	v_lshlrev_b32_e32 v162, 16, v163
	v_and_b32_e32 v163, 0xffff0000, v163
	v_lshlrev_b32_e32 v164, 16, v166
	v_and_b32_e32 v165, 0xffff0000, v166
	v_lshlrev_b32_e32 v166, 16, v167
	v_and_b32_e32 v167, 0xffff0000, v167
	v_lshlrev_b32_e32 v168, 16, v170
	v_and_b32_e32 v169, 0xffff0000, v170
	v_lshlrev_b32_e32 v170, 16, v171
	v_and_b32_e32 v171, 0xffff0000, v171
	v_lshlrev_b32_e32 v172, 16, v174
	v_and_b32_e32 v173, 0xffff0000, v174
	v_lshlrev_b32_e32 v174, 16, v175
	v_and_b32_e32 v175, 0xffff0000, v175
	v_mul_f32_e32 v10, v128, v128
	v_fmac_f32_e32 v10, v129, v129
	v_fmac_f32_e32 v10, v130, v130
	v_fmac_f32_e32 v10, v131, v131
	v_fmac_f32_e32 v10, v132, v132
	v_fmac_f32_e32 v10, v133, v133
	v_fmac_f32_e32 v10, v134, v134
	v_fmac_f32_e32 v10, v135, v135
	v_fmac_f32_e32 v10, v136, v136
	v_fmac_f32_e32 v10, v137, v137
	v_fmac_f32_e32 v10, v138, v138
	v_fmac_f32_e32 v10, v139, v139
	v_fmac_f32_e32 v10, v140, v140
	v_fmac_f32_e32 v10, v141, v141
	v_fmac_f32_e32 v10, v142, v142
	v_fmac_f32_e32 v10, v143, v143
	v_mul_f32_e32 v11, v160, v160
	v_fmac_f32_e32 v11, v161, v161
	v_fmac_f32_e32 v11, v162, v162
	v_fmac_f32_e32 v11, v163, v163
	v_fmac_f32_e32 v11, v164, v164
	v_fmac_f32_e32 v11, v165, v165
	v_fmac_f32_e32 v11, v166, v166
	v_fmac_f32_e32 v11, v167, v167
	v_fmac_f32_e32 v11, v168, v168
	v_fmac_f32_e32 v11, v169, v169
	v_fmac_f32_e32 v11, v170, v170
	v_fmac_f32_e32 v11, v171, v171
	v_fmac_f32_e32 v11, v172, v172
	v_fmac_f32_e32 v11, v173, v173
	v_fmac_f32_e32 v11, v174, v174
	v_fmac_f32_e32 v11, v175, v175
	ds_bpermute_b32 v12, v4, v10
	ds_bpermute_b32 v13, v4, v11
	s_waitcnt lgkmcnt(0)
	v_add_f32_e32 v10, v10, v12
	v_add_f32_e32 v11, v11, v13
	ds_bpermute_b32 v12, v5, v10
	ds_bpermute_b32 v13, v5, v11
	s_waitcnt lgkmcnt(0)
	v_add_f32_e32 v10, v10, v12
	v_add_f32_e32 v11, v11, v13
	ds_bpermute_b32 v12, v6, v10
	ds_bpermute_b32 v13, v6, v11
	s_waitcnt lgkmcnt(0)
	v_add_f32_e32 v10, v10, v12
	v_add_f32_e32 v11, v11, v13
	ds_bpermute_b32 v12, v7, v10
	ds_bpermute_b32 v13, v7, v11
	s_waitcnt lgkmcnt(0)
	v_add_f32_e32 v10, v10, v12
	v_add_f32_e32 v11, v11, v13
	ds_bpermute_b32 v12, v8, v10
	ds_bpermute_b32 v13, v8, v11
	s_waitcnt lgkmcnt(0)
	v_add_f32_e32 v10, v10, v12
	v_add_f32_e32 v11, v11, v13
	ds_bpermute_b32 v12, v9, v10
	ds_bpermute_b32 v13, v9, v11
	s_waitcnt lgkmcnt(0)
	v_add_f32_e32 v10, v10, v12
	v_add_f32_e32 v11, v11, v13
	v_fma_f32 v14, v10, s17, v3
	v_fma_f32 v15, v11, s17, v3
	v_rsq_f32_e32 v14, v14
	v_rsq_f32_e32 v15, v15
	s_nop 0
	v_mul_f32_e32 v128, v128, v14
	v_mul_f32_e32 v129, v129, v14
	v_mul_f32_e32 v130, v130, v14
	v_mul_f32_e32 v131, v131, v14
	v_mul_f32_e32 v132, v132, v14
	v_mul_f32_e32 v133, v133, v14
	v_mul_f32_e32 v134, v134, v14
	v_mul_f32_e32 v135, v135, v14
	v_mul_f32_e32 v136, v136, v14
	v_mul_f32_e32 v137, v137, v14
	v_mul_f32_e32 v138, v138, v14
	v_mul_f32_e32 v139, v139, v14
	v_mul_f32_e32 v140, v140, v14
	v_mul_f32_e32 v141, v141, v14
	v_mul_f32_e32 v142, v142, v14
	v_mul_f32_e32 v143, v143, v14
	v_fmac_f32_e32 v144, v128, v20
	v_fmac_f32_e32 v145, v129, v21
	v_fmac_f32_e32 v146, v130, v22
	v_fmac_f32_e32 v147, v131, v23
	v_fmac_f32_e32 v148, v132, v24
	v_fmac_f32_e32 v149, v133, v25
	v_fmac_f32_e32 v150, v134, v26
	v_fmac_f32_e32 v151, v135, v27
	v_fmac_f32_e32 v152, v136, v28
	v_fmac_f32_e32 v153, v137, v29
	v_fmac_f32_e32 v154, v138, v30
	v_fmac_f32_e32 v155, v139, v31
	v_fmac_f32_e32 v156, v140, v32
	v_fmac_f32_e32 v157, v141, v33
	v_fmac_f32_e32 v158, v142, v34
	v_fmac_f32_e32 v159, v143, v35
	global_store_dwordx4 v1, v[144:147], s[40:41] offset:0
	global_store_dwordx4 v1, v[148:151], s[40:41] offset:1024
	global_store_dwordx4 v1, v[152:155], s[40:41] offset:2048
	global_store_dwordx4 v1, v[156:159], s[40:41] offset:3072
	v_mul_f32_e32 v160, v160, v15
	v_mul_f32_e32 v161, v161, v15
	v_mul_f32_e32 v162, v162, v15
	v_mul_f32_e32 v163, v163, v15
	v_mul_f32_e32 v164, v164, v15
	v_mul_f32_e32 v165, v165, v15
	v_mul_f32_e32 v166, v166, v15
	v_mul_f32_e32 v167, v167, v15
	v_mul_f32_e32 v168, v168, v15
	v_mul_f32_e32 v169, v169, v15
	v_mul_f32_e32 v170, v170, v15
	v_mul_f32_e32 v171, v171, v15
	v_mul_f32_e32 v172, v172, v15
	v_mul_f32_e32 v173, v173, v15
	v_mul_f32_e32 v174, v174, v15
	v_mul_f32_e32 v175, v175, v15
	v_fmac_f32_e32 v176, v160, v20
	v_fmac_f32_e32 v177, v161, v21
	v_fmac_f32_e32 v178, v162, v22
	v_fmac_f32_e32 v179, v163, v23
	v_fmac_f32_e32 v180, v164, v24
	v_fmac_f32_e32 v181, v165, v25
	v_fmac_f32_e32 v182, v166, v26
	v_fmac_f32_e32 v183, v167, v27
	v_fmac_f32_e32 v184, v168, v28
	v_fmac_f32_e32 v185, v169, v29
	v_fmac_f32_e32 v186, v170, v30
	v_fmac_f32_e32 v187, v171, v31
	v_fmac_f32_e32 v188, v172, v32
	v_fmac_f32_e32 v189, v173, v33
	v_fmac_f32_e32 v190, v174, v34
	v_fmac_f32_e32 v191, v175, v35
	global_store_dwordx4 v1, v[176:179], s[48:49] offset:0
	global_store_dwordx4 v1, v[180:183], s[48:49] offset:1024
	global_store_dwordx4 v1, v[184:187], s[48:49] offset:2048
	global_store_dwordx4 v1, v[188:191], s[48:49] offset:3072
	v_mul_f32_e32 v10, v144, v144
	v_fmac_f32_e32 v10, v145, v145
	v_fmac_f32_e32 v10, v146, v146
	v_fmac_f32_e32 v10, v147, v147
	v_fmac_f32_e32 v10, v148, v148
	v_fmac_f32_e32 v10, v149, v149
	v_fmac_f32_e32 v10, v150, v150
	v_fmac_f32_e32 v10, v151, v151
	v_fmac_f32_e32 v10, v152, v152
	v_fmac_f32_e32 v10, v153, v153
	v_fmac_f32_e32 v10, v154, v154
	v_fmac_f32_e32 v10, v155, v155
	v_fmac_f32_e32 v10, v156, v156
	v_fmac_f32_e32 v10, v157, v157
	v_fmac_f32_e32 v10, v158, v158
	v_fmac_f32_e32 v10, v159, v159
	v_mul_f32_e32 v11, v176, v176
	v_fmac_f32_e32 v11, v177, v177
	v_fmac_f32_e32 v11, v178, v178
	v_fmac_f32_e32 v11, v179, v179
	v_fmac_f32_e32 v11, v180, v180
	v_fmac_f32_e32 v11, v181, v181
	v_fmac_f32_e32 v11, v182, v182
	v_fmac_f32_e32 v11, v183, v183
	v_fmac_f32_e32 v11, v184, v184
	v_fmac_f32_e32 v11, v185, v185
	v_fmac_f32_e32 v11, v186, v186
	v_fmac_f32_e32 v11, v187, v187
	v_fmac_f32_e32 v11, v188, v188
	v_fmac_f32_e32 v11, v189, v189
	v_fmac_f32_e32 v11, v190, v190
	v_fmac_f32_e32 v11, v191, v191
	ds_bpermute_b32 v12, v4, v10
	ds_bpermute_b32 v13, v4, v11
	s_waitcnt lgkmcnt(0)
	v_add_f32_e32 v10, v10, v12
	v_add_f32_e32 v11, v11, v13
	ds_bpermute_b32 v12, v5, v10
	ds_bpermute_b32 v13, v5, v11
	s_waitcnt lgkmcnt(0)
	v_add_f32_e32 v10, v10, v12
	v_add_f32_e32 v11, v11, v13
	ds_bpermute_b32 v12, v6, v10
	ds_bpermute_b32 v13, v6, v11
	s_waitcnt lgkmcnt(0)
	v_add_f32_e32 v10, v10, v12
	v_add_f32_e32 v11, v11, v13
	ds_bpermute_b32 v12, v7, v10
	ds_bpermute_b32 v13, v7, v11
	s_waitcnt lgkmcnt(0)
	v_add_f32_e32 v10, v10, v12
	v_add_f32_e32 v11, v11, v13
	ds_bpermute_b32 v12, v8, v10
	ds_bpermute_b32 v13, v8, v11
	s_waitcnt lgkmcnt(0)
	v_add_f32_e32 v10, v10, v12
	v_add_f32_e32 v11, v11, v13
	ds_bpermute_b32 v12, v9, v10
	ds_bpermute_b32 v13, v9, v11
	s_waitcnt lgkmcnt(0)
	v_add_f32_e32 v10, v10, v12
	v_add_f32_e32 v11, v11, v13
	v_fma_f32 v14, v10, s17, v3
	v_fma_f32 v15, v11, s17, v3
	v_rsq_f32_e32 v14, v14
	v_rsq_f32_e32 v15, v15
	s_nop 0
	v_mul_f32_e32 v128, v144, v14
	v_mul_f32_e32 v129, v145, v14
	v_mul_f32_e32 v130, v146, v14
	v_mul_f32_e32 v131, v147, v14
	v_mul_f32_e32 v132, v148, v14
	v_mul_f32_e32 v133, v149, v14
	v_mul_f32_e32 v134, v150, v14
	v_mul_f32_e32 v135, v151, v14
	v_mul_f32_e32 v136, v152, v14
	v_mul_f32_e32 v137, v153, v14
	v_mul_f32_e32 v138, v154, v14
	v_mul_f32_e32 v139, v155, v14
	v_mul_f32_e32 v140, v156, v14
	v_mul_f32_e32 v141, v157, v14
	v_mul_f32_e32 v142, v158, v14
	v_mul_f32_e32 v143, v159, v14
	v_mul_f32_e32 v128, v128, v36
	v_mul_f32_e32 v129, v129, v37
	v_mul_f32_e32 v130, v130, v38
	v_mul_f32_e32 v131, v131, v39
	v_mul_f32_e32 v132, v132, v40
	v_mul_f32_e32 v133, v133, v41
	v_mul_f32_e32 v134, v134, v42
	v_mul_f32_e32 v135, v135, v43
	v_mul_f32_e32 v136, v136, v44
	v_mul_f32_e32 v137, v137, v45
	v_mul_f32_e32 v138, v138, v46
	v_mul_f32_e32 v139, v139, v47
	v_mul_f32_e32 v140, v140, v48
	v_mul_f32_e32 v141, v141, v49
	v_mul_f32_e32 v142, v142, v50
	v_mul_f32_e32 v143, v143, v51
	v_cvt_pk_bf16_f32 v128, v128, v129
	v_cvt_pk_bf16_f32 v129, v130, v131
	v_cvt_pk_bf16_f32 v132, v132, v133
	v_cvt_pk_bf16_f32 v133, v134, v135
	v_cvt_pk_bf16_f32 v136, v136, v137
	v_cvt_pk_bf16_f32 v137, v138, v139
	v_cvt_pk_bf16_f32 v140, v140, v141
	v_cvt_pk_bf16_f32 v141, v142, v143
	global_store_dwordx2 v2, v[128:129], s[42:43] offset:0
	global_store_dwordx2 v2, v[132:133], s[42:43] offset:512
	global_store_dwordx2 v2, v[136:137], s[42:43] offset:1024
	global_store_dwordx2 v2, v[140:141], s[42:43] offset:1536
	v_mul_f32_e32 v160, v176, v15
	v_mul_f32_e32 v161, v177, v15
	v_mul_f32_e32 v162, v178, v15
	v_mul_f32_e32 v163, v179, v15
	v_mul_f32_e32 v164, v180, v15
	v_mul_f32_e32 v165, v181, v15
	v_mul_f32_e32 v166, v182, v15
	v_mul_f32_e32 v167, v183, v15
	v_mul_f32_e32 v168, v184, v15
	v_mul_f32_e32 v169, v185, v15
	v_mul_f32_e32 v170, v186, v15
	v_mul_f32_e32 v171, v187, v15
	v_mul_f32_e32 v172, v188, v15
	v_mul_f32_e32 v173, v189, v15
	v_mul_f32_e32 v174, v190, v15
	v_mul_f32_e32 v175, v191, v15
	v_mul_f32_e32 v160, v160, v36
	v_mul_f32_e32 v161, v161, v37
	v_mul_f32_e32 v162, v162, v38
	v_mul_f32_e32 v163, v163, v39
	v_mul_f32_e32 v164, v164, v40
	v_mul_f32_e32 v165, v165, v41
	v_mul_f32_e32 v166, v166, v42
	v_mul_f32_e32 v167, v167, v43
	v_mul_f32_e32 v168, v168, v44
	v_mul_f32_e32 v169, v169, v45
	v_mul_f32_e32 v170, v170, v46
	v_mul_f32_e32 v171, v171, v47
	v_mul_f32_e32 v172, v172, v48
	v_mul_f32_e32 v173, v173, v49
	v_mul_f32_e32 v174, v174, v50
	v_mul_f32_e32 v175, v175, v51
	v_cvt_pk_bf16_f32 v160, v160, v161
	v_cvt_pk_bf16_f32 v161, v162, v163
	v_cvt_pk_bf16_f32 v164, v164, v165
	v_cvt_pk_bf16_f32 v165, v166, v167
	v_cvt_pk_bf16_f32 v168, v168, v169
	v_cvt_pk_bf16_f32 v169, v170, v171
	v_cvt_pk_bf16_f32 v172, v172, v173
	v_cvt_pk_bf16_f32 v173, v174, v175
	global_store_dwordx2 v2, v[160:161], s[50:51] offset:0
	global_store_dwordx2 v2, v[164:165], s[50:51] offset:512
	global_store_dwordx2 v2, v[168:169], s[50:51] offset:1024
	global_store_dwordx2 v2, v[172:173], s[50:51] offset:1536
	s_add_u32 s53, s16, 0x3000
	s_lshl_b32 s18, s53, 12
	s_lshl_b32 s19, s53, 11
	s_add_u32 s36, s4, s18
	s_addc_u32 s37, s5, 0
	s_add_u32 s38, s6, s19
	s_addc_u32 s39, s7, 0
	s_add_u32 s38, s38, 0x5200000
	s_addc_u32 s39, s39, 0
	s_add_u32 s40, s4, s18
	s_addc_u32 s41, s5, 0
	s_add_u32 s42, s6, s19
	s_addc_u32 s43, s7, 0
	s_add_u32 s42, s42, 0x3100000
	s_addc_u32 s43, s43, 0
	global_load_dwordx2 v[130:131], v2, s[38:39] offset:0
	global_load_dwordx2 v[134:135], v2, s[38:39] offset:512
	global_load_dwordx2 v[138:139], v2, s[38:39] offset:1024
	global_load_dwordx2 v[142:143], v2, s[38:39] offset:1536
	global_load_dwordx4 v[144:147], v1, s[36:37] offset:0
	global_load_dwordx4 v[148:151], v1, s[36:37] offset:1024
	global_load_dwordx4 v[152:155], v1, s[36:37] offset:2048
	global_load_dwordx4 v[156:159], v1, s[36:37] offset:3072
	s_add_u32 s53, s16, 0x3800
	s_lshl_b32 s18, s53, 12
	s_lshl_b32 s19, s53, 11
	s_add_u32 s44, s4, s18
	s_addc_u32 s45, s5, 0
	s_add_u32 s46, s6, s19
	s_addc_u32 s47, s7, 0
	s_add_u32 s46, s46, 0x5200000
	s_addc_u32 s47, s47, 0
	s_add_u32 s48, s4, s18
	s_addc_u32 s49, s5, 0
	s_add_u32 s50, s6, s19
	s_addc_u32 s51, s7, 0
	s_add_u32 s50, s50, 0x3100000
	s_addc_u32 s51, s51, 0
	global_load_dwordx2 v[162:163], v2, s[46:47] offset:0
	global_load_dwordx2 v[166:167], v2, s[46:47] offset:512
	global_load_dwordx2 v[170:171], v2, s[46:47] offset:1024
	global_load_dwordx2 v[174:175], v2, s[46:47] offset:1536
	global_load_dwordx4 v[176:179], v1, s[44:45] offset:0
	global_load_dwordx4 v[180:183], v1, s[44:45] offset:1024
	global_load_dwordx4 v[184:187], v1, s[44:45] offset:2048
	global_load_dwordx4 v[188:191], v1, s[44:45] offset:3072
	s_waitcnt vmcnt(32)
	v_lshlrev_b32_e32 v64, 16, v66
	v_and_b32_e32 v65, 0xffff0000, v66
	v_lshlrev_b32_e32 v66, 16, v67
	v_and_b32_e32 v67, 0xffff0000, v67
	v_lshlrev_b32_e32 v68, 16, v70
	v_and_b32_e32 v69, 0xffff0000, v70
	v_lshlrev_b32_e32 v70, 16, v71
	v_and_b32_e32 v71, 0xffff0000, v71
	v_lshlrev_b32_e32 v72, 16, v74
	v_and_b32_e32 v73, 0xffff0000, v74
	v_lshlrev_b32_e32 v74, 16, v75
	v_and_b32_e32 v75, 0xffff0000, v75
	v_lshlrev_b32_e32 v76, 16, v78
	v_and_b32_e32 v77, 0xffff0000, v78
	v_lshlrev_b32_e32 v78, 16, v79
	v_and_b32_e32 v79, 0xffff0000, v79
	v_lshlrev_b32_e32 v96, 16, v98
	v_and_b32_e32 v97, 0xffff0000, v98
	v_lshlrev_b32_e32 v98, 16, v99
	v_and_b32_e32 v99, 0xffff0000, v99
	v_lshlrev_b32_e32 v100, 16, v102
	v_and_b32_e32 v101, 0xffff0000, v102
	v_lshlrev_b32_e32 v102, 16, v103
	v_and_b32_e32 v103, 0xffff0000, v103
	v_lshlrev_b32_e32 v104, 16, v106
	v_and_b32_e32 v105, 0xffff0000, v106
	v_lshlrev_b32_e32 v106, 16, v107
	v_and_b32_e32 v107, 0xffff0000, v107
	v_lshlrev_b32_e32 v108, 16, v110
	v_and_b32_e32 v109, 0xffff0000, v110
	v_lshlrev_b32_e32 v110, 16, v111
	v_and_b32_e32 v111, 0xffff0000, v111
	v_mul_f32_e32 v10, v64, v64
	v_fmac_f32_e32 v10, v65, v65
	v_fmac_f32_e32 v10, v66, v66
	v_fmac_f32_e32 v10, v67, v67
	v_fmac_f32_e32 v10, v68, v68
	v_fmac_f32_e32 v10, v69, v69
	v_fmac_f32_e32 v10, v70, v70
	v_fmac_f32_e32 v10, v71, v71
	v_fmac_f32_e32 v10, v72, v72
	v_fmac_f32_e32 v10, v73, v73
	v_fmac_f32_e32 v10, v74, v74
	v_fmac_f32_e32 v10, v75, v75
	v_fmac_f32_e32 v10, v76, v76
	v_fmac_f32_e32 v10, v77, v77
	v_fmac_f32_e32 v10, v78, v78
	v_fmac_f32_e32 v10, v79, v79
	v_mul_f32_e32 v11, v96, v96
	v_fmac_f32_e32 v11, v97, v97
	v_fmac_f32_e32 v11, v98, v98
	v_fmac_f32_e32 v11, v99, v99
	v_fmac_f32_e32 v11, v100, v100
	v_fmac_f32_e32 v11, v101, v101
	v_fmac_f32_e32 v11, v102, v102
	v_fmac_f32_e32 v11, v103, v103
	v_fmac_f32_e32 v11, v104, v104
	v_fmac_f32_e32 v11, v105, v105
	v_fmac_f32_e32 v11, v106, v106
	v_fmac_f32_e32 v11, v107, v107
	v_fmac_f32_e32 v11, v108, v108
	v_fmac_f32_e32 v11, v109, v109
	v_fmac_f32_e32 v11, v110, v110
	v_fmac_f32_e32 v11, v111, v111
	ds_bpermute_b32 v12, v4, v10
	ds_bpermute_b32 v13, v4, v11
	s_waitcnt lgkmcnt(0)
	v_add_f32_e32 v10, v10, v12
	v_add_f32_e32 v11, v11, v13
	ds_bpermute_b32 v12, v5, v10
	ds_bpermute_b32 v13, v5, v11
	s_waitcnt lgkmcnt(0)
	v_add_f32_e32 v10, v10, v12
	v_add_f32_e32 v11, v11, v13
	ds_bpermute_b32 v12, v6, v10
	ds_bpermute_b32 v13, v6, v11
	s_waitcnt lgkmcnt(0)
	v_add_f32_e32 v10, v10, v12
	v_add_f32_e32 v11, v11, v13
	ds_bpermute_b32 v12, v7, v10
	ds_bpermute_b32 v13, v7, v11
	s_waitcnt lgkmcnt(0)
	v_add_f32_e32 v10, v10, v12
	v_add_f32_e32 v11, v11, v13
	ds_bpermute_b32 v12, v8, v10
	ds_bpermute_b32 v13, v8, v11
	s_waitcnt lgkmcnt(0)
	v_add_f32_e32 v10, v10, v12
	v_add_f32_e32 v11, v11, v13
	ds_bpermute_b32 v12, v9, v10
	ds_bpermute_b32 v13, v9, v11
	s_waitcnt lgkmcnt(0)
	v_add_f32_e32 v10, v10, v12
	v_add_f32_e32 v11, v11, v13
	v_fma_f32 v14, v10, s17, v3
	v_fma_f32 v15, v11, s17, v3
	v_rsq_f32_e32 v14, v14
	v_rsq_f32_e32 v15, v15
	s_nop 0
	v_mul_f32_e32 v64, v64, v14
	v_mul_f32_e32 v65, v65, v14
	v_mul_f32_e32 v66, v66, v14
	v_mul_f32_e32 v67, v67, v14
	v_mul_f32_e32 v68, v68, v14
	v_mul_f32_e32 v69, v69, v14
	v_mul_f32_e32 v70, v70, v14
	v_mul_f32_e32 v71, v71, v14
	v_mul_f32_e32 v72, v72, v14
	v_mul_f32_e32 v73, v73, v14
	v_mul_f32_e32 v74, v74, v14
	v_mul_f32_e32 v75, v75, v14
	v_mul_f32_e32 v76, v76, v14
	v_mul_f32_e32 v77, v77, v14
	v_mul_f32_e32 v78, v78, v14
	v_mul_f32_e32 v79, v79, v14
	v_fmac_f32_e32 v80, v64, v20
	v_fmac_f32_e32 v81, v65, v21
	v_fmac_f32_e32 v82, v66, v22
	v_fmac_f32_e32 v83, v67, v23
	v_fmac_f32_e32 v84, v68, v24
	v_fmac_f32_e32 v85, v69, v25
	v_fmac_f32_e32 v86, v70, v26
	v_fmac_f32_e32 v87, v71, v27
	v_fmac_f32_e32 v88, v72, v28
	v_fmac_f32_e32 v89, v73, v29
	v_fmac_f32_e32 v90, v74, v30
	v_fmac_f32_e32 v91, v75, v31
	v_fmac_f32_e32 v92, v76, v32
	v_fmac_f32_e32 v93, v77, v33
	v_fmac_f32_e32 v94, v78, v34
	v_fmac_f32_e32 v95, v79, v35
	global_store_dwordx4 v1, v[80:83], s[24:25] offset:0
	global_store_dwordx4 v1, v[84:87], s[24:25] offset:1024
	global_store_dwordx4 v1, v[88:91], s[24:25] offset:2048
	global_store_dwordx4 v1, v[92:95], s[24:25] offset:3072
	v_mul_f32_e32 v96, v96, v15
	v_mul_f32_e32 v97, v97, v15
	v_mul_f32_e32 v98, v98, v15
	v_mul_f32_e32 v99, v99, v15
	v_mul_f32_e32 v100, v100, v15
	v_mul_f32_e32 v101, v101, v15
	v_mul_f32_e32 v102, v102, v15
	v_mul_f32_e32 v103, v103, v15
	v_mul_f32_e32 v104, v104, v15
	v_mul_f32_e32 v105, v105, v15
	v_mul_f32_e32 v106, v106, v15
	v_mul_f32_e32 v107, v107, v15
	v_mul_f32_e32 v108, v108, v15
	v_mul_f32_e32 v109, v109, v15
	v_mul_f32_e32 v110, v110, v15
	v_mul_f32_e32 v111, v111, v15
	v_fmac_f32_e32 v112, v96, v20
	v_fmac_f32_e32 v113, v97, v21
	v_fmac_f32_e32 v114, v98, v22
	v_fmac_f32_e32 v115, v99, v23
	v_fmac_f32_e32 v116, v100, v24
	v_fmac_f32_e32 v117, v101, v25
	v_fmac_f32_e32 v118, v102, v26
	v_fmac_f32_e32 v119, v103, v27
	v_fmac_f32_e32 v120, v104, v28
	v_fmac_f32_e32 v121, v105, v29
	v_fmac_f32_e32 v122, v106, v30
	v_fmac_f32_e32 v123, v107, v31
	v_fmac_f32_e32 v124, v108, v32
	v_fmac_f32_e32 v125, v109, v33
	v_fmac_f32_e32 v126, v110, v34
	v_fmac_f32_e32 v127, v111, v35
	global_store_dwordx4 v1, v[112:115], s[32:33] offset:0
	global_store_dwordx4 v1, v[116:119], s[32:33] offset:1024
	global_store_dwordx4 v1, v[120:123], s[32:33] offset:2048
	global_store_dwordx4 v1, v[124:127], s[32:33] offset:3072
	v_mul_f32_e32 v10, v80, v80
	v_fmac_f32_e32 v10, v81, v81
	v_fmac_f32_e32 v10, v82, v82
	v_fmac_f32_e32 v10, v83, v83
	v_fmac_f32_e32 v10, v84, v84
	v_fmac_f32_e32 v10, v85, v85
	v_fmac_f32_e32 v10, v86, v86
	v_fmac_f32_e32 v10, v87, v87
	v_fmac_f32_e32 v10, v88, v88
	v_fmac_f32_e32 v10, v89, v89
	v_fmac_f32_e32 v10, v90, v90
	v_fmac_f32_e32 v10, v91, v91
	v_fmac_f32_e32 v10, v92, v92
	v_fmac_f32_e32 v10, v93, v93
	v_fmac_f32_e32 v10, v94, v94
	v_fmac_f32_e32 v10, v95, v95
	v_mul_f32_e32 v11, v112, v112
	v_fmac_f32_e32 v11, v113, v113
	v_fmac_f32_e32 v11, v114, v114
	v_fmac_f32_e32 v11, v115, v115
	v_fmac_f32_e32 v11, v116, v116
	v_fmac_f32_e32 v11, v117, v117
	v_fmac_f32_e32 v11, v118, v118
	v_fmac_f32_e32 v11, v119, v119
	v_fmac_f32_e32 v11, v120, v120
	v_fmac_f32_e32 v11, v121, v121
	v_fmac_f32_e32 v11, v122, v122
	v_fmac_f32_e32 v11, v123, v123
	v_fmac_f32_e32 v11, v124, v124
	v_fmac_f32_e32 v11, v125, v125
	v_fmac_f32_e32 v11, v126, v126
	v_fmac_f32_e32 v11, v127, v127
	ds_bpermute_b32 v12, v4, v10
	ds_bpermute_b32 v13, v4, v11
	s_waitcnt lgkmcnt(0)
	v_add_f32_e32 v10, v10, v12
	v_add_f32_e32 v11, v11, v13
	ds_bpermute_b32 v12, v5, v10
	ds_bpermute_b32 v13, v5, v11
	s_waitcnt lgkmcnt(0)
	v_add_f32_e32 v10, v10, v12
	v_add_f32_e32 v11, v11, v13
	ds_bpermute_b32 v12, v6, v10
	ds_bpermute_b32 v13, v6, v11
	s_waitcnt lgkmcnt(0)
	v_add_f32_e32 v10, v10, v12
	v_add_f32_e32 v11, v11, v13
	ds_bpermute_b32 v12, v7, v10
	ds_bpermute_b32 v13, v7, v11
	s_waitcnt lgkmcnt(0)
	v_add_f32_e32 v10, v10, v12
	v_add_f32_e32 v11, v11, v13
	ds_bpermute_b32 v12, v8, v10
	ds_bpermute_b32 v13, v8, v11
	s_waitcnt lgkmcnt(0)
	v_add_f32_e32 v10, v10, v12
	v_add_f32_e32 v11, v11, v13
	ds_bpermute_b32 v12, v9, v10
	ds_bpermute_b32 v13, v9, v11
	s_waitcnt lgkmcnt(0)
	v_add_f32_e32 v10, v10, v12
	v_add_f32_e32 v11, v11, v13
	v_fma_f32 v14, v10, s17, v3
	v_fma_f32 v15, v11, s17, v3
	v_rsq_f32_e32 v14, v14
	v_rsq_f32_e32 v15, v15
	s_nop 0
	v_mul_f32_e32 v64, v80, v14
	v_mul_f32_e32 v65, v81, v14
	v_mul_f32_e32 v66, v82, v14
	v_mul_f32_e32 v67, v83, v14
	v_mul_f32_e32 v68, v84, v14
	v_mul_f32_e32 v69, v85, v14
	v_mul_f32_e32 v70, v86, v14
	v_mul_f32_e32 v71, v87, v14
	v_mul_f32_e32 v72, v88, v14
	v_mul_f32_e32 v73, v89, v14
	v_mul_f32_e32 v74, v90, v14
	v_mul_f32_e32 v75, v91, v14
	v_mul_f32_e32 v76, v92, v14
	v_mul_f32_e32 v77, v93, v14
	v_mul_f32_e32 v78, v94, v14
	v_mul_f32_e32 v79, v95, v14
	v_mul_f32_e32 v64, v64, v36
	v_mul_f32_e32 v65, v65, v37
	v_mul_f32_e32 v66, v66, v38
	v_mul_f32_e32 v67, v67, v39
	v_mul_f32_e32 v68, v68, v40
	v_mul_f32_e32 v69, v69, v41
	v_mul_f32_e32 v70, v70, v42
	v_mul_f32_e32 v71, v71, v43
	v_mul_f32_e32 v72, v72, v44
	v_mul_f32_e32 v73, v73, v45
	v_mul_f32_e32 v74, v74, v46
	v_mul_f32_e32 v75, v75, v47
	v_mul_f32_e32 v76, v76, v48
	v_mul_f32_e32 v77, v77, v49
	v_mul_f32_e32 v78, v78, v50
	v_mul_f32_e32 v79, v79, v51
	v_cvt_pk_bf16_f32 v64, v64, v65
	v_cvt_pk_bf16_f32 v65, v66, v67
	v_cvt_pk_bf16_f32 v68, v68, v69
	v_cvt_pk_bf16_f32 v69, v70, v71
	v_cvt_pk_bf16_f32 v72, v72, v73
	v_cvt_pk_bf16_f32 v73, v74, v75
	v_cvt_pk_bf16_f32 v76, v76, v77
	v_cvt_pk_bf16_f32 v77, v78, v79
	global_store_dwordx2 v2, v[64:65], s[26:27] offset:0
	global_store_dwordx2 v2, v[68:69], s[26:27] offset:512
	global_store_dwordx2 v2, v[72:73], s[26:27] offset:1024
	global_store_dwordx2 v2, v[76:77], s[26:27] offset:1536
	v_mul_f32_e32 v96, v112, v15
	v_mul_f32_e32 v97, v113, v15
	v_mul_f32_e32 v98, v114, v15
	v_mul_f32_e32 v99, v115, v15
	v_mul_f32_e32 v100, v116, v15
	v_mul_f32_e32 v101, v117, v15
	v_mul_f32_e32 v102, v118, v15
	v_mul_f32_e32 v103, v119, v15
	v_mul_f32_e32 v104, v120, v15
	v_mul_f32_e32 v105, v121, v15
	v_mul_f32_e32 v106, v122, v15
	v_mul_f32_e32 v107, v123, v15
	v_mul_f32_e32 v108, v124, v15
	v_mul_f32_e32 v109, v125, v15
	v_mul_f32_e32 v110, v126, v15
	v_mul_f32_e32 v111, v127, v15
	v_mul_f32_e32 v96, v96, v36
	v_mul_f32_e32 v97, v97, v37
	v_mul_f32_e32 v98, v98, v38
	v_mul_f32_e32 v99, v99, v39
	v_mul_f32_e32 v100, v100, v40
	v_mul_f32_e32 v101, v101, v41
	v_mul_f32_e32 v102, v102, v42
	v_mul_f32_e32 v103, v103, v43
	v_mul_f32_e32 v104, v104, v44
	v_mul_f32_e32 v105, v105, v45
	v_mul_f32_e32 v106, v106, v46
	v_mul_f32_e32 v107, v107, v47
	v_mul_f32_e32 v108, v108, v48
	v_mul_f32_e32 v109, v109, v49
	v_mul_f32_e32 v110, v110, v50
	v_mul_f32_e32 v111, v111, v51
	v_cvt_pk_bf16_f32 v96, v96, v97
	v_cvt_pk_bf16_f32 v97, v98, v99
	v_cvt_pk_bf16_f32 v100, v100, v101
	v_cvt_pk_bf16_f32 v101, v102, v103
	v_cvt_pk_bf16_f32 v104, v104, v105
	v_cvt_pk_bf16_f32 v105, v106, v107
	v_cvt_pk_bf16_f32 v108, v108, v109
	v_cvt_pk_bf16_f32 v109, v110, v111
	global_store_dwordx2 v2, v[96:97], s[34:35] offset:0
	global_store_dwordx2 v2, v[100:101], s[34:35] offset:512
	global_store_dwordx2 v2, v[104:105], s[34:35] offset:1024
	global_store_dwordx2 v2, v[108:109], s[34:35] offset:1536
	s_waitcnt vmcnt(16)
	v_lshlrev_b32_e32 v128, 16, v130
	v_and_b32_e32 v129, 0xffff0000, v130
	v_lshlrev_b32_e32 v130, 16, v131
	v_and_b32_e32 v131, 0xffff0000, v131
	v_lshlrev_b32_e32 v132, 16, v134
	v_and_b32_e32 v133, 0xffff0000, v134
	v_lshlrev_b32_e32 v134, 16, v135
	v_and_b32_e32 v135, 0xffff0000, v135
	v_lshlrev_b32_e32 v136, 16, v138
	v_and_b32_e32 v137, 0xffff0000, v138
	v_lshlrev_b32_e32 v138, 16, v139
	v_and_b32_e32 v139, 0xffff0000, v139
	v_lshlrev_b32_e32 v140, 16, v142
	v_and_b32_e32 v141, 0xffff0000, v142
	v_lshlrev_b32_e32 v142, 16, v143
	v_and_b32_e32 v143, 0xffff0000, v143
	v_lshlrev_b32_e32 v160, 16, v162
	v_and_b32_e32 v161, 0xffff0000, v162
	v_lshlrev_b32_e32 v162, 16, v163
	v_and_b32_e32 v163, 0xffff0000, v163
	v_lshlrev_b32_e32 v164, 16, v166
	v_and_b32_e32 v165, 0xffff0000, v166
	v_lshlrev_b32_e32 v166, 16, v167
	v_and_b32_e32 v167, 0xffff0000, v167
	v_lshlrev_b32_e32 v168, 16, v170
	v_and_b32_e32 v169, 0xffff0000, v170
	v_lshlrev_b32_e32 v170, 16, v171
	v_and_b32_e32 v171, 0xffff0000, v171
	v_lshlrev_b32_e32 v172, 16, v174
	v_and_b32_e32 v173, 0xffff0000, v174
	v_lshlrev_b32_e32 v174, 16, v175
	v_and_b32_e32 v175, 0xffff0000, v175
	v_mul_f32_e32 v10, v128, v128
	v_fmac_f32_e32 v10, v129, v129
	v_fmac_f32_e32 v10, v130, v130
	v_fmac_f32_e32 v10, v131, v131
	v_fmac_f32_e32 v10, v132, v132
	v_fmac_f32_e32 v10, v133, v133
	v_fmac_f32_e32 v10, v134, v134
	v_fmac_f32_e32 v10, v135, v135
	v_fmac_f32_e32 v10, v136, v136
	v_fmac_f32_e32 v10, v137, v137
	v_fmac_f32_e32 v10, v138, v138
	v_fmac_f32_e32 v10, v139, v139
	v_fmac_f32_e32 v10, v140, v140
	v_fmac_f32_e32 v10, v141, v141
	v_fmac_f32_e32 v10, v142, v142
	v_fmac_f32_e32 v10, v143, v143
	v_mul_f32_e32 v11, v160, v160
	v_fmac_f32_e32 v11, v161, v161
	v_fmac_f32_e32 v11, v162, v162
	v_fmac_f32_e32 v11, v163, v163
	v_fmac_f32_e32 v11, v164, v164
	v_fmac_f32_e32 v11, v165, v165
	v_fmac_f32_e32 v11, v166, v166
	v_fmac_f32_e32 v11, v167, v167
	v_fmac_f32_e32 v11, v168, v168
	v_fmac_f32_e32 v11, v169, v169
	v_fmac_f32_e32 v11, v170, v170
	v_fmac_f32_e32 v11, v171, v171
	v_fmac_f32_e32 v11, v172, v172
	v_fmac_f32_e32 v11, v173, v173
	v_fmac_f32_e32 v11, v174, v174
	v_fmac_f32_e32 v11, v175, v175
	ds_bpermute_b32 v12, v4, v10
	ds_bpermute_b32 v13, v4, v11
	s_waitcnt lgkmcnt(0)
	v_add_f32_e32 v10, v10, v12
	v_add_f32_e32 v11, v11, v13
	ds_bpermute_b32 v12, v5, v10
	ds_bpermute_b32 v13, v5, v11
	s_waitcnt lgkmcnt(0)
	v_add_f32_e32 v10, v10, v12
	v_add_f32_e32 v11, v11, v13
	ds_bpermute_b32 v12, v6, v10
	ds_bpermute_b32 v13, v6, v11
	s_waitcnt lgkmcnt(0)
	v_add_f32_e32 v10, v10, v12
	v_add_f32_e32 v11, v11, v13
	ds_bpermute_b32 v12, v7, v10
	ds_bpermute_b32 v13, v7, v11
	s_waitcnt lgkmcnt(0)
	v_add_f32_e32 v10, v10, v12
	v_add_f32_e32 v11, v11, v13
	ds_bpermute_b32 v12, v8, v10
	ds_bpermute_b32 v13, v8, v11
	s_waitcnt lgkmcnt(0)
	v_add_f32_e32 v10, v10, v12
	v_add_f32_e32 v11, v11, v13
	ds_bpermute_b32 v12, v9, v10
	ds_bpermute_b32 v13, v9, v11
	s_waitcnt lgkmcnt(0)
	v_add_f32_e32 v10, v10, v12
	v_add_f32_e32 v11, v11, v13
	v_fma_f32 v14, v10, s17, v3
	v_fma_f32 v15, v11, s17, v3
	v_rsq_f32_e32 v14, v14
	v_rsq_f32_e32 v15, v15
	s_nop 0
	v_mul_f32_e32 v128, v128, v14
	v_mul_f32_e32 v129, v129, v14
	v_mul_f32_e32 v130, v130, v14
	v_mul_f32_e32 v131, v131, v14
	v_mul_f32_e32 v132, v132, v14
	v_mul_f32_e32 v133, v133, v14
	v_mul_f32_e32 v134, v134, v14
	v_mul_f32_e32 v135, v135, v14
	v_mul_f32_e32 v136, v136, v14
	v_mul_f32_e32 v137, v137, v14
	v_mul_f32_e32 v138, v138, v14
	v_mul_f32_e32 v139, v139, v14
	v_mul_f32_e32 v140, v140, v14
	v_mul_f32_e32 v141, v141, v14
	v_mul_f32_e32 v142, v142, v14
	v_mul_f32_e32 v143, v143, v14
	v_fmac_f32_e32 v144, v128, v20
	v_fmac_f32_e32 v145, v129, v21
	v_fmac_f32_e32 v146, v130, v22
	v_fmac_f32_e32 v147, v131, v23
	v_fmac_f32_e32 v148, v132, v24
	v_fmac_f32_e32 v149, v133, v25
	v_fmac_f32_e32 v150, v134, v26
	v_fmac_f32_e32 v151, v135, v27
	v_fmac_f32_e32 v152, v136, v28
	v_fmac_f32_e32 v153, v137, v29
	v_fmac_f32_e32 v154, v138, v30
	v_fmac_f32_e32 v155, v139, v31
	v_fmac_f32_e32 v156, v140, v32
	v_fmac_f32_e32 v157, v141, v33
	v_fmac_f32_e32 v158, v142, v34
	v_fmac_f32_e32 v159, v143, v35
	global_store_dwordx4 v1, v[144:147], s[40:41] offset:0
	global_store_dwordx4 v1, v[148:151], s[40:41] offset:1024
	global_store_dwordx4 v1, v[152:155], s[40:41] offset:2048
	global_store_dwordx4 v1, v[156:159], s[40:41] offset:3072
	v_mul_f32_e32 v160, v160, v15
	v_mul_f32_e32 v161, v161, v15
	v_mul_f32_e32 v162, v162, v15
	v_mul_f32_e32 v163, v163, v15
	v_mul_f32_e32 v164, v164, v15
	v_mul_f32_e32 v165, v165, v15
	v_mul_f32_e32 v166, v166, v15
	v_mul_f32_e32 v167, v167, v15
	v_mul_f32_e32 v168, v168, v15
	v_mul_f32_e32 v169, v169, v15
	v_mul_f32_e32 v170, v170, v15
	v_mul_f32_e32 v171, v171, v15
	v_mul_f32_e32 v172, v172, v15
	v_mul_f32_e32 v173, v173, v15
	v_mul_f32_e32 v174, v174, v15
	v_mul_f32_e32 v175, v175, v15
	v_fmac_f32_e32 v176, v160, v20
	v_fmac_f32_e32 v177, v161, v21
	v_fmac_f32_e32 v178, v162, v22
	v_fmac_f32_e32 v179, v163, v23
	v_fmac_f32_e32 v180, v164, v24
	v_fmac_f32_e32 v181, v165, v25
	v_fmac_f32_e32 v182, v166, v26
	v_fmac_f32_e32 v183, v167, v27
	v_fmac_f32_e32 v184, v168, v28
	v_fmac_f32_e32 v185, v169, v29
	v_fmac_f32_e32 v186, v170, v30
	v_fmac_f32_e32 v187, v171, v31
	v_fmac_f32_e32 v188, v172, v32
	v_fmac_f32_e32 v189, v173, v33
	v_fmac_f32_e32 v190, v174, v34
	v_fmac_f32_e32 v191, v175, v35
	global_store_dwordx4 v1, v[176:179], s[48:49] offset:0
	global_store_dwordx4 v1, v[180:183], s[48:49] offset:1024
	global_store_dwordx4 v1, v[184:187], s[48:49] offset:2048
	global_store_dwordx4 v1, v[188:191], s[48:49] offset:3072
	v_mul_f32_e32 v10, v144, v144
	v_fmac_f32_e32 v10, v145, v145
	v_fmac_f32_e32 v10, v146, v146
	v_fmac_f32_e32 v10, v147, v147
	v_fmac_f32_e32 v10, v148, v148
	v_fmac_f32_e32 v10, v149, v149
	v_fmac_f32_e32 v10, v150, v150
	v_fmac_f32_e32 v10, v151, v151
	v_fmac_f32_e32 v10, v152, v152
	v_fmac_f32_e32 v10, v153, v153
	v_fmac_f32_e32 v10, v154, v154
	v_fmac_f32_e32 v10, v155, v155
	v_fmac_f32_e32 v10, v156, v156
	v_fmac_f32_e32 v10, v157, v157
	v_fmac_f32_e32 v10, v158, v158
	v_fmac_f32_e32 v10, v159, v159
	v_mul_f32_e32 v11, v176, v176
	v_fmac_f32_e32 v11, v177, v177
	v_fmac_f32_e32 v11, v178, v178
	v_fmac_f32_e32 v11, v179, v179
	v_fmac_f32_e32 v11, v180, v180
	v_fmac_f32_e32 v11, v181, v181
	v_fmac_f32_e32 v11, v182, v182
	v_fmac_f32_e32 v11, v183, v183
	v_fmac_f32_e32 v11, v184, v184
	v_fmac_f32_e32 v11, v185, v185
	v_fmac_f32_e32 v11, v186, v186
	v_fmac_f32_e32 v11, v187, v187
	v_fmac_f32_e32 v11, v188, v188
	v_fmac_f32_e32 v11, v189, v189
	v_fmac_f32_e32 v11, v190, v190
	v_fmac_f32_e32 v11, v191, v191
	ds_bpermute_b32 v12, v4, v10
	ds_bpermute_b32 v13, v4, v11
	s_waitcnt lgkmcnt(0)
	v_add_f32_e32 v10, v10, v12
	v_add_f32_e32 v11, v11, v13
	ds_bpermute_b32 v12, v5, v10
	ds_bpermute_b32 v13, v5, v11
	s_waitcnt lgkmcnt(0)
	v_add_f32_e32 v10, v10, v12
	v_add_f32_e32 v11, v11, v13
	ds_bpermute_b32 v12, v6, v10
	ds_bpermute_b32 v13, v6, v11
	s_waitcnt lgkmcnt(0)
	v_add_f32_e32 v10, v10, v12
	v_add_f32_e32 v11, v11, v13
	ds_bpermute_b32 v12, v7, v10
	ds_bpermute_b32 v13, v7, v11
	s_waitcnt lgkmcnt(0)
	v_add_f32_e32 v10, v10, v12
	v_add_f32_e32 v11, v11, v13
	ds_bpermute_b32 v12, v8, v10
	ds_bpermute_b32 v13, v8, v11
	s_waitcnt lgkmcnt(0)
	v_add_f32_e32 v10, v10, v12
	v_add_f32_e32 v11, v11, v13
	ds_bpermute_b32 v12, v9, v10
	ds_bpermute_b32 v13, v9, v11
	s_waitcnt lgkmcnt(0)
	v_add_f32_e32 v10, v10, v12
	v_add_f32_e32 v11, v11, v13
	v_fma_f32 v14, v10, s17, v3
	v_fma_f32 v15, v11, s17, v3
	v_rsq_f32_e32 v14, v14
	v_rsq_f32_e32 v15, v15
	s_nop 0
	v_mul_f32_e32 v128, v144, v14
	v_mul_f32_e32 v129, v145, v14
	v_mul_f32_e32 v130, v146, v14
	v_mul_f32_e32 v131, v147, v14
	v_mul_f32_e32 v132, v148, v14
	v_mul_f32_e32 v133, v149, v14
	v_mul_f32_e32 v134, v150, v14
	v_mul_f32_e32 v135, v151, v14
	v_mul_f32_e32 v136, v152, v14
	v_mul_f32_e32 v137, v153, v14
	v_mul_f32_e32 v138, v154, v14
	v_mul_f32_e32 v139, v155, v14
	v_mul_f32_e32 v140, v156, v14
	v_mul_f32_e32 v141, v157, v14
	v_mul_f32_e32 v142, v158, v14
	v_mul_f32_e32 v143, v159, v14
	v_mul_f32_e32 v128, v128, v36
	v_mul_f32_e32 v129, v129, v37
	v_mul_f32_e32 v130, v130, v38
	v_mul_f32_e32 v131, v131, v39
	v_mul_f32_e32 v132, v132, v40
	v_mul_f32_e32 v133, v133, v41
	v_mul_f32_e32 v134, v134, v42
	v_mul_f32_e32 v135, v135, v43
	v_mul_f32_e32 v136, v136, v44
	v_mul_f32_e32 v137, v137, v45
	v_mul_f32_e32 v138, v138, v46
	v_mul_f32_e32 v139, v139, v47
	v_mul_f32_e32 v140, v140, v48
	v_mul_f32_e32 v141, v141, v49
	v_mul_f32_e32 v142, v142, v50
	v_mul_f32_e32 v143, v143, v51
	v_cvt_pk_bf16_f32 v128, v128, v129
	v_cvt_pk_bf16_f32 v129, v130, v131
	v_cvt_pk_bf16_f32 v132, v132, v133
	v_cvt_pk_bf16_f32 v133, v134, v135
	v_cvt_pk_bf16_f32 v136, v136, v137
	v_cvt_pk_bf16_f32 v137, v138, v139
	v_cvt_pk_bf16_f32 v140, v140, v141
	v_cvt_pk_bf16_f32 v141, v142, v143
	global_store_dwordx2 v2, v[128:129], s[42:43] offset:0
	global_store_dwordx2 v2, v[132:133], s[42:43] offset:512
	global_store_dwordx2 v2, v[136:137], s[42:43] offset:1024
	global_store_dwordx2 v2, v[140:141], s[42:43] offset:1536
	v_mul_f32_e32 v160, v176, v15
	v_mul_f32_e32 v161, v177, v15
	v_mul_f32_e32 v162, v178, v15
	v_mul_f32_e32 v163, v179, v15
	v_mul_f32_e32 v164, v180, v15
	v_mul_f32_e32 v165, v181, v15
	v_mul_f32_e32 v166, v182, v15
	v_mul_f32_e32 v167, v183, v15
	v_mul_f32_e32 v168, v184, v15
	v_mul_f32_e32 v169, v185, v15
	v_mul_f32_e32 v170, v186, v15
	v_mul_f32_e32 v171, v187, v15
	v_mul_f32_e32 v172, v188, v15
	v_mul_f32_e32 v173, v189, v15
	v_mul_f32_e32 v174, v190, v15
	v_mul_f32_e32 v175, v191, v15
	v_mul_f32_e32 v160, v160, v36
	v_mul_f32_e32 v161, v161, v37
	v_mul_f32_e32 v162, v162, v38
	v_mul_f32_e32 v163, v163, v39
	v_mul_f32_e32 v164, v164, v40
	v_mul_f32_e32 v165, v165, v41
	v_mul_f32_e32 v166, v166, v42
	v_mul_f32_e32 v167, v167, v43
	v_mul_f32_e32 v168, v168, v44
	v_mul_f32_e32 v169, v169, v45
	v_mul_f32_e32 v170, v170, v46
	v_mul_f32_e32 v171, v171, v47
	v_mul_f32_e32 v172, v172, v48
	v_mul_f32_e32 v173, v173, v49
	v_mul_f32_e32 v174, v174, v50
	v_mul_f32_e32 v175, v175, v51
	v_cvt_pk_bf16_f32 v160, v160, v161
	v_cvt_pk_bf16_f32 v161, v162, v163
	v_cvt_pk_bf16_f32 v164, v164, v165
	v_cvt_pk_bf16_f32 v165, v166, v167
	v_cvt_pk_bf16_f32 v168, v168, v169
	v_cvt_pk_bf16_f32 v169, v170, v171
	v_cvt_pk_bf16_f32 v172, v172, v173
	v_cvt_pk_bf16_f32 v173, v174, v175
	global_store_dwordx2 v2, v[160:161], s[50:51] offset:0
	global_store_dwordx2 v2, v[164:165], s[50:51] offset:512
	global_store_dwordx2 v2, v[168:169], s[50:51] offset:1024
	global_store_dwordx2 v2, v[172:173], s[50:51] offset:1536
	v_add_f32_e32 v208, v208, v212
	v_add_f32_e32 v209, v209, v213
	v_add_f32_e32 v210, v210, v214
	v_add_f32_e32 v211, v211, v215
	v_add_f32_e32 v216, v216, v220
	v_add_f32_e32 v217, v217, v221
	v_add_f32_e32 v218, v218, v222
	v_add_f32_e32 v219, v219, v223
	v_add_f32_e32 v224, v224, v228
	v_add_f32_e32 v225, v225, v229
	v_add_f32_e32 v226, v226, v230
	v_add_f32_e32 v227, v227, v231
	v_add_f32_e32 v232, v232, v236
	v_add_f32_e32 v233, v233, v237
	v_add_f32_e32 v234, v234, v238
	v_add_f32_e32 v235, v235, v239
	v_add_f32_e32 v208, v208, v216
	v_add_f32_e32 v209, v209, v217
	v_add_f32_e32 v210, v210, v218
	v_add_f32_e32 v211, v211, v219
	v_add_f32_e32 v224, v224, v232
	v_add_f32_e32 v225, v225, v233
	v_add_f32_e32 v226, v226, v234
	v_add_f32_e32 v227, v227, v235
	v_add_f32_e32 v208, v208, v224
	v_add_f32_e32 v209, v209, v225
	v_add_f32_e32 v210, v210, v226
	v_add_f32_e32 v211, v211, v227
	v_readfirstlane_b32 s18, v0
	s_lshr_b32 s18, s18, 6
	s_lshl_b32 s19, s18, 2
	s_and_b32 s52, s18, 4
	s_lshl_b32 s52, s52, 2
	v_mov_b32_e32 v16, s19
	v_mov_b32_e32 v17, s52
	v_mul_f32_e32 v10, v208, v208
	v_fmac_f32_e32 v10, v209, v209
	v_fmac_f32_e32 v10, v210, v210
	v_fmac_f32_e32 v10, v211, v211
	ds_bpermute_b32 v11, v4, v10
	s_waitcnt lgkmcnt(0)
	v_add_f32_e32 v10, v10, v11
	ds_bpermute_b32 v11, v5, v10
	s_waitcnt lgkmcnt(0)
	v_add_f32_e32 v10, v10, v11
	ds_bpermute_b32 v11, v6, v10
	s_waitcnt lgkmcnt(0)
	v_add_f32_e32 v10, v10, v11
	ds_bpermute_b32 v11, v7, v10
	s_waitcnt lgkmcnt(0)
	v_add_f32_e32 v10, v10, v11
	ds_bpermute_b32 v11, v8, v10
	s_waitcnt lgkmcnt(0)
	v_add_f32_e32 v10, v10, v11
	ds_bpermute_b32 v11, v9, v10
	s_waitcnt lgkmcnt(0)
	v_add_f32_e32 v10, v10, v11
	ds_write_b32 v16, v10 offset:0
	s_waitcnt lgkmcnt(0)
	s_barrier
	ds_read_b128 v[12:15], v17 offset:0
	s_waitcnt lgkmcnt(0)
	v_add_f32_e32 v12, v12, v13
	v_add_f32_e32 v14, v14, v15
	v_add_f32_e32 v10, v12, v14
	v_fma_f32 v11, v10, s17, v3
	v_rsq_f32_e32 v11, v11
	s_nop 0
	v_mul_f32_e32 v208, v208, v11
	v_mul_f32_e32 v209, v209, v11
	v_mul_f32_e32 v210, v210, v11
	v_mul_f32_e32 v211, v211, v11
	v_fmac_f32_e32 v240, v208, v244
	v_fmac_f32_e32 v241, v209, v245
	v_fmac_f32_e32 v242, v210, v246
	v_fmac_f32_e32 v243, v211, v247
	s_lshl_b32 s18, s54, 12
	s_add_u32 s18, s18, s55
	s_add_u32 s56, s4, s18
	s_addc_u32 s57, s5, 0
	s_add_u32 s56, s56, 0x4000000
	s_addc_u32 s57, s57, 0
	global_store_dwordx4 v1, v[240:243], s[56:57]
	v_mul_f32_e32 v10, v240, v240
	v_fmac_f32_e32 v10, v241, v241
	v_fmac_f32_e32 v10, v242, v242
	v_fmac_f32_e32 v10, v243, v243
	ds_bpermute_b32 v11, v4, v10
	s_waitcnt lgkmcnt(0)
	v_add_f32_e32 v10, v10, v11
	ds_bpermute_b32 v11, v5, v10
	s_waitcnt lgkmcnt(0)
	v_add_f32_e32 v10, v10, v11
	ds_bpermute_b32 v11, v6, v10
	s_waitcnt lgkmcnt(0)
	v_add_f32_e32 v10, v10, v11
	ds_bpermute_b32 v11, v7, v10
	s_waitcnt lgkmcnt(0)
	v_add_f32_e32 v10, v10, v11
	ds_bpermute_b32 v11, v8, v10
	s_waitcnt lgkmcnt(0)
	v_add_f32_e32 v10, v10, v11
	ds_bpermute_b32 v11, v9, v10
	s_waitcnt lgkmcnt(0)
	v_add_f32_e32 v10, v10, v11
	ds_write_b32 v16, v10 offset:64
	s_waitcnt lgkmcnt(0)
	s_barrier
	ds_read_b128 v[12:15], v17 offset:64
	s_waitcnt lgkmcnt(0)
	v_add_f32_e32 v12, v12, v13
	v_add_f32_e32 v14, v14, v15
	v_add_f32_e32 v10, v12, v14
	v_fma_f32 v11, v10, s17, v3
	v_rsq_f32_e32 v11, v11
	s_nop 0
	v_mul_f32_e32 v208, v240, v11
	v_mul_f32_e32 v209, v241, v11
	v_mul_f32_e32 v210, v242, v11
	v_mul_f32_e32 v211, v243, v11
	v_mul_f32_e32 v208, v208, v248
	v_mul_f32_e32 v209, v209, v249
	v_mul_f32_e32 v210, v210, v250
	v_mul_f32_e32 v211, v211, v251
	v_cvt_pk_bf16_f32 v208, v208, v209
	v_cvt_pk_bf16_f32 v209, v210, v211
	s_lshl_b32 s18, s54, 11
	s_lshr_b32 s19, s55, 1
	s_add_u32 s18, s18, s19
	s_add_u32 s56, s6, s18
	s_addc_u32 s57, s7, 0
	s_add_u32 s56, s56, 0x5100000
	s_addc_u32 s57, s57, 0
	global_store_dwordx2 v2, v[208:209], s[56:57]

	.amdhsa_kernel _Z10fwd_kernelILi7ELi8EEv4Args
		.amdhsa_group_segment_fixed_size 0
		.amdhsa_private_segment_fixed_size 0
		.amdhsa_kernarg_size 488
		.amdhsa_user_sgpr_count 2
		.amdhsa_user_sgpr_dispatch_ptr 0
		.amdhsa_user_sgpr_queue_ptr 0
		.amdhsa_user_sgpr_kernarg_segment_ptr 1
		.amdhsa_user_sgpr_dispatch_id 0
		.amdhsa_user_sgpr_kernarg_preload_length 0
		.amdhsa_user_sgpr_kernarg_preload_offset 0
		.amdhsa_user_sgpr_private_segment_size 0
		.amdhsa_uses_dynamic_stack 0
		.amdhsa_enable_private_segment 0
		.amdhsa_system_sgpr_workgroup_id_x 1
		.amdhsa_system_sgpr_workgroup_id_y 0
		.amdhsa_system_sgpr_workgroup_id_z 0
		.amdhsa_system_sgpr_workgroup_info 0
		.amdhsa_system_vgpr_workitem_id 0
		.amdhsa_next_free_vgpr 256
		.amdhsa_next_free_sgpr 60
		.amdhsa_accum_offset 256
		.amdhsa_reserve_vcc 1
		.amdhsa_float_round_mode_32 0
		.amdhsa_float_round_mode_16_64 0
		.amdhsa_float_denorm_mode_32 3
		.amdhsa_float_denorm_mode_16_64 3
		.amdhsa_dx10_clamp 1
		.amdhsa_ieee_mode 1
		.amdhsa_fp16_overflow 0
		.amdhsa_tg_split 0
		.amdhsa_exception_fp_ieee_invalid_op 0
		.amdhsa_exception_fp_denorm_src 0
		.amdhsa_exception_fp_ieee_div_zero 0
		.amdhsa_exception_fp_ieee_overflow 0
		.amdhsa_exception_fp_ieee_underflow 0
		.amdhsa_exception_fp_ieee_inexact 0
		.amdhsa_exception_int_div_zero 0
	.end_amdhsa_kernel

_Z10fwd_kernelILi8ELi9EEv4Args:
	v_mov_b32_e32 v1, v0
	s_load_dword s3, s[0:1], 0xe8
	s_waitcnt lgkmcnt(0)
	s_load_dwordx2 s[16:17], s[0:1], 0xd8
	s_load_dwordx2 s[40:41], s[0:1], 0xd0
	v_readfirstlane_b32 s4, v0
	s_lshr_b32 s4, s4, 6
	s_and_b32 s5, s4, 3
	s_lshr_b32 s6, s4, 2
	s_mov_b32 s12, s2
	v_and_b32_e32 v202, 15, v0
	v_bfe_u32 v203, v0, 4, 2
	v_and_b32_e32 v205, 63, v0
	v_lshlrev_b32_e32 v204, 11, v202
	v_lshl_add_u32 v204, v203, 4, v204
	s_lshl_b32 s7, s5, 9
	v_add_u32_e32 v204, s7, v204
	s_lshl_b32 s7, s4, 14
	v_lshl_add_u32 v206, v205, 4, s7
	s_lshl_b32 s7, s6, 16
	s_lshl_b32 s8, s5, 12
	s_add_u32 s7, s7, s8
	v_lshl_add_u32 v207, v205, 4, s7
	s_lshl_b32 s7, s5, 4
	v_add_u32_e32 v208, s7, v202
	v_mul_u32_u24_e32 v209, 0x1800, v208
	v_lshl_add_u32 v209, v203, 3, v209
	v_lshlrev_b32_e32 v210, 12, v208
	v_lshl_add_u32 v210, v203, 4, v210
	s_waitcnt lgkmcnt(0)
.Linp8_unit:
	s_lshr_b32 s29, s12, 3
	s_cmp_gt_u32 s29, 23
	s_cbranch_scc1 .Linp8_next
	s_add_u32 s20, s16, 0x5100000
	s_addc_u32 s21, s17, 0
	s_add_u32 s22, s16, 0x1900000
	s_addc_u32 s23, s17, 0
	s_add_u32 s24, s16, 0xd400000
	s_addc_u32 s25, s17, 0
	s_and_b32 s28, s12, 7
	s_lshl_b32 s29, s29, 1
	s_add_u32 s29, s29, s6
	s_lshr_b32 s30, s29, 3
	s_mul_i32 s28, s28, 6
	s_add_u32 s30, s30, s28
	s_and_b32 s31, s29, 7
	s_lshl_b32 s33, s31, 17
	s_lshl_b32 s34, s30, 17
	v_add_u32_e32 v194, s33, v204
	v_add_u32_e32 v198, s34, v204
	v_add_u32_e32 v195, s33, v204
	v_add_u32_e32 v199, s34, v204
	v_add_u32_e32 v196, s33, v204
	v_add_u32_e32 v200, s34, v204
	v_add_u32_e32 v197, s33, v204
	v_add_u32_e32 v201, s34, v204
	v_add_u32_e32 v195, 0x8000, v195
	v_add_u32_e32 v199, 0x8000, v199
	v_add_u32_e32 v196, 0x10000, v196
	v_add_u32_e32 v200, 0x10000, v200
	v_add_u32_e32 v197, 0x18000, v197
	v_add_u32_e32 v201, 0x18000, v201
	s_mul_i32 s33, s31, 0x60000
	s_lshl_b32 s34, s30, 7
	s_add_u32 s33, s33, s34
	v_add_u32_e32 v211, s33, v209
	s_lshr_b32 s35, s30, 4
	s_and_b32 s36, s30, 15
	s_lshl_b32 s36, s36, 8
	s_mov_b32 s37, 0x3f800000
	s_mov_b32 s42, 1
	s_cmp_eq_u32 s35, 0
	s_cselect_b32 s37, 0x3e38aa3b, s37
	s_cselect_b32 s42, 0, s42
	s_sub_u32 s43, s35, 1
	s_lshl_b32 s43, s43, 24
	s_lshl_b32 s44, s31, 21
	s_add_u32 s43, s43, s44
	s_add_u32 s43, s43, s36
	s_add_u32 s38, s40, s43
	s_addc_u32 s39, s41, 0
	s_add_u32 s38, s38, 0xd844000
	s_addc_u32 s39, s39, 0
	global_load_dwordx4 v[66:69], v194, s[20:21] offset:0
	global_load_dwordx4 v[82:85], v198, s[22:23] offset:0
	global_load_dwordx4 v[70:73], v195, s[20:21] offset:0
	global_load_dwordx4 v[86:89], v199, s[22:23] offset:0
	global_load_dwordx4 v[74:77], v196, s[20:21] offset:0
	global_load_dwordx4 v[90:93], v200, s[22:23] offset:0
	global_load_dwordx4 v[78:81], v197, s[20:21] offset:0
	global_load_dwordx4 v[94:97], v201, s[22:23] offset:0
	global_load_dwordx4 v[98:101], v194, s[20:21] offset:64
	global_load_dwordx4 v[114:117], v198, s[22:23] offset:64
	global_load_dwordx4 v[102:105], v195, s[20:21] offset:64
	global_load_dwordx4 v[118:121], v199, s[22:23] offset:64
	global_load_dwordx4 v[106:109], v196, s[20:21] offset:64
	global_load_dwordx4 v[122:125], v200, s[22:23] offset:64
	global_load_dwordx4 v[110:113], v197, s[20:21] offset:64
	global_load_dwordx4 v[126:129], v201, s[22:23] offset:64
	global_load_dwordx4 v[130:133], v194, s[20:21] offset:128
	global_load_dwordx4 v[146:149], v198, s[22:23] offset:128
	global_load_dwordx4 v[134:137], v195, s[20:21] offset:128
	global_load_dwordx4 v[150:153], v199, s[22:23] offset:128
	global_load_dwordx4 v[138:141], v196, s[20:21] offset:128
	global_load_dwordx4 v[154:157], v200, s[22:23] offset:128
	global_load_dwordx4 v[142:145], v197, s[20:21] offset:128
	global_load_dwordx4 v[158:161], v201, s[22:23] offset:128
	global_load_dwordx4 v[162:165], v194, s[20:21] offset:192
	global_load_dwordx4 v[178:181], v198, s[22:23] offset:192
	global_load_dwordx4 v[166:169], v195, s[20:21] offset:192
	global_load_dwordx4 v[182:185], v199, s[22:23] offset:192
	global_load_dwordx4 v[170:173], v196, s[20:21] offset:192
	global_load_dwordx4 v[186:189], v200, s[22:23] offset:192
	global_load_dwordx4 v[174:177], v197, s[20:21] offset:192
	global_load_dwordx4 v[190:193], v201, s[22:23] offset:192
	s_waitcnt vmcnt(28)
	v_mfma_f32_16x16x32_bf16 v[2:5], v[82:85], v[66:69], 0
	v_mfma_f32_16x16x32_bf16 v[6:9], v[86:89], v[66:69], 0
	v_mfma_f32_16x16x32_bf16 v[18:21], v[82:85], v[70:73], 0
	v_mfma_f32_16x16x32_bf16 v[22:25], v[86:89], v[70:73], 0
	s_waitcnt vmcnt(24)
	v_mfma_f32_16x16x32_bf16 v[10:13], v[90:93], v[66:69], 0
	v_mfma_f32_16x16x32_bf16 v[14:17], v[94:97], v[66:69], 0
	v_mfma_f32_16x16x32_bf16 v[26:29], v[90:93], v[70:73], 0
	v_mfma_f32_16x16x32_bf16 v[30:33], v[94:97], v[70:73], 0
	v_mfma_f32_16x16x32_bf16 v[34:37], v[82:85], v[74:77], 0
	v_mfma_f32_16x16x32_bf16 v[38:41], v[86:89], v[74:77], 0
	v_mfma_f32_16x16x32_bf16 v[42:45], v[90:93], v[74:77], 0
	v_mfma_f32_16x16x32_bf16 v[46:49], v[94:97], v[74:77], 0
	v_mfma_f32_16x16x32_bf16 v[50:53], v[82:85], v[78:81], 0
	v_mfma_f32_16x16x32_bf16 v[54:57], v[86:89], v[78:81], 0
	v_mfma_f32_16x16x32_bf16 v[58:61], v[90:93], v[78:81], 0
	v_mfma_f32_16x16x32_bf16 v[62:65], v[94:97], v[78:81], 0
	global_load_dwordx4 v[66:69], v194, s[20:21] offset:256
	global_load_dwordx4 v[82:85], v198, s[22:23] offset:256
	global_load_dwordx4 v[70:73], v195, s[20:21] offset:256
	global_load_dwordx4 v[86:89], v199, s[22:23] offset:256
	global_load_dwordx4 v[74:77], v196, s[20:21] offset:256
	global_load_dwordx4 v[90:93], v200, s[22:23] offset:256
	global_load_dwordx4 v[78:81], v197, s[20:21] offset:256
	global_load_dwordx4 v[94:97], v201, s[22:23] offset:256
	s_waitcnt vmcnt(28)
	v_mfma_f32_16x16x32_bf16 v[2:5], v[114:117], v[98:101], v[2:5]
	v_mfma_f32_16x16x32_bf16 v[6:9], v[118:121], v[98:101], v[6:9]
	v_mfma_f32_16x16x32_bf16 v[18:21], v[114:117], v[102:105], v[18:21]
	v_mfma_f32_16x16x32_bf16 v[22:25], v[118:121], v[102:105], v[22:25]
	s_waitcnt vmcnt(24)
	v_mfma_f32_16x16x32_bf16 v[10:13], v[122:125], v[98:101], v[10:13]
	v_mfma_f32_16x16x32_bf16 v[14:17], v[126:129], v[98:101], v[14:17]
	v_mfma_f32_16x16x32_bf16 v[26:29], v[122:125], v[102:105], v[26:29]
	v_mfma_f32_16x16x32_bf16 v[30:33], v[126:129], v[102:105], v[30:33]
	v_mfma_f32_16x16x32_bf16 v[34:37], v[114:117], v[106:109], v[34:37]
	v_mfma_f32_16x16x32_bf16 v[38:41], v[118:121], v[106:109], v[38:41]
	v_mfma_f32_16x16x32_bf16 v[42:45], v[122:125], v[106:109], v[42:45]
	v_mfma_f32_16x16x32_bf16 v[46:49], v[126:129], v[106:109], v[46:49]
	v_mfma_f32_16x16x32_bf16 v[50:53], v[114:117], v[110:113], v[50:53]
	v_mfma_f32_16x16x32_bf16 v[54:57], v[118:121], v[110:113], v[54:57]
	v_mfma_f32_16x16x32_bf16 v[58:61], v[122:125], v[110:113], v[58:61]
	v_mfma_f32_16x16x32_bf16 v[62:65], v[126:129], v[110:113], v[62:65]
	global_load_dwordx4 v[98:101], v194, s[20:21] offset:320
	global_load_dwordx4 v[114:117], v198, s[22:23] offset:320
	global_load_dwordx4 v[102:105], v195, s[20:21] offset:320
	global_load_dwordx4 v[118:121], v199, s[22:23] offset:320
	global_load_dwordx4 v[106:109], v196, s[20:21] offset:320
	global_load_dwordx4 v[122:125], v200, s[22:23] offset:320
	global_load_dwordx4 v[110:113], v197, s[20:21] offset:320
	global_load_dwordx4 v[126:129], v201, s[22:23] offset:320
	s_waitcnt vmcnt(28)
	v_mfma_f32_16x16x32_bf16 v[2:5], v[146:149], v[130:133], v[2:5]
	v_mfma_f32_16x16x32_bf16 v[6:9], v[150:153], v[130:133], v[6:9]
	v_mfma_f32_16x16x32_bf16 v[18:21], v[146:149], v[134:137], v[18:21]
	v_mfma_f32_16x16x32_bf16 v[22:25], v[150:153], v[134:137], v[22:25]
	s_waitcnt vmcnt(24)
	v_mfma_f32_16x16x32_bf16 v[10:13], v[154:157], v[130:133], v[10:13]
	v_mfma_f32_16x16x32_bf16 v[14:17], v[158:161], v[130:133], v[14:17]
	v_mfma_f32_16x16x32_bf16 v[26:29], v[154:157], v[134:137], v[26:29]
	v_mfma_f32_16x16x32_bf16 v[30:33], v[158:161], v[134:137], v[30:33]
	v_mfma_f32_16x16x32_bf16 v[34:37], v[146:149], v[138:141], v[34:37]
	v_mfma_f32_16x16x32_bf16 v[38:41], v[150:153], v[138:141], v[38:41]
	v_mfma_f32_16x16x32_bf16 v[42:45], v[154:157], v[138:141], v[42:45]
	v_mfma_f32_16x16x32_bf16 v[46:49], v[158:161], v[138:141], v[46:49]
	v_mfma_f32_16x16x32_bf16 v[50:53], v[146:149], v[142:145], v[50:53]
	v_mfma_f32_16x16x32_bf16 v[54:57], v[150:153], v[142:145], v[54:57]
	v_mfma_f32_16x16x32_bf16 v[58:61], v[154:157], v[142:145], v[58:61]
	v_mfma_f32_16x16x32_bf16 v[62:65], v[158:161], v[142:145], v[62:65]
	global_load_dwordx4 v[130:133], v194, s[20:21] offset:384
	global_load_dwordx4 v[146:149], v198, s[22:23] offset:384
	global_load_dwordx4 v[134:137], v195, s[20:21] offset:384
	global_load_dwordx4 v[150:153], v199, s[22:23] offset:384
	global_load_dwordx4 v[138:141], v196, s[20:21] offset:384
	global_load_dwordx4 v[154:157], v200, s[22:23] offset:384
	global_load_dwordx4 v[142:145], v197, s[20:21] offset:384
	global_load_dwordx4 v[158:161], v201, s[22:23] offset:384
	s_waitcnt vmcnt(28)
	v_mfma_f32_16x16x32_bf16 v[2:5], v[178:181], v[162:165], v[2:5]
	v_mfma_f32_16x16x32_bf16 v[6:9], v[182:185], v[162:165], v[6:9]
	v_mfma_f32_16x16x32_bf16 v[18:21], v[178:181], v[166:169], v[18:21]
	v_mfma_f32_16x16x32_bf16 v[22:25], v[182:185], v[166:169], v[22:25]
	s_waitcnt vmcnt(24)
	v_mfma_f32_16x16x32_bf16 v[10:13], v[186:189], v[162:165], v[10:13]
	v_mfma_f32_16x16x32_bf16 v[14:17], v[190:193], v[162:165], v[14:17]
	v_mfma_f32_16x16x32_bf16 v[26:29], v[186:189], v[166:169], v[26:29]
	v_mfma_f32_16x16x32_bf16 v[30:33], v[190:193], v[166:169], v[30:33]
	v_mfma_f32_16x16x32_bf16 v[34:37], v[178:181], v[170:173], v[34:37]
	v_mfma_f32_16x16x32_bf16 v[38:41], v[182:185], v[170:173], v[38:41]
	v_mfma_f32_16x16x32_bf16 v[42:45], v[186:189], v[170:173], v[42:45]
	v_mfma_f32_16x16x32_bf16 v[46:49], v[190:193], v[170:173], v[46:49]
	v_mfma_f32_16x16x32_bf16 v[50:53], v[178:181], v[174:177], v[50:53]
	v_mfma_f32_16x16x32_bf16 v[54:57], v[182:185], v[174:177], v[54:57]
	v_mfma_f32_16x16x32_bf16 v[58:61], v[186:189], v[174:177], v[58:61]
	v_mfma_f32_16x16x32_bf16 v[62:65], v[190:193], v[174:177], v[62:65]
	global_load_dwordx4 v[162:165], v194, s[20:21] offset:448
	global_load_dwordx4 v[178:181], v198, s[22:23] offset:448
	global_load_dwordx4 v[166:169], v195, s[20:21] offset:448
	global_load_dwordx4 v[182:185], v199, s[22:23] offset:448
	global_load_dwordx4 v[170:173], v196, s[20:21] offset:448
	global_load_dwordx4 v[186:189], v200, s[22:23] offset:448
	global_load_dwordx4 v[174:177], v197, s[20:21] offset:448
	global_load_dwordx4 v[190:193], v201, s[22:23] offset:448
	s_waitcnt vmcnt(28)
	v_mfma_f32_16x16x32_bf16 v[2:5], v[82:85], v[66:69], v[2:5]
	v_mfma_f32_16x16x32_bf16 v[6:9], v[86:89], v[66:69], v[6:9]
	v_mfma_f32_16x16x32_bf16 v[18:21], v[82:85], v[70:73], v[18:21]
	v_mfma_f32_16x16x32_bf16 v[22:25], v[86:89], v[70:73], v[22:25]
	s_waitcnt vmcnt(24)
	v_mfma_f32_16x16x32_bf16 v[10:13], v[90:93], v[66:69], v[10:13]
	v_mfma_f32_16x16x32_bf16 v[14:17], v[94:97], v[66:69], v[14:17]
	v_mfma_f32_16x16x32_bf16 v[26:29], v[90:93], v[70:73], v[26:29]
	v_mfma_f32_16x16x32_bf16 v[30:33], v[94:97], v[70:73], v[30:33]
	v_mfma_f32_16x16x32_bf16 v[34:37], v[82:85], v[74:77], v[34:37]
	v_mfma_f32_16x16x32_bf16 v[38:41], v[86:89], v[74:77], v[38:41]
	v_mfma_f32_16x16x32_bf16 v[42:45], v[90:93], v[74:77], v[42:45]
	v_mfma_f32_16x16x32_bf16 v[46:49], v[94:97], v[74:77], v[46:49]
	v_mfma_f32_16x16x32_bf16 v[50:53], v[82:85], v[78:81], v[50:53]
	v_mfma_f32_16x16x32_bf16 v[54:57], v[86:89], v[78:81], v[54:57]
	v_mfma_f32_16x16x32_bf16 v[58:61], v[90:93], v[78:81], v[58:61]
	v_mfma_f32_16x16x32_bf16 v[62:65], v[94:97], v[78:81], v[62:65]
	s_waitcnt vmcnt(20)
	v_mfma_f32_16x16x32_bf16 v[2:5], v[114:117], v[98:101], v[2:5]
	v_mfma_f32_16x16x32_bf16 v[6:9], v[118:121], v[98:101], v[6:9]
	v_mfma_f32_16x16x32_bf16 v[18:21], v[114:117], v[102:105], v[18:21]
	v_mfma_f32_16x16x32_bf16 v[22:25], v[118:121], v[102:105], v[22:25]
	s_waitcnt vmcnt(16)
	v_mfma_f32_16x16x32_bf16 v[10:13], v[122:125], v[98:101], v[10:13]
	v_mfma_f32_16x16x32_bf16 v[14:17], v[126:129], v[98:101], v[14:17]
	v_mfma_f32_16x16x32_bf16 v[26:29], v[122:125], v[102:105], v[26:29]
	v_mfma_f32_16x16x32_bf16 v[30:33], v[126:129], v[102:105], v[30:33]
	v_mfma_f32_16x16x32_bf16 v[34:37], v[114:117], v[106:109], v[34:37]
	v_mfma_f32_16x16x32_bf16 v[38:41], v[118:121], v[106:109], v[38:41]
	v_mfma_f32_16x16x32_bf16 v[42:45], v[122:125], v[106:109], v[42:45]
	v_mfma_f32_16x16x32_bf16 v[46:49], v[126:129], v[106:109], v[46:49]
	v_mfma_f32_16x16x32_bf16 v[50:53], v[114:117], v[110:113], v[50:53]
	v_mfma_f32_16x16x32_bf16 v[54:57], v[118:121], v[110:113], v[54:57]
	v_mfma_f32_16x16x32_bf16 v[58:61], v[122:125], v[110:113], v[58:61]
	v_mfma_f32_16x16x32_bf16 v[62:65], v[126:129], v[110:113], v[62:65]
	s_waitcnt vmcnt(12)
	v_mfma_f32_16x16x32_bf16 v[2:5], v[146:149], v[130:133], v[2:5]
	v_mfma_f32_16x16x32_bf16 v[6:9], v[150:153], v[130:133], v[6:9]
	v_mfma_f32_16x16x32_bf16 v[18:21], v[146:149], v[134:137], v[18:21]
	v_mfma_f32_16x16x32_bf16 v[22:25], v[150:153], v[134:137], v[22:25]
	s_waitcnt vmcnt(8)
	v_mfma_f32_16x16x32_bf16 v[10:13], v[154:157], v[130:133], v[10:13]
	v_mfma_f32_16x16x32_bf16 v[14:17], v[158:161], v[130:133], v[14:17]
	v_mfma_f32_16x16x32_bf16 v[26:29], v[154:157], v[134:137], v[26:29]
	v_mfma_f32_16x16x32_bf16 v[30:33], v[158:161], v[134:137], v[30:33]
	v_mfma_f32_16x16x32_bf16 v[34:37], v[146:149], v[138:141], v[34:37]
	v_mfma_f32_16x16x32_bf16 v[38:41], v[150:153], v[138:141], v[38:41]
	v_mfma_f32_16x16x32_bf16 v[42:45], v[154:157], v[138:141], v[42:45]
	v_mfma_f32_16x16x32_bf16 v[46:49], v[158:161], v[138:141], v[46:49]
	v_mfma_f32_16x16x32_bf16 v[50:53], v[146:149], v[142:145], v[50:53]
	v_mfma_f32_16x16x32_bf16 v[54:57], v[150:153], v[142:145], v[54:57]
	v_mfma_f32_16x16x32_bf16 v[58:61], v[154:157], v[142:145], v[58:61]
	v_mfma_f32_16x16x32_bf16 v[62:65], v[158:161], v[142:145], v[62:65]
	s_waitcnt vmcnt(4)
	v_mfma_f32_16x16x32_bf16 v[2:5], v[178:181], v[162:165], v[2:5]
	v_mfma_f32_16x16x32_bf16 v[6:9], v[182:185], v[162:165], v[6:9]
	v_mfma_f32_16x16x32_bf16 v[18:21], v[178:181], v[166:169], v[18:21]
	v_mfma_f32_16x16x32_bf16 v[22:25], v[182:185], v[166:169], v[22:25]
	s_waitcnt vmcnt(0)
	v_mfma_f32_16x16x32_bf16 v[10:13], v[186:189], v[162:165], v[10:13]
	v_mfma_f32_16x16x32_bf16 v[14:17], v[190:193], v[162:165], v[14:17]
	v_mfma_f32_16x16x32_bf16 v[26:29], v[186:189], v[166:169], v[26:29]
	v_mfma_f32_16x16x32_bf16 v[30:33], v[190:193], v[166:169], v[30:33]
	v_mfma_f32_16x16x32_bf16 v[34:37], v[178:181], v[170:173], v[34:37]
	v_mfma_f32_16x16x32_bf16 v[38:41], v[182:185], v[170:173], v[38:41]
	v_mfma_f32_16x16x32_bf16 v[42:45], v[186:189], v[170:173], v[42:45]
	v_mfma_f32_16x16x32_bf16 v[46:49], v[190:193], v[170:173], v[46:49]
	v_mfma_f32_16x16x32_bf16 v[50:53], v[178:181], v[174:177], v[50:53]
	v_mfma_f32_16x16x32_bf16 v[54:57], v[182:185], v[174:177], v[54:57]
	v_mfma_f32_16x16x32_bf16 v[58:61], v[186:189], v[174:177], v[58:61]
	v_mfma_f32_16x16x32_bf16 v[62:65], v[190:193], v[174:177], v[62:65]
	s_nop 7
	ds_write_b128 v206, v[2:5] offset:0
	ds_write_b128 v206, v[6:9] offset:1024
	ds_write_b128 v206, v[10:13] offset:2048
	ds_write_b128 v206, v[14:17] offset:3072
	ds_write_b128 v206, v[18:21] offset:4096
	ds_write_b128 v206, v[22:25] offset:5120
	ds_write_b128 v206, v[26:29] offset:6144
	ds_write_b128 v206, v[30:33] offset:7168
	ds_write_b128 v206, v[34:37] offset:8192
	ds_write_b128 v206, v[38:41] offset:9216
	ds_write_b128 v206, v[42:45] offset:10240
	ds_write_b128 v206, v[46:49] offset:11264
	ds_write_b128 v206, v[50:53] offset:12288
	ds_write_b128 v206, v[54:57] offset:13312
	ds_write_b128 v206, v[58:61] offset:14336
	ds_write_b128 v206, v[62:65] offset:15360
	s_waitcnt lgkmcnt(0)
	s_barrier
	ds_read_b128 v[2:5], v207 offset:0
	ds_read_b128 v[6:9], v207 offset:16384
	ds_read_b128 v[10:13], v207 offset:32768
	ds_read_b128 v[14:17], v207 offset:49152
	ds_read_b128 v[18:21], v207 offset:1024
	ds_read_b128 v[22:25], v207 offset:17408
	ds_read_b128 v[26:29], v207 offset:33792
	ds_read_b128 v[30:33], v207 offset:50176
	ds_read_b128 v[34:37], v207 offset:2048
	ds_read_b128 v[38:41], v207 offset:18432
	ds_read_b128 v[42:45], v207 offset:34816
	ds_read_b128 v[46:49], v207 offset:51200
	ds_read_b128 v[50:53], v207 offset:3072
	ds_read_b128 v[54:57], v207 offset:19456
	ds_read_b128 v[58:61], v207 offset:35840
	ds_read_b128 v[62:65], v207 offset:52224
	s_waitcnt lgkmcnt(12)
	v_add_f32_e32 v2, v2, v6
	v_add_f32_e32 v3, v3, v7
	v_add_f32_e32 v4, v4, v8
	v_add_f32_e32 v5, v5, v9
	v_add_f32_e32 v10, v10, v14
	v_add_f32_e32 v11, v11, v15
	v_add_f32_e32 v12, v12, v16
	v_add_f32_e32 v13, v13, v17
	v_add_f32_e32 v2, v2, v10
	v_add_f32_e32 v3, v3, v11
	v_add_f32_e32 v4, v4, v12
	v_add_f32_e32 v5, v5, v13
	s_waitcnt lgkmcnt(8)
	v_add_f32_e32 v18, v18, v22
	v_add_f32_e32 v19, v19, v23
	v_add_f32_e32 v20, v20, v24
	v_add_f32_e32 v21, v21, v25
	v_add_f32_e32 v26, v26, v30
	v_add_f32_e32 v27, v27, v31
	v_add_f32_e32 v28, v28, v32
	v_add_f32_e32 v29, v29, v33
	v_add_f32_e32 v18, v18, v26
	v_add_f32_e32 v19, v19, v27
	v_add_f32_e32 v20, v20, v28
	v_add_f32_e32 v21, v21, v29
	s_waitcnt lgkmcnt(4)
	v_add_f32_e32 v34, v34, v38
	v_add_f32_e32 v35, v35, v39
	v_add_f32_e32 v36, v36, v40
	v_add_f32_e32 v37, v37, v41
	v_add_f32_e32 v42, v42, v46
	v_add_f32_e32 v43, v43, v47
	v_add_f32_e32 v44, v44, v48
	v_add_f32_e32 v45, v45, v49
	v_add_f32_e32 v34, v34, v42
	v_add_f32_e32 v35, v35, v43
	v_add_f32_e32 v36, v36, v44
	v_add_f32_e32 v37, v37, v45
	s_waitcnt lgkmcnt(0)
	v_add_f32_e32 v50, v50, v54
	v_add_f32_e32 v51, v51, v55
	v_add_f32_e32 v52, v52, v56
	v_add_f32_e32 v53, v53, v57
	v_add_f32_e32 v58, v58, v62
	v_add_f32_e32 v59, v59, v63
	v_add_f32_e32 v60, v60, v64
	v_add_f32_e32 v61, v61, v65
	v_add_f32_e32 v50, v50, v58
	v_add_f32_e32 v51, v51, v59
	v_add_f32_e32 v52, v52, v60
	v_add_f32_e32 v53, v53, v61
	s_cmp_eq_u32 s42, 0
	s_cbranch_scc1 .Linp8_nof32
	global_store_dwordx4 v210, v[2:5], s[38:39] offset:0
	global_store_dwordx4 v210, v[18:21], s[38:39] offset:64
	global_store_dwordx4 v210, v[34:37], s[38:39] offset:128
	global_store_dwordx4 v210, v[50:53], s[38:39] offset:192
	s_nop 1

.Linp8_next:
	s_add_i32 s12, s12, s3
	s_cmpk_lt_u32 s12, 0x100
	s_cbranch_scc1 .Linp8_unit
	s_cmpk_lt_i32 s2, 0x300
	s_waitcnt lgkmcnt(0)
	s_cselect_b64 s[6:7], -1, 0
	s_cmpk_gt_i32 s2, 0x2ff
	v_readfirstlane_b32 s16, v0
	s_cbranch_scc0 .LBB8_3
	s_andn2_b64 vcc, exec, s[6:7]
	s_cbranch_vccz .LBB8_4

.LBB8_6:
	s_lshl_b32 s1, s1, 5
	s_mov_b64 s[14:15], 0x80
	s_and_b32 s6, s1, 0x60
	s_add_i32 m0, s40, 0x18000
	v_lshl_add_u64 v[8:9], v[8:9], 0, s[14:15]
	s_lshl_b32 s44, s0, 6
	s_lshl_b32 s5, s0, 13
	s_lshl_b32 s1, s6, 7
	s_waitcnt vmcnt(2)
	s_barrier
	global_load_lds_dwordx4 v[8:9], off
	v_lshl_add_u64 v[6:7], v[6:7], 0, s[14:15]
	s_add_i32 m0, s40, 0x1a000
	s_add_i32 s45, s40, 0x8000
	s_add_i32 s46, s40, 0xa000
	global_load_lds_dwordx4 v[6:7], off
	v_lshl_add_u64 v[2:3], v[2:3], 0, s[14:15]
	s_mov_b32 m0, s45
	s_add_u32 s18, s26, 0x40080
	global_load_lds_dwordx4 v[2:3], off
	v_lshl_add_u64 v[2:3], v[4:5], 0, s[14:15]
	s_mov_b32 m0, s46
	s_addc_u32 s19, s27, 0
	global_load_lds_dwordx4 v[2:3], off
	s_add_i32 m0, s40, 0x1c000
	v_lshl_add_u64 v[2:3], s[18:19], 0, v[130:131]
	global_load_lds_dwordx4 v[2:3], off
	v_lshl_add_u64 v[2:3], s[18:19], 0, v[134:135]
	s_add_i32 m0, s40, 0x1e000
	s_cmpk_lt_u32 s16, 0x100
	global_load_lds_dwordx4 v[2:3], off
	v_bfe_u32 v3, v0, 4, 2
	v_and_b32_e32 v2, 15, v0
	v_lshlrev_b32_e32 v4, 4, v3
	v_lshlrev_b32_e32 v0, 2, v0
	v_lshl_or_b32 v5, v2, 6, v4
	v_and_b32_e32 v0, 32, v0
	v_bitop3_b32 v6, v5, s5, v0 bitop3:0xde
	v_bitop3_b32 v152, v5, s1, v0 bitop3:0xde
	v_lshlrev_b32_e32 v0, 12, v2
	v_lshl_or_b32 v136, v3, 5, v0
	v_mul_u32_u24_e32 v0, 0x1800, v2
	v_or_b32_e32 v2, v4, v0
	v_mov_b32_e32 v3, v131
	v_lshlrev_b32_e32 v0, 14, v12
	s_cselect_b64 s[16:17], -1, 0
	s_lshl_b32 s50, s0, 9
	v_lshl_add_u64 v[2:3], s[10:11], 0, v[2:3]
	s_mov_b64 s[0:1], 0x7400000
	v_and_b32_e32 v0, 0xffff8000, v0
	v_lshl_add_u64 v[138:139], v[2:3], 0, s[0:1]
	v_lshl_add_u32 v0, v13, 11, v0
	v_and_b32_e32 v2, 1, v12
	v_lshl_or_b32 v0, v2, 6, v0
	v_lshl_add_u32 v140, v14, 1, v0
	v_lshlrev_b32_e32 v0, 14, v1
	v_and_b32_e32 v0, 0xffff8000, v0
	s_waitcnt vmcnt(6)
	v_lshl_add_u32 v0, v10, 11, v0
	v_and_b32_e32 v1, 1, v1
	v_lshl_or_b32 v0, v1, 6, v0
	s_add_i32 s52, 0, 0x10000
	s_add_i32 s53, 0, 0x14000
	s_add_i32 s47, s44, 0xfffff200
	v_mov_b32_e32 v137, v131
	s_ashr_i32 s48, s3, 31
	s_ashr_i32 s49, s2, 31
	s_add_i32 s50, s50, 0xfffe01c0
	v_mov_b32_e32 v141, v131
	v_lshl_add_u32 v142, v11, 1, v0
	v_mov_b32_e32 v143, v131
	v_mov_b64_e32 v[144:145], 0x300
	v_mov_b64_e32 v[146:147], 0x2ff
	s_movk_i32 s51, 0x61
	v_add_u32_e32 v153, s52, v152
	v_add_u32_e32 v154, s53, v152
	v_add_u32_e32 v155, 0, v6
	s_mov_b32 s54, 0xc280000
	s_mov_b32 s55, 0xd684000
	s_mov_b32 s56, 0x48000
	s_mov_b32 s57, 0x400000
	s_mov_b32 s58, 0xc0000
	s_mov_b32 s59, 0x410000
	s_mov_b32 s60, 0xd8000
	s_mov_b32 s61, 0x420000
	s_mov_b32 s62, 0xf0000
	s_mov_b32 s63, 0x430000
	s_mov_b32 s64, s7
	s_barrier
	s_branch .LBB8_9

.LBB8_9:
	s_add_i32 s64, s64, 1
	s_mul_i32 s0, s64, s48
	s_mul_hi_u32 s1, s64, s3
	s_add_i32 s1, s1, s0
	s_mul_i32 s0, s64, s3
	s_add_u32 s0, s0, s2
	s_addc_u32 s1, s1, s49
	v_cmp_gt_i64_e32 vcc, s[0:1], v[146:147]
	s_cbranch_vccnz .LBB8_11
	s_ashr_i32 s5, s0, 31
	s_lshr_b32 s5, s5, 29
	s_add_i32 s5, s0, s5
	s_ashr_i32 s10, s5, 3
	s_and_b32 s5, s5, -8
	s_sub_i32 s5, s0, s5
	s_cmp_lt_i32 s5, 0
	s_cselect_b32 s11, s51, 0x60
	s_mul_i32 s5, s5, s11
	s_add_i32 s5, s5, s10
	s_mul_hi_i32 s10, s5, 0x2aaaaaab
	s_lshr_b32 s11, s10, 31
	s_ashr_i32 s10, s10, 4
	s_add_i32 s10, s10, s11
	s_lshl_b32 s11, s10, 3
	s_sub_i32 s18, 0x40, s11
	s_min_i32 s18, s18, 8
	s_abs_i32 s19, s18
	v_cvt_f32_u32_e32 v0, s19
	s_sub_i32 s21, 0, s19
	s_mulk_i32 s10, 0x60
	s_sub_i32 s5, s5, s10
	v_rcp_iflag_f32_e32 v0, v0
	s_abs_i32 s10, s5
	s_xor_b32 s20, s5, s18
	s_ashr_i32 s20, s20, 31
	v_mul_f32_e32 v0, 0x4f7ffffe, v0
	v_cvt_u32_f32_e32 v0, v0
	s_nop 0
	v_readfirstlane_b32 s22, v0
	s_mul_i32 s21, s21, s22
	s_mul_hi_u32 s21, s22, s21
	s_add_i32 s22, s22, s21
	s_mul_hi_u32 s21, s10, s22
	s_mul_i32 s22, s21, s19
	s_sub_i32 s10, s10, s22
	s_add_i32 s23, s21, 1
	s_sub_i32 s22, s10, s19
	s_cmp_ge_u32 s10, s19
	s_cselect_b32 s21, s23, s21
	s_cselect_b32 s10, s22, s10
	s_add_i32 s22, s21, 1
	s_cmp_ge_u32 s10, s19
	s_cselect_b32 s10, s22, s21
	s_xor_b32 s10, s10, s20
	s_sub_i32 s10, s10, s20
	s_mul_i32 s18, s10, s18
	s_sub_i32 s5, s5, s18
	s_add_i32 s18, s11, s5

.LBB9_137:
	ds_read_b64_tr_b16 v[174:175], v129 offset:39936
	ds_read_b64_tr_b16 v[176:177], v129 offset:42496
	ds_read_b64_tr_b16 v[180:181], v129 offset:42560
	ds_read_b64_tr_b16 v[178:179], v129 offset:40000
	ds_read_b64_tr_b16 v[182:183], v129 offset:45056
	ds_read_b64_tr_b16 v[184:185], v129 offset:47616
	ds_read_b64_tr_b16 v[188:189], v129 offset:47680
	ds_read_b64_tr_b16 v[186:187], v129 offset:45120
	ds_read_b64_tr_b16 v[190:191], v129 offset:50176
	ds_read_b64_tr_b16 v[192:193], v129 offset:52736
	ds_read_b64_tr_b16 v[196:197], v129 offset:52800
	ds_read_b64_tr_b16 v[194:195], v129 offset:50240
	v_exp_f32_e32 v137, v36
	v_exp_f32_e32 v145, v52
	v_exp_f32_e32 v68, v37
	v_exp_f32_e32 v52, v53
	v_exp_f32_e32 v146, v54
	v_add_f32_e32 v53, v145, v137
	v_exp_f32_e32 v54, v55
	v_pk_add_f32 v[36:37], v[52:53], v[68:69]
	v_exp_f32_e32 v53, v38
	v_pk_add_f32 v[70:71], v[36:37], v[36:37] op_sel_hi:[0,1]
	v_exp_f32_e32 v70, v39
	v_add_f32_e32 v55, v146, v53
	v_pk_add_f32 v[36:37], v[54:55], v[70:71]
	s_nop 0
	v_pk_add_f32 v[38:39], v[36:37], v[36:37] op_sel_hi:[0,1]
	v_exp_f32_e32 v55, v40
	v_exp_f32_e32 v71, v56
	v_exp_f32_e32 v38, v41
	v_exp_f32_e32 v56, v57
	v_add_f32_e32 v57, v71, v55
	v_pk_add_f32 v[36:37], v[56:57], v[38:39]
	s_nop 0
	v_pk_add_f32 v[40:41], v[36:37], v[36:37] op_sel_hi:[0,1]
	v_exp_f32_e32 v39, v42
	v_exp_f32_e32 v57, v58
	v_exp_f32_e32 v40, v43
	v_exp_f32_e32 v58, v59
	v_cvt_pk_bf16_f32 v38, v55, v38
	v_add_f32_e32 v59, v57, v39
	v_cvt_pk_bf16_f32 v39, v39, v40
	v_pk_add_f32 v[36:37], v[58:59], v[40:41]
	v_exp_f32_e32 v41, v44
	v_pk_add_f32 v[42:43], v[36:37], v[36:37] op_sel_hi:[0,1]
	v_exp_f32_e32 v59, v60
	v_exp_f32_e32 v42, v45
	v_exp_f32_e32 v60, v61
	v_add_f32_e32 v61, v59, v41
	v_cvt_pk_bf16_f32 v40, v41, v42
	v_pk_add_f32 v[36:37], v[60:61], v[42:43]
	v_exp_f32_e32 v43, v46
	v_pk_add_f32 v[44:45], v[36:37], v[36:37] op_sel_hi:[0,1]
	v_exp_f32_e32 v61, v62
	v_exp_f32_e32 v44, v47
	v_exp_f32_e32 v62, v63
	v_add_f32_e32 v63, v61, v43
	v_cvt_pk_bf16_f32 v41, v43, v44
	v_pk_add_f32 v[36:37], v[62:63], v[44:45]
	v_exp_f32_e32 v45, v48
	v_pk_add_f32 v[46:47], v[36:37], v[36:37] op_sel_hi:[0,1]
	v_exp_f32_e32 v63, v64
	v_exp_f32_e32 v46, v49
	v_exp_f32_e32 v64, v65
	v_cvt_pk_bf16_f32 v44, v145, v52
	v_add_f32_e32 v65, v63, v45
	v_cvt_pk_bf16_f32 v42, v45, v46
	v_pk_add_f32 v[36:37], v[64:65], v[46:47]
	v_exp_f32_e32 v47, v50
	v_pk_add_f32 v[48:49], v[36:37], v[36:37] op_sel_hi:[0,1]
	v_exp_f32_e32 v65, v66
	v_exp_f32_e32 v48, v51
	v_exp_f32_e32 v66, v67
	v_cvt_pk_bf16_f32 v45, v146, v54
	v_add_f32_e32 v67, v65, v47
	v_cvt_pk_bf16_f32 v43, v47, v48
	v_pk_add_f32 v[36:37], v[66:67], v[48:49]
	v_cvt_pk_bf16_f32 v46, v71, v56
	v_add_f32_e32 v67, v36, v37
	v_cvt_pk_bf16_f32 v37, v53, v70
	v_cvt_pk_bf16_f32 v36, v137, v68
	v_cvt_pk_bf16_f32 v47, v57, v58
	v_cvt_pk_bf16_f32 v56, v59, v60
	v_cvt_pk_bf16_f32 v57, v61, v62
	v_cvt_pk_bf16_f32 v58, v63, v64
	v_cvt_pk_bf16_f32 v59, v65, v66
	s_waitcnt lgkmcnt(0)
	v_mfma_f32_32x32x16_bf16 v[2:17], v[124:127], v[36:39], v[2:17]
	v_mfma_f32_32x32x16_bf16 v[18:33], v[120:123], v[36:39], v[18:33]
	v_mfma_f32_32x32x16_bf16 v[2:17], v[174:177], v[40:43], v[2:17]
	v_mfma_f32_32x32x16_bf16 v[18:33], v[178:181], v[40:43], v[18:33]
	v_mfma_f32_32x32x16_bf16 v[2:17], v[182:185], v[44:47], v[2:17]
	v_mfma_f32_32x32x16_bf16 v[18:33], v[186:189], v[44:47], v[18:33]
	v_mfma_f32_32x32x16_bf16 v[2:17], v[190:193], v[56:59], v[2:17]
	v_mfma_f32_32x32x16_bf16 v[18:33], v[194:197], v[56:59], v[18:33]
	v_add_f32_e32 v34, v34, v67
	s_mov_b64 s[10:11], 0

.LBB9_156:
	ds_read_b64_tr_b16 v[174:175], v129 offset:60416
	ds_read_b64_tr_b16 v[176:177], v129 offset:62976
	ds_read_b64_tr_b16 v[180:181], v129 offset:63040
	ds_read_b64_tr_b16 v[178:179], v129 offset:60480
	ds_read_b64_tr_b16 v[182:183], v142 offset:10240
	ds_read_b64_tr_b16 v[184:185], v142 offset:12800
	ds_read_b64_tr_b16 v[188:189], v142 offset:12864
	ds_read_b64_tr_b16 v[186:187], v142 offset:10304
	ds_read_b64_tr_b16 v[190:191], v142 offset:15360
	ds_read_b64_tr_b16 v[192:193], v142 offset:17920
	ds_read_b64_tr_b16 v[196:197], v142 offset:17984
	ds_read_b64_tr_b16 v[194:195], v142 offset:15424
	v_exp_f32_e32 v137, v36
	v_exp_f32_e32 v145, v52
	v_exp_f32_e32 v68, v37
	v_exp_f32_e32 v52, v53
	v_exp_f32_e32 v146, v54
	v_add_f32_e32 v53, v145, v137
	v_exp_f32_e32 v54, v55
	v_pk_add_f32 v[36:37], v[52:53], v[68:69]
	v_exp_f32_e32 v53, v38
	v_pk_add_f32 v[70:71], v[36:37], v[36:37] op_sel_hi:[0,1]
	v_exp_f32_e32 v70, v39
	v_add_f32_e32 v55, v146, v53
	v_pk_add_f32 v[36:37], v[54:55], v[70:71]
	s_nop 0
	v_pk_add_f32 v[38:39], v[36:37], v[36:37] op_sel_hi:[0,1]
	v_exp_f32_e32 v55, v40
	v_exp_f32_e32 v71, v56
	v_exp_f32_e32 v38, v41
	v_exp_f32_e32 v56, v57
	v_add_f32_e32 v57, v71, v55
	v_pk_add_f32 v[36:37], v[56:57], v[38:39]
	s_nop 0
	v_pk_add_f32 v[40:41], v[36:37], v[36:37] op_sel_hi:[0,1]
	v_exp_f32_e32 v39, v42
	v_exp_f32_e32 v57, v58
	v_exp_f32_e32 v40, v43
	v_exp_f32_e32 v58, v59
	v_cvt_pk_bf16_f32 v38, v55, v38
	v_add_f32_e32 v59, v57, v39
	v_cvt_pk_bf16_f32 v39, v39, v40
	v_pk_add_f32 v[36:37], v[58:59], v[40:41]
	v_exp_f32_e32 v41, v44
	v_pk_add_f32 v[42:43], v[36:37], v[36:37] op_sel_hi:[0,1]
	v_exp_f32_e32 v59, v60
	v_exp_f32_e32 v42, v45
	v_exp_f32_e32 v60, v61
	v_add_f32_e32 v61, v59, v41
	v_cvt_pk_bf16_f32 v40, v41, v42
	v_pk_add_f32 v[36:37], v[60:61], v[42:43]
	v_exp_f32_e32 v43, v46
	v_pk_add_f32 v[44:45], v[36:37], v[36:37] op_sel_hi:[0,1]
	v_exp_f32_e32 v61, v62
	v_exp_f32_e32 v44, v47
	v_exp_f32_e32 v62, v63
	v_add_f32_e32 v63, v61, v43
	v_cvt_pk_bf16_f32 v41, v43, v44
	v_pk_add_f32 v[36:37], v[62:63], v[44:45]
	v_exp_f32_e32 v45, v48
	v_pk_add_f32 v[46:47], v[36:37], v[36:37] op_sel_hi:[0,1]
	v_exp_f32_e32 v63, v64
	v_exp_f32_e32 v46, v49
	v_exp_f32_e32 v64, v65
	v_cvt_pk_bf16_f32 v44, v145, v52
	v_add_f32_e32 v65, v63, v45
	v_cvt_pk_bf16_f32 v42, v45, v46
	v_pk_add_f32 v[36:37], v[64:65], v[46:47]
	v_exp_f32_e32 v47, v50
	v_pk_add_f32 v[48:49], v[36:37], v[36:37] op_sel_hi:[0,1]
	v_exp_f32_e32 v65, v66
	v_exp_f32_e32 v48, v51
	v_exp_f32_e32 v66, v67
	v_cvt_pk_bf16_f32 v45, v146, v54
	v_add_f32_e32 v67, v65, v47
	v_cvt_pk_bf16_f32 v43, v47, v48
	v_pk_add_f32 v[36:37], v[66:67], v[48:49]
	v_cvt_pk_bf16_f32 v46, v71, v56
	v_add_f32_e32 v67, v36, v37
	v_cvt_pk_bf16_f32 v37, v53, v70
	v_cvt_pk_bf16_f32 v36, v137, v68
	v_cvt_pk_bf16_f32 v47, v57, v58
	v_cvt_pk_bf16_f32 v56, v59, v60
	v_cvt_pk_bf16_f32 v57, v61, v62
	v_cvt_pk_bf16_f32 v58, v63, v64
	v_cvt_pk_bf16_f32 v59, v65, v66
	s_waitcnt lgkmcnt(0)
	v_mfma_f32_32x32x16_bf16 v[2:17], v[124:127], v[36:39], v[2:17]
	v_mfma_f32_32x32x16_bf16 v[18:33], v[120:123], v[36:39], v[18:33]
	v_mfma_f32_32x32x16_bf16 v[2:17], v[174:177], v[40:43], v[2:17]
	v_mfma_f32_32x32x16_bf16 v[18:33], v[178:181], v[40:43], v[18:33]
	v_mfma_f32_32x32x16_bf16 v[2:17], v[182:185], v[44:47], v[2:17]
	v_mfma_f32_32x32x16_bf16 v[18:33], v[186:189], v[44:47], v[18:33]
	v_mfma_f32_32x32x16_bf16 v[2:17], v[190:193], v[56:59], v[2:17]
	v_mfma_f32_32x32x16_bf16 v[18:33], v[194:197], v[56:59], v[18:33]
	v_add_f32_e32 v34, v34, v67
	s_mov_b64 s[10:11], 0

	.amdhsa_kernel _Z10fwd_kernelILi9ELi10EEv4Args
		.amdhsa_group_segment_fixed_size 0
		.amdhsa_private_segment_fixed_size 0
		.amdhsa_kernarg_size 488
		.amdhsa_user_sgpr_count 2
		.amdhsa_user_sgpr_dispatch_ptr 0
		.amdhsa_user_sgpr_queue_ptr 0
		.amdhsa_user_sgpr_kernarg_segment_ptr 1
		.amdhsa_user_sgpr_dispatch_id 0
		.amdhsa_user_sgpr_kernarg_preload_length 0
		.amdhsa_user_sgpr_kernarg_preload_offset 0
		.amdhsa_user_sgpr_private_segment_size 0
		.amdhsa_uses_dynamic_stack 0
		.amdhsa_enable_private_segment 0
		.amdhsa_system_sgpr_workgroup_id_x 1
		.amdhsa_system_sgpr_workgroup_id_y 0
		.amdhsa_system_sgpr_workgroup_id_z 0
		.amdhsa_system_sgpr_workgroup_info 0
		.amdhsa_system_vgpr_workitem_id 0
		.amdhsa_next_free_vgpr 200
		.amdhsa_next_free_sgpr 76
		.amdhsa_accum_offset 200
		.amdhsa_reserve_vcc 1
		.amdhsa_float_round_mode_32 0
		.amdhsa_float_round_mode_16_64 0
		.amdhsa_float_denorm_mode_32 3
		.amdhsa_float_denorm_mode_16_64 3
		.amdhsa_dx10_clamp 1
		.amdhsa_ieee_mode 1
		.amdhsa_fp16_overflow 0
		.amdhsa_tg_split 0
		.amdhsa_exception_fp_ieee_invalid_op 0
		.amdhsa_exception_fp_denorm_src 0
		.amdhsa_exception_fp_ieee_div_zero 0
		.amdhsa_exception_fp_ieee_overflow 0
		.amdhsa_exception_fp_ieee_underflow 0
		.amdhsa_exception_fp_ieee_inexact 0
		.amdhsa_exception_int_div_zero 0
	.end_amdhsa_kernel

_Z10fwd_kernelILi11ELi12EEv4Args:
	s_load_dword s3, s[0:1], 0xe8
	s_load_dwordx4 s[4:7], s[0:1], 0xd0
	s_load_dwordx2 s[8:9], s[0:1], 0xa8
	s_load_dwordx2 s[10:11], s[0:1], 0xb0
	s_waitcnt lgkmcnt(0)
	s_cmp_lg_u32 s3, 0x100
	s_cbranch_scc1 .Lrows11_orig
	s_add_u32 s8, s8, 0x1000
	s_addc_u32 s9, s9, 0
	s_add_u32 s10, s10, 0x1000
	s_addc_u32 s11, s11, 0
	v_readfirstlane_b32 s16, v0
	s_lshr_b32 s16, s16, 6
	s_lshl_b32 s18, s2, 3
	s_add_u32 s16, s16, s18
	s_mov_b32 s17, 0x3a800000
	v_mov_b32_e32 v3, 0x358637bd
	v_and_b32_e32 v10, 63, v0
	v_lshlrev_b32_e32 v1, 4, v10
	v_lshlrev_b32_e32 v2, 3, v10
	v_xor_b32_e32 v4, 1, v10
	v_xor_b32_e32 v5, 2, v10
	v_xor_b32_e32 v6, 4, v10
	v_xor_b32_e32 v7, 8, v10
	v_xor_b32_e32 v8, 16, v10
	v_xor_b32_e32 v9, 32, v10
	v_lshlrev_b32_e32 v4, 2, v4
	v_lshlrev_b32_e32 v5, 2, v5
	v_lshlrev_b32_e32 v6, 2, v6
	v_lshlrev_b32_e32 v7, 2, v7
	v_lshlrev_b32_e32 v8, 2, v8
	v_lshlrev_b32_e32 v9, 2, v9
	global_load_dwordx4 v[20:23], v1, s[8:9] offset:0
	global_load_dwordx4 v[24:27], v1, s[8:9] offset:1024
	global_load_dwordx4 v[28:31], v1, s[8:9] offset:2048
	global_load_dwordx4 v[32:35], v1, s[8:9] offset:3072
	global_load_dwordx4 v[36:39], v1, s[10:11] offset:0
	global_load_dwordx4 v[40:43], v1, s[10:11] offset:1024
	global_load_dwordx4 v[44:47], v1, s[10:11] offset:2048
	global_load_dwordx4 v[48:51], v1, s[10:11] offset:3072
	s_lshr_b32 s54, s16, 2
	s_and_b32 s55, s16, 3
	s_lshl_b32 s55, s55, 10
	s_lshl_b32 s18, s54, 12
	s_add_u32 s18, s18, s55
	s_add_u32 s56, s6, s18
	s_addc_u32 s57, s7, 0
	s_add_u32 s56, s56, 0x7400000
	s_addc_u32 s57, s57, 0
	global_load_dwordx4 v[208:211], v1, s[56:57]
	s_add_u32 s56, s56, 0x200000
	s_addc_u32 s57, s57, 0
	global_load_dwordx4 v[212:215], v1, s[56:57]
	s_add_u32 s56, s4, s18
	s_addc_u32 s57, s5, 0
	s_add_u32 s56, s56, 0x4000000
	s_addc_u32 s57, s57, 0
	global_load_dwordx4 v[240:243], v1, s[56:57]
	s_add_u32 s56, s8, s55
	s_addc_u32 s57, s9, 0
	global_load_dwordx4 v[244:247], v1, s[56:57]
	s_add_u32 s56, s10, s55
	s_addc_u32 s57, s11, 0
	global_load_dwordx4 v[248:251], v1, s[56:57]
	s_add_u32 s53, s16, 0x0
	s_lshl_b32 s18, s53, 12
	s_lshl_b32 s19, s53, 11
	s_add_u32 s20, s4, s18
	s_addc_u32 s21, s5, 0
	s_add_u32 s22, s6, s19
	s_addc_u32 s23, s7, 0
	s_add_u32 s22, s22, 0x5200000
	s_addc_u32 s23, s23, 0
	s_add_u32 s24, s4, s18
	s_addc_u32 s25, s5, 0
	s_add_u32 s26, s6, s19
	s_addc_u32 s27, s7, 0
	s_add_u32 s26, s26, 0x3100000
	s_addc_u32 s27, s27, 0
	global_load_dwordx2 v[66:67], v2, s[22:23] offset:0
	global_load_dwordx2 v[70:71], v2, s[22:23] offset:512
	global_load_dwordx2 v[74:75], v2, s[22:23] offset:1024
	global_load_dwordx2 v[78:79], v2, s[22:23] offset:1536
	global_load_dwordx4 v[80:83], v1, s[20:21] offset:0
	global_load_dwordx4 v[84:87], v1, s[20:21] offset:1024
	global_load_dwordx4 v[88:91], v1, s[20:21] offset:2048
	global_load_dwordx4 v[92:95], v1, s[20:21] offset:3072
	s_add_u32 s53, s16, 0x800
	s_lshl_b32 s18, s53, 12
	s_lshl_b32 s19, s53, 11
	s_add_u32 s28, s4, s18
	s_addc_u32 s29, s5, 0
	s_add_u32 s30, s6, s19
	s_addc_u32 s31, s7, 0
	s_add_u32 s30, s30, 0x5200000
	s_addc_u32 s31, s31, 0
	s_add_u32 s32, s4, s18
	s_addc_u32 s33, s5, 0
	s_add_u32 s34, s6, s19
	s_addc_u32 s35, s7, 0
	s_add_u32 s34, s34, 0x3100000
	s_addc_u32 s35, s35, 0
	global_load_dwordx2 v[98:99], v2, s[30:31] offset:0
	global_load_dwordx2 v[102:103], v2, s[30:31] offset:512
	global_load_dwordx2 v[106:107], v2, s[30:31] offset:1024
	global_load_dwordx2 v[110:111], v2, s[30:31] offset:1536
	global_load_dwordx4 v[112:115], v1, s[28:29] offset:0
	global_load_dwordx4 v[116:119], v1, s[28:29] offset:1024
	global_load_dwordx4 v[120:123], v1, s[28:29] offset:2048
	global_load_dwordx4 v[124:127], v1, s[28:29] offset:3072
	s_add_u32 s53, s16, 0x1000
	s_lshl_b32 s18, s53, 12
	s_lshl_b32 s19, s53, 11
	s_add_u32 s36, s4, s18
	s_addc_u32 s37, s5, 0
	s_add_u32 s38, s6, s19
	s_addc_u32 s39, s7, 0
	s_add_u32 s38, s38, 0x5200000
	s_addc_u32 s39, s39, 0
	s_add_u32 s40, s4, s18
	s_addc_u32 s41, s5, 0
	s_add_u32 s42, s6, s19
	s_addc_u32 s43, s7, 0
	s_add_u32 s42, s42, 0x3100000
	s_addc_u32 s43, s43, 0
	global_load_dwordx2 v[130:131], v2, s[38:39] offset:0
	global_load_dwordx2 v[134:135], v2, s[38:39] offset:512
	global_load_dwordx2 v[138:139], v2, s[38:39] offset:1024
	global_load_dwordx2 v[142:143], v2, s[38:39] offset:1536
	global_load_dwordx4 v[144:147], v1, s[36:37] offset:0
	global_load_dwordx4 v[148:151], v1, s[36:37] offset:1024
	global_load_dwordx4 v[152:155], v1, s[36:37] offset:2048
	global_load_dwordx4 v[156:159], v1, s[36:37] offset:3072
	s_add_u32 s53, s16, 0x1800
	s_lshl_b32 s18, s53, 12
	s_lshl_b32 s19, s53, 11
	s_add_u32 s44, s4, s18
	s_addc_u32 s45, s5, 0
	s_add_u32 s46, s6, s19
	s_addc_u32 s47, s7, 0
	s_add_u32 s46, s46, 0x5200000
	s_addc_u32 s47, s47, 0
	s_add_u32 s48, s4, s18
	s_addc_u32 s49, s5, 0
	s_add_u32 s50, s6, s19
	s_addc_u32 s51, s7, 0
	s_add_u32 s50, s50, 0x3100000
	s_addc_u32 s51, s51, 0
	global_load_dwordx2 v[162:163], v2, s[46:47] offset:0
	global_load_dwordx2 v[166:167], v2, s[46:47] offset:512
	global_load_dwordx2 v[170:171], v2, s[46:47] offset:1024
	global_load_dwordx2 v[174:175], v2, s[46:47] offset:1536
	global_load_dwordx4 v[176:179], v1, s[44:45] offset:0
	global_load_dwordx4 v[180:183], v1, s[44:45] offset:1024
	global_load_dwordx4 v[184:187], v1, s[44:45] offset:2048
	global_load_dwordx4 v[188:191], v1, s[44:45] offset:3072
	s_waitcnt vmcnt(16)
	v_lshlrev_b32_e32 v64, 16, v66
	v_and_b32_e32 v65, 0xffff0000, v66
	v_lshlrev_b32_e32 v66, 16, v67
	v_and_b32_e32 v67, 0xffff0000, v67
	v_lshlrev_b32_e32 v68, 16, v70
	v_and_b32_e32 v69, 0xffff0000, v70
	v_lshlrev_b32_e32 v70, 16, v71
	v_and_b32_e32 v71, 0xffff0000, v71
	v_lshlrev_b32_e32 v72, 16, v74
	v_and_b32_e32 v73, 0xffff0000, v74
	v_lshlrev_b32_e32 v74, 16, v75
	v_and_b32_e32 v75, 0xffff0000, v75
	v_lshlrev_b32_e32 v76, 16, v78
	v_and_b32_e32 v77, 0xffff0000, v78
	v_lshlrev_b32_e32 v78, 16, v79
	v_and_b32_e32 v79, 0xffff0000, v79
	v_lshlrev_b32_e32 v96, 16, v98
	v_and_b32_e32 v97, 0xffff0000, v98
	v_lshlrev_b32_e32 v98, 16, v99
	v_and_b32_e32 v99, 0xffff0000, v99
	v_lshlrev_b32_e32 v100, 16, v102
	v_and_b32_e32 v101, 0xffff0000, v102
	v_lshlrev_b32_e32 v102, 16, v103
	v_and_b32_e32 v103, 0xffff0000, v103
	v_lshlrev_b32_e32 v104, 16, v106
	v_and_b32_e32 v105, 0xffff0000, v106
	v_lshlrev_b32_e32 v106, 16, v107
	v_and_b32_e32 v107, 0xffff0000, v107
	v_lshlrev_b32_e32 v108, 16, v110
	v_and_b32_e32 v109, 0xffff0000, v110
	v_lshlrev_b32_e32 v110, 16, v111
	v_and_b32_e32 v111, 0xffff0000, v111
	v_mul_f32_e32 v10, v64, v64
	v_fmac_f32_e32 v10, v65, v65
	v_fmac_f32_e32 v10, v66, v66
	v_fmac_f32_e32 v10, v67, v67
	v_fmac_f32_e32 v10, v68, v68
	v_fmac_f32_e32 v10, v69, v69
	v_fmac_f32_e32 v10, v70, v70
	v_fmac_f32_e32 v10, v71, v71
	v_fmac_f32_e32 v10, v72, v72
	v_fmac_f32_e32 v10, v73, v73
	v_fmac_f32_e32 v10, v74, v74
	v_fmac_f32_e32 v10, v75, v75
	v_fmac_f32_e32 v10, v76, v76
	v_fmac_f32_e32 v10, v77, v77
	v_fmac_f32_e32 v10, v78, v78
	v_fmac_f32_e32 v10, v79, v79
	v_mul_f32_e32 v11, v96, v96
	v_fmac_f32_e32 v11, v97, v97
	v_fmac_f32_e32 v11, v98, v98
	v_fmac_f32_e32 v11, v99, v99
	v_fmac_f32_e32 v11, v100, v100
	v_fmac_f32_e32 v11, v101, v101
	v_fmac_f32_e32 v11, v102, v102
	v_fmac_f32_e32 v11, v103, v103
	v_fmac_f32_e32 v11, v104, v104
	v_fmac_f32_e32 v11, v105, v105
	v_fmac_f32_e32 v11, v106, v106
	v_fmac_f32_e32 v11, v107, v107
	v_fmac_f32_e32 v11, v108, v108
	v_fmac_f32_e32 v11, v109, v109
	v_fmac_f32_e32 v11, v110, v110
	v_fmac_f32_e32 v11, v111, v111
	ds_bpermute_b32 v12, v4, v10
	ds_bpermute_b32 v13, v4, v11
	s_waitcnt lgkmcnt(0)
	v_add_f32_e32 v10, v10, v12
	v_add_f32_e32 v11, v11, v13
	ds_bpermute_b32 v12, v5, v10
	ds_bpermute_b32 v13, v5, v11
	s_waitcnt lgkmcnt(0)
	v_add_f32_e32 v10, v10, v12
	v_add_f32_e32 v11, v11, v13
	ds_bpermute_b32 v12, v6, v10
	ds_bpermute_b32 v13, v6, v11
	s_waitcnt lgkmcnt(0)
	v_add_f32_e32 v10, v10, v12
	v_add_f32_e32 v11, v11, v13
	ds_bpermute_b32 v12, v7, v10
	ds_bpermute_b32 v13, v7, v11
	s_waitcnt lgkmcnt(0)
	v_add_f32_e32 v10, v10, v12
	v_add_f32_e32 v11, v11, v13
	ds_bpermute_b32 v12, v8, v10
	ds_bpermute_b32 v13, v8, v11
	s_waitcnt lgkmcnt(0)
	v_add_f32_e32 v10, v10, v12
	v_add_f32_e32 v11, v11, v13
	ds_bpermute_b32 v12, v9, v10
	ds_bpermute_b32 v13, v9, v11
	s_waitcnt lgkmcnt(0)
	v_add_f32_e32 v10, v10, v12
	v_add_f32_e32 v11, v11, v13
	v_fma_f32 v14, v10, s17, v3
	v_fma_f32 v15, v11, s17, v3
	v_rsq_f32_e32 v14, v14
	v_rsq_f32_e32 v15, v15
	s_nop 0
	v_mul_f32_e32 v64, v64, v14
	v_mul_f32_e32 v65, v65, v14
	v_mul_f32_e32 v66, v66, v14
	v_mul_f32_e32 v67, v67, v14
	v_mul_f32_e32 v68, v68, v14
	v_mul_f32_e32 v69, v69, v14
	v_mul_f32_e32 v70, v70, v14
	v_mul_f32_e32 v71, v71, v14
	v_mul_f32_e32 v72, v72, v14
	v_mul_f32_e32 v73, v73, v14
	v_mul_f32_e32 v74, v74, v14
	v_mul_f32_e32 v75, v75, v14
	v_mul_f32_e32 v76, v76, v14
	v_mul_f32_e32 v77, v77, v14
	v_mul_f32_e32 v78, v78, v14
	v_mul_f32_e32 v79, v79, v14
	v_fmac_f32_e32 v80, v64, v20
	v_fmac_f32_e32 v81, v65, v21
	v_fmac_f32_e32 v82, v66, v22
	v_fmac_f32_e32 v83, v67, v23
	v_fmac_f32_e32 v84, v68, v24
	v_fmac_f32_e32 v85, v69, v25
	v_fmac_f32_e32 v86, v70, v26
	v_fmac_f32_e32 v87, v71, v27
	v_fmac_f32_e32 v88, v72, v28
	v_fmac_f32_e32 v89, v73, v29
	v_fmac_f32_e32 v90, v74, v30
	v_fmac_f32_e32 v91, v75, v31
	v_fmac_f32_e32 v92, v76, v32
	v_fmac_f32_e32 v93, v77, v33
	v_fmac_f32_e32 v94, v78, v34
	v_fmac_f32_e32 v95, v79, v35
	global_store_dwordx4 v1, v[80:83], s[24:25] offset:0
	global_store_dwordx4 v1, v[84:87], s[24:25] offset:1024
	global_store_dwordx4 v1, v[88:91], s[24:25] offset:2048
	global_store_dwordx4 v1, v[92:95], s[24:25] offset:3072
	v_mul_f32_e32 v96, v96, v15
	v_mul_f32_e32 v97, v97, v15
	v_mul_f32_e32 v98, v98, v15
	v_mul_f32_e32 v99, v99, v15
	v_mul_f32_e32 v100, v100, v15
	v_mul_f32_e32 v101, v101, v15
	v_mul_f32_e32 v102, v102, v15
	v_mul_f32_e32 v103, v103, v15
	v_mul_f32_e32 v104, v104, v15
	v_mul_f32_e32 v105, v105, v15
	v_mul_f32_e32 v106, v106, v15
	v_mul_f32_e32 v107, v107, v15
	v_mul_f32_e32 v108, v108, v15
	v_mul_f32_e32 v109, v109, v15
	v_mul_f32_e32 v110, v110, v15
	v_mul_f32_e32 v111, v111, v15
	v_fmac_f32_e32 v112, v96, v20
	v_fmac_f32_e32 v113, v97, v21
	v_fmac_f32_e32 v114, v98, v22
	v_fmac_f32_e32 v115, v99, v23
	v_fmac_f32_e32 v116, v100, v24
	v_fmac_f32_e32 v117, v101, v25
	v_fmac_f32_e32 v118, v102, v26
	v_fmac_f32_e32 v119, v103, v27
	v_fmac_f32_e32 v120, v104, v28
	v_fmac_f32_e32 v121, v105, v29
	v_fmac_f32_e32 v122, v106, v30
	v_fmac_f32_e32 v123, v107, v31
	v_fmac_f32_e32 v124, v108, v32
	v_fmac_f32_e32 v125, v109, v33
	v_fmac_f32_e32 v126, v110, v34
	v_fmac_f32_e32 v127, v111, v35
	global_store_dwordx4 v1, v[112:115], s[32:33] offset:0
	global_store_dwordx4 v1, v[116:119], s[32:33] offset:1024
	global_store_dwordx4 v1, v[120:123], s[32:33] offset:2048
	global_store_dwordx4 v1, v[124:127], s[32:33] offset:3072
	v_mul_f32_e32 v10, v80, v80
	v_fmac_f32_e32 v10, v81, v81
	v_fmac_f32_e32 v10, v82, v82
	v_fmac_f32_e32 v10, v83, v83
	v_fmac_f32_e32 v10, v84, v84
	v_fmac_f32_e32 v10, v85, v85
	v_fmac_f32_e32 v10, v86, v86
	v_fmac_f32_e32 v10, v87, v87
	v_fmac_f32_e32 v10, v88, v88
	v_fmac_f32_e32 v10, v89, v89
	v_fmac_f32_e32 v10, v90, v90
	v_fmac_f32_e32 v10, v91, v91
	v_fmac_f32_e32 v10, v92, v92
	v_fmac_f32_e32 v10, v93, v93
	v_fmac_f32_e32 v10, v94, v94
	v_fmac_f32_e32 v10, v95, v95
	v_mul_f32_e32 v11, v112, v112
	v_fmac_f32_e32 v11, v113, v113
	v_fmac_f32_e32 v11, v114, v114
	v_fmac_f32_e32 v11, v115, v115
	v_fmac_f32_e32 v11, v116, v116
	v_fmac_f32_e32 v11, v117, v117
	v_fmac_f32_e32 v11, v118, v118
	v_fmac_f32_e32 v11, v119, v119
	v_fmac_f32_e32 v11, v120, v120
	v_fmac_f32_e32 v11, v121, v121
	v_fmac_f32_e32 v11, v122, v122
	v_fmac_f32_e32 v11, v123, v123
	v_fmac_f32_e32 v11, v124, v124
	v_fmac_f32_e32 v11, v125, v125
	v_fmac_f32_e32 v11, v126, v126
	v_fmac_f32_e32 v11, v127, v127
	ds_bpermute_b32 v12, v4, v10
	ds_bpermute_b32 v13, v4, v11
	s_waitcnt lgkmcnt(0)
	v_add_f32_e32 v10, v10, v12
	v_add_f32_e32 v11, v11, v13
	ds_bpermute_b32 v12, v5, v10
	ds_bpermute_b32 v13, v5, v11
	s_waitcnt lgkmcnt(0)
	v_add_f32_e32 v10, v10, v12
	v_add_f32_e32 v11, v11, v13
	ds_bpermute_b32 v12, v6, v10
	ds_bpermute_b32 v13, v6, v11
	s_waitcnt lgkmcnt(0)
	v_add_f32_e32 v10, v10, v12
	v_add_f32_e32 v11, v11, v13
	ds_bpermute_b32 v12, v7, v10
	ds_bpermute_b32 v13, v7, v11
	s_waitcnt lgkmcnt(0)
	v_add_f32_e32 v10, v10, v12
	v_add_f32_e32 v11, v11, v13
	ds_bpermute_b32 v12, v8, v10
	ds_bpermute_b32 v13, v8, v11
	s_waitcnt lgkmcnt(0)
	v_add_f32_e32 v10, v10, v12
	v_add_f32_e32 v11, v11, v13
	ds_bpermute_b32 v12, v9, v10
	ds_bpermute_b32 v13, v9, v11
	s_waitcnt lgkmcnt(0)
	v_add_f32_e32 v10, v10, v12
	v_add_f32_e32 v11, v11, v13
	v_fma_f32 v14, v10, s17, v3
	v_fma_f32 v15, v11, s17, v3
	v_rsq_f32_e32 v14, v14
	v_rsq_f32_e32 v15, v15
	s_nop 0
	v_mul_f32_e32 v64, v80, v14
	v_mul_f32_e32 v65, v81, v14
	v_mul_f32_e32 v66, v82, v14
	v_mul_f32_e32 v67, v83, v14
	v_mul_f32_e32 v68, v84, v14
	v_mul_f32_e32 v69, v85, v14
	v_mul_f32_e32 v70, v86, v14
	v_mul_f32_e32 v71, v87, v14
	v_mul_f32_e32 v72, v88, v14
	v_mul_f32_e32 v73, v89, v14
	v_mul_f32_e32 v74, v90, v14
	v_mul_f32_e32 v75, v91, v14
	v_mul_f32_e32 v76, v92, v14
	v_mul_f32_e32 v77, v93, v14
	v_mul_f32_e32 v78, v94, v14
	v_mul_f32_e32 v79, v95, v14
	v_mul_f32_e32 v64, v64, v36
	v_mul_f32_e32 v65, v65, v37
	v_mul_f32_e32 v66, v66, v38
	v_mul_f32_e32 v67, v67, v39
	v_mul_f32_e32 v68, v68, v40
	v_mul_f32_e32 v69, v69, v41
	v_mul_f32_e32 v70, v70, v42
	v_mul_f32_e32 v71, v71, v43
	v_mul_f32_e32 v72, v72, v44
	v_mul_f32_e32 v73, v73, v45
	v_mul_f32_e32 v74, v74, v46
	v_mul_f32_e32 v75, v75, v47
	v_mul_f32_e32 v76, v76, v48
	v_mul_f32_e32 v77, v77, v49
	v_mul_f32_e32 v78, v78, v50
	v_mul_f32_e32 v79, v79, v51
	v_cvt_pk_bf16_f32 v64, v64, v65
	v_cvt_pk_bf16_f32 v65, v66, v67
	v_cvt_pk_bf16_f32 v68, v68, v69
	v_cvt_pk_bf16_f32 v69, v70, v71
	v_cvt_pk_bf16_f32 v72, v72, v73
	v_cvt_pk_bf16_f32 v73, v74, v75
	v_cvt_pk_bf16_f32 v76, v76, v77
	v_cvt_pk_bf16_f32 v77, v78, v79
	global_store_dwordx2 v2, v[64:65], s[26:27] offset:0
	global_store_dwordx2 v2, v[68:69], s[26:27] offset:512
	global_store_dwordx2 v2, v[72:73], s[26:27] offset:1024
	global_store_dwordx2 v2, v[76:77], s[26:27] offset:1536
	v_mul_f32_e32 v96, v112, v15
	v_mul_f32_e32 v97, v113, v15
	v_mul_f32_e32 v98, v114, v15
	v_mul_f32_e32 v99, v115, v15
	v_mul_f32_e32 v100, v116, v15
	v_mul_f32_e32 v101, v117, v15
	v_mul_f32_e32 v102, v118, v15
	v_mul_f32_e32 v103, v119, v15
	v_mul_f32_e32 v104, v120, v15
	v_mul_f32_e32 v105, v121, v15
	v_mul_f32_e32 v106, v122, v15
	v_mul_f32_e32 v107, v123, v15
	v_mul_f32_e32 v108, v124, v15
	v_mul_f32_e32 v109, v125, v15
	v_mul_f32_e32 v110, v126, v15
	v_mul_f32_e32 v111, v127, v15
	v_mul_f32_e32 v96, v96, v36
	v_mul_f32_e32 v97, v97, v37
	v_mul_f32_e32 v98, v98, v38
	v_mul_f32_e32 v99, v99, v39
	v_mul_f32_e32 v100, v100, v40
	v_mul_f32_e32 v101, v101, v41
	v_mul_f32_e32 v102, v102, v42
	v_mul_f32_e32 v103, v103, v43
	v_mul_f32_e32 v104, v104, v44
	v_mul_f32_e32 v105, v105, v45
	v_mul_f32_e32 v106, v106, v46
	v_mul_f32_e32 v107, v107, v47
	v_mul_f32_e32 v108, v108, v48
	v_mul_f32_e32 v109, v109, v49
	v_mul_f32_e32 v110, v110, v50
	v_mul_f32_e32 v111, v111, v51
	v_cvt_pk_bf16_f32 v96, v96, v97
	v_cvt_pk_bf16_f32 v97, v98, v99
	v_cvt_pk_bf16_f32 v100, v100, v101
	v_cvt_pk_bf16_f32 v101, v102, v103
	v_cvt_pk_bf16_f32 v104, v104, v105
	v_cvt_pk_bf16_f32 v105, v106, v107
	v_cvt_pk_bf16_f32 v108, v108, v109
	v_cvt_pk_bf16_f32 v109, v110, v111
	global_store_dwordx2 v2, v[96:97], s[34:35] offset:0
	global_store_dwordx2 v2, v[100:101], s[34:35] offset:512
	global_store_dwordx2 v2, v[104:105], s[34:35] offset:1024
	global_store_dwordx2 v2, v[108:109], s[34:35] offset:1536
	s_add_u32 s53, s16, 0x2000
	s_lshl_b32 s18, s53, 12
	s_lshl_b32 s19, s53, 11
	s_add_u32 s20, s4, s18
	s_addc_u32 s21, s5, 0
	s_add_u32 s22, s6, s19
	s_addc_u32 s23, s7, 0
	s_add_u32 s22, s22, 0x5200000
	s_addc_u32 s23, s23, 0
	s_add_u32 s24, s4, s18
	s_addc_u32 s25, s5, 0
	s_add_u32 s26, s6, s19
	s_addc_u32 s27, s7, 0
	s_add_u32 s26, s26, 0x3100000
	s_addc_u32 s27, s27, 0
	global_load_dwordx2 v[66:67], v2, s[22:23] offset:0
	global_load_dwordx2 v[70:71], v2, s[22:23] offset:512
	global_load_dwordx2 v[74:75], v2, s[22:23] offset:1024
	global_load_dwordx2 v[78:79], v2, s[22:23] offset:1536
	global_load_dwordx4 v[80:83], v1, s[20:21] offset:0
	global_load_dwordx4 v[84:87], v1, s[20:21] offset:1024
	global_load_dwordx4 v[88:91], v1, s[20:21] offset:2048
	global_load_dwordx4 v[92:95], v1, s[20:21] offset:3072
	s_add_u32 s53, s16, 0x2800
	s_lshl_b32 s18, s53, 12
	s_lshl_b32 s19, s53, 11
	s_add_u32 s28, s4, s18
	s_addc_u32 s29, s5, 0
	s_add_u32 s30, s6, s19
	s_addc_u32 s31, s7, 0
	s_add_u32 s30, s30, 0x5200000
	s_addc_u32 s31, s31, 0
	s_add_u32 s32, s4, s18
	s_addc_u32 s33, s5, 0
	s_add_u32 s34, s6, s19
	s_addc_u32 s35, s7, 0
	s_add_u32 s34, s34, 0x3100000
	s_addc_u32 s35, s35, 0
	global_load_dwordx2 v[98:99], v2, s[30:31] offset:0
	global_load_dwordx2 v[102:103], v2, s[30:31] offset:512
	global_load_dwordx2 v[106:107], v2, s[30:31] offset:1024
	global_load_dwordx2 v[110:111], v2, s[30:31] offset:1536
	global_load_dwordx4 v[112:115], v1, s[28:29] offset:0
	global_load_dwordx4 v[116:119], v1, s[28:29] offset:1024
	global_load_dwordx4 v[120:123], v1, s[28:29] offset:2048
	global_load_dwordx4 v[124:127], v1, s[28:29] offset:3072
	s_waitcnt vmcnt(32)
	v_lshlrev_b32_e32 v128, 16, v130
	v_and_b32_e32 v129, 0xffff0000, v130
	v_lshlrev_b32_e32 v130, 16, v131
	v_and_b32_e32 v131, 0xffff0000, v131
	v_lshlrev_b32_e32 v132, 16, v134
	v_and_b32_e32 v133, 0xffff0000, v134
	v_lshlrev_b32_e32 v134, 16, v135
	v_and_b32_e32 v135, 0xffff0000, v135
	v_lshlrev_b32_e32 v136, 16, v138
	v_and_b32_e32 v137, 0xffff0000, v138
	v_lshlrev_b32_e32 v138, 16, v139
	v_and_b32_e32 v139, 0xffff0000, v139
	v_lshlrev_b32_e32 v140, 16, v142
	v_and_b32_e32 v141, 0xffff0000, v142
	v_lshlrev_b32_e32 v142, 16, v143
	v_and_b32_e32 v143, 0xffff0000, v143
	v_lshlrev_b32_e32 v160, 16, v162
	v_and_b32_e32 v161, 0xffff0000, v162
	v_lshlrev_b32_e32 v162, 16, v163
	v_and_b32_e32 v163, 0xffff0000, v163
	v_lshlrev_b32_e32 v164, 16, v166
	v_and_b32_e32 v165, 0xffff0000, v166
	v_lshlrev_b32_e32 v166, 16, v167
	v_and_b32_e32 v167, 0xffff0000, v167
	v_lshlrev_b32_e32 v168, 16, v170
	v_and_b32_e32 v169, 0xffff0000, v170
	v_lshlrev_b32_e32 v170, 16, v171
	v_and_b32_e32 v171, 0xffff0000, v171
	v_lshlrev_b32_e32 v172, 16, v174
	v_and_b32_e32 v173, 0xffff0000, v174
	v_lshlrev_b32_e32 v174, 16, v175
	v_and_b32_e32 v175, 0xffff0000, v175
	v_mul_f32_e32 v10, v128, v128
	v_fmac_f32_e32 v10, v129, v129
	v_fmac_f32_e32 v10, v130, v130
	v_fmac_f32_e32 v10, v131, v131
	v_fmac_f32_e32 v10, v132, v132
	v_fmac_f32_e32 v10, v133, v133
	v_fmac_f32_e32 v10, v134, v134
	v_fmac_f32_e32 v10, v135, v135
	v_fmac_f32_e32 v10, v136, v136
	v_fmac_f32_e32 v10, v137, v137
	v_fmac_f32_e32 v10, v138, v138
	v_fmac_f32_e32 v10, v139, v139
	v_fmac_f32_e32 v10, v140, v140
	v_fmac_f32_e32 v10, v141, v141
	v_fmac_f32_e32 v10, v142, v142
	v_fmac_f32_e32 v10, v143, v143
	v_mul_f32_e32 v11, v160, v160
	v_fmac_f32_e32 v11, v161, v161
	v_fmac_f32_e32 v11, v162, v162
	v_fmac_f32_e32 v11, v163, v163
	v_fmac_f32_e32 v11, v164, v164
	v_fmac_f32_e32 v11, v165, v165
	v_fmac_f32_e32 v11, v166, v166
	v_fmac_f32_e32 v11, v167, v167
	v_fmac_f32_e32 v11, v168, v168
	v_fmac_f32_e32 v11, v169, v169
	v_fmac_f32_e32 v11, v170, v170
	v_fmac_f32_e32 v11, v171, v171
	v_fmac_f32_e32 v11, v172, v172
	v_fmac_f32_e32 v11, v173, v173
	v_fmac_f32_e32 v11, v174, v174
	v_fmac_f32_e32 v11, v175, v175
	ds_bpermute_b32 v12, v4, v10
	ds_bpermute_b32 v13, v4, v11
	s_waitcnt lgkmcnt(0)
	v_add_f32_e32 v10, v10, v12
	v_add_f32_e32 v11, v11, v13
	ds_bpermute_b32 v12, v5, v10
	ds_bpermute_b32 v13, v5, v11
	s_waitcnt lgkmcnt(0)
	v_add_f32_e32 v10, v10, v12
	v_add_f32_e32 v11, v11, v13
	ds_bpermute_b32 v12, v6, v10
	ds_bpermute_b32 v13, v6, v11
	s_waitcnt lgkmcnt(0)
	v_add_f32_e32 v10, v10, v12
	v_add_f32_e32 v11, v11, v13
	ds_bpermute_b32 v12, v7, v10
	ds_bpermute_b32 v13, v7, v11
	s_waitcnt lgkmcnt(0)
	v_add_f32_e32 v10, v10, v12
	v_add_f32_e32 v11, v11, v13
	ds_bpermute_b32 v12, v8, v10
	ds_bpermute_b32 v13, v8, v11
	s_waitcnt lgkmcnt(0)
	v_add_f32_e32 v10, v10, v12
	v_add_f32_e32 v11, v11, v13
	ds_bpermute_b32 v12, v9, v10
	ds_bpermute_b32 v13, v9, v11
	s_waitcnt lgkmcnt(0)
	v_add_f32_e32 v10, v10, v12
	v_add_f32_e32 v11, v11, v13
	v_fma_f32 v14, v10, s17, v3
	v_fma_f32 v15, v11, s17, v3
	v_rsq_f32_e32 v14, v14
	v_rsq_f32_e32 v15, v15
	s_nop 0
	v_mul_f32_e32 v128, v128, v14
	v_mul_f32_e32 v129, v129, v14
	v_mul_f32_e32 v130, v130, v14
	v_mul_f32_e32 v131, v131, v14
	v_mul_f32_e32 v132, v132, v14
	v_mul_f32_e32 v133, v133, v14
	v_mul_f32_e32 v134, v134, v14
	v_mul_f32_e32 v135, v135, v14
	v_mul_f32_e32 v136, v136, v14
	v_mul_f32_e32 v137, v137, v14
	v_mul_f32_e32 v138, v138, v14
	v_mul_f32_e32 v139, v139, v14
	v_mul_f32_e32 v140, v140, v14
	v_mul_f32_e32 v141, v141, v14
	v_mul_f32_e32 v142, v142, v14
	v_mul_f32_e32 v143, v143, v14
	v_fmac_f32_e32 v144, v128, v20
	v_fmac_f32_e32 v145, v129, v21
	v_fmac_f32_e32 v146, v130, v22
	v_fmac_f32_e32 v147, v131, v23
	v_fmac_f32_e32 v148, v132, v24
	v_fmac_f32_e32 v149, v133, v25
	v_fmac_f32_e32 v150, v134, v26
	v_fmac_f32_e32 v151, v135, v27
	v_fmac_f32_e32 v152, v136, v28
	v_fmac_f32_e32 v153, v137, v29
	v_fmac_f32_e32 v154, v138, v30
	v_fmac_f32_e32 v155, v139, v31
	v_fmac_f32_e32 v156, v140, v32
	v_fmac_f32_e32 v157, v141, v33
	v_fmac_f32_e32 v158, v142, v34
	v_fmac_f32_e32 v159, v143, v35
	global_store_dwordx4 v1, v[144:147], s[40:41] offset:0
	global_store_dwordx4 v1, v[148:151], s[40:41] offset:1024
	global_store_dwordx4 v1, v[152:155], s[40:41] offset:2048
	global_store_dwordx4 v1, v[156:159], s[40:41] offset:3072
	v_mul_f32_e32 v160, v160, v15
	v_mul_f32_e32 v161, v161, v15
	v_mul_f32_e32 v162, v162, v15
	v_mul_f32_e32 v163, v163, v15
	v_mul_f32_e32 v164, v164, v15
	v_mul_f32_e32 v165, v165, v15
	v_mul_f32_e32 v166, v166, v15
	v_mul_f32_e32 v167, v167, v15
	v_mul_f32_e32 v168, v168, v15
	v_mul_f32_e32 v169, v169, v15
	v_mul_f32_e32 v170, v170, v15
	v_mul_f32_e32 v171, v171, v15
	v_mul_f32_e32 v172, v172, v15
	v_mul_f32_e32 v173, v173, v15
	v_mul_f32_e32 v174, v174, v15
	v_mul_f32_e32 v175, v175, v15
	v_fmac_f32_e32 v176, v160, v20
	v_fmac_f32_e32 v177, v161, v21
	v_fmac_f32_e32 v178, v162, v22
	v_fmac_f32_e32 v179, v163, v23
	v_fmac_f32_e32 v180, v164, v24
	v_fmac_f32_e32 v181, v165, v25
	v_fmac_f32_e32 v182, v166, v26
	v_fmac_f32_e32 v183, v167, v27
	v_fmac_f32_e32 v184, v168, v28
	v_fmac_f32_e32 v185, v169, v29
	v_fmac_f32_e32 v186, v170, v30
	v_fmac_f32_e32 v187, v171, v31
	v_fmac_f32_e32 v188, v172, v32
	v_fmac_f32_e32 v189, v173, v33
	v_fmac_f32_e32 v190, v174, v34
	v_fmac_f32_e32 v191, v175, v35
	global_store_dwordx4 v1, v[176:179], s[48:49] offset:0
	global_store_dwordx4 v1, v[180:183], s[48:49] offset:1024
	global_store_dwordx4 v1, v[184:187], s[48:49] offset:2048
	global_store_dwordx4 v1, v[188:191], s[48:49] offset:3072
	v_mul_f32_e32 v10, v144, v144
	v_fmac_f32_e32 v10, v145, v145
	v_fmac_f32_e32 v10, v146, v146
	v_fmac_f32_e32 v10, v147, v147
	v_fmac_f32_e32 v10, v148, v148
	v_fmac_f32_e32 v10, v149, v149
	v_fmac_f32_e32 v10, v150, v150
	v_fmac_f32_e32 v10, v151, v151
	v_fmac_f32_e32 v10, v152, v152
	v_fmac_f32_e32 v10, v153, v153
	v_fmac_f32_e32 v10, v154, v154
	v_fmac_f32_e32 v10, v155, v155
	v_fmac_f32_e32 v10, v156, v156
	v_fmac_f32_e32 v10, v157, v157
	v_fmac_f32_e32 v10, v158, v158
	v_fmac_f32_e32 v10, v159, v159
	v_mul_f32_e32 v11, v176, v176
	v_fmac_f32_e32 v11, v177, v177
	v_fmac_f32_e32 v11, v178, v178
	v_fmac_f32_e32 v11, v179, v179
	v_fmac_f32_e32 v11, v180, v180
	v_fmac_f32_e32 v11, v181, v181
	v_fmac_f32_e32 v11, v182, v182
	v_fmac_f32_e32 v11, v183, v183
	v_fmac_f32_e32 v11, v184, v184
	v_fmac_f32_e32 v11, v185, v185
	v_fmac_f32_e32 v11, v186, v186
	v_fmac_f32_e32 v11, v187, v187
	v_fmac_f32_e32 v11, v188, v188
	v_fmac_f32_e32 v11, v189, v189
	v_fmac_f32_e32 v11, v190, v190
	v_fmac_f32_e32 v11, v191, v191
	ds_bpermute_b32 v12, v4, v10
	ds_bpermute_b32 v13, v4, v11
	s_waitcnt lgkmcnt(0)
	v_add_f32_e32 v10, v10, v12
	v_add_f32_e32 v11, v11, v13
	ds_bpermute_b32 v12, v5, v10
	ds_bpermute_b32 v13, v5, v11
	s_waitcnt lgkmcnt(0)
	v_add_f32_e32 v10, v10, v12
	v_add_f32_e32 v11, v11, v13
	ds_bpermute_b32 v12, v6, v10
	ds_bpermute_b32 v13, v6, v11
	s_waitcnt lgkmcnt(0)
	v_add_f32_e32 v10, v10, v12
	v_add_f32_e32 v11, v11, v13
	ds_bpermute_b32 v12, v7, v10
	ds_bpermute_b32 v13, v7, v11
	s_waitcnt lgkmcnt(0)
	v_add_f32_e32 v10, v10, v12
	v_add_f32_e32 v11, v11, v13
	ds_bpermute_b32 v12, v8, v10
	ds_bpermute_b32 v13, v8, v11
	s_waitcnt lgkmcnt(0)
	v_add_f32_e32 v10, v10, v12
	v_add_f32_e32 v11, v11, v13
	ds_bpermute_b32 v12, v9, v10
	ds_bpermute_b32 v13, v9, v11
	s_waitcnt lgkmcnt(0)
	v_add_f32_e32 v10, v10, v12
	v_add_f32_e32 v11, v11, v13
	v_fma_f32 v14, v10, s17, v3
	v_fma_f32 v15, v11, s17, v3
	v_rsq_f32_e32 v14, v14
	v_rsq_f32_e32 v15, v15
	s_nop 0
	v_mul_f32_e32 v128, v144, v14
	v_mul_f32_e32 v129, v145, v14
	v_mul_f32_e32 v130, v146, v14
	v_mul_f32_e32 v131, v147, v14
	v_mul_f32_e32 v132, v148, v14
	v_mul_f32_e32 v133, v149, v14
	v_mul_f32_e32 v134, v150, v14
	v_mul_f32_e32 v135, v151, v14
	v_mul_f32_e32 v136, v152, v14
	v_mul_f32_e32 v137, v153, v14
	v_mul_f32_e32 v138, v154, v14
	v_mul_f32_e32 v139, v155, v14
	v_mul_f32_e32 v140, v156, v14
	v_mul_f32_e32 v141, v157, v14
	v_mul_f32_e32 v142, v158, v14
	v_mul_f32_e32 v143, v159, v14
	v_mul_f32_e32 v128, v128, v36
	v_mul_f32_e32 v129, v129, v37
	v_mul_f32_e32 v130, v130, v38
	v_mul_f32_e32 v131, v131, v39
	v_mul_f32_e32 v132, v132, v40
	v_mul_f32_e32 v133, v133, v41
	v_mul_f32_e32 v134, v134, v42
	v_mul_f32_e32 v135, v135, v43
	v_mul_f32_e32 v136, v136, v44
	v_mul_f32_e32 v137, v137, v45
	v_mul_f32_e32 v138, v138, v46
	v_mul_f32_e32 v139, v139, v47
	v_mul_f32_e32 v140, v140, v48
	v_mul_f32_e32 v141, v141, v49
	v_mul_f32_e32 v142, v142, v50
	v_mul_f32_e32 v143, v143, v51
	v_cvt_pk_bf16_f32 v128, v128, v129
	v_cvt_pk_bf16_f32 v129, v130, v131
	v_cvt_pk_bf16_f32 v132, v132, v133
	v_cvt_pk_bf16_f32 v133, v134, v135
	v_cvt_pk_bf16_f32 v136, v136, v137
	v_cvt_pk_bf16_f32 v137, v138, v139
	v_cvt_pk_bf16_f32 v140, v140, v141
	v_cvt_pk_bf16_f32 v141, v142, v143
	global_store_dwordx2 v2, v[128:129], s[42:43] offset:0
	global_store_dwordx2 v2, v[132:133], s[42:43] offset:512
	global_store_dwordx2 v2, v[136:137], s[42:43] offset:1024
	global_store_dwordx2 v2, v[140:141], s[42:43] offset:1536
	v_mul_f32_e32 v160, v176, v15
	v_mul_f32_e32 v161, v177, v15
	v_mul_f32_e32 v162, v178, v15
	v_mul_f32_e32 v163, v179, v15
	v_mul_f32_e32 v164, v180, v15
	v_mul_f32_e32 v165, v181, v15
	v_mul_f32_e32 v166, v182, v15
	v_mul_f32_e32 v167, v183, v15
	v_mul_f32_e32 v168, v184, v15
	v_mul_f32_e32 v169, v185, v15
	v_mul_f32_e32 v170, v186, v15
	v_mul_f32_e32 v171, v187, v15
	v_mul_f32_e32 v172, v188, v15
	v_mul_f32_e32 v173, v189, v15
	v_mul_f32_e32 v174, v190, v15
	v_mul_f32_e32 v175, v191, v15
	v_mul_f32_e32 v160, v160, v36
	v_mul_f32_e32 v161, v161, v37
	v_mul_f32_e32 v162, v162, v38
	v_mul_f32_e32 v163, v163, v39
	v_mul_f32_e32 v164, v164, v40
	v_mul_f32_e32 v165, v165, v41
	v_mul_f32_e32 v166, v166, v42
	v_mul_f32_e32 v167, v167, v43
	v_mul_f32_e32 v168, v168, v44
	v_mul_f32_e32 v169, v169, v45
	v_mul_f32_e32 v170, v170, v46
	v_mul_f32_e32 v171, v171, v47
	v_mul_f32_e32 v172, v172, v48
	v_mul_f32_e32 v173, v173, v49
	v_mul_f32_e32 v174, v174, v50
	v_mul_f32_e32 v175, v175, v51
	v_cvt_pk_bf16_f32 v160, v160, v161
	v_cvt_pk_bf16_f32 v161, v162, v163
	v_cvt_pk_bf16_f32 v164, v164, v165
	v_cvt_pk_bf16_f32 v165, v166, v167
	v_cvt_pk_bf16_f32 v168, v168, v169
	v_cvt_pk_bf16_f32 v169, v170, v171
	v_cvt_pk_bf16_f32 v172, v172, v173
	v_cvt_pk_bf16_f32 v173, v174, v175
	global_store_dwordx2 v2, v[160:161], s[50:51] offset:0
	global_store_dwordx2 v2, v[164:165], s[50:51] offset:512
	global_store_dwordx2 v2, v[168:169], s[50:51] offset:1024
	global_store_dwordx2 v2, v[172:173], s[50:51] offset:1536
	s_add_u32 s53, s16, 0x3000
	s_lshl_b32 s18, s53, 12
	s_lshl_b32 s19, s53, 11
	s_add_u32 s36, s4, s18
	s_addc_u32 s37, s5, 0
	s_add_u32 s38, s6, s19
	s_addc_u32 s39, s7, 0
	s_add_u32 s38, s38, 0x5200000
	s_addc_u32 s39, s39, 0
	s_add_u32 s40, s4, s18
	s_addc_u32 s41, s5, 0
	s_add_u32 s42, s6, s19
	s_addc_u32 s43, s7, 0
	s_add_u32 s42, s42, 0x3100000
	s_addc_u32 s43, s43, 0
	global_load_dwordx2 v[130:131], v2, s[38:39] offset:0
	global_load_dwordx2 v[134:135], v2, s[38:39] offset:512
	global_load_dwordx2 v[138:139], v2, s[38:39] offset:1024
	global_load_dwordx2 v[142:143], v2, s[38:39] offset:1536
	global_load_dwordx4 v[144:147], v1, s[36:37] offset:0
	global_load_dwordx4 v[148:151], v1, s[36:37] offset:1024
	global_load_dwordx4 v[152:155], v1, s[36:37] offset:2048
	global_load_dwordx4 v[156:159], v1, s[36:37] offset:3072
	s_add_u32 s53, s16, 0x3800
	s_lshl_b32 s18, s53, 12
	s_lshl_b32 s19, s53, 11
	s_add_u32 s44, s4, s18
	s_addc_u32 s45, s5, 0
	s_add_u32 s46, s6, s19
	s_addc_u32 s47, s7, 0
	s_add_u32 s46, s46, 0x5200000
	s_addc_u32 s47, s47, 0
	s_add_u32 s48, s4, s18
	s_addc_u32 s49, s5, 0
	s_add_u32 s50, s6, s19
	s_addc_u32 s51, s7, 0
	s_add_u32 s50, s50, 0x3100000
	s_addc_u32 s51, s51, 0
	global_load_dwordx2 v[162:163], v2, s[46:47] offset:0
	global_load_dwordx2 v[166:167], v2, s[46:47] offset:512
	global_load_dwordx2 v[170:171], v2, s[46:47] offset:1024
	global_load_dwordx2 v[174:175], v2, s[46:47] offset:1536
	global_load_dwordx4 v[176:179], v1, s[44:45] offset:0
	global_load_dwordx4 v[180:183], v1, s[44:45] offset:1024
	global_load_dwordx4 v[184:187], v1, s[44:45] offset:2048
	global_load_dwordx4 v[188:191], v1, s[44:45] offset:3072
	s_waitcnt vmcnt(32)
	v_lshlrev_b32_e32 v64, 16, v66
	v_and_b32_e32 v65, 0xffff0000, v66
	v_lshlrev_b32_e32 v66, 16, v67
	v_and_b32_e32 v67, 0xffff0000, v67
	v_lshlrev_b32_e32 v68, 16, v70
	v_and_b32_e32 v69, 0xffff0000, v70
	v_lshlrev_b32_e32 v70, 16, v71
	v_and_b32_e32 v71, 0xffff0000, v71
	v_lshlrev_b32_e32 v72, 16, v74
	v_and_b32_e32 v73, 0xffff0000, v74
	v_lshlrev_b32_e32 v74, 16, v75
	v_and_b32_e32 v75, 0xffff0000, v75
	v_lshlrev_b32_e32 v76, 16, v78
	v_and_b32_e32 v77, 0xffff0000, v78
	v_lshlrev_b32_e32 v78, 16, v79
	v_and_b32_e32 v79, 0xffff0000, v79
	v_lshlrev_b32_e32 v96, 16, v98
	v_and_b32_e32 v97, 0xffff0000, v98
	v_lshlrev_b32_e32 v98, 16, v99
	v_and_b32_e32 v99, 0xffff0000, v99
	v_lshlrev_b32_e32 v100, 16, v102
	v_and_b32_e32 v101, 0xffff0000, v102
	v_lshlrev_b32_e32 v102, 16, v103
	v_and_b32_e32 v103, 0xffff0000, v103
	v_lshlrev_b32_e32 v104, 16, v106
	v_and_b32_e32 v105, 0xffff0000, v106
	v_lshlrev_b32_e32 v106, 16, v107
	v_and_b32_e32 v107, 0xffff0000, v107
	v_lshlrev_b32_e32 v108, 16, v110
	v_and_b32_e32 v109, 0xffff0000, v110
	v_lshlrev_b32_e32 v110, 16, v111
	v_and_b32_e32 v111, 0xffff0000, v111
	v_mul_f32_e32 v10, v64, v64
	v_fmac_f32_e32 v10, v65, v65
	v_fmac_f32_e32 v10, v66, v66
	v_fmac_f32_e32 v10, v67, v67
	v_fmac_f32_e32 v10, v68, v68
	v_fmac_f32_e32 v10, v69, v69
	v_fmac_f32_e32 v10, v70, v70
	v_fmac_f32_e32 v10, v71, v71
	v_fmac_f32_e32 v10, v72, v72
	v_fmac_f32_e32 v10, v73, v73
	v_fmac_f32_e32 v10, v74, v74
	v_fmac_f32_e32 v10, v75, v75
	v_fmac_f32_e32 v10, v76, v76
	v_fmac_f32_e32 v10, v77, v77
	v_fmac_f32_e32 v10, v78, v78
	v_fmac_f32_e32 v10, v79, v79
	v_mul_f32_e32 v11, v96, v96
	v_fmac_f32_e32 v11, v97, v97
	v_fmac_f32_e32 v11, v98, v98
	v_fmac_f32_e32 v11, v99, v99
	v_fmac_f32_e32 v11, v100, v100
	v_fmac_f32_e32 v11, v101, v101
	v_fmac_f32_e32 v11, v102, v102
	v_fmac_f32_e32 v11, v103, v103
	v_fmac_f32_e32 v11, v104, v104
	v_fmac_f32_e32 v11, v105, v105
	v_fmac_f32_e32 v11, v106, v106
	v_fmac_f32_e32 v11, v107, v107
	v_fmac_f32_e32 v11, v108, v108
	v_fmac_f32_e32 v11, v109, v109
	v_fmac_f32_e32 v11, v110, v110
	v_fmac_f32_e32 v11, v111, v111
	ds_bpermute_b32 v12, v4, v10
	ds_bpermute_b32 v13, v4, v11
	s_waitcnt lgkmcnt(0)
	v_add_f32_e32 v10, v10, v12
	v_add_f32_e32 v11, v11, v13
	ds_bpermute_b32 v12, v5, v10
	ds_bpermute_b32 v13, v5, v11
	s_waitcnt lgkmcnt(0)
	v_add_f32_e32 v10, v10, v12
	v_add_f32_e32 v11, v11, v13
	ds_bpermute_b32 v12, v6, v10
	ds_bpermute_b32 v13, v6, v11
	s_waitcnt lgkmcnt(0)
	v_add_f32_e32 v10, v10, v12
	v_add_f32_e32 v11, v11, v13
	ds_bpermute_b32 v12, v7, v10
	ds_bpermute_b32 v13, v7, v11
	s_waitcnt lgkmcnt(0)
	v_add_f32_e32 v10, v10, v12
	v_add_f32_e32 v11, v11, v13
	ds_bpermute_b32 v12, v8, v10
	ds_bpermute_b32 v13, v8, v11
	s_waitcnt lgkmcnt(0)
	v_add_f32_e32 v10, v10, v12
	v_add_f32_e32 v11, v11, v13
	ds_bpermute_b32 v12, v9, v10
	ds_bpermute_b32 v13, v9, v11
	s_waitcnt lgkmcnt(0)
	v_add_f32_e32 v10, v10, v12
	v_add_f32_e32 v11, v11, v13
	v_fma_f32 v14, v10, s17, v3
	v_fma_f32 v15, v11, s17, v3
	v_rsq_f32_e32 v14, v14
	v_rsq_f32_e32 v15, v15
	s_nop 0
	v_mul_f32_e32 v64, v64, v14
	v_mul_f32_e32 v65, v65, v14
	v_mul_f32_e32 v66, v66, v14
	v_mul_f32_e32 v67, v67, v14
	v_mul_f32_e32 v68, v68, v14
	v_mul_f32_e32 v69, v69, v14
	v_mul_f32_e32 v70, v70, v14
	v_mul_f32_e32 v71, v71, v14
	v_mul_f32_e32 v72, v72, v14
	v_mul_f32_e32 v73, v73, v14
	v_mul_f32_e32 v74, v74, v14
	v_mul_f32_e32 v75, v75, v14
	v_mul_f32_e32 v76, v76, v14
	v_mul_f32_e32 v77, v77, v14
	v_mul_f32_e32 v78, v78, v14
	v_mul_f32_e32 v79, v79, v14
	v_fmac_f32_e32 v80, v64, v20
	v_fmac_f32_e32 v81, v65, v21
	v_fmac_f32_e32 v82, v66, v22
	v_fmac_f32_e32 v83, v67, v23
	v_fmac_f32_e32 v84, v68, v24
	v_fmac_f32_e32 v85, v69, v25
	v_fmac_f32_e32 v86, v70, v26
	v_fmac_f32_e32 v87, v71, v27
	v_fmac_f32_e32 v88, v72, v28
	v_fmac_f32_e32 v89, v73, v29
	v_fmac_f32_e32 v90, v74, v30
	v_fmac_f32_e32 v91, v75, v31
	v_fmac_f32_e32 v92, v76, v32
	v_fmac_f32_e32 v93, v77, v33
	v_fmac_f32_e32 v94, v78, v34
	v_fmac_f32_e32 v95, v79, v35
	global_store_dwordx4 v1, v[80:83], s[24:25] offset:0
	global_store_dwordx4 v1, v[84:87], s[24:25] offset:1024
	global_store_dwordx4 v1, v[88:91], s[24:25] offset:2048
	global_store_dwordx4 v1, v[92:95], s[24:25] offset:3072
	v_mul_f32_e32 v96, v96, v15
	v_mul_f32_e32 v97, v97, v15
	v_mul_f32_e32 v98, v98, v15
	v_mul_f32_e32 v99, v99, v15
	v_mul_f32_e32 v100, v100, v15
	v_mul_f32_e32 v101, v101, v15
	v_mul_f32_e32 v102, v102, v15
	v_mul_f32_e32 v103, v103, v15
	v_mul_f32_e32 v104, v104, v15
	v_mul_f32_e32 v105, v105, v15
	v_mul_f32_e32 v106, v106, v15
	v_mul_f32_e32 v107, v107, v15
	v_mul_f32_e32 v108, v108, v15
	v_mul_f32_e32 v109, v109, v15
	v_mul_f32_e32 v110, v110, v15
	v_mul_f32_e32 v111, v111, v15
	v_fmac_f32_e32 v112, v96, v20
	v_fmac_f32_e32 v113, v97, v21
	v_fmac_f32_e32 v114, v98, v22
	v_fmac_f32_e32 v115, v99, v23
	v_fmac_f32_e32 v116, v100, v24
	v_fmac_f32_e32 v117, v101, v25
	v_fmac_f32_e32 v118, v102, v26
	v_fmac_f32_e32 v119, v103, v27
	v_fmac_f32_e32 v120, v104, v28
	v_fmac_f32_e32 v121, v105, v29
	v_fmac_f32_e32 v122, v106, v30
	v_fmac_f32_e32 v123, v107, v31
	v_fmac_f32_e32 v124, v108, v32
	v_fmac_f32_e32 v125, v109, v33
	v_fmac_f32_e32 v126, v110, v34
	v_fmac_f32_e32 v127, v111, v35
	global_store_dwordx4 v1, v[112:115], s[32:33] offset:0
	global_store_dwordx4 v1, v[116:119], s[32:33] offset:1024
	global_store_dwordx4 v1, v[120:123], s[32:33] offset:2048
	global_store_dwordx4 v1, v[124:127], s[32:33] offset:3072
	v_mul_f32_e32 v10, v80, v80
	v_fmac_f32_e32 v10, v81, v81
	v_fmac_f32_e32 v10, v82, v82
	v_fmac_f32_e32 v10, v83, v83
	v_fmac_f32_e32 v10, v84, v84
	v_fmac_f32_e32 v10, v85, v85
	v_fmac_f32_e32 v10, v86, v86
	v_fmac_f32_e32 v10, v87, v87
	v_fmac_f32_e32 v10, v88, v88
	v_fmac_f32_e32 v10, v89, v89
	v_fmac_f32_e32 v10, v90, v90
	v_fmac_f32_e32 v10, v91, v91
	v_fmac_f32_e32 v10, v92, v92
	v_fmac_f32_e32 v10, v93, v93
	v_fmac_f32_e32 v10, v94, v94
	v_fmac_f32_e32 v10, v95, v95
	v_mul_f32_e32 v11, v112, v112
	v_fmac_f32_e32 v11, v113, v113
	v_fmac_f32_e32 v11, v114, v114
	v_fmac_f32_e32 v11, v115, v115
	v_fmac_f32_e32 v11, v116, v116
	v_fmac_f32_e32 v11, v117, v117
	v_fmac_f32_e32 v11, v118, v118
	v_fmac_f32_e32 v11, v119, v119
	v_fmac_f32_e32 v11, v120, v120
	v_fmac_f32_e32 v11, v121, v121
	v_fmac_f32_e32 v11, v122, v122
	v_fmac_f32_e32 v11, v123, v123
	v_fmac_f32_e32 v11, v124, v124
	v_fmac_f32_e32 v11, v125, v125
	v_fmac_f32_e32 v11, v126, v126
	v_fmac_f32_e32 v11, v127, v127
	ds_bpermute_b32 v12, v4, v10
	ds_bpermute_b32 v13, v4, v11
	s_waitcnt lgkmcnt(0)
	v_add_f32_e32 v10, v10, v12
	v_add_f32_e32 v11, v11, v13
	ds_bpermute_b32 v12, v5, v10
	ds_bpermute_b32 v13, v5, v11
	s_waitcnt lgkmcnt(0)
	v_add_f32_e32 v10, v10, v12
	v_add_f32_e32 v11, v11, v13
	ds_bpermute_b32 v12, v6, v10
	ds_bpermute_b32 v13, v6, v11
	s_waitcnt lgkmcnt(0)
	v_add_f32_e32 v10, v10, v12
	v_add_f32_e32 v11, v11, v13
	ds_bpermute_b32 v12, v7, v10
	ds_bpermute_b32 v13, v7, v11
	s_waitcnt lgkmcnt(0)
	v_add_f32_e32 v10, v10, v12
	v_add_f32_e32 v11, v11, v13
	ds_bpermute_b32 v12, v8, v10
	ds_bpermute_b32 v13, v8, v11
	s_waitcnt lgkmcnt(0)
	v_add_f32_e32 v10, v10, v12
	v_add_f32_e32 v11, v11, v13
	ds_bpermute_b32 v12, v9, v10
	ds_bpermute_b32 v13, v9, v11
	s_waitcnt lgkmcnt(0)
	v_add_f32_e32 v10, v10, v12
	v_add_f32_e32 v11, v11, v13
	v_fma_f32 v14, v10, s17, v3
	v_fma_f32 v15, v11, s17, v3
	v_rsq_f32_e32 v14, v14
	v_rsq_f32_e32 v15, v15
	s_nop 0
	v_mul_f32_e32 v64, v80, v14
	v_mul_f32_e32 v65, v81, v14
	v_mul_f32_e32 v66, v82, v14
	v_mul_f32_e32 v67, v83, v14
	v_mul_f32_e32 v68, v84, v14
	v_mul_f32_e32 v69, v85, v14
	v_mul_f32_e32 v70, v86, v14
	v_mul_f32_e32 v71, v87, v14
	v_mul_f32_e32 v72, v88, v14
	v_mul_f32_e32 v73, v89, v14
	v_mul_f32_e32 v74, v90, v14
	v_mul_f32_e32 v75, v91, v14
	v_mul_f32_e32 v76, v92, v14
	v_mul_f32_e32 v77, v93, v14
	v_mul_f32_e32 v78, v94, v14
	v_mul_f32_e32 v79, v95, v14
	v_mul_f32_e32 v64, v64, v36
	v_mul_f32_e32 v65, v65, v37
	v_mul_f32_e32 v66, v66, v38
	v_mul_f32_e32 v67, v67, v39
	v_mul_f32_e32 v68, v68, v40
	v_mul_f32_e32 v69, v69, v41
	v_mul_f32_e32 v70, v70, v42
	v_mul_f32_e32 v71, v71, v43
	v_mul_f32_e32 v72, v72, v44
	v_mul_f32_e32 v73, v73, v45
	v_mul_f32_e32 v74, v74, v46
	v_mul_f32_e32 v75, v75, v47
	v_mul_f32_e32 v76, v76, v48
	v_mul_f32_e32 v77, v77, v49
	v_mul_f32_e32 v78, v78, v50
	v_mul_f32_e32 v79, v79, v51
	v_cvt_pk_bf16_f32 v64, v64, v65
	v_cvt_pk_bf16_f32 v65, v66, v67
	v_cvt_pk_bf16_f32 v68, v68, v69
	v_cvt_pk_bf16_f32 v69, v70, v71
	v_cvt_pk_bf16_f32 v72, v72, v73
	v_cvt_pk_bf16_f32 v73, v74, v75
	v_cvt_pk_bf16_f32 v76, v76, v77
	v_cvt_pk_bf16_f32 v77, v78, v79
	global_store_dwordx2 v2, v[64:65], s[26:27] offset:0
	global_store_dwordx2 v2, v[68:69], s[26:27] offset:512
	global_store_dwordx2 v2, v[72:73], s[26:27] offset:1024
	global_store_dwordx2 v2, v[76:77], s[26:27] offset:1536
	v_mul_f32_e32 v96, v112, v15
	v_mul_f32_e32 v97, v113, v15
	v_mul_f32_e32 v98, v114, v15
	v_mul_f32_e32 v99, v115, v15
	v_mul_f32_e32 v100, v116, v15
	v_mul_f32_e32 v101, v117, v15
	v_mul_f32_e32 v102, v118, v15
	v_mul_f32_e32 v103, v119, v15
	v_mul_f32_e32 v104, v120, v15
	v_mul_f32_e32 v105, v121, v15
	v_mul_f32_e32 v106, v122, v15
	v_mul_f32_e32 v107, v123, v15
	v_mul_f32_e32 v108, v124, v15
	v_mul_f32_e32 v109, v125, v15
	v_mul_f32_e32 v110, v126, v15
	v_mul_f32_e32 v111, v127, v15
	v_mul_f32_e32 v96, v96, v36
	v_mul_f32_e32 v97, v97, v37
	v_mul_f32_e32 v98, v98, v38
	v_mul_f32_e32 v99, v99, v39
	v_mul_f32_e32 v100, v100, v40
	v_mul_f32_e32 v101, v101, v41
	v_mul_f32_e32 v102, v102, v42
	v_mul_f32_e32 v103, v103, v43
	v_mul_f32_e32 v104, v104, v44
	v_mul_f32_e32 v105, v105, v45
	v_mul_f32_e32 v106, v106, v46
	v_mul_f32_e32 v107, v107, v47
	v_mul_f32_e32 v108, v108, v48
	v_mul_f32_e32 v109, v109, v49
	v_mul_f32_e32 v110, v110, v50
	v_mul_f32_e32 v111, v111, v51
	v_cvt_pk_bf16_f32 v96, v96, v97
	v_cvt_pk_bf16_f32 v97, v98, v99
	v_cvt_pk_bf16_f32 v100, v100, v101
	v_cvt_pk_bf16_f32 v101, v102, v103
	v_cvt_pk_bf16_f32 v104, v104, v105
	v_cvt_pk_bf16_f32 v105, v106, v107
	v_cvt_pk_bf16_f32 v108, v108, v109
	v_cvt_pk_bf16_f32 v109, v110, v111
	global_store_dwordx2 v2, v[96:97], s[34:35] offset:0
	global_store_dwordx2 v2, v[100:101], s[34:35] offset:512
	global_store_dwordx2 v2, v[104:105], s[34:35] offset:1024
	global_store_dwordx2 v2, v[108:109], s[34:35] offset:1536
	s_waitcnt vmcnt(16)
	v_lshlrev_b32_e32 v128, 16, v130
	v_and_b32_e32 v129, 0xffff0000, v130
	v_lshlrev_b32_e32 v130, 16, v131
	v_and_b32_e32 v131, 0xffff0000, v131
	v_lshlrev_b32_e32 v132, 16, v134
	v_and_b32_e32 v133, 0xffff0000, v134
	v_lshlrev_b32_e32 v134, 16, v135
	v_and_b32_e32 v135, 0xffff0000, v135
	v_lshlrev_b32_e32 v136, 16, v138
	v_and_b32_e32 v137, 0xffff0000, v138
	v_lshlrev_b32_e32 v138, 16, v139
	v_and_b32_e32 v139, 0xffff0000, v139
	v_lshlrev_b32_e32 v140, 16, v142
	v_and_b32_e32 v141, 0xffff0000, v142
	v_lshlrev_b32_e32 v142, 16, v143
	v_and_b32_e32 v143, 0xffff0000, v143
	v_lshlrev_b32_e32 v160, 16, v162
	v_and_b32_e32 v161, 0xffff0000, v162
	v_lshlrev_b32_e32 v162, 16, v163
	v_and_b32_e32 v163, 0xffff0000, v163
	v_lshlrev_b32_e32 v164, 16, v166
	v_and_b32_e32 v165, 0xffff0000, v166
	v_lshlrev_b32_e32 v166, 16, v167
	v_and_b32_e32 v167, 0xffff0000, v167
	v_lshlrev_b32_e32 v168, 16, v170
	v_and_b32_e32 v169, 0xffff0000, v170
	v_lshlrev_b32_e32 v170, 16, v171
	v_and_b32_e32 v171, 0xffff0000, v171
	v_lshlrev_b32_e32 v172, 16, v174
	v_and_b32_e32 v173, 0xffff0000, v174
	v_lshlrev_b32_e32 v174, 16, v175
	v_and_b32_e32 v175, 0xffff0000, v175
	v_mul_f32_e32 v10, v128, v128
	v_fmac_f32_e32 v10, v129, v129
	v_fmac_f32_e32 v10, v130, v130
	v_fmac_f32_e32 v10, v131, v131
	v_fmac_f32_e32 v10, v132, v132
	v_fmac_f32_e32 v10, v133, v133
	v_fmac_f32_e32 v10, v134, v134
	v_fmac_f32_e32 v10, v135, v135
	v_fmac_f32_e32 v10, v136, v136
	v_fmac_f32_e32 v10, v137, v137
	v_fmac_f32_e32 v10, v138, v138
	v_fmac_f32_e32 v10, v139, v139
	v_fmac_f32_e32 v10, v140, v140
	v_fmac_f32_e32 v10, v141, v141
	v_fmac_f32_e32 v10, v142, v142
	v_fmac_f32_e32 v10, v143, v143
	v_mul_f32_e32 v11, v160, v160
	v_fmac_f32_e32 v11, v161, v161
	v_fmac_f32_e32 v11, v162, v162
	v_fmac_f32_e32 v11, v163, v163
	v_fmac_f32_e32 v11, v164, v164
	v_fmac_f32_e32 v11, v165, v165
	v_fmac_f32_e32 v11, v166, v166
	v_fmac_f32_e32 v11, v167, v167
	v_fmac_f32_e32 v11, v168, v168
	v_fmac_f32_e32 v11, v169, v169
	v_fmac_f32_e32 v11, v170, v170
	v_fmac_f32_e32 v11, v171, v171
	v_fmac_f32_e32 v11, v172, v172
	v_fmac_f32_e32 v11, v173, v173
	v_fmac_f32_e32 v11, v174, v174
	v_fmac_f32_e32 v11, v175, v175
	ds_bpermute_b32 v12, v4, v10
	ds_bpermute_b32 v13, v4, v11
	s_waitcnt lgkmcnt(0)
	v_add_f32_e32 v10, v10, v12
	v_add_f32_e32 v11, v11, v13
	ds_bpermute_b32 v12, v5, v10
	ds_bpermute_b32 v13, v5, v11
	s_waitcnt lgkmcnt(0)
	v_add_f32_e32 v10, v10, v12
	v_add_f32_e32 v11, v11, v13
	ds_bpermute_b32 v12, v6, v10
	ds_bpermute_b32 v13, v6, v11
	s_waitcnt lgkmcnt(0)
	v_add_f32_e32 v10, v10, v12
	v_add_f32_e32 v11, v11, v13
	ds_bpermute_b32 v12, v7, v10
	ds_bpermute_b32 v13, v7, v11
	s_waitcnt lgkmcnt(0)
	v_add_f32_e32 v10, v10, v12
	v_add_f32_e32 v11, v11, v13
	ds_bpermute_b32 v12, v8, v10
	ds_bpermute_b32 v13, v8, v11
	s_waitcnt lgkmcnt(0)
	v_add_f32_e32 v10, v10, v12
	v_add_f32_e32 v11, v11, v13
	ds_bpermute_b32 v12, v9, v10
	ds_bpermute_b32 v13, v9, v11
	s_waitcnt lgkmcnt(0)
	v_add_f32_e32 v10, v10, v12
	v_add_f32_e32 v11, v11, v13
	v_fma_f32 v14, v10, s17, v3
	v_fma_f32 v15, v11, s17, v3
	v_rsq_f32_e32 v14, v14
	v_rsq_f32_e32 v15, v15
	s_nop 0
	v_mul_f32_e32 v128, v128, v14
	v_mul_f32_e32 v129, v129, v14
	v_mul_f32_e32 v130, v130, v14
	v_mul_f32_e32 v131, v131, v14
	v_mul_f32_e32 v132, v132, v14
	v_mul_f32_e32 v133, v133, v14
	v_mul_f32_e32 v134, v134, v14
	v_mul_f32_e32 v135, v135, v14
	v_mul_f32_e32 v136, v136, v14
	v_mul_f32_e32 v137, v137, v14
	v_mul_f32_e32 v138, v138, v14
	v_mul_f32_e32 v139, v139, v14
	v_mul_f32_e32 v140, v140, v14
	v_mul_f32_e32 v141, v141, v14
	v_mul_f32_e32 v142, v142, v14
	v_mul_f32_e32 v143, v143, v14
	v_fmac_f32_e32 v144, v128, v20
	v_fmac_f32_e32 v145, v129, v21
	v_fmac_f32_e32 v146, v130, v22
	v_fmac_f32_e32 v147, v131, v23
	v_fmac_f32_e32 v148, v132, v24
	v_fmac_f32_e32 v149, v133, v25
	v_fmac_f32_e32 v150, v134, v26
	v_fmac_f32_e32 v151, v135, v27
	v_fmac_f32_e32 v152, v136, v28
	v_fmac_f32_e32 v153, v137, v29
	v_fmac_f32_e32 v154, v138, v30
	v_fmac_f32_e32 v155, v139, v31
	v_fmac_f32_e32 v156, v140, v32
	v_fmac_f32_e32 v157, v141, v33
	v_fmac_f32_e32 v158, v142, v34
	v_fmac_f32_e32 v159, v143, v35
	global_store_dwordx4 v1, v[144:147], s[40:41] offset:0
	global_store_dwordx4 v1, v[148:151], s[40:41] offset:1024
	global_store_dwordx4 v1, v[152:155], s[40:41] offset:2048
	global_store_dwordx4 v1, v[156:159], s[40:41] offset:3072
	v_mul_f32_e32 v160, v160, v15
	v_mul_f32_e32 v161, v161, v15
	v_mul_f32_e32 v162, v162, v15
	v_mul_f32_e32 v163, v163, v15
	v_mul_f32_e32 v164, v164, v15
	v_mul_f32_e32 v165, v165, v15
	v_mul_f32_e32 v166, v166, v15
	v_mul_f32_e32 v167, v167, v15
	v_mul_f32_e32 v168, v168, v15
	v_mul_f32_e32 v169, v169, v15
	v_mul_f32_e32 v170, v170, v15
	v_mul_f32_e32 v171, v171, v15
	v_mul_f32_e32 v172, v172, v15
	v_mul_f32_e32 v173, v173, v15
	v_mul_f32_e32 v174, v174, v15
	v_mul_f32_e32 v175, v175, v15
	v_fmac_f32_e32 v176, v160, v20
	v_fmac_f32_e32 v177, v161, v21
	v_fmac_f32_e32 v178, v162, v22
	v_fmac_f32_e32 v179, v163, v23
	v_fmac_f32_e32 v180, v164, v24
	v_fmac_f32_e32 v181, v165, v25
	v_fmac_f32_e32 v182, v166, v26
	v_fmac_f32_e32 v183, v167, v27
	v_fmac_f32_e32 v184, v168, v28
	v_fmac_f32_e32 v185, v169, v29
	v_fmac_f32_e32 v186, v170, v30
	v_fmac_f32_e32 v187, v171, v31
	v_fmac_f32_e32 v188, v172, v32
	v_fmac_f32_e32 v189, v173, v33
	v_fmac_f32_e32 v190, v174, v34
	v_fmac_f32_e32 v191, v175, v35
	global_store_dwordx4 v1, v[176:179], s[48:49] offset:0
	global_store_dwordx4 v1, v[180:183], s[48:49] offset:1024
	global_store_dwordx4 v1, v[184:187], s[48:49] offset:2048
	global_store_dwordx4 v1, v[188:191], s[48:49] offset:3072
	v_mul_f32_e32 v10, v144, v144
	v_fmac_f32_e32 v10, v145, v145
	v_fmac_f32_e32 v10, v146, v146
	v_fmac_f32_e32 v10, v147, v147
	v_fmac_f32_e32 v10, v148, v148
	v_fmac_f32_e32 v10, v149, v149
	v_fmac_f32_e32 v10, v150, v150
	v_fmac_f32_e32 v10, v151, v151
	v_fmac_f32_e32 v10, v152, v152
	v_fmac_f32_e32 v10, v153, v153
	v_fmac_f32_e32 v10, v154, v154
	v_fmac_f32_e32 v10, v155, v155
	v_fmac_f32_e32 v10, v156, v156
	v_fmac_f32_e32 v10, v157, v157
	v_fmac_f32_e32 v10, v158, v158
	v_fmac_f32_e32 v10, v159, v159
	v_mul_f32_e32 v11, v176, v176
	v_fmac_f32_e32 v11, v177, v177
	v_fmac_f32_e32 v11, v178, v178
	v_fmac_f32_e32 v11, v179, v179
	v_fmac_f32_e32 v11, v180, v180
	v_fmac_f32_e32 v11, v181, v181
	v_fmac_f32_e32 v11, v182, v182
	v_fmac_f32_e32 v11, v183, v183
	v_fmac_f32_e32 v11, v184, v184
	v_fmac_f32_e32 v11, v185, v185
	v_fmac_f32_e32 v11, v186, v186
	v_fmac_f32_e32 v11, v187, v187
	v_fmac_f32_e32 v11, v188, v188
	v_fmac_f32_e32 v11, v189, v189
	v_fmac_f32_e32 v11, v190, v190
	v_fmac_f32_e32 v11, v191, v191
	ds_bpermute_b32 v12, v4, v10
	ds_bpermute_b32 v13, v4, v11
	s_waitcnt lgkmcnt(0)
	v_add_f32_e32 v10, v10, v12
	v_add_f32_e32 v11, v11, v13
	ds_bpermute_b32 v12, v5, v10
	ds_bpermute_b32 v13, v5, v11
	s_waitcnt lgkmcnt(0)
	v_add_f32_e32 v10, v10, v12
	v_add_f32_e32 v11, v11, v13
	ds_bpermute_b32 v12, v6, v10
	ds_bpermute_b32 v13, v6, v11
	s_waitcnt lgkmcnt(0)
	v_add_f32_e32 v10, v10, v12
	v_add_f32_e32 v11, v11, v13
	ds_bpermute_b32 v12, v7, v10
	ds_bpermute_b32 v13, v7, v11
	s_waitcnt lgkmcnt(0)
	v_add_f32_e32 v10, v10, v12
	v_add_f32_e32 v11, v11, v13
	ds_bpermute_b32 v12, v8, v10
	ds_bpermute_b32 v13, v8, v11
	s_waitcnt lgkmcnt(0)
	v_add_f32_e32 v10, v10, v12
	v_add_f32_e32 v11, v11, v13
	ds_bpermute_b32 v12, v9, v10
	ds_bpermute_b32 v13, v9, v11
	s_waitcnt lgkmcnt(0)
	v_add_f32_e32 v10, v10, v12
	v_add_f32_e32 v11, v11, v13
	v_fma_f32 v14, v10, s17, v3
	v_fma_f32 v15, v11, s17, v3
	v_rsq_f32_e32 v14, v14
	v_rsq_f32_e32 v15, v15
	s_nop 0
	v_mul_f32_e32 v128, v144, v14
	v_mul_f32_e32 v129, v145, v14
	v_mul_f32_e32 v130, v146, v14
	v_mul_f32_e32 v131, v147, v14
	v_mul_f32_e32 v132, v148, v14
	v_mul_f32_e32 v133, v149, v14
	v_mul_f32_e32 v134, v150, v14
	v_mul_f32_e32 v135, v151, v14
	v_mul_f32_e32 v136, v152, v14
	v_mul_f32_e32 v137, v153, v14
	v_mul_f32_e32 v138, v154, v14
	v_mul_f32_e32 v139, v155, v14
	v_mul_f32_e32 v140, v156, v14
	v_mul_f32_e32 v141, v157, v14
	v_mul_f32_e32 v142, v158, v14
	v_mul_f32_e32 v143, v159, v14
	v_mul_f32_e32 v128, v128, v36
	v_mul_f32_e32 v129, v129, v37
	v_mul_f32_e32 v130, v130, v38
	v_mul_f32_e32 v131, v131, v39
	v_mul_f32_e32 v132, v132, v40
	v_mul_f32_e32 v133, v133, v41
	v_mul_f32_e32 v134, v134, v42
	v_mul_f32_e32 v135, v135, v43
	v_mul_f32_e32 v136, v136, v44
	v_mul_f32_e32 v137, v137, v45
	v_mul_f32_e32 v138, v138, v46
	v_mul_f32_e32 v139, v139, v47
	v_mul_f32_e32 v140, v140, v48
	v_mul_f32_e32 v141, v141, v49
	v_mul_f32_e32 v142, v142, v50
	v_mul_f32_e32 v143, v143, v51
	v_cvt_pk_bf16_f32 v128, v128, v129
	v_cvt_pk_bf16_f32 v129, v130, v131
	v_cvt_pk_bf16_f32 v132, v132, v133
	v_cvt_pk_bf16_f32 v133, v134, v135
	v_cvt_pk_bf16_f32 v136, v136, v137
	v_cvt_pk_bf16_f32 v137, v138, v139
	v_cvt_pk_bf16_f32 v140, v140, v141
	v_cvt_pk_bf16_f32 v141, v142, v143
	global_store_dwordx2 v2, v[128:129], s[42:43] offset:0
	global_store_dwordx2 v2, v[132:133], s[42:43] offset:512
	global_store_dwordx2 v2, v[136:137], s[42:43] offset:1024
	global_store_dwordx2 v2, v[140:141], s[42:43] offset:1536
	v_mul_f32_e32 v160, v176, v15
	v_mul_f32_e32 v161, v177, v15
	v_mul_f32_e32 v162, v178, v15
	v_mul_f32_e32 v163, v179, v15
	v_mul_f32_e32 v164, v180, v15
	v_mul_f32_e32 v165, v181, v15
	v_mul_f32_e32 v166, v182, v15
	v_mul_f32_e32 v167, v183, v15
	v_mul_f32_e32 v168, v184, v15
	v_mul_f32_e32 v169, v185, v15
	v_mul_f32_e32 v170, v186, v15
	v_mul_f32_e32 v171, v187, v15
	v_mul_f32_e32 v172, v188, v15
	v_mul_f32_e32 v173, v189, v15
	v_mul_f32_e32 v174, v190, v15
	v_mul_f32_e32 v175, v191, v15
	v_mul_f32_e32 v160, v160, v36
	v_mul_f32_e32 v161, v161, v37
	v_mul_f32_e32 v162, v162, v38
	v_mul_f32_e32 v163, v163, v39
	v_mul_f32_e32 v164, v164, v40
	v_mul_f32_e32 v165, v165, v41
	v_mul_f32_e32 v166, v166, v42
	v_mul_f32_e32 v167, v167, v43
	v_mul_f32_e32 v168, v168, v44
	v_mul_f32_e32 v169, v169, v45
	v_mul_f32_e32 v170, v170, v46
	v_mul_f32_e32 v171, v171, v47
	v_mul_f32_e32 v172, v172, v48
	v_mul_f32_e32 v173, v173, v49
	v_mul_f32_e32 v174, v174, v50
	v_mul_f32_e32 v175, v175, v51
	v_cvt_pk_bf16_f32 v160, v160, v161
	v_cvt_pk_bf16_f32 v161, v162, v163
	v_cvt_pk_bf16_f32 v164, v164, v165
	v_cvt_pk_bf16_f32 v165, v166, v167
	v_cvt_pk_bf16_f32 v168, v168, v169
	v_cvt_pk_bf16_f32 v169, v170, v171
	v_cvt_pk_bf16_f32 v172, v172, v173
	v_cvt_pk_bf16_f32 v173, v174, v175
	global_store_dwordx2 v2, v[160:161], s[50:51] offset:0
	global_store_dwordx2 v2, v[164:165], s[50:51] offset:512
	global_store_dwordx2 v2, v[168:169], s[50:51] offset:1024
	global_store_dwordx2 v2, v[172:173], s[50:51] offset:1536
	v_add_f32_e32 v208, v208, v212
	v_add_f32_e32 v209, v209, v213
	v_add_f32_e32 v210, v210, v214
	v_add_f32_e32 v211, v211, v215
	v_readfirstlane_b32 s18, v0
	s_lshr_b32 s18, s18, 6
	s_lshl_b32 s19, s18, 2
	s_and_b32 s52, s18, 4
	s_lshl_b32 s52, s52, 2
	v_mov_b32_e32 v16, s19
	v_mov_b32_e32 v17, s52
	v_mul_f32_e32 v10, v208, v208
	v_fmac_f32_e32 v10, v209, v209
	v_fmac_f32_e32 v10, v210, v210
	v_fmac_f32_e32 v10, v211, v211
	ds_bpermute_b32 v11, v4, v10
	s_waitcnt lgkmcnt(0)
	v_add_f32_e32 v10, v10, v11
	ds_bpermute_b32 v11, v5, v10
	s_waitcnt lgkmcnt(0)
	v_add_f32_e32 v10, v10, v11
	ds_bpermute_b32 v11, v6, v10
	s_waitcnt lgkmcnt(0)
	v_add_f32_e32 v10, v10, v11
	ds_bpermute_b32 v11, v7, v10
	s_waitcnt lgkmcnt(0)
	v_add_f32_e32 v10, v10, v11
	ds_bpermute_b32 v11, v8, v10
	s_waitcnt lgkmcnt(0)
	v_add_f32_e32 v10, v10, v11
	ds_bpermute_b32 v11, v9, v10
	s_waitcnt lgkmcnt(0)
	v_add_f32_e32 v10, v10, v11
	ds_write_b32 v16, v10 offset:0
	s_waitcnt lgkmcnt(0)
	s_barrier
	ds_read_b128 v[12:15], v17 offset:0
	s_waitcnt lgkmcnt(0)
	v_add_f32_e32 v12, v12, v13
	v_add_f32_e32 v14, v14, v15
	v_add_f32_e32 v10, v12, v14
	v_fma_f32 v11, v10, s17, v3
	v_rsq_f32_e32 v11, v11
	s_nop 0
	v_mul_f32_e32 v208, v208, v11
	v_mul_f32_e32 v209, v209, v11
	v_mul_f32_e32 v210, v210, v11
	v_mul_f32_e32 v211, v211, v11
	v_fmac_f32_e32 v240, v208, v244
	v_fmac_f32_e32 v241, v209, v245
	v_fmac_f32_e32 v242, v210, v246
	v_fmac_f32_e32 v243, v211, v247
	s_lshl_b32 s18, s54, 12
	s_add_u32 s18, s18, s55
	s_add_u32 s56, s4, s18
	s_addc_u32 s57, s5, 0
	s_add_u32 s56, s56, 0x4000000
	s_addc_u32 s57, s57, 0
	global_store_dwordx4 v1, v[240:243], s[56:57]
	v_mul_f32_e32 v10, v240, v240
	v_fmac_f32_e32 v10, v241, v241
	v_fmac_f32_e32 v10, v242, v242
	v_fmac_f32_e32 v10, v243, v243
	ds_bpermute_b32 v11, v4, v10
	s_waitcnt lgkmcnt(0)
	v_add_f32_e32 v10, v10, v11
	ds_bpermute_b32 v11, v5, v10
	s_waitcnt lgkmcnt(0)
	v_add_f32_e32 v10, v10, v11
	ds_bpermute_b32 v11, v6, v10
	s_waitcnt lgkmcnt(0)
	v_add_f32_e32 v10, v10, v11
	ds_bpermute_b32 v11, v7, v10
	s_waitcnt lgkmcnt(0)
	v_add_f32_e32 v10, v10, v11
	ds_bpermute_b32 v11, v8, v10
	s_waitcnt lgkmcnt(0)
	v_add_f32_e32 v10, v10, v11
	ds_bpermute_b32 v11, v9, v10
	s_waitcnt lgkmcnt(0)
	v_add_f32_e32 v10, v10, v11
	ds_write_b32 v16, v10 offset:64
	s_waitcnt lgkmcnt(0)
	s_barrier
	ds_read_b128 v[12:15], v17 offset:64
	s_waitcnt lgkmcnt(0)
	v_add_f32_e32 v12, v12, v13
	v_add_f32_e32 v14, v14, v15
	v_add_f32_e32 v10, v12, v14
	v_fma_f32 v11, v10, s17, v3
	v_rsq_f32_e32 v11, v11
	s_nop 0
	v_mul_f32_e32 v208, v240, v11
	v_mul_f32_e32 v209, v241, v11
	v_mul_f32_e32 v210, v242, v11
	v_mul_f32_e32 v211, v243, v11
	v_mul_f32_e32 v208, v208, v248
	v_mul_f32_e32 v209, v209, v249
	v_mul_f32_e32 v210, v210, v250
	v_mul_f32_e32 v211, v211, v251
	v_cvt_pk_bf16_f32 v208, v208, v209
	v_cvt_pk_bf16_f32 v209, v210, v211
	s_lshl_b32 s18, s54, 11
	s_lshr_b32 s19, s55, 1
	s_add_u32 s18, s18, s19
	s_add_u32 s56, s6, s18
	s_addc_u32 s57, s7, 0
	s_add_u32 s56, s56, 0x5100000
	s_addc_u32 s57, s57, 0
	global_store_dwordx2 v2, v[208:209], s[56:57]

	.amdhsa_kernel _Z10fwd_kernelILi11ELi12EEv4Args
		.amdhsa_group_segment_fixed_size 0
		.amdhsa_private_segment_fixed_size 0
		.amdhsa_kernarg_size 488
		.amdhsa_user_sgpr_count 2
		.amdhsa_user_sgpr_dispatch_ptr 0
		.amdhsa_user_sgpr_queue_ptr 0
		.amdhsa_user_sgpr_kernarg_segment_ptr 1
		.amdhsa_user_sgpr_dispatch_id 0
		.amdhsa_user_sgpr_kernarg_preload_length 0
		.amdhsa_user_sgpr_kernarg_preload_offset 0
		.amdhsa_user_sgpr_private_segment_size 0
		.amdhsa_uses_dynamic_stack 0
		.amdhsa_enable_private_segment 0
		.amdhsa_system_sgpr_workgroup_id_x 1
		.amdhsa_system_sgpr_workgroup_id_y 0
		.amdhsa_system_sgpr_workgroup_id_z 0
		.amdhsa_system_sgpr_workgroup_info 0
		.amdhsa_system_vgpr_workitem_id 0
		.amdhsa_next_free_vgpr 256
		.amdhsa_next_free_sgpr 60
		.amdhsa_accum_offset 256
		.amdhsa_reserve_vcc 1
		.amdhsa_float_round_mode_32 0
		.amdhsa_float_round_mode_16_64 0
		.amdhsa_float_denorm_mode_32 3
		.amdhsa_float_denorm_mode_16_64 3
		.amdhsa_dx10_clamp 1
		.amdhsa_ieee_mode 1
		.amdhsa_fp16_overflow 0
		.amdhsa_tg_split 0
		.amdhsa_exception_fp_ieee_invalid_op 0
		.amdhsa_exception_fp_denorm_src 0
		.amdhsa_exception_fp_ieee_div_zero 0
		.amdhsa_exception_fp_ieee_overflow 0
		.amdhsa_exception_fp_ieee_underflow 0
		.amdhsa_exception_fp_ieee_inexact 0
		.amdhsa_exception_int_div_zero 0
	.end_amdhsa_kernel

_Z10fwd_kernelILi14ELi15EEv4Args:
	s_load_dword s3, s[0:1], 0xe8
	s_load_dwordx4 s[4:7], s[0:1], 0xd0
	s_load_dwordx2 s[8:9], s[0:1], 0xb8
	s_waitcnt lgkmcnt(0)
	s_cmp_lg_u32 s3, 0x100
	s_cbranch_scc1 .Lrows14_orig
	s_add_u32 s8, s8, 0x1000
	s_addc_u32 s9, s9, 0
	v_readfirstlane_b32 s16, v0
	s_lshr_b32 s16, s16, 6
	s_lshl_b32 s18, s2, 3
	s_add_u32 s16, s16, s18
	s_mov_b32 s17, 0x3a800000
	v_mov_b32_e32 v3, 0x358637bd
	v_and_b32_e32 v10, 63, v0
	v_lshlrev_b32_e32 v1, 4, v10
	v_lshlrev_b32_e32 v2, 3, v10
	v_xor_b32_e32 v4, 1, v10
	v_xor_b32_e32 v5, 2, v10
	v_xor_b32_e32 v6, 4, v10
	v_xor_b32_e32 v7, 8, v10
	v_xor_b32_e32 v8, 16, v10
	v_xor_b32_e32 v9, 32, v10
	v_lshlrev_b32_e32 v4, 2, v4
	v_lshlrev_b32_e32 v5, 2, v5
	v_lshlrev_b32_e32 v6, 2, v6
	v_lshlrev_b32_e32 v7, 2, v7
	v_lshlrev_b32_e32 v8, 2, v8
	v_lshlrev_b32_e32 v9, 2, v9
	global_load_dwordx4 v[20:23], v1, s[8:9] offset:0
	global_load_dwordx4 v[24:27], v1, s[8:9] offset:1024
	global_load_dwordx4 v[28:31], v1, s[8:9] offset:2048
	global_load_dwordx4 v[32:35], v1, s[8:9] offset:3072
	s_lshr_b32 s54, s16, 2
	s_and_b32 s55, s16, 3
	s_lshl_b32 s55, s55, 10
	s_lshl_b32 s18, s54, 12
	s_add_u32 s18, s18, s55
	s_add_u32 s56, s6, s18
	s_addc_u32 s57, s7, 0
	s_add_u32 s56, s56, 0x100000
	s_addc_u32 s57, s57, 0
	global_load_dwordx4 v[208:211], v1, s[56:57]
	s_add_u32 s56, s56, 0x200000
	s_addc_u32 s57, s57, 0
	global_load_dwordx4 v[212:215], v1, s[56:57]
	s_add_u32 s56, s56, 0x200000
	s_addc_u32 s57, s57, 0
	global_load_dwordx4 v[216:219], v1, s[56:57]
	s_add_u32 s56, s56, 0x200000
	s_addc_u32 s57, s57, 0
	global_load_dwordx4 v[220:223], v1, s[56:57]
	s_add_u32 s56, s56, 0x200000
	s_addc_u32 s57, s57, 0
	global_load_dwordx4 v[224:227], v1, s[56:57]
	s_add_u32 s56, s56, 0x200000
	s_addc_u32 s57, s57, 0
	global_load_dwordx4 v[228:231], v1, s[56:57]
	s_add_u32 s56, s56, 0x200000
	s_addc_u32 s57, s57, 0
	global_load_dwordx4 v[232:235], v1, s[56:57]
	s_add_u32 s56, s56, 0x200000
	s_addc_u32 s57, s57, 0
	global_load_dwordx4 v[236:239], v1, s[56:57]
	s_add_u32 s56, s4, s18
	s_addc_u32 s57, s5, 0
	s_add_u32 s56, s56, 0x4000000
	s_addc_u32 s57, s57, 0
	global_load_dwordx4 v[240:243], v1, s[56:57]
	s_add_u32 s56, s8, s55
	s_addc_u32 s57, s9, 0
	global_load_dwordx4 v[244:247], v1, s[56:57]
	s_add_u32 s53, s16, 0x0
	s_lshl_b32 s18, s53, 12
	s_lshl_b32 s19, s53, 11
	s_add_u32 s20, s4, s18
	s_addc_u32 s21, s5, 0
	s_add_u32 s22, s6, s19
	s_addc_u32 s23, s7, 0
	s_add_u32 s22, s22, 0x5200000
	s_addc_u32 s23, s23, 0
	s_add_u32 s24, s4, s18
	s_addc_u32 s25, s5, 0
	global_load_dwordx2 v[66:67], v2, s[22:23] offset:0
	global_load_dwordx2 v[70:71], v2, s[22:23] offset:512
	global_load_dwordx2 v[74:75], v2, s[22:23] offset:1024
	global_load_dwordx2 v[78:79], v2, s[22:23] offset:1536
	global_load_dwordx4 v[80:83], v1, s[20:21] offset:0
	global_load_dwordx4 v[84:87], v1, s[20:21] offset:1024
	global_load_dwordx4 v[88:91], v1, s[20:21] offset:2048
	global_load_dwordx4 v[92:95], v1, s[20:21] offset:3072
	s_add_u32 s53, s16, 0x800
	s_lshl_b32 s18, s53, 12
	s_lshl_b32 s19, s53, 11
	s_add_u32 s28, s4, s18
	s_addc_u32 s29, s5, 0
	s_add_u32 s30, s6, s19
	s_addc_u32 s31, s7, 0
	s_add_u32 s30, s30, 0x5200000
	s_addc_u32 s31, s31, 0
	s_add_u32 s32, s4, s18
	s_addc_u32 s33, s5, 0
	global_load_dwordx2 v[98:99], v2, s[30:31] offset:0
	global_load_dwordx2 v[102:103], v2, s[30:31] offset:512
	global_load_dwordx2 v[106:107], v2, s[30:31] offset:1024
	global_load_dwordx2 v[110:111], v2, s[30:31] offset:1536
	global_load_dwordx4 v[112:115], v1, s[28:29] offset:0
	global_load_dwordx4 v[116:119], v1, s[28:29] offset:1024
	global_load_dwordx4 v[120:123], v1, s[28:29] offset:2048
	global_load_dwordx4 v[124:127], v1, s[28:29] offset:3072
	s_add_u32 s53, s16, 0x1000
	s_lshl_b32 s18, s53, 12
	s_lshl_b32 s19, s53, 11
	s_add_u32 s36, s4, s18
	s_addc_u32 s37, s5, 0
	s_add_u32 s38, s6, s19
	s_addc_u32 s39, s7, 0
	s_add_u32 s38, s38, 0x5200000
	s_addc_u32 s39, s39, 0
	s_add_u32 s40, s4, s18
	s_addc_u32 s41, s5, 0
	global_load_dwordx2 v[130:131], v2, s[38:39] offset:0
	global_load_dwordx2 v[134:135], v2, s[38:39] offset:512
	global_load_dwordx2 v[138:139], v2, s[38:39] offset:1024
	global_load_dwordx2 v[142:143], v2, s[38:39] offset:1536
	global_load_dwordx4 v[144:147], v1, s[36:37] offset:0
	global_load_dwordx4 v[148:151], v1, s[36:37] offset:1024
	global_load_dwordx4 v[152:155], v1, s[36:37] offset:2048
	global_load_dwordx4 v[156:159], v1, s[36:37] offset:3072
	s_add_u32 s53, s16, 0x1800
	s_lshl_b32 s18, s53, 12
	s_lshl_b32 s19, s53, 11
	s_add_u32 s44, s4, s18
	s_addc_u32 s45, s5, 0
	s_add_u32 s46, s6, s19
	s_addc_u32 s47, s7, 0
	s_add_u32 s46, s46, 0x5200000
	s_addc_u32 s47, s47, 0
	s_add_u32 s48, s4, s18
	s_addc_u32 s49, s5, 0
	global_load_dwordx2 v[162:163], v2, s[46:47] offset:0
	global_load_dwordx2 v[166:167], v2, s[46:47] offset:512
	global_load_dwordx2 v[170:171], v2, s[46:47] offset:1024
	global_load_dwordx2 v[174:175], v2, s[46:47] offset:1536
	global_load_dwordx4 v[176:179], v1, s[44:45] offset:0
	global_load_dwordx4 v[180:183], v1, s[44:45] offset:1024
	global_load_dwordx4 v[184:187], v1, s[44:45] offset:2048
	global_load_dwordx4 v[188:191], v1, s[44:45] offset:3072
	s_waitcnt vmcnt(16)
	v_lshlrev_b32_e32 v64, 16, v66
	v_and_b32_e32 v65, 0xffff0000, v66
	v_lshlrev_b32_e32 v66, 16, v67
	v_and_b32_e32 v67, 0xffff0000, v67
	v_lshlrev_b32_e32 v68, 16, v70
	v_and_b32_e32 v69, 0xffff0000, v70
	v_lshlrev_b32_e32 v70, 16, v71
	v_and_b32_e32 v71, 0xffff0000, v71
	v_lshlrev_b32_e32 v72, 16, v74
	v_and_b32_e32 v73, 0xffff0000, v74
	v_lshlrev_b32_e32 v74, 16, v75
	v_and_b32_e32 v75, 0xffff0000, v75
	v_lshlrev_b32_e32 v76, 16, v78
	v_and_b32_e32 v77, 0xffff0000, v78
	v_lshlrev_b32_e32 v78, 16, v79
	v_and_b32_e32 v79, 0xffff0000, v79
	v_lshlrev_b32_e32 v96, 16, v98
	v_and_b32_e32 v97, 0xffff0000, v98
	v_lshlrev_b32_e32 v98, 16, v99
	v_and_b32_e32 v99, 0xffff0000, v99
	v_lshlrev_b32_e32 v100, 16, v102
	v_and_b32_e32 v101, 0xffff0000, v102
	v_lshlrev_b32_e32 v102, 16, v103
	v_and_b32_e32 v103, 0xffff0000, v103
	v_lshlrev_b32_e32 v104, 16, v106
	v_and_b32_e32 v105, 0xffff0000, v106
	v_lshlrev_b32_e32 v106, 16, v107
	v_and_b32_e32 v107, 0xffff0000, v107
	v_lshlrev_b32_e32 v108, 16, v110
	v_and_b32_e32 v109, 0xffff0000, v110
	v_lshlrev_b32_e32 v110, 16, v111
	v_and_b32_e32 v111, 0xffff0000, v111
	v_mul_f32_e32 v10, v64, v64
	v_fmac_f32_e32 v10, v65, v65
	v_fmac_f32_e32 v10, v66, v66
	v_fmac_f32_e32 v10, v67, v67
	v_fmac_f32_e32 v10, v68, v68
	v_fmac_f32_e32 v10, v69, v69
	v_fmac_f32_e32 v10, v70, v70
	v_fmac_f32_e32 v10, v71, v71
	v_fmac_f32_e32 v10, v72, v72
	v_fmac_f32_e32 v10, v73, v73
	v_fmac_f32_e32 v10, v74, v74
	v_fmac_f32_e32 v10, v75, v75
	v_fmac_f32_e32 v10, v76, v76
	v_fmac_f32_e32 v10, v77, v77
	v_fmac_f32_e32 v10, v78, v78
	v_fmac_f32_e32 v10, v79, v79
	v_mul_f32_e32 v11, v96, v96
	v_fmac_f32_e32 v11, v97, v97
	v_fmac_f32_e32 v11, v98, v98
	v_fmac_f32_e32 v11, v99, v99
	v_fmac_f32_e32 v11, v100, v100
	v_fmac_f32_e32 v11, v101, v101
	v_fmac_f32_e32 v11, v102, v102
	v_fmac_f32_e32 v11, v103, v103
	v_fmac_f32_e32 v11, v104, v104
	v_fmac_f32_e32 v11, v105, v105
	v_fmac_f32_e32 v11, v106, v106
	v_fmac_f32_e32 v11, v107, v107
	v_fmac_f32_e32 v11, v108, v108
	v_fmac_f32_e32 v11, v109, v109
	v_fmac_f32_e32 v11, v110, v110
	v_fmac_f32_e32 v11, v111, v111
	ds_bpermute_b32 v12, v4, v10
	ds_bpermute_b32 v13, v4, v11
	s_waitcnt lgkmcnt(0)
	v_add_f32_e32 v10, v10, v12
	v_add_f32_e32 v11, v11, v13
	ds_bpermute_b32 v12, v5, v10
	ds_bpermute_b32 v13, v5, v11
	s_waitcnt lgkmcnt(0)
	v_add_f32_e32 v10, v10, v12
	v_add_f32_e32 v11, v11, v13
	ds_bpermute_b32 v12, v6, v10
	ds_bpermute_b32 v13, v6, v11
	s_waitcnt lgkmcnt(0)
	v_add_f32_e32 v10, v10, v12
	v_add_f32_e32 v11, v11, v13
	ds_bpermute_b32 v12, v7, v10
	ds_bpermute_b32 v13, v7, v11
	s_waitcnt lgkmcnt(0)
	v_add_f32_e32 v10, v10, v12
	v_add_f32_e32 v11, v11, v13
	ds_bpermute_b32 v12, v8, v10
	ds_bpermute_b32 v13, v8, v11
	s_waitcnt lgkmcnt(0)
	v_add_f32_e32 v10, v10, v12
	v_add_f32_e32 v11, v11, v13
	ds_bpermute_b32 v12, v9, v10
	ds_bpermute_b32 v13, v9, v11
	s_waitcnt lgkmcnt(0)
	v_add_f32_e32 v10, v10, v12
	v_add_f32_e32 v11, v11, v13
	v_fma_f32 v14, v10, s17, v3
	v_fma_f32 v15, v11, s17, v3
	v_rsq_f32_e32 v14, v14
	v_rsq_f32_e32 v15, v15
	s_nop 0
	v_mul_f32_e32 v64, v64, v14
	v_mul_f32_e32 v65, v65, v14
	v_mul_f32_e32 v66, v66, v14
	v_mul_f32_e32 v67, v67, v14
	v_mul_f32_e32 v68, v68, v14
	v_mul_f32_e32 v69, v69, v14
	v_mul_f32_e32 v70, v70, v14
	v_mul_f32_e32 v71, v71, v14
	v_mul_f32_e32 v72, v72, v14
	v_mul_f32_e32 v73, v73, v14
	v_mul_f32_e32 v74, v74, v14
	v_mul_f32_e32 v75, v75, v14
	v_mul_f32_e32 v76, v76, v14
	v_mul_f32_e32 v77, v77, v14
	v_mul_f32_e32 v78, v78, v14
	v_mul_f32_e32 v79, v79, v14
	v_fmac_f32_e32 v80, v64, v20
	v_fmac_f32_e32 v81, v65, v21
	v_fmac_f32_e32 v82, v66, v22
	v_fmac_f32_e32 v83, v67, v23
	v_fmac_f32_e32 v84, v68, v24
	v_fmac_f32_e32 v85, v69, v25
	v_fmac_f32_e32 v86, v70, v26
	v_fmac_f32_e32 v87, v71, v27
	v_fmac_f32_e32 v88, v72, v28
	v_fmac_f32_e32 v89, v73, v29
	v_fmac_f32_e32 v90, v74, v30
	v_fmac_f32_e32 v91, v75, v31
	v_fmac_f32_e32 v92, v76, v32
	v_fmac_f32_e32 v93, v77, v33
	v_fmac_f32_e32 v94, v78, v34
	v_fmac_f32_e32 v95, v79, v35
	global_store_dwordx4 v1, v[80:83], s[24:25] offset:0
	global_store_dwordx4 v1, v[84:87], s[24:25] offset:1024
	global_store_dwordx4 v1, v[88:91], s[24:25] offset:2048
	global_store_dwordx4 v1, v[92:95], s[24:25] offset:3072
	v_mul_f32_e32 v96, v96, v15
	v_mul_f32_e32 v97, v97, v15
	v_mul_f32_e32 v98, v98, v15
	v_mul_f32_e32 v99, v99, v15
	v_mul_f32_e32 v100, v100, v15
	v_mul_f32_e32 v101, v101, v15
	v_mul_f32_e32 v102, v102, v15
	v_mul_f32_e32 v103, v103, v15
	v_mul_f32_e32 v104, v104, v15
	v_mul_f32_e32 v105, v105, v15
	v_mul_f32_e32 v106, v106, v15
	v_mul_f32_e32 v107, v107, v15
	v_mul_f32_e32 v108, v108, v15
	v_mul_f32_e32 v109, v109, v15
	v_mul_f32_e32 v110, v110, v15
	v_mul_f32_e32 v111, v111, v15
	v_fmac_f32_e32 v112, v96, v20
	v_fmac_f32_e32 v113, v97, v21
	v_fmac_f32_e32 v114, v98, v22
	v_fmac_f32_e32 v115, v99, v23
	v_fmac_f32_e32 v116, v100, v24
	v_fmac_f32_e32 v117, v101, v25
	v_fmac_f32_e32 v118, v102, v26
	v_fmac_f32_e32 v119, v103, v27
	v_fmac_f32_e32 v120, v104, v28
	v_fmac_f32_e32 v121, v105, v29
	v_fmac_f32_e32 v122, v106, v30
	v_fmac_f32_e32 v123, v107, v31
	v_fmac_f32_e32 v124, v108, v32
	v_fmac_f32_e32 v125, v109, v33
	v_fmac_f32_e32 v126, v110, v34
	v_fmac_f32_e32 v127, v111, v35
	global_store_dwordx4 v1, v[112:115], s[32:33] offset:0
	global_store_dwordx4 v1, v[116:119], s[32:33] offset:1024
	global_store_dwordx4 v1, v[120:123], s[32:33] offset:2048
	global_store_dwordx4 v1, v[124:127], s[32:33] offset:3072
	s_add_u32 s53, s16, 0x2000
	s_lshl_b32 s18, s53, 12
	s_lshl_b32 s19, s53, 11
	s_add_u32 s20, s4, s18
	s_addc_u32 s21, s5, 0
	s_add_u32 s22, s6, s19
	s_addc_u32 s23, s7, 0
	s_add_u32 s22, s22, 0x5200000
	s_addc_u32 s23, s23, 0
	s_add_u32 s24, s4, s18
	s_addc_u32 s25, s5, 0
	global_load_dwordx2 v[66:67], v2, s[22:23] offset:0
	global_load_dwordx2 v[70:71], v2, s[22:23] offset:512
	global_load_dwordx2 v[74:75], v2, s[22:23] offset:1024
	global_load_dwordx2 v[78:79], v2, s[22:23] offset:1536
	global_load_dwordx4 v[80:83], v1, s[20:21] offset:0
	global_load_dwordx4 v[84:87], v1, s[20:21] offset:1024
	global_load_dwordx4 v[88:91], v1, s[20:21] offset:2048
	global_load_dwordx4 v[92:95], v1, s[20:21] offset:3072
	s_add_u32 s53, s16, 0x2800
	s_lshl_b32 s18, s53, 12
	s_lshl_b32 s19, s53, 11
	s_add_u32 s28, s4, s18
	s_addc_u32 s29, s5, 0
	s_add_u32 s30, s6, s19
	s_addc_u32 s31, s7, 0
	s_add_u32 s30, s30, 0x5200000
	s_addc_u32 s31, s31, 0
	s_add_u32 s32, s4, s18
	s_addc_u32 s33, s5, 0
	global_load_dwordx2 v[98:99], v2, s[30:31] offset:0
	global_load_dwordx2 v[102:103], v2, s[30:31] offset:512
	global_load_dwordx2 v[106:107], v2, s[30:31] offset:1024
	global_load_dwordx2 v[110:111], v2, s[30:31] offset:1536
	global_load_dwordx4 v[112:115], v1, s[28:29] offset:0
	global_load_dwordx4 v[116:119], v1, s[28:29] offset:1024
	global_load_dwordx4 v[120:123], v1, s[28:29] offset:2048
	global_load_dwordx4 v[124:127], v1, s[28:29] offset:3072
	s_waitcnt vmcnt(24)
	v_lshlrev_b32_e32 v128, 16, v130
	v_and_b32_e32 v129, 0xffff0000, v130
	v_lshlrev_b32_e32 v130, 16, v131
	v_and_b32_e32 v131, 0xffff0000, v131
	v_lshlrev_b32_e32 v132, 16, v134
	v_and_b32_e32 v133, 0xffff0000, v134
	v_lshlrev_b32_e32 v134, 16, v135
	v_and_b32_e32 v135, 0xffff0000, v135
	v_lshlrev_b32_e32 v136, 16, v138
	v_and_b32_e32 v137, 0xffff0000, v138
	v_lshlrev_b32_e32 v138, 16, v139
	v_and_b32_e32 v139, 0xffff0000, v139
	v_lshlrev_b32_e32 v140, 16, v142
	v_and_b32_e32 v141, 0xffff0000, v142
	v_lshlrev_b32_e32 v142, 16, v143
	v_and_b32_e32 v143, 0xffff0000, v143
	v_lshlrev_b32_e32 v160, 16, v162
	v_and_b32_e32 v161, 0xffff0000, v162
	v_lshlrev_b32_e32 v162, 16, v163
	v_and_b32_e32 v163, 0xffff0000, v163
	v_lshlrev_b32_e32 v164, 16, v166
	v_and_b32_e32 v165, 0xffff0000, v166
	v_lshlrev_b32_e32 v166, 16, v167
	v_and_b32_e32 v167, 0xffff0000, v167
	v_lshlrev_b32_e32 v168, 16, v170
	v_and_b32_e32 v169, 0xffff0000, v170
	v_lshlrev_b32_e32 v170, 16, v171
	v_and_b32_e32 v171, 0xffff0000, v171
	v_lshlrev_b32_e32 v172, 16, v174
	v_and_b32_e32 v173, 0xffff0000, v174
	v_lshlrev_b32_e32 v174, 16, v175
	v_and_b32_e32 v175, 0xffff0000, v175
	v_mul_f32_e32 v10, v128, v128
	v_fmac_f32_e32 v10, v129, v129
	v_fmac_f32_e32 v10, v130, v130
	v_fmac_f32_e32 v10, v131, v131
	v_fmac_f32_e32 v10, v132, v132
	v_fmac_f32_e32 v10, v133, v133
	v_fmac_f32_e32 v10, v134, v134
	v_fmac_f32_e32 v10, v135, v135
	v_fmac_f32_e32 v10, v136, v136
	v_fmac_f32_e32 v10, v137, v137
	v_fmac_f32_e32 v10, v138, v138
	v_fmac_f32_e32 v10, v139, v139
	v_fmac_f32_e32 v10, v140, v140
	v_fmac_f32_e32 v10, v141, v141
	v_fmac_f32_e32 v10, v142, v142
	v_fmac_f32_e32 v10, v143, v143
	v_mul_f32_e32 v11, v160, v160
	v_fmac_f32_e32 v11, v161, v161
	v_fmac_f32_e32 v11, v162, v162
	v_fmac_f32_e32 v11, v163, v163
	v_fmac_f32_e32 v11, v164, v164
	v_fmac_f32_e32 v11, v165, v165
	v_fmac_f32_e32 v11, v166, v166
	v_fmac_f32_e32 v11, v167, v167
	v_fmac_f32_e32 v11, v168, v168
	v_fmac_f32_e32 v11, v169, v169
	v_fmac_f32_e32 v11, v170, v170
	v_fmac_f32_e32 v11, v171, v171
	v_fmac_f32_e32 v11, v172, v172
	v_fmac_f32_e32 v11, v173, v173
	v_fmac_f32_e32 v11, v174, v174
	v_fmac_f32_e32 v11, v175, v175
	ds_bpermute_b32 v12, v4, v10
	ds_bpermute_b32 v13, v4, v11
	s_waitcnt lgkmcnt(0)
	v_add_f32_e32 v10, v10, v12
	v_add_f32_e32 v11, v11, v13
	ds_bpermute_b32 v12, v5, v10
	ds_bpermute_b32 v13, v5, v11
	s_waitcnt lgkmcnt(0)
	v_add_f32_e32 v10, v10, v12
	v_add_f32_e32 v11, v11, v13
	ds_bpermute_b32 v12, v6, v10
	ds_bpermute_b32 v13, v6, v11
	s_waitcnt lgkmcnt(0)
	v_add_f32_e32 v10, v10, v12
	v_add_f32_e32 v11, v11, v13
	ds_bpermute_b32 v12, v7, v10
	ds_bpermute_b32 v13, v7, v11
	s_waitcnt lgkmcnt(0)
	v_add_f32_e32 v10, v10, v12
	v_add_f32_e32 v11, v11, v13
	ds_bpermute_b32 v12, v8, v10
	ds_bpermute_b32 v13, v8, v11
	s_waitcnt lgkmcnt(0)
	v_add_f32_e32 v10, v10, v12
	v_add_f32_e32 v11, v11, v13
	ds_bpermute_b32 v12, v9, v10
	ds_bpermute_b32 v13, v9, v11
	s_waitcnt lgkmcnt(0)
	v_add_f32_e32 v10, v10, v12
	v_add_f32_e32 v11, v11, v13
	v_fma_f32 v14, v10, s17, v3
	v_fma_f32 v15, v11, s17, v3
	v_rsq_f32_e32 v14, v14
	v_rsq_f32_e32 v15, v15
	s_nop 0
	v_mul_f32_e32 v128, v128, v14
	v_mul_f32_e32 v129, v129, v14
	v_mul_f32_e32 v130, v130, v14
	v_mul_f32_e32 v131, v131, v14
	v_mul_f32_e32 v132, v132, v14
	v_mul_f32_e32 v133, v133, v14
	v_mul_f32_e32 v134, v134, v14
	v_mul_f32_e32 v135, v135, v14
	v_mul_f32_e32 v136, v136, v14
	v_mul_f32_e32 v137, v137, v14
	v_mul_f32_e32 v138, v138, v14
	v_mul_f32_e32 v139, v139, v14
	v_mul_f32_e32 v140, v140, v14
	v_mul_f32_e32 v141, v141, v14
	v_mul_f32_e32 v142, v142, v14
	v_mul_f32_e32 v143, v143, v14
	v_fmac_f32_e32 v144, v128, v20
	v_fmac_f32_e32 v145, v129, v21
	v_fmac_f32_e32 v146, v130, v22
	v_fmac_f32_e32 v147, v131, v23
	v_fmac_f32_e32 v148, v132, v24
	v_fmac_f32_e32 v149, v133, v25
	v_fmac_f32_e32 v150, v134, v26
	v_fmac_f32_e32 v151, v135, v27
	v_fmac_f32_e32 v152, v136, v28
	v_fmac_f32_e32 v153, v137, v29
	v_fmac_f32_e32 v154, v138, v30
	v_fmac_f32_e32 v155, v139, v31
	v_fmac_f32_e32 v156, v140, v32
	v_fmac_f32_e32 v157, v141, v33
	v_fmac_f32_e32 v158, v142, v34
	v_fmac_f32_e32 v159, v143, v35
	global_store_dwordx4 v1, v[144:147], s[40:41] offset:0
	global_store_dwordx4 v1, v[148:151], s[40:41] offset:1024
	global_store_dwordx4 v1, v[152:155], s[40:41] offset:2048
	global_store_dwordx4 v1, v[156:159], s[40:41] offset:3072
	v_mul_f32_e32 v160, v160, v15
	v_mul_f32_e32 v161, v161, v15
	v_mul_f32_e32 v162, v162, v15
	v_mul_f32_e32 v163, v163, v15
	v_mul_f32_e32 v164, v164, v15
	v_mul_f32_e32 v165, v165, v15
	v_mul_f32_e32 v166, v166, v15
	v_mul_f32_e32 v167, v167, v15
	v_mul_f32_e32 v168, v168, v15
	v_mul_f32_e32 v169, v169, v15
	v_mul_f32_e32 v170, v170, v15
	v_mul_f32_e32 v171, v171, v15
	v_mul_f32_e32 v172, v172, v15
	v_mul_f32_e32 v173, v173, v15
	v_mul_f32_e32 v174, v174, v15
	v_mul_f32_e32 v175, v175, v15
	v_fmac_f32_e32 v176, v160, v20
	v_fmac_f32_e32 v177, v161, v21
	v_fmac_f32_e32 v178, v162, v22
	v_fmac_f32_e32 v179, v163, v23
	v_fmac_f32_e32 v180, v164, v24
	v_fmac_f32_e32 v181, v165, v25
	v_fmac_f32_e32 v182, v166, v26
	v_fmac_f32_e32 v183, v167, v27
	v_fmac_f32_e32 v184, v168, v28
	v_fmac_f32_e32 v185, v169, v29
	v_fmac_f32_e32 v186, v170, v30
	v_fmac_f32_e32 v187, v171, v31
	v_fmac_f32_e32 v188, v172, v32
	v_fmac_f32_e32 v189, v173, v33
	v_fmac_f32_e32 v190, v174, v34
	v_fmac_f32_e32 v191, v175, v35
	global_store_dwordx4 v1, v[176:179], s[48:49] offset:0
	global_store_dwordx4 v1, v[180:183], s[48:49] offset:1024
	global_store_dwordx4 v1, v[184:187], s[48:49] offset:2048
	global_store_dwordx4 v1, v[188:191], s[48:49] offset:3072
	s_add_u32 s53, s16, 0x3000
	s_lshl_b32 s18, s53, 12
	s_lshl_b32 s19, s53, 11
	s_add_u32 s36, s4, s18
	s_addc_u32 s37, s5, 0
	s_add_u32 s38, s6, s19
	s_addc_u32 s39, s7, 0
	s_add_u32 s38, s38, 0x5200000
	s_addc_u32 s39, s39, 0
	s_add_u32 s40, s4, s18
	s_addc_u32 s41, s5, 0
	global_load_dwordx2 v[130:131], v2, s[38:39] offset:0
	global_load_dwordx2 v[134:135], v2, s[38:39] offset:512
	global_load_dwordx2 v[138:139], v2, s[38:39] offset:1024
	global_load_dwordx2 v[142:143], v2, s[38:39] offset:1536
	global_load_dwordx4 v[144:147], v1, s[36:37] offset:0
	global_load_dwordx4 v[148:151], v1, s[36:37] offset:1024
	global_load_dwordx4 v[152:155], v1, s[36:37] offset:2048
	global_load_dwordx4 v[156:159], v1, s[36:37] offset:3072
	s_add_u32 s53, s16, 0x3800
	s_lshl_b32 s18, s53, 12
	s_lshl_b32 s19, s53, 11
	s_add_u32 s44, s4, s18
	s_addc_u32 s45, s5, 0
	s_add_u32 s46, s6, s19
	s_addc_u32 s47, s7, 0
	s_add_u32 s46, s46, 0x5200000
	s_addc_u32 s47, s47, 0
	s_add_u32 s48, s4, s18
	s_addc_u32 s49, s5, 0
	global_load_dwordx2 v[162:163], v2, s[46:47] offset:0
	global_load_dwordx2 v[166:167], v2, s[46:47] offset:512
	global_load_dwordx2 v[170:171], v2, s[46:47] offset:1024
	global_load_dwordx2 v[174:175], v2, s[46:47] offset:1536
	global_load_dwordx4 v[176:179], v1, s[44:45] offset:0
	global_load_dwordx4 v[180:183], v1, s[44:45] offset:1024
	global_load_dwordx4 v[184:187], v1, s[44:45] offset:2048
	global_load_dwordx4 v[188:191], v1, s[44:45] offset:3072
	s_waitcnt vmcnt(24)
	v_lshlrev_b32_e32 v64, 16, v66
	v_and_b32_e32 v65, 0xffff0000, v66
	v_lshlrev_b32_e32 v66, 16, v67
	v_and_b32_e32 v67, 0xffff0000, v67
	v_lshlrev_b32_e32 v68, 16, v70
	v_and_b32_e32 v69, 0xffff0000, v70
	v_lshlrev_b32_e32 v70, 16, v71
	v_and_b32_e32 v71, 0xffff0000, v71
	v_lshlrev_b32_e32 v72, 16, v74
	v_and_b32_e32 v73, 0xffff0000, v74
	v_lshlrev_b32_e32 v74, 16, v75
	v_and_b32_e32 v75, 0xffff0000, v75
	v_lshlrev_b32_e32 v76, 16, v78
	v_and_b32_e32 v77, 0xffff0000, v78
	v_lshlrev_b32_e32 v78, 16, v79
	v_and_b32_e32 v79, 0xffff0000, v79
	v_lshlrev_b32_e32 v96, 16, v98
	v_and_b32_e32 v97, 0xffff0000, v98
	v_lshlrev_b32_e32 v98, 16, v99
	v_and_b32_e32 v99, 0xffff0000, v99
	v_lshlrev_b32_e32 v100, 16, v102
	v_and_b32_e32 v101, 0xffff0000, v102
	v_lshlrev_b32_e32 v102, 16, v103
	v_and_b32_e32 v103, 0xffff0000, v103
	v_lshlrev_b32_e32 v104, 16, v106
	v_and_b32_e32 v105, 0xffff0000, v106
	v_lshlrev_b32_e32 v106, 16, v107
	v_and_b32_e32 v107, 0xffff0000, v107
	v_lshlrev_b32_e32 v108, 16, v110
	v_and_b32_e32 v109, 0xffff0000, v110
	v_lshlrev_b32_e32 v110, 16, v111
	v_and_b32_e32 v111, 0xffff0000, v111
	v_mul_f32_e32 v10, v64, v64
	v_fmac_f32_e32 v10, v65, v65
	v_fmac_f32_e32 v10, v66, v66
	v_fmac_f32_e32 v10, v67, v67
	v_fmac_f32_e32 v10, v68, v68
	v_fmac_f32_e32 v10, v69, v69
	v_fmac_f32_e32 v10, v70, v70
	v_fmac_f32_e32 v10, v71, v71
	v_fmac_f32_e32 v10, v72, v72
	v_fmac_f32_e32 v10, v73, v73
	v_fmac_f32_e32 v10, v74, v74
	v_fmac_f32_e32 v10, v75, v75
	v_fmac_f32_e32 v10, v76, v76
	v_fmac_f32_e32 v10, v77, v77
	v_fmac_f32_e32 v10, v78, v78
	v_fmac_f32_e32 v10, v79, v79
	v_mul_f32_e32 v11, v96, v96
	v_fmac_f32_e32 v11, v97, v97
	v_fmac_f32_e32 v11, v98, v98
	v_fmac_f32_e32 v11, v99, v99
	v_fmac_f32_e32 v11, v100, v100
	v_fmac_f32_e32 v11, v101, v101
	v_fmac_f32_e32 v11, v102, v102
	v_fmac_f32_e32 v11, v103, v103
	v_fmac_f32_e32 v11, v104, v104
	v_fmac_f32_e32 v11, v105, v105
	v_fmac_f32_e32 v11, v106, v106
	v_fmac_f32_e32 v11, v107, v107
	v_fmac_f32_e32 v11, v108, v108
	v_fmac_f32_e32 v11, v109, v109
	v_fmac_f32_e32 v11, v110, v110
	v_fmac_f32_e32 v11, v111, v111
	ds_bpermute_b32 v12, v4, v10
	ds_bpermute_b32 v13, v4, v11
	s_waitcnt lgkmcnt(0)
	v_add_f32_e32 v10, v10, v12
	v_add_f32_e32 v11, v11, v13
	ds_bpermute_b32 v12, v5, v10
	ds_bpermute_b32 v13, v5, v11
	s_waitcnt lgkmcnt(0)
	v_add_f32_e32 v10, v10, v12
	v_add_f32_e32 v11, v11, v13
	ds_bpermute_b32 v12, v6, v10
	ds_bpermute_b32 v13, v6, v11
	s_waitcnt lgkmcnt(0)
	v_add_f32_e32 v10, v10, v12
	v_add_f32_e32 v11, v11, v13
	ds_bpermute_b32 v12, v7, v10
	ds_bpermute_b32 v13, v7, v11
	s_waitcnt lgkmcnt(0)
	v_add_f32_e32 v10, v10, v12
	v_add_f32_e32 v11, v11, v13
	ds_bpermute_b32 v12, v8, v10
	ds_bpermute_b32 v13, v8, v11
	s_waitcnt lgkmcnt(0)
	v_add_f32_e32 v10, v10, v12
	v_add_f32_e32 v11, v11, v13
	ds_bpermute_b32 v12, v9, v10
	ds_bpermute_b32 v13, v9, v11
	s_waitcnt lgkmcnt(0)
	v_add_f32_e32 v10, v10, v12
	v_add_f32_e32 v11, v11, v13
	v_fma_f32 v14, v10, s17, v3
	v_fma_f32 v15, v11, s17, v3
	v_rsq_f32_e32 v14, v14
	v_rsq_f32_e32 v15, v15
	s_nop 0
	v_mul_f32_e32 v64, v64, v14
	v_mul_f32_e32 v65, v65, v14
	v_mul_f32_e32 v66, v66, v14
	v_mul_f32_e32 v67, v67, v14
	v_mul_f32_e32 v68, v68, v14
	v_mul_f32_e32 v69, v69, v14
	v_mul_f32_e32 v70, v70, v14
	v_mul_f32_e32 v71, v71, v14
	v_mul_f32_e32 v72, v72, v14
	v_mul_f32_e32 v73, v73, v14
	v_mul_f32_e32 v74, v74, v14
	v_mul_f32_e32 v75, v75, v14
	v_mul_f32_e32 v76, v76, v14
	v_mul_f32_e32 v77, v77, v14
	v_mul_f32_e32 v78, v78, v14
	v_mul_f32_e32 v79, v79, v14
	v_fmac_f32_e32 v80, v64, v20
	v_fmac_f32_e32 v81, v65, v21
	v_fmac_f32_e32 v82, v66, v22
	v_fmac_f32_e32 v83, v67, v23
	v_fmac_f32_e32 v84, v68, v24
	v_fmac_f32_e32 v85, v69, v25
	v_fmac_f32_e32 v86, v70, v26
	v_fmac_f32_e32 v87, v71, v27
	v_fmac_f32_e32 v88, v72, v28
	v_fmac_f32_e32 v89, v73, v29
	v_fmac_f32_e32 v90, v74, v30
	v_fmac_f32_e32 v91, v75, v31
	v_fmac_f32_e32 v92, v76, v32
	v_fmac_f32_e32 v93, v77, v33
	v_fmac_f32_e32 v94, v78, v34
	v_fmac_f32_e32 v95, v79, v35
	global_store_dwordx4 v1, v[80:83], s[24:25] offset:0
	global_store_dwordx4 v1, v[84:87], s[24:25] offset:1024
	global_store_dwordx4 v1, v[88:91], s[24:25] offset:2048
	global_store_dwordx4 v1, v[92:95], s[24:25] offset:3072
	v_mul_f32_e32 v96, v96, v15
	v_mul_f32_e32 v97, v97, v15
	v_mul_f32_e32 v98, v98, v15
	v_mul_f32_e32 v99, v99, v15
	v_mul_f32_e32 v100, v100, v15
	v_mul_f32_e32 v101, v101, v15
	v_mul_f32_e32 v102, v102, v15
	v_mul_f32_e32 v103, v103, v15
	v_mul_f32_e32 v104, v104, v15
	v_mul_f32_e32 v105, v105, v15
	v_mul_f32_e32 v106, v106, v15
	v_mul_f32_e32 v107, v107, v15
	v_mul_f32_e32 v108, v108, v15
	v_mul_f32_e32 v109, v109, v15
	v_mul_f32_e32 v110, v110, v15
	v_mul_f32_e32 v111, v111, v15
	v_fmac_f32_e32 v112, v96, v20
	v_fmac_f32_e32 v113, v97, v21
	v_fmac_f32_e32 v114, v98, v22
	v_fmac_f32_e32 v115, v99, v23
	v_fmac_f32_e32 v116, v100, v24
	v_fmac_f32_e32 v117, v101, v25
	v_fmac_f32_e32 v118, v102, v26
	v_fmac_f32_e32 v119, v103, v27
	v_fmac_f32_e32 v120, v104, v28
	v_fmac_f32_e32 v121, v105, v29
	v_fmac_f32_e32 v122, v106, v30
	v_fmac_f32_e32 v123, v107, v31
	v_fmac_f32_e32 v124, v108, v32
	v_fmac_f32_e32 v125, v109, v33
	v_fmac_f32_e32 v126, v110, v34
	v_fmac_f32_e32 v127, v111, v35
	global_store_dwordx4 v1, v[112:115], s[32:33] offset:0
	global_store_dwordx4 v1, v[116:119], s[32:33] offset:1024
	global_store_dwordx4 v1, v[120:123], s[32:33] offset:2048
	global_store_dwordx4 v1, v[124:127], s[32:33] offset:3072
	s_waitcnt vmcnt(8)
	v_lshlrev_b32_e32 v128, 16, v130
	v_and_b32_e32 v129, 0xffff0000, v130
	v_lshlrev_b32_e32 v130, 16, v131
	v_and_b32_e32 v131, 0xffff0000, v131
	v_lshlrev_b32_e32 v132, 16, v134
	v_and_b32_e32 v133, 0xffff0000, v134
	v_lshlrev_b32_e32 v134, 16, v135
	v_and_b32_e32 v135, 0xffff0000, v135
	v_lshlrev_b32_e32 v136, 16, v138
	v_and_b32_e32 v137, 0xffff0000, v138
	v_lshlrev_b32_e32 v138, 16, v139
	v_and_b32_e32 v139, 0xffff0000, v139
	v_lshlrev_b32_e32 v140, 16, v142
	v_and_b32_e32 v141, 0xffff0000, v142
	v_lshlrev_b32_e32 v142, 16, v143
	v_and_b32_e32 v143, 0xffff0000, v143
	v_lshlrev_b32_e32 v160, 16, v162
	v_and_b32_e32 v161, 0xffff0000, v162
	v_lshlrev_b32_e32 v162, 16, v163
	v_and_b32_e32 v163, 0xffff0000, v163
	v_lshlrev_b32_e32 v164, 16, v166
	v_and_b32_e32 v165, 0xffff0000, v166
	v_lshlrev_b32_e32 v166, 16, v167
	v_and_b32_e32 v167, 0xffff0000, v167
	v_lshlrev_b32_e32 v168, 16, v170
	v_and_b32_e32 v169, 0xffff0000, v170
	v_lshlrev_b32_e32 v170, 16, v171
	v_and_b32_e32 v171, 0xffff0000, v171
	v_lshlrev_b32_e32 v172, 16, v174
	v_and_b32_e32 v173, 0xffff0000, v174
	v_lshlrev_b32_e32 v174, 16, v175
	v_and_b32_e32 v175, 0xffff0000, v175
	v_mul_f32_e32 v10, v128, v128
	v_fmac_f32_e32 v10, v129, v129
	v_fmac_f32_e32 v10, v130, v130
	v_fmac_f32_e32 v10, v131, v131
	v_fmac_f32_e32 v10, v132, v132
	v_fmac_f32_e32 v10, v133, v133
	v_fmac_f32_e32 v10, v134, v134
	v_fmac_f32_e32 v10, v135, v135
	v_fmac_f32_e32 v10, v136, v136
	v_fmac_f32_e32 v10, v137, v137
	v_fmac_f32_e32 v10, v138, v138
	v_fmac_f32_e32 v10, v139, v139
	v_fmac_f32_e32 v10, v140, v140
	v_fmac_f32_e32 v10, v141, v141
	v_fmac_f32_e32 v10, v142, v142
	v_fmac_f32_e32 v10, v143, v143
	v_mul_f32_e32 v11, v160, v160
	v_fmac_f32_e32 v11, v161, v161
	v_fmac_f32_e32 v11, v162, v162
	v_fmac_f32_e32 v11, v163, v163
	v_fmac_f32_e32 v11, v164, v164
	v_fmac_f32_e32 v11, v165, v165
	v_fmac_f32_e32 v11, v166, v166
	v_fmac_f32_e32 v11, v167, v167
	v_fmac_f32_e32 v11, v168, v168
	v_fmac_f32_e32 v11, v169, v169
	v_fmac_f32_e32 v11, v170, v170
	v_fmac_f32_e32 v11, v171, v171
	v_fmac_f32_e32 v11, v172, v172
	v_fmac_f32_e32 v11, v173, v173
	v_fmac_f32_e32 v11, v174, v174
	v_fmac_f32_e32 v11, v175, v175
	ds_bpermute_b32 v12, v4, v10
	ds_bpermute_b32 v13, v4, v11
	s_waitcnt lgkmcnt(0)
	v_add_f32_e32 v10, v10, v12
	v_add_f32_e32 v11, v11, v13
	ds_bpermute_b32 v12, v5, v10
	ds_bpermute_b32 v13, v5, v11
	s_waitcnt lgkmcnt(0)
	v_add_f32_e32 v10, v10, v12
	v_add_f32_e32 v11, v11, v13
	ds_bpermute_b32 v12, v6, v10
	ds_bpermute_b32 v13, v6, v11
	s_waitcnt lgkmcnt(0)
	v_add_f32_e32 v10, v10, v12
	v_add_f32_e32 v11, v11, v13
	ds_bpermute_b32 v12, v7, v10
	ds_bpermute_b32 v13, v7, v11
	s_waitcnt lgkmcnt(0)
	v_add_f32_e32 v10, v10, v12
	v_add_f32_e32 v11, v11, v13
	ds_bpermute_b32 v12, v8, v10
	ds_bpermute_b32 v13, v8, v11
	s_waitcnt lgkmcnt(0)
	v_add_f32_e32 v10, v10, v12
	v_add_f32_e32 v11, v11, v13
	ds_bpermute_b32 v12, v9, v10
	ds_bpermute_b32 v13, v9, v11
	s_waitcnt lgkmcnt(0)
	v_add_f32_e32 v10, v10, v12
	v_add_f32_e32 v11, v11, v13
	v_fma_f32 v14, v10, s17, v3
	v_fma_f32 v15, v11, s17, v3
	v_rsq_f32_e32 v14, v14
	v_rsq_f32_e32 v15, v15
	s_nop 0
	v_mul_f32_e32 v128, v128, v14
	v_mul_f32_e32 v129, v129, v14
	v_mul_f32_e32 v130, v130, v14
	v_mul_f32_e32 v131, v131, v14
	v_mul_f32_e32 v132, v132, v14
	v_mul_f32_e32 v133, v133, v14
	v_mul_f32_e32 v134, v134, v14
	v_mul_f32_e32 v135, v135, v14
	v_mul_f32_e32 v136, v136, v14
	v_mul_f32_e32 v137, v137, v14
	v_mul_f32_e32 v138, v138, v14
	v_mul_f32_e32 v139, v139, v14
	v_mul_f32_e32 v140, v140, v14
	v_mul_f32_e32 v141, v141, v14
	v_mul_f32_e32 v142, v142, v14
	v_mul_f32_e32 v143, v143, v14
	v_fmac_f32_e32 v144, v128, v20
	v_fmac_f32_e32 v145, v129, v21
	v_fmac_f32_e32 v146, v130, v22
	v_fmac_f32_e32 v147, v131, v23
	v_fmac_f32_e32 v148, v132, v24
	v_fmac_f32_e32 v149, v133, v25
	v_fmac_f32_e32 v150, v134, v26
	v_fmac_f32_e32 v151, v135, v27
	v_fmac_f32_e32 v152, v136, v28
	v_fmac_f32_e32 v153, v137, v29
	v_fmac_f32_e32 v154, v138, v30
	v_fmac_f32_e32 v155, v139, v31
	v_fmac_f32_e32 v156, v140, v32
	v_fmac_f32_e32 v157, v141, v33
	v_fmac_f32_e32 v158, v142, v34
	v_fmac_f32_e32 v159, v143, v35
	global_store_dwordx4 v1, v[144:147], s[40:41] offset:0
	global_store_dwordx4 v1, v[148:151], s[40:41] offset:1024
	global_store_dwordx4 v1, v[152:155], s[40:41] offset:2048
	global_store_dwordx4 v1, v[156:159], s[40:41] offset:3072
	v_mul_f32_e32 v160, v160, v15
	v_mul_f32_e32 v161, v161, v15
	v_mul_f32_e32 v162, v162, v15
	v_mul_f32_e32 v163, v163, v15
	v_mul_f32_e32 v164, v164, v15
	v_mul_f32_e32 v165, v165, v15
	v_mul_f32_e32 v166, v166, v15
	v_mul_f32_e32 v167, v167, v15
	v_mul_f32_e32 v168, v168, v15
	v_mul_f32_e32 v169, v169, v15
	v_mul_f32_e32 v170, v170, v15
	v_mul_f32_e32 v171, v171, v15
	v_mul_f32_e32 v172, v172, v15
	v_mul_f32_e32 v173, v173, v15
	v_mul_f32_e32 v174, v174, v15
	v_mul_f32_e32 v175, v175, v15
	v_fmac_f32_e32 v176, v160, v20
	v_fmac_f32_e32 v177, v161, v21
	v_fmac_f32_e32 v178, v162, v22
	v_fmac_f32_e32 v179, v163, v23
	v_fmac_f32_e32 v180, v164, v24
	v_fmac_f32_e32 v181, v165, v25
	v_fmac_f32_e32 v182, v166, v26
	v_fmac_f32_e32 v183, v167, v27
	v_fmac_f32_e32 v184, v168, v28
	v_fmac_f32_e32 v185, v169, v29
	v_fmac_f32_e32 v186, v170, v30
	v_fmac_f32_e32 v187, v171, v31
	v_fmac_f32_e32 v188, v172, v32
	v_fmac_f32_e32 v189, v173, v33
	v_fmac_f32_e32 v190, v174, v34
	v_fmac_f32_e32 v191, v175, v35
	global_store_dwordx4 v1, v[176:179], s[48:49] offset:0
	global_store_dwordx4 v1, v[180:183], s[48:49] offset:1024
	global_store_dwordx4 v1, v[184:187], s[48:49] offset:2048
	global_store_dwordx4 v1, v[188:191], s[48:49] offset:3072
	v_add_f32_e32 v208, v208, v212
	v_add_f32_e32 v209, v209, v213
	v_add_f32_e32 v210, v210, v214
	v_add_f32_e32 v211, v211, v215
	v_add_f32_e32 v216, v216, v220
	v_add_f32_e32 v217, v217, v221
	v_add_f32_e32 v218, v218, v222
	v_add_f32_e32 v219, v219, v223
	v_add_f32_e32 v224, v224, v228
	v_add_f32_e32 v225, v225, v229
	v_add_f32_e32 v226, v226, v230
	v_add_f32_e32 v227, v227, v231
	v_add_f32_e32 v232, v232, v236
	v_add_f32_e32 v233, v233, v237
	v_add_f32_e32 v234, v234, v238
	v_add_f32_e32 v235, v235, v239
	v_add_f32_e32 v208, v208, v216
	v_add_f32_e32 v209, v209, v217
	v_add_f32_e32 v210, v210, v218
	v_add_f32_e32 v211, v211, v219
	v_add_f32_e32 v224, v224, v232
	v_add_f32_e32 v225, v225, v233
	v_add_f32_e32 v226, v226, v234
	v_add_f32_e32 v227, v227, v235
	v_add_f32_e32 v208, v208, v224
	v_add_f32_e32 v209, v209, v225
	v_add_f32_e32 v210, v210, v226
	v_add_f32_e32 v211, v211, v227
	v_readfirstlane_b32 s18, v0
	s_lshr_b32 s18, s18, 6
	s_lshl_b32 s19, s18, 2
	s_and_b32 s52, s18, 4
	s_lshl_b32 s52, s52, 2
	v_mov_b32_e32 v16, s19
	v_mov_b32_e32 v17, s52
	v_mul_f32_e32 v10, v208, v208
	v_fmac_f32_e32 v10, v209, v209
	v_fmac_f32_e32 v10, v210, v210
	v_fmac_f32_e32 v10, v211, v211
	ds_bpermute_b32 v11, v4, v10
	s_waitcnt lgkmcnt(0)
	v_add_f32_e32 v10, v10, v11
	ds_bpermute_b32 v11, v5, v10
	s_waitcnt lgkmcnt(0)
	v_add_f32_e32 v10, v10, v11
	ds_bpermute_b32 v11, v6, v10
	s_waitcnt lgkmcnt(0)
	v_add_f32_e32 v10, v10, v11
	ds_bpermute_b32 v11, v7, v10
	s_waitcnt lgkmcnt(0)
	v_add_f32_e32 v10, v10, v11
	ds_bpermute_b32 v11, v8, v10
	s_waitcnt lgkmcnt(0)
	v_add_f32_e32 v10, v10, v11
	ds_bpermute_b32 v11, v9, v10
	s_waitcnt lgkmcnt(0)
	v_add_f32_e32 v10, v10, v11
	ds_write_b32 v16, v10 offset:0
	s_waitcnt lgkmcnt(0)
	s_barrier
	ds_read_b128 v[12:15], v17 offset:0
	s_waitcnt lgkmcnt(0)
	v_add_f32_e32 v12, v12, v13
	v_add_f32_e32 v14, v14, v15
	v_add_f32_e32 v10, v12, v14
	v_fma_f32 v11, v10, s17, v3
	v_rsq_f32_e32 v11, v11
	s_nop 0
	v_mul_f32_e32 v208, v208, v11
	v_mul_f32_e32 v209, v209, v11
	v_mul_f32_e32 v210, v210, v11
	v_mul_f32_e32 v211, v211, v11
	v_fmac_f32_e32 v240, v208, v244
	v_fmac_f32_e32 v241, v209, v245
	v_fmac_f32_e32 v242, v210, v246
	v_fmac_f32_e32 v243, v211, v247
	s_lshl_b32 s18, s54, 12
	s_add_u32 s18, s18, s55
	s_add_u32 s56, s4, s18
	s_addc_u32 s57, s5, 0
	s_add_u32 s56, s56, 0x4000000
	s_addc_u32 s57, s57, 0
	global_store_dwordx4 v1, v[240:243], s[56:57]

	.amdhsa_kernel _Z10fwd_kernelILi14ELi15EEv4Args
		.amdhsa_group_segment_fixed_size 0
		.amdhsa_private_segment_fixed_size 0
		.amdhsa_kernarg_size 488
		.amdhsa_user_sgpr_count 2
		.amdhsa_user_sgpr_dispatch_ptr 0
		.amdhsa_user_sgpr_queue_ptr 0
		.amdhsa_user_sgpr_kernarg_segment_ptr 1
		.amdhsa_user_sgpr_dispatch_id 0
		.amdhsa_user_sgpr_kernarg_preload_length 0
		.amdhsa_user_sgpr_kernarg_preload_offset 0
		.amdhsa_user_sgpr_private_segment_size 0
		.amdhsa_uses_dynamic_stack 0
		.amdhsa_enable_private_segment 0
		.amdhsa_system_sgpr_workgroup_id_x 1
		.amdhsa_system_sgpr_workgroup_id_y 0
		.amdhsa_system_sgpr_workgroup_id_z 0
		.amdhsa_system_sgpr_workgroup_info 0
		.amdhsa_system_vgpr_workitem_id 0
		.amdhsa_next_free_vgpr 256
		.amdhsa_next_free_sgpr 60
		.amdhsa_accum_offset 256
		.amdhsa_reserve_vcc 1
		.amdhsa_float_round_mode_32 0
		.amdhsa_float_round_mode_16_64 0
		.amdhsa_float_denorm_mode_32 3
		.amdhsa_float_denorm_mode_16_64 3
		.amdhsa_dx10_clamp 1
		.amdhsa_ieee_mode 1
		.amdhsa_fp16_overflow 0
		.amdhsa_tg_split 0
		.amdhsa_exception_fp_ieee_invalid_op 0
		.amdhsa_exception_fp_denorm_src 0
		.amdhsa_exception_fp_ieee_div_zero 0
		.amdhsa_exception_fp_ieee_overflow 0
		.amdhsa_exception_fp_ieee_underflow 0
		.amdhsa_exception_fp_ieee_inexact 0
		.amdhsa_exception_int_div_zero 0
	.end_amdhsa_kernel

amdhsa.kernels:
  - .agpr_count:     0
    .args:
      - .offset:         0
        .size:           232
        .value_kind:     by_value
      - .offset:         232
        .size:           4
        .value_kind:     hidden_block_count_x
      - .offset:         236
        .size:           4
        .value_kind:     hidden_block_count_y
      - .offset:         240
        .size:           4
        .value_kind:     hidden_block_count_z
      - .offset:         244
        .size:           2
        .value_kind:     hidden_group_size_x
      - .offset:         246
        .size:           2
        .value_kind:     hidden_group_size_y
      - .offset:         248
        .size:           2
        .value_kind:     hidden_group_size_z
      - .offset:         250
        .size:           2
        .value_kind:     hidden_remainder_x
      - .offset:         252
        .size:           2
        .value_kind:     hidden_remainder_y
      - .offset:         254
        .size:           2
        .value_kind:     hidden_remainder_z
      - .offset:         272
        .size:           8
        .value_kind:     hidden_global_offset_x
      - .offset:         280
        .size:           8
        .value_kind:     hidden_global_offset_y
      - .offset:         288
        .size:           8
        .value_kind:     hidden_global_offset_z
      - .offset:         296
        .size:           2
        .value_kind:     hidden_grid_dims
      - .offset:         352
        .size:           4
        .value_kind:     hidden_dynamic_lds_size
    .group_segment_fixed_size: 0
    .kernarg_segment_align: 8
    .kernarg_segment_size: 488
    .language:       OpenCL C
    .language_version:
      - 2
      - 0
    .max_flat_workgroup_size: 512
    .name:           _Z10fwd_kernelILi0ELi1EEv4Args
    .private_segment_fixed_size: 0
    .sgpr_count:     106
    .sgpr_spill_count: 0
    .symbol:         _Z10fwd_kernelILi0ELi1EEv4Args.kd
    .uniform_work_group_size: 1
    .uses_dynamic_stack: false
    .vgpr_count:     224
    .vgpr_spill_count: 0
    .wavefront_size: 64
  - .agpr_count:     0
    .args:
      - .offset:         0
        .size:           232
        .value_kind:     by_value
      - .offset:         232
        .size:           4
        .value_kind:     hidden_block_count_x
      - .offset:         236
        .size:           4
        .value_kind:     hidden_block_count_y
      - .offset:         240
        .size:           4
        .value_kind:     hidden_block_count_z
      - .offset:         244
        .size:           2
        .value_kind:     hidden_group_size_x
      - .offset:         246
        .size:           2
        .value_kind:     hidden_group_size_y
      - .offset:         248
        .size:           2
        .value_kind:     hidden_group_size_z
      - .offset:         250
        .size:           2
        .value_kind:     hidden_remainder_x
      - .offset:         252
        .size:           2
        .value_kind:     hidden_remainder_y
      - .offset:         254
        .size:           2
        .value_kind:     hidden_remainder_z
      - .offset:         272
        .size:           8
        .value_kind:     hidden_global_offset_x
      - .offset:         280
        .size:           8
        .value_kind:     hidden_global_offset_y
      - .offset:         288
        .size:           8
        .value_kind:     hidden_global_offset_z
      - .offset:         296
        .size:           2
        .value_kind:     hidden_grid_dims
      - .offset:         352
        .size:           4
        .value_kind:     hidden_dynamic_lds_size
    .group_segment_fixed_size: 0
    .kernarg_segment_align: 8
    .kernarg_segment_size: 488
    .language:       OpenCL C
    .language_version:
      - 2
      - 0
    .max_flat_workgroup_size: 512
    .name:           _Z10fwd_kernelILi1ELi2EEv4Args
    .private_segment_fixed_size: 0
    .sgpr_count:     64
    .sgpr_spill_count: 0
    .symbol:         _Z10fwd_kernelILi1ELi2EEv4Args.kd
    .uniform_work_group_size: 1
    .uses_dynamic_stack: false
    .vgpr_count:     226
    .vgpr_spill_count: 0
    .wavefront_size: 64
  - .agpr_count:     0
    .args:
      - .offset:         0
        .size:           232
        .value_kind:     by_value
      - .offset:         232
        .size:           4
        .value_kind:     hidden_block_count_x
      - .offset:         236
        .size:           4
        .value_kind:     hidden_block_count_y
      - .offset:         240
        .size:           4
        .value_kind:     hidden_block_count_z
      - .offset:         244
        .size:           2
        .value_kind:     hidden_group_size_x
      - .offset:         246
        .size:           2
        .value_kind:     hidden_group_size_y
      - .offset:         248
        .size:           2
        .value_kind:     hidden_group_size_z
      - .offset:         250
        .size:           2
        .value_kind:     hidden_remainder_x
      - .offset:         252
        .size:           2
        .value_kind:     hidden_remainder_y
      - .offset:         254
        .size:           2
        .value_kind:     hidden_remainder_z
      - .offset:         272
        .size:           8
        .value_kind:     hidden_global_offset_x
      - .offset:         280
        .size:           8
        .value_kind:     hidden_global_offset_y
      - .offset:         288
        .size:           8
        .value_kind:     hidden_global_offset_z
      - .offset:         296
        .size:           2
        .value_kind:     hidden_grid_dims
      - .offset:         352
        .size:           4
        .value_kind:     hidden_dynamic_lds_size
    .group_segment_fixed_size: 0
    .kernarg_segment_align: 8
    .kernarg_segment_size: 488
    .language:       OpenCL C
    .language_version:
      - 2
      - 0
    .max_flat_workgroup_size: 512
    .name:           _Z10fwd_kernelILi2ELi3EEv4Args
    .private_segment_fixed_size: 0
    .sgpr_count:     106
    .sgpr_spill_count: 11
    .symbol:         _Z10fwd_kernelILi2ELi3EEv4Args.kd
    .uniform_work_group_size: 1
    .uses_dynamic_stack: false
    .vgpr_count:     252
    .vgpr_spill_count: 0
    .wavefront_size: 64
  - .agpr_count:     0
    .args:
      - .offset:         0
        .size:           232
        .value_kind:     by_value
      - .offset:         232
        .size:           4
        .value_kind:     hidden_block_count_x
      - .offset:         236
        .size:           4
        .value_kind:     hidden_block_count_y
      - .offset:         240
        .size:           4
        .value_kind:     hidden_block_count_z
      - .offset:         244
        .size:           2
        .value_kind:     hidden_group_size_x
      - .offset:         246
        .size:           2
        .value_kind:     hidden_group_size_y
      - .offset:         248
        .size:           2
        .value_kind:     hidden_group_size_z
      - .offset:         250
        .size:           2
        .value_kind:     hidden_remainder_x
      - .offset:         252
        .size:           2
        .value_kind:     hidden_remainder_y
      - .offset:         254
        .size:           2
        .value_kind:     hidden_remainder_z
      - .offset:         272
        .size:           8
        .value_kind:     hidden_global_offset_x
      - .offset:         280
        .size:           8
        .value_kind:     hidden_global_offset_y
      - .offset:         288
        .size:           8
        .value_kind:     hidden_global_offset_z
      - .offset:         296
        .size:           2
        .value_kind:     hidden_grid_dims
      - .offset:         352
        .size:           4
        .value_kind:     hidden_dynamic_lds_size
    .group_segment_fixed_size: 0
    .kernarg_segment_align: 8
    .kernarg_segment_size: 488
    .language:       OpenCL C
    .language_version:
      - 2
      - 0
    .max_flat_workgroup_size: 512
    .name:           _Z10fwd_kernelILi3ELi4EEv4Args
    .private_segment_fixed_size: 0
    .sgpr_count:     67
    .sgpr_spill_count: 0
    .symbol:         _Z10fwd_kernelILi3ELi4EEv4Args.kd
    .uniform_work_group_size: 1
    .uses_dynamic_stack: false
    .vgpr_count:     240
    .vgpr_spill_count: 0
    .wavefront_size: 64
  - .agpr_count:     0
    .args:
      - .offset:         0
        .size:           232
        .value_kind:     by_value
      - .offset:         232
        .size:           4
        .value_kind:     hidden_block_count_x
      - .offset:         236
        .size:           4
        .value_kind:     hidden_block_count_y
      - .offset:         240
        .size:           4
        .value_kind:     hidden_block_count_z
      - .offset:         244
        .size:           2
        .value_kind:     hidden_group_size_x
      - .offset:         246
        .size:           2
        .value_kind:     hidden_group_size_y
      - .offset:         248
        .size:           2
        .value_kind:     hidden_group_size_z
      - .offset:         250
        .size:           2
        .value_kind:     hidden_remainder_x
      - .offset:         252
        .size:           2
        .value_kind:     hidden_remainder_y
      - .offset:         254
        .size:           2
        .value_kind:     hidden_remainder_z
      - .offset:         272
        .size:           8
        .value_kind:     hidden_global_offset_x
      - .offset:         280
        .size:           8
        .value_kind:     hidden_global_offset_y
      - .offset:         288
        .size:           8
        .value_kind:     hidden_global_offset_z
      - .offset:         296
        .size:           2
        .value_kind:     hidden_grid_dims
    .group_segment_fixed_size: 0
    .kernarg_segment_align: 8
    .kernarg_segment_size: 488
    .language:       OpenCL C
    .language_version:
      - 2
      - 0
    .max_flat_workgroup_size: 512
    .name:           _Z10fwd_kernelILi4ELi5EEv4Args
    .private_segment_fixed_size: 0
    .sgpr_count:     66
    .sgpr_spill_count: 0
    .symbol:         _Z10fwd_kernelILi4ELi5EEv4Args.kd
    .uniform_work_group_size: 1
    .uses_dynamic_stack: false
    .vgpr_count:     256
    .vgpr_spill_count: 0
    .wavefront_size: 64
  - .agpr_count:     0
    .args:
      - .offset:         0
        .size:           232
        .value_kind:     by_value
      - .offset:         232
        .size:           4
        .value_kind:     hidden_block_count_x
      - .offset:         236
        .size:           4
        .value_kind:     hidden_block_count_y
      - .offset:         240
        .size:           4
        .value_kind:     hidden_block_count_z
      - .offset:         244
        .size:           2
        .value_kind:     hidden_group_size_x
      - .offset:         246
        .size:           2
        .value_kind:     hidden_group_size_y
      - .offset:         248
        .size:           2
        .value_kind:     hidden_group_size_z
      - .offset:         250
        .size:           2
        .value_kind:     hidden_remainder_x
      - .offset:         252
        .size:           2
        .value_kind:     hidden_remainder_y
      - .offset:         254
        .size:           2
        .value_kind:     hidden_remainder_z
      - .offset:         272
        .size:           8
        .value_kind:     hidden_global_offset_x
      - .offset:         280
        .size:           8
        .value_kind:     hidden_global_offset_y
      - .offset:         288
        .size:           8
        .value_kind:     hidden_global_offset_z
      - .offset:         296
        .size:           2
        .value_kind:     hidden_grid_dims
      - .offset:         352
        .size:           4
        .value_kind:     hidden_dynamic_lds_size
    .group_segment_fixed_size: 0
    .kernarg_segment_align: 8
    .kernarg_segment_size: 488
    .language:       OpenCL C
    .language_version:
      - 2
      - 0
    .max_flat_workgroup_size: 512
    .name:           _Z10fwd_kernelILi5ELi6EEv4Args
    .private_segment_fixed_size: 0
    .sgpr_count:     68
    .sgpr_spill_count: 0
    .symbol:         _Z10fwd_kernelILi5ELi6EEv4Args.kd
    .uniform_work_group_size: 1
    .uses_dynamic_stack: false
    .vgpr_count:     224
    .vgpr_spill_count: 0
    .wavefront_size: 64
  - .agpr_count:     0
    .args:
      - .offset:         0
        .size:           232
        .value_kind:     by_value
      - .offset:         232
        .size:           4
        .value_kind:     hidden_block_count_x
      - .offset:         236
        .size:           4
        .value_kind:     hidden_block_count_y
      - .offset:         240
        .size:           4
        .value_kind:     hidden_block_count_z
      - .offset:         244
        .size:           2
        .value_kind:     hidden_group_size_x
      - .offset:         246
        .size:           2
        .value_kind:     hidden_group_size_y
      - .offset:         248
        .size:           2
        .value_kind:     hidden_group_size_z
      - .offset:         250
        .size:           2
        .value_kind:     hidden_remainder_x
      - .offset:         252
        .size:           2
        .value_kind:     hidden_remainder_y
      - .offset:         254
        .size:           2
        .value_kind:     hidden_remainder_z
      - .offset:         272
        .size:           8
        .value_kind:     hidden_global_offset_x
      - .offset:         280
        .size:           8
        .value_kind:     hidden_global_offset_y
      - .offset:         288
        .size:           8
        .value_kind:     hidden_global_offset_z
      - .offset:         296
        .size:           2
        .value_kind:     hidden_grid_dims
      - .offset:         352
        .size:           4
        .value_kind:     hidden_dynamic_lds_size
    .group_segment_fixed_size: 0
    .kernarg_segment_align: 8
    .kernarg_segment_size: 488
    .language:       OpenCL C
    .language_version:
      - 2
      - 0
    .max_flat_workgroup_size: 512
    .name:           _Z10fwd_kernelILi6ELi7EEv4Args
    .private_segment_fixed_size: 0
    .sgpr_count:     67
    .sgpr_spill_count: 0
    .symbol:         _Z10fwd_kernelILi6ELi7EEv4Args.kd
    .uniform_work_group_size: 1
    .uses_dynamic_stack: false
    .vgpr_count:     240
    .vgpr_spill_count: 0
    .wavefront_size: 64
  - .agpr_count:     0
    .args:
      - .offset:         0
        .size:           232
        .value_kind:     by_value
      - .offset:         232
        .size:           4
        .value_kind:     hidden_block_count_x
      - .offset:         236
        .size:           4
        .value_kind:     hidden_block_count_y
      - .offset:         240
        .size:           4
        .value_kind:     hidden_block_count_z
      - .offset:         244
        .size:           2
        .value_kind:     hidden_group_size_x
      - .offset:         246
        .size:           2
        .value_kind:     hidden_group_size_y
      - .offset:         248
        .size:           2
        .value_kind:     hidden_group_size_z
      - .offset:         250
        .size:           2
        .value_kind:     hidden_remainder_x
      - .offset:         252
        .size:           2
        .value_kind:     hidden_remainder_y
      - .offset:         254
        .size:           2
        .value_kind:     hidden_remainder_z
      - .offset:         272
        .size:           8
        .value_kind:     hidden_global_offset_x
      - .offset:         280
        .size:           8
        .value_kind:     hidden_global_offset_y
      - .offset:         288
        .size:           8
        .value_kind:     hidden_global_offset_z
      - .offset:         296
        .size:           2
        .value_kind:     hidden_grid_dims
    .group_segment_fixed_size: 0
    .kernarg_segment_align: 8
    .kernarg_segment_size: 488
    .language:       OpenCL C
    .language_version:
      - 2
      - 0
    .max_flat_workgroup_size: 512
    .name:           _Z10fwd_kernelILi7ELi8EEv4Args
    .private_segment_fixed_size: 0
    .sgpr_count:     66
    .sgpr_spill_count: 0
    .symbol:         _Z10fwd_kernelILi7ELi8EEv4Args.kd
    .uniform_work_group_size: 1
    .uses_dynamic_stack: false
    .vgpr_count:     256
    .vgpr_spill_count: 0
    .wavefront_size: 64
  - .agpr_count:     0
    .args:
      - .offset:         0
        .size:           232
        .value_kind:     by_value
      - .offset:         232
        .size:           4
        .value_kind:     hidden_block_count_x
      - .offset:         236
        .size:           4
        .value_kind:     hidden_block_count_y
      - .offset:         240
        .size:           4
        .value_kind:     hidden_block_count_z
      - .offset:         244
        .size:           2
        .value_kind:     hidden_group_size_x
      - .offset:         246
        .size:           2
        .value_kind:     hidden_group_size_y
      - .offset:         248
        .size:           2
        .value_kind:     hidden_group_size_z
      - .offset:         250
        .size:           2
        .value_kind:     hidden_remainder_x
      - .offset:         252
        .size:           2
        .value_kind:     hidden_remainder_y
      - .offset:         254
        .size:           2
        .value_kind:     hidden_remainder_z
      - .offset:         272
        .size:           8
        .value_kind:     hidden_global_offset_x
      - .offset:         280
        .size:           8
        .value_kind:     hidden_global_offset_y
      - .offset:         288
        .size:           8
        .value_kind:     hidden_global_offset_z
      - .offset:         296
        .size:           2
        .value_kind:     hidden_grid_dims
      - .offset:         352
        .size:           4
        .value_kind:     hidden_dynamic_lds_size
    .group_segment_fixed_size: 0
    .kernarg_segment_align: 8
    .kernarg_segment_size: 488
    .language:       OpenCL C
    .language_version:
      - 2
      - 0
    .max_flat_workgroup_size: 512
    .name:           _Z10fwd_kernelILi8ELi9EEv4Args
    .private_segment_fixed_size: 0
    .sgpr_count:     75
    .sgpr_spill_count: 0
    .symbol:         _Z10fwd_kernelILi8ELi9EEv4Args.kd
    .uniform_work_group_size: 1
    .uses_dynamic_stack: false
    .vgpr_count:     226
    .vgpr_spill_count: 0
    .wavefront_size: 64
  - .agpr_count:     0
    .args:
      - .offset:         0
        .size:           232
        .value_kind:     by_value
      - .offset:         232
        .size:           4
        .value_kind:     hidden_block_count_x
      - .offset:         236
        .size:           4
        .value_kind:     hidden_block_count_y
      - .offset:         240
        .size:           4
        .value_kind:     hidden_block_count_z
      - .offset:         244
        .size:           2
        .value_kind:     hidden_group_size_x
      - .offset:         246
        .size:           2
        .value_kind:     hidden_group_size_y
      - .offset:         248
        .size:           2
        .value_kind:     hidden_group_size_z
      - .offset:         250
        .size:           2
        .value_kind:     hidden_remainder_x
      - .offset:         252
        .size:           2
        .value_kind:     hidden_remainder_y
      - .offset:         254
        .size:           2
        .value_kind:     hidden_remainder_z
      - .offset:         272
        .size:           8
        .value_kind:     hidden_global_offset_x
      - .offset:         280
        .size:           8
        .value_kind:     hidden_global_offset_y
      - .offset:         288
        .size:           8
        .value_kind:     hidden_global_offset_z
      - .offset:         296
        .size:           2
        .value_kind:     hidden_grid_dims
      - .offset:         352
        .size:           4
        .value_kind:     hidden_dynamic_lds_size
    .group_segment_fixed_size: 0
    .kernarg_segment_align: 8
    .kernarg_segment_size: 488
    .language:       OpenCL C
    .language_version:
      - 2
      - 0
    .max_flat_workgroup_size: 512
    .name:           _Z10fwd_kernelILi9ELi10EEv4Args
    .private_segment_fixed_size: 0
    .sgpr_count:     82
    .sgpr_spill_count: 0
    .symbol:         _Z10fwd_kernelILi9ELi10EEv4Args.kd
    .uniform_work_group_size: 1
    .uses_dynamic_stack: false
    .vgpr_count:     200
    .vgpr_spill_count: 0
    .wavefront_size: 64
  - .agpr_count:     0
    .args:
      - .offset:         0
        .size:           232
        .value_kind:     by_value
      - .offset:         232
        .size:           4
        .value_kind:     hidden_block_count_x
      - .offset:         236
        .size:           4
        .value_kind:     hidden_block_count_y
      - .offset:         240
        .size:           4
        .value_kind:     hidden_block_count_z
      - .offset:         244
        .size:           2
        .value_kind:     hidden_group_size_x
      - .offset:         246
        .size:           2
        .value_kind:     hidden_group_size_y
      - .offset:         248
        .size:           2
        .value_kind:     hidden_group_size_z
      - .offset:         250
        .size:           2
        .value_kind:     hidden_remainder_x
      - .offset:         252
        .size:           2
        .value_kind:     hidden_remainder_y
      - .offset:         254
        .size:           2
        .value_kind:     hidden_remainder_z
      - .offset:         272
        .size:           8
        .value_kind:     hidden_global_offset_x
      - .offset:         280
        .size:           8
        .value_kind:     hidden_global_offset_y
      - .offset:         288
        .size:           8
        .value_kind:     hidden_global_offset_z
      - .offset:         296
        .size:           2
        .value_kind:     hidden_grid_dims
      - .offset:         352
        .size:           4
        .value_kind:     hidden_dynamic_lds_size
    .group_segment_fixed_size: 0
    .kernarg_segment_align: 8
    .kernarg_segment_size: 488
    .language:       OpenCL C
    .language_version:
      - 2
      - 0
    .max_flat_workgroup_size: 512
    .name:           _Z10fwd_kernelILi10ELi11EEv4Args
    .private_segment_fixed_size: 0
    .sgpr_count:     67
    .sgpr_spill_count: 0
    .symbol:         _Z10fwd_kernelILi10ELi11EEv4Args.kd
    .uniform_work_group_size: 1
    .uses_dynamic_stack: false
    .vgpr_count:     240
    .vgpr_spill_count: 0
    .wavefront_size: 64
  - .agpr_count:     0
    .args:
      - .offset:         0
        .size:           232
        .value_kind:     by_value
      - .offset:         232
        .size:           4
        .value_kind:     hidden_block_count_x
      - .offset:         236
        .size:           4
        .value_kind:     hidden_block_count_y
      - .offset:         240
        .size:           4
        .value_kind:     hidden_block_count_z
      - .offset:         244
        .size:           2
        .value_kind:     hidden_group_size_x
      - .offset:         246
        .size:           2
        .value_kind:     hidden_group_size_y
      - .offset:         248
        .size:           2
        .value_kind:     hidden_group_size_z
      - .offset:         250
        .size:           2
        .value_kind:     hidden_remainder_x
      - .offset:         252
        .size:           2
        .value_kind:     hidden_remainder_y
      - .offset:         254
        .size:           2
        .value_kind:     hidden_remainder_z
      - .offset:         272
        .size:           8
        .value_kind:     hidden_global_offset_x
      - .offset:         280
        .size:           8
        .value_kind:     hidden_global_offset_y
      - .offset:         288
        .size:           8
        .value_kind:     hidden_global_offset_z
      - .offset:         296
        .size:           2
        .value_kind:     hidden_grid_dims
    .group_segment_fixed_size: 0
    .kernarg_segment_align: 8
    .kernarg_segment_size: 488
    .language:       OpenCL C
    .language_version:
      - 2
      - 0
    .max_flat_workgroup_size: 512
    .name:           _Z10fwd_kernelILi11ELi12EEv4Args
    .private_segment_fixed_size: 0
    .sgpr_count:     66
    .sgpr_spill_count: 0
    .symbol:         _Z10fwd_kernelILi11ELi12EEv4Args.kd
    .uniform_work_group_size: 1
    .uses_dynamic_stack: false
    .vgpr_count:     256
    .vgpr_spill_count: 0
    .wavefront_size: 64
  - .agpr_count:     0
    .args:
      - .offset:         0
        .size:           232
        .value_kind:     by_value
      - .offset:         232
        .size:           4
        .value_kind:     hidden_block_count_x
      - .offset:         236
        .size:           4
        .value_kind:     hidden_block_count_y
      - .offset:         240
        .size:           4
        .value_kind:     hidden_block_count_z
      - .offset:         244
        .size:           2
        .value_kind:     hidden_group_size_x
      - .offset:         246
        .size:           2
        .value_kind:     hidden_group_size_y
      - .offset:         248
        .size:           2
        .value_kind:     hidden_group_size_z
      - .offset:         250
        .size:           2
        .value_kind:     hidden_remainder_x
      - .offset:         252
        .size:           2
        .value_kind:     hidden_remainder_y
      - .offset:         254
        .size:           2
        .value_kind:     hidden_remainder_z
      - .offset:         272
        .size:           8
        .value_kind:     hidden_global_offset_x
      - .offset:         280
        .size:           8
        .value_kind:     hidden_global_offset_y
      - .offset:         288
        .size:           8
        .value_kind:     hidden_global_offset_z
      - .offset:         296
        .size:           2
        .value_kind:     hidden_grid_dims
      - .offset:         352
        .size:           4
        .value_kind:     hidden_dynamic_lds_size
    .group_segment_fixed_size: 0
    .kernarg_segment_align: 8
    .kernarg_segment_size: 488
    .language:       OpenCL C
    .language_version:
      - 2
      - 0
    .max_flat_workgroup_size: 512
    .name:           _Z10fwd_kernelILi12ELi13EEv4Args
    .private_segment_fixed_size: 0
    .sgpr_count:     68
    .sgpr_spill_count: 0
    .symbol:         _Z10fwd_kernelILi12ELi13EEv4Args.kd
    .uniform_work_group_size: 1
    .uses_dynamic_stack: false
    .vgpr_count:     224
    .vgpr_spill_count: 0
    .wavefront_size: 64
  - .agpr_count:     0
    .args:
      - .offset:         0
        .size:           232
        .value_kind:     by_value
      - .offset:         232
        .size:           4
        .value_kind:     hidden_block_count_x
      - .offset:         236
        .size:           4
        .value_kind:     hidden_block_count_y
      - .offset:         240
        .size:           4
        .value_kind:     hidden_block_count_z
      - .offset:         244
        .size:           2
        .value_kind:     hidden_group_size_x
      - .offset:         246
        .size:           2
        .value_kind:     hidden_group_size_y
      - .offset:         248
        .size:           2
        .value_kind:     hidden_group_size_z
      - .offset:         250
        .size:           2
        .value_kind:     hidden_remainder_x
      - .offset:         252
        .size:           2
        .value_kind:     hidden_remainder_y
      - .offset:         254
        .size:           2
        .value_kind:     hidden_remainder_z
      - .offset:         272
        .size:           8
        .value_kind:     hidden_global_offset_x
      - .offset:         280
        .size:           8
        .value_kind:     hidden_global_offset_y
      - .offset:         288
        .size:           8
        .value_kind:     hidden_global_offset_z
      - .offset:         296
        .size:           2
        .value_kind:     hidden_grid_dims
      - .offset:         352
        .size:           4
        .value_kind:     hidden_dynamic_lds_size
    .group_segment_fixed_size: 0
    .kernarg_segment_align: 8
    .kernarg_segment_size: 488
    .language:       OpenCL C
    .language_version:
      - 2
      - 0
    .max_flat_workgroup_size: 512
    .name:           _Z10fwd_kernelILi13ELi14EEv4Args
    .private_segment_fixed_size: 0
    .sgpr_count:     67
    .sgpr_spill_count: 0
    .symbol:         _Z10fwd_kernelILi13ELi14EEv4Args.kd
    .uniform_work_group_size: 1
    .uses_dynamic_stack: false
    .vgpr_count:     240
    .vgpr_spill_count: 0
    .wavefront_size: 64
  - .agpr_count:     0
    .args:
      - .offset:         0
        .size:           232
        .value_kind:     by_value
      - .offset:         232
        .size:           4
        .value_kind:     hidden_block_count_x
      - .offset:         236
        .size:           4
        .value_kind:     hidden_block_count_y
      - .offset:         240
        .size:           4
        .value_kind:     hidden_block_count_z
      - .offset:         244
        .size:           2
        .value_kind:     hidden_group_size_x
      - .offset:         246
        .size:           2
        .value_kind:     hidden_group_size_y
      - .offset:         248
        .size:           2
        .value_kind:     hidden_group_size_z
      - .offset:         250
        .size:           2
        .value_kind:     hidden_remainder_x
      - .offset:         252
        .size:           2
        .value_kind:     hidden_remainder_y
      - .offset:         254
        .size:           2
        .value_kind:     hidden_remainder_z
      - .offset:         272
        .size:           8
        .value_kind:     hidden_global_offset_x
      - .offset:         280
        .size:           8
        .value_kind:     hidden_global_offset_y
      - .offset:         288
        .size:           8
        .value_kind:     hidden_global_offset_z
      - .offset:         296
        .size:           2
        .value_kind:     hidden_grid_dims
    .group_segment_fixed_size: 0
    .kernarg_segment_align: 8
    .kernarg_segment_size: 488
    .language:       OpenCL C
    .language_version:
      - 2
      - 0
    .max_flat_workgroup_size: 512
    .name:           _Z10fwd_kernelILi14ELi15EEv4Args
    .private_segment_fixed_size: 0
    .sgpr_count:     66
    .sgpr_spill_count: 0
    .symbol:         _Z10fwd_kernelILi14ELi15EEv4Args.kd
    .uniform_work_group_size: 1
    .uses_dynamic_stack: false
    .vgpr_count:     256
    .vgpr_spill_count: 0
    .wavefront_size: 64
